# GEMM main loops: compiler's repeated lgkmcnt(0) after s_setprio 1 at each MMA segment head deleted (already waited before the barrier)
# baseline (speedup 1.0000x reference)
; #define PG8_STAGE(bufoff, gbase, voff) do { _Pragma("unroll") for (int _i = 0; _i < 2; ++_i) \
;         __builtin_amdgcn_global_load_lds((const unsigned*)((const char*)(gbase) + (voff)[_i]), (PG8_LAS unsigned*)(lds + (bufoff) + ldsw + _i * 8192), 16, 0, 0); } while (0)
; #define PG8_LDA(dst, b, h) do { _Pragma("unroll") for (int m = 0; m < 4; ++m) _Pragma("unroll") for (int k = 0; k < 2; ++k) dst[m][k] = *(const PG8_LAS bf16x8*)(lds + PG8_SA(b, h) + aoff + m * 2048 + k * 1024); } while (0)
; #define PG8_LDB(dst, b, h) do { _Pragma("unroll") for (int n = 0; n < 2; ++n) _Pragma("unroll") for (int k = 0; k < 2; ++k) dst[n][k] = *(const PG8_LAS bf16x8*)(lds + PG8_SB(b, h) + boff + n * 2048 + k * 1024); } while (0)
; #define PG8_MMA(ai, bj, At, Bt) do { __builtin_amdgcn_s_setprio(1); _Pragma("unroll") for (int m = 0; m < 4; ++m) _Pragma("unroll") for (int n = 0; n < 2; ++n) _Pragma("unroll") for (int k = 0; k < 2; ++k) \
;         acc[ai][bj][m][n] = __builtin_amdgcn_mfma_f32_16x16x32_bf16(Bt[n][k], At[m][k], acc[ai][bj][m][n], 0, 0, 0); __builtin_amdgcn_s_setprio(0); } while (0)
; #define PG8_WAIT_V(n) asm volatile("s_waitcnt vmcnt(" #n ")" ::: "memory")
; #define PG8_WAIT_L(n) asm volatile("s_waitcnt lgkmcnt(" #n ")" ::: "memory")
; template <class Epi, class Sched, bool ALIGN_EPI = false, bool SP2 = false>
; __device__ __forceinline__ void gemm_phase(PG8_LAS unsigned char* lds, const Gemm g, const Sched& S, const Epi& E, int tid_in) {
;     ...
;             const char* a1 = cA + (size_t)(t + 1) * kstep + (t >= jt ? jb : 0);
;             const char* a2 = last ? nA : cA + (size_t)(t + 2) * kstep + (t + 2 >= jt ? jb : 0); const char* b2 = last ? nB : cB + (size_t)(t + 2) * kstep;
;             const char* a3 = a2 + kstep; const char* b3 = b2 + kstep;
;             if (last && has_next) S.a_ready(nxt);
;             if constexpr (SP2) {
;             PG8_LDB(B0, 0, 0); PG8_LDB(B1, 0, 1); PG8_SCHED; PG8_LDA(At, 0, 0); PG8_STAGE(PG8_SA(1, 1), a1 + hsA, voffA);
;             PG8_WAIT_V(8); PG8_WAIT_L(0); PG8_BAR; PG8_MMA(0, 0, At, B0); PG8_MMA(0, 1, At, B1); PG8_BAR; PG8_SCHED;
;             PG8_LDA(At, 0, 1); PG8_STAGE(PG8_SB(0, 0), b2, voffB); PG8_STAGE(PG8_SB(0, 1), b2 + hsB, voffB); PG8_STAGE(PG8_SA(0, 0), a2, voffA);
;             PG8_WAIT_V(8); PG8_WAIT_L(0); PG8_BAR; PG8_MMA(1, 0, At, B0); PG8_MMA(1, 1, At, B1); PG8_BAR; PG8_SCHED;
.LBB0_244:
	s_add_i32 s24, s53, -2
	s_cmp_ge_i32 s24, s28
	s_cselect_b32 s54, s29, 0
	s_cselect_b32 s55, s44, 0
	s_cmp_ge_i32 s53, s28
	s_cselect_b32 s25, s29, 0
	s_cselect_b32 s24, s44, 0
	s_add_u32 s25, s22, s25
	s_addc_u32 s24, s23, s24
	s_add_u32 s58, s25, 0x80
	s_addc_u32 s24, s24, 0
	s_add_i32 s60, 0, 0x10000
	s_cmp_eq_u32 s43, s53
	s_cselect_b32 s25, s5, s24
	s_cselect_b32 s24, s4, s58
	s_cselect_b32 s59, s21, s52
	s_cselect_b32 s58, s20, s51
	s_add_i32 s61, 0, 0x14000
	v_add_u32_e32 v160, s60, v142
	v_add_u32_e32 v176, s61, v142
	ds_read_b128 v[148:151], v160
	ds_read_b128 v[152:155], v160 offset:1024
	ds_read_b128 v[156:159], v160 offset:2048
	ds_read_b128 v[160:163], v160 offset:3072
	ds_read_b128 v[164:167], v176
	ds_read_b128 v[168:171], v176 offset:1024
	ds_read_b128 v[172:175], v176 offset:2048
	ds_read_b128 v[176:179], v176 offset:3072
	v_lshl_add_u64 v[230:231], s[22:23], 0, v[140:141]
	v_lshl_add_u64 v[230:231], v[230:231], 0, s[54:55]
	s_add_i32 m0, s37, 0xc000
	ds_read_b128 v[180:183], v147
	ds_read_b128 v[184:187], v147 offset:1024
	ds_read_b128 v[188:191], v147 offset:2048
	ds_read_b128 v[204:207], v147 offset:3072
	ds_read_b128 v[208:211], v147 offset:4096
	ds_read_b128 v[212:215], v147 offset:5120
	ds_read_b128 v[216:219], v147 offset:6144
	ds_read_b128 v[220:223], v147 offset:7168
	global_load_lds_dwordx4 v[230:231], off
	v_lshl_add_u64 v[230:231], s[22:23], 0, v[138:139]
	v_lshl_add_u64 v[230:231], v[230:231], 0, s[54:55]
	s_add_i32 m0, s37, 0xe000
	s_nop 0
	global_load_lds_dwordx4 v[230:231], off
	s_waitcnt vmcnt(8)
	s_waitcnt lgkmcnt(0)
	s_barrier
	s_setprio 1
	v_mfma_f32_16x16x32_bf16 v[124:127], v[148:151], v[180:183], v[124:127]
	v_mfma_f32_16x16x32_bf16 v[120:123], v[156:159], v[180:183], v[120:123]
	v_mfma_f32_16x16x32_bf16 v[112:115], v[148:151], v[188:191], v[112:115]
	v_mfma_f32_16x16x32_bf16 v[104:107], v[156:159], v[188:191], v[104:107]
	v_mfma_f32_16x16x32_bf16 v[96:99], v[148:151], v[208:211], v[96:99]
	v_mfma_f32_16x16x32_bf16 v[88:91], v[156:159], v[208:211], v[88:91]
	v_mfma_f32_16x16x32_bf16 v[80:83], v[148:151], v[216:219], v[80:83]
	v_mfma_f32_16x16x32_bf16 v[72:75], v[156:159], v[216:219], v[72:75]
	v_mfma_f32_16x16x32_bf16 v[124:127], v[152:155], v[184:187], v[124:127]
	v_mfma_f32_16x16x32_bf16 v[120:123], v[160:163], v[184:187], v[120:123]
	v_mfma_f32_16x16x32_bf16 v[112:115], v[152:155], v[204:207], v[112:115]
	v_mfma_f32_16x16x32_bf16 v[104:107], v[160:163], v[204:207], v[104:107]
	v_mfma_f32_16x16x32_bf16 v[96:99], v[152:155], v[212:215], v[96:99]
	v_mfma_f32_16x16x32_bf16 v[88:91], v[160:163], v[212:215], v[88:91]
	v_mfma_f32_16x16x32_bf16 v[80:83], v[152:155], v[220:223], v[80:83]
	v_mfma_f32_16x16x32_bf16 v[72:75], v[160:163], v[220:223], v[72:75]
	s_setprio 0
	s_setprio 1
	v_mfma_f32_16x16x32_bf16 v[128:131], v[164:167], v[180:183], v[128:131]
	v_mfma_f32_16x16x32_bf16 v[116:119], v[172:175], v[180:183], v[116:119]
	v_mfma_f32_16x16x32_bf16 v[108:111], v[164:167], v[188:191], v[108:111]
	v_mfma_f32_16x16x32_bf16 v[100:103], v[172:175], v[188:191], v[100:103]
	v_mfma_f32_16x16x32_bf16 v[92:95], v[164:167], v[208:211], v[92:95]
	v_mfma_f32_16x16x32_bf16 v[84:87], v[172:175], v[208:211], v[84:87]
	v_mfma_f32_16x16x32_bf16 v[76:79], v[164:167], v[216:219], v[76:79]
	v_mfma_f32_16x16x32_bf16 v[68:71], v[172:175], v[216:219], v[68:71]
	v_mfma_f32_16x16x32_bf16 v[128:131], v[168:171], v[184:187], v[128:131]
	v_mfma_f32_16x16x32_bf16 v[116:119], v[176:179], v[184:187], v[116:119]
	v_mfma_f32_16x16x32_bf16 v[108:111], v[168:171], v[204:207], v[108:111]
	v_mfma_f32_16x16x32_bf16 v[100:103], v[176:179], v[204:207], v[100:103]
	v_mfma_f32_16x16x32_bf16 v[92:95], v[168:171], v[212:215], v[92:95]
	v_mfma_f32_16x16x32_bf16 v[84:87], v[176:179], v[212:215], v[84:87]
	v_mfma_f32_16x16x32_bf16 v[76:79], v[168:171], v[220:223], v[76:79]
	v_mfma_f32_16x16x32_bf16 v[68:71], v[176:179], v[220:223], v[68:71]
	s_setprio 0
	s_barrier
	s_add_i32 s54, s60, s35
	v_lshl_add_u64 v[230:231], s[58:59], 0, v[134:135]
	s_mov_b32 m0, s54
	ds_read_b128 v[180:183], v147 offset:16384
	ds_read_b128 v[184:187], v147 offset:17408
	ds_read_b128 v[188:191], v147 offset:18432
	ds_read_b128 v[204:207], v147 offset:19456
	ds_read_b128 v[208:211], v147 offset:20480
	ds_read_b128 v[212:215], v147 offset:21504
	ds_read_b128 v[216:219], v147 offset:22528
	ds_read_b128 v[220:223], v147 offset:23552
	global_load_lds_dwordx4 v[230:231], off
	s_add_i32 m0, s54, 0x2000
	s_add_u32 s54, s58, s6
	v_lshl_add_u64 v[232:233], s[58:59], 0, v[0:1]
	s_addc_u32 s55, s59, s7
	s_add_i32 s58, s61, s35
	global_load_lds_dwordx4 v[232:233], off
	v_lshl_add_u64 v[238:239], s[54:55], 0, v[134:135]
	s_mov_b32 m0, s58
	v_lshl_add_u64 v[240:241], s[54:55], 0, v[0:1]
	global_load_lds_dwordx4 v[238:239], off
	s_add_i32 m0, s58, 0x2000
	v_lshl_add_u64 v[242:243], s[24:25], 0, v[136:137]
	global_load_lds_dwordx4 v[240:241], off
	s_mov_b32 m0, s37
	v_lshl_add_u64 v[244:245], s[24:25], 0, v[132:133]
	global_load_lds_dwordx4 v[242:243], off
	s_mov_b32 m0, s38
	s_nop 0
	global_load_lds_dwordx4 v[244:245], off
	s_waitcnt vmcnt(8)
	s_waitcnt lgkmcnt(0)
	s_barrier
; #define PG8_STAGE(bufoff, gbase, voff) do { _Pragma("unroll") for (int _i = 0; _i < 2; ++_i) \
;         __builtin_amdgcn_global_load_lds((const unsigned*)((const char*)(gbase) + (voff)[_i]), (PG8_LAS unsigned*)(lds + (bufoff) + ldsw + _i * 8192), 16, 0, 0); } while (0)
; #define PG8_LDA(dst, b, h) do { _Pragma("unroll") for (int m = 0; m < 4; ++m) _Pragma("unroll") for (int k = 0; k < 2; ++k) dst[m][k] = *(const PG8_LAS bf16x8*)(lds + PG8_SA(b, h) + aoff + m * 2048 + k * 1024); } while (0)
; #define PG8_LDB(dst, b, h) do { _Pragma("unroll") for (int n = 0; n < 2; ++n) _Pragma("unroll") for (int k = 0; k < 2; ++k) dst[n][k] = *(const PG8_LAS bf16x8*)(lds + PG8_SB(b, h) + boff + n * 2048 + k * 1024); } while (0)
; #define PG8_MMA(ai, bj, At, Bt) do { __builtin_amdgcn_s_setprio(1); _Pragma("unroll") for (int m = 0; m < 4; ++m) _Pragma("unroll") for (int n = 0; n < 2; ++n) _Pragma("unroll") for (int k = 0; k < 2; ++k) \
;         acc[ai][bj][m][n] = __builtin_amdgcn_mfma_f32_16x16x32_bf16(Bt[n][k], At[m][k], acc[ai][bj][m][n], 0, 0, 0); __builtin_amdgcn_s_setprio(0); } while (0)
; #define PG8_WAIT_V(n) asm volatile("s_waitcnt vmcnt(" #n ")" ::: "memory")
; #define PG8_WAIT_L(n) asm volatile("s_waitcnt lgkmcnt(" #n ")" ::: "memory")
; #define PG8_BAR __builtin_amdgcn_s_barrier()
; #define PG8_SCHED __builtin_amdgcn_sched_barrier(0)
; template <class Epi, class Sched, bool ALIGN_EPI = false, bool SP2 = false>
; __device__ __forceinline__ void gemm_phase(PG8_LAS unsigned char* lds, const Gemm g, const Sched& S, const Epi& E, int tid_in) {
;     ...
;             PG8_WAIT_V(8); PG8_WAIT_L(0); PG8_BAR; PG8_MMA(1, 0, At, B0); PG8_MMA(1, 1, At, B1); PG8_BAR; PG8_SCHED;
;             PG8_LDB(B0, 1, 0); PG8_LDB(B1, 1, 1); PG8_SCHED; PG8_LDA(At, 1, 0); PG8_STAGE(PG8_SA(0, 1), a2 + hsA, voffA);
;             PG8_WAIT_V(8); PG8_WAIT_L(0); PG8_BAR; PG8_MMA(0, 0, At, B0); PG8_MMA(0, 1, At, B1); PG8_BAR; PG8_SCHED;
	s_setprio 1
	v_mfma_f32_16x16x32_bf16 v[64:67], v[148:151], v[180:183], v[64:67]
	v_mfma_f32_16x16x32_bf16 v[56:59], v[156:159], v[180:183], v[56:59]
	v_mfma_f32_16x16x32_bf16 v[48:51], v[148:151], v[188:191], v[48:51]
	v_mfma_f32_16x16x32_bf16 v[40:43], v[156:159], v[188:191], v[40:43]
	v_mfma_f32_16x16x32_bf16 v[32:35], v[148:151], v[208:211], v[32:35]
	v_mfma_f32_16x16x32_bf16 v[24:27], v[156:159], v[208:211], v[24:27]
	v_mfma_f32_16x16x32_bf16 v[16:19], v[148:151], v[216:219], v[16:19]
	v_mfma_f32_16x16x32_bf16 v[8:11], v[156:159], v[216:219], v[8:11]
	v_mfma_f32_16x16x32_bf16 v[64:67], v[152:155], v[184:187], v[64:67]
	v_mfma_f32_16x16x32_bf16 v[56:59], v[160:163], v[184:187], v[56:59]
	v_mfma_f32_16x16x32_bf16 v[48:51], v[152:155], v[204:207], v[48:51]
	v_mfma_f32_16x16x32_bf16 v[40:43], v[160:163], v[204:207], v[40:43]
	v_mfma_f32_16x16x32_bf16 v[32:35], v[152:155], v[212:215], v[32:35]
	v_mfma_f32_16x16x32_bf16 v[24:27], v[160:163], v[212:215], v[24:27]
	v_mfma_f32_16x16x32_bf16 v[16:19], v[152:155], v[220:223], v[16:19]
	v_mfma_f32_16x16x32_bf16 v[8:11], v[160:163], v[220:223], v[8:11]
	s_setprio 0
	s_setprio 1
	v_mfma_f32_16x16x32_bf16 v[60:63], v[164:167], v[180:183], v[60:63]
	v_mfma_f32_16x16x32_bf16 v[52:55], v[172:175], v[180:183], v[52:55]
	v_mfma_f32_16x16x32_bf16 v[44:47], v[164:167], v[188:191], v[44:47]
	v_mfma_f32_16x16x32_bf16 v[36:39], v[172:175], v[188:191], v[36:39]
	v_mfma_f32_16x16x32_bf16 v[28:31], v[164:167], v[208:211], v[28:31]
	v_mfma_f32_16x16x32_bf16 v[20:23], v[172:175], v[208:211], v[20:23]
	v_mfma_f32_16x16x32_bf16 v[12:15], v[164:167], v[216:219], v[12:15]
	v_mfma_f32_16x16x32_bf16 v[4:7], v[172:175], v[216:219], v[4:7]
	v_mfma_f32_16x16x32_bf16 v[60:63], v[168:171], v[184:187], v[60:63]
	v_mfma_f32_16x16x32_bf16 v[52:55], v[176:179], v[184:187], v[52:55]
	v_mfma_f32_16x16x32_bf16 v[44:47], v[168:171], v[204:207], v[44:47]
	v_mfma_f32_16x16x32_bf16 v[36:39], v[176:179], v[204:207], v[36:39]
	v_mfma_f32_16x16x32_bf16 v[28:31], v[168:171], v[212:215], v[28:31]
	v_mfma_f32_16x16x32_bf16 v[20:23], v[176:179], v[212:215], v[20:23]
	v_mfma_f32_16x16x32_bf16 v[12:15], v[168:171], v[220:223], v[12:15]
	v_mfma_f32_16x16x32_bf16 v[4:7], v[176:179], v[220:223], v[4:7]
	s_setprio 0
	s_barrier
	s_add_i32 s54, 0, 0x18000
	s_add_i32 s55, 0, 0x1c000
	v_add_u32_e32 v160, s54, v142
	v_add_u32_e32 v176, s55, v142
	ds_read_b128 v[148:151], v160
	ds_read_b128 v[152:155], v160 offset:1024
	ds_read_b128 v[156:159], v160 offset:2048
	ds_read_b128 v[160:163], v160 offset:3072
	ds_read_b128 v[164:167], v176
	ds_read_b128 v[168:171], v176 offset:1024
	ds_read_b128 v[172:175], v176 offset:2048
	ds_read_b128 v[176:179], v176 offset:3072
	s_add_u32 s24, s24, s0
	s_addc_u32 s25, s25, s1
	s_mov_b32 m0, s39
	v_lshl_add_u64 v[246:247], s[24:25], 0, v[136:137]
	ds_read_b128 v[180:183], v147 offset:32768
	ds_read_b128 v[184:187], v147 offset:33792
	ds_read_b128 v[188:191], v147 offset:34816
	ds_read_b128 v[204:207], v147 offset:35840
	ds_read_b128 v[208:211], v147 offset:36864
	ds_read_b128 v[212:215], v147 offset:37888
	ds_read_b128 v[216:219], v147 offset:38912
	ds_read_b128 v[220:223], v147 offset:39936
	global_load_lds_dwordx4 v[246:247], off
	v_lshl_add_u64 v[246:247], s[24:25], 0, v[132:133]
	s_mov_b32 m0, s40
	s_nop 0
	global_load_lds_dwordx4 v[246:247], off
	s_waitcnt vmcnt(8)
	s_waitcnt lgkmcnt(0)
	s_barrier
	s_setprio 1
	v_mfma_f32_16x16x32_bf16 v[124:127], v[148:151], v[180:183], v[124:127]
	v_mfma_f32_16x16x32_bf16 v[120:123], v[156:159], v[180:183], v[120:123]
	v_mfma_f32_16x16x32_bf16 v[112:115], v[148:151], v[188:191], v[112:115]
	v_mfma_f32_16x16x32_bf16 v[104:107], v[156:159], v[188:191], v[104:107]
	v_mfma_f32_16x16x32_bf16 v[96:99], v[148:151], v[208:211], v[96:99]
	v_mfma_f32_16x16x32_bf16 v[88:91], v[156:159], v[208:211], v[88:91]
	v_mfma_f32_16x16x32_bf16 v[80:83], v[148:151], v[216:219], v[80:83]
	v_mfma_f32_16x16x32_bf16 v[72:75], v[156:159], v[216:219], v[72:75]
	v_mfma_f32_16x16x32_bf16 v[124:127], v[152:155], v[184:187], v[124:127]
	v_mfma_f32_16x16x32_bf16 v[120:123], v[160:163], v[184:187], v[120:123]
	v_mfma_f32_16x16x32_bf16 v[112:115], v[152:155], v[204:207], v[112:115]
	v_mfma_f32_16x16x32_bf16 v[104:107], v[160:163], v[204:207], v[104:107]
	v_mfma_f32_16x16x32_bf16 v[96:99], v[152:155], v[212:215], v[96:99]
	v_mfma_f32_16x16x32_bf16 v[88:91], v[160:163], v[212:215], v[88:91]
	v_mfma_f32_16x16x32_bf16 v[80:83], v[152:155], v[220:223], v[80:83]
	v_mfma_f32_16x16x32_bf16 v[72:75], v[160:163], v[220:223], v[72:75]
	s_setprio 0
	s_setprio 1
	v_mfma_f32_16x16x32_bf16 v[128:131], v[164:167], v[180:183], v[128:131]
	v_mfma_f32_16x16x32_bf16 v[116:119], v[172:175], v[180:183], v[116:119]
	v_mfma_f32_16x16x32_bf16 v[108:111], v[164:167], v[188:191], v[108:111]
	v_mfma_f32_16x16x32_bf16 v[100:103], v[172:175], v[188:191], v[100:103]
	v_mfma_f32_16x16x32_bf16 v[92:95], v[164:167], v[208:211], v[92:95]
	v_mfma_f32_16x16x32_bf16 v[84:87], v[172:175], v[208:211], v[84:87]
	v_mfma_f32_16x16x32_bf16 v[76:79], v[164:167], v[216:219], v[76:79]
	v_mfma_f32_16x16x32_bf16 v[68:71], v[172:175], v[216:219], v[68:71]
	v_mfma_f32_16x16x32_bf16 v[128:131], v[168:171], v[184:187], v[128:131]
	v_mfma_f32_16x16x32_bf16 v[116:119], v[176:179], v[184:187], v[116:119]
	v_mfma_f32_16x16x32_bf16 v[108:111], v[168:171], v[204:207], v[108:111]
	v_mfma_f32_16x16x32_bf16 v[100:103], v[176:179], v[204:207], v[100:103]
	v_mfma_f32_16x16x32_bf16 v[92:95], v[168:171], v[212:215], v[92:95]
	v_mfma_f32_16x16x32_bf16 v[84:87], v[176:179], v[212:215], v[84:87]
	v_mfma_f32_16x16x32_bf16 v[76:79], v[168:171], v[220:223], v[76:79]
	v_mfma_f32_16x16x32_bf16 v[68:71], v[176:179], v[220:223], v[68:71]
	s_setprio 0
	s_barrier
; #define PG8_STAGE(bufoff, gbase, voff) do { _Pragma("unroll") for (int _i = 0; _i < 2; ++_i) \
;         __builtin_amdgcn_global_load_lds((const unsigned*)((const char*)(gbase) + (voff)[_i]), (PG8_LAS unsigned*)(lds + (bufoff) + ldsw + _i * 8192), 16, 0, 0); } while (0)
; #define PG8_LDA(dst, b, h) do { _Pragma("unroll") for (int m = 0; m < 4; ++m) _Pragma("unroll") for (int k = 0; k < 2; ++k) dst[m][k] = *(const PG8_LAS bf16x8*)(lds + PG8_SA(b, h) + aoff + m * 2048 + k * 1024); } while (0)
; #define PG8_MMA(ai, bj, At, Bt) do { __builtin_amdgcn_s_setprio(1); _Pragma("unroll") for (int m = 0; m < 4; ++m) _Pragma("unroll") for (int n = 0; n < 2; ++n) _Pragma("unroll") for (int k = 0; k < 2; ++k) \
;         acc[ai][bj][m][n] = __builtin_amdgcn_mfma_f32_16x16x32_bf16(Bt[n][k], At[m][k], acc[ai][bj][m][n], 0, 0, 0); __builtin_amdgcn_s_setprio(0); } while (0)
; #define PG8_WAIT_V(n) asm volatile("s_waitcnt vmcnt(" #n ")" ::: "memory")
; #define PG8_WAIT_L(n) asm volatile("s_waitcnt lgkmcnt(" #n ")" ::: "memory")
; #define PG8_BAR __builtin_amdgcn_s_barrier()
; #define PG8_SCHED __builtin_amdgcn_sched_barrier(0)
; template <class Epi, class Sched, bool ALIGN_EPI = false, bool SP2 = false>
; __device__ __forceinline__ void gemm_phase(PG8_LAS unsigned char* lds, const Gemm g, const Sched& S, const Epi& E, int tid_in) {
;     ...
;             PG8_LDA(At, 1, 1); PG8_STAGE(PG8_SB(1, 0), b3, voffB); PG8_STAGE(PG8_SB(1, 1), b3 + hsB, voffB); PG8_STAGE(PG8_SA(1, 0), a3, voffA);
;             PG8_WAIT_V(8); PG8_WAIT_L(0); PG8_BAR; PG8_MMA(1, 0, At, B0); PG8_MMA(1, 1, At, B1); PG8_BAR; PG8_SCHED;
	s_add_i32 s24, s54, s35
	v_lshl_add_u64 v[230:231], v[230:231], 0, s[80:81]
	s_mov_b32 m0, s24
	ds_read_b128 v[180:183], v147 offset:49152
	ds_read_b128 v[184:187], v147 offset:50176
	ds_read_b128 v[188:191], v147 offset:51200
	ds_read_b128 v[204:207], v147 offset:52224
	ds_read_b128 v[208:211], v147 offset:53248
	ds_read_b128 v[212:215], v147 offset:54272
	ds_read_b128 v[216:219], v147 offset:55296
	ds_read_b128 v[220:223], v147 offset:56320
	global_load_lds_dwordx4 v[230:231], off
	v_lshl_add_u64 v[230:231], v[232:233], 0, s[80:81]
	s_add_i32 m0, s24, 0x2000
	s_add_i32 s24, s55, s35
	global_load_lds_dwordx4 v[230:231], off
	v_lshl_add_u64 v[230:231], v[238:239], 0, s[80:81]
	s_mov_b32 m0, s24
	s_nop 0
	global_load_lds_dwordx4 v[230:231], off
	v_lshl_add_u64 v[230:231], v[240:241], 0, s[80:81]
	s_add_i32 m0, s24, 0x2000
	s_nop 0
	global_load_lds_dwordx4 v[230:231], off
	v_lshl_add_u64 v[230:231], v[242:243], 0, s[80:81]
	s_mov_b32 m0, s41
	s_nop 0
	global_load_lds_dwordx4 v[230:231], off
	v_lshl_add_u64 v[230:231], v[244:245], 0, s[80:81]
	s_mov_b32 m0, s42
	s_nop 0
	global_load_lds_dwordx4 v[230:231], off
	s_waitcnt vmcnt(8)
	s_waitcnt lgkmcnt(0)
	s_barrier
	s_setprio 1
	v_mfma_f32_16x16x32_bf16 v[64:67], v[148:151], v[180:183], v[64:67]
	v_mfma_f32_16x16x32_bf16 v[56:59], v[156:159], v[180:183], v[56:59]
	v_mfma_f32_16x16x32_bf16 v[48:51], v[148:151], v[188:191], v[48:51]
	v_mfma_f32_16x16x32_bf16 v[40:43], v[156:159], v[188:191], v[40:43]
	v_mfma_f32_16x16x32_bf16 v[32:35], v[148:151], v[208:211], v[32:35]
	v_mfma_f32_16x16x32_bf16 v[24:27], v[156:159], v[208:211], v[24:27]
	v_mfma_f32_16x16x32_bf16 v[16:19], v[148:151], v[216:219], v[16:19]
	v_mfma_f32_16x16x32_bf16 v[8:11], v[156:159], v[216:219], v[8:11]
	v_mfma_f32_16x16x32_bf16 v[64:67], v[152:155], v[184:187], v[64:67]
	v_mfma_f32_16x16x32_bf16 v[56:59], v[160:163], v[184:187], v[56:59]
	v_mfma_f32_16x16x32_bf16 v[48:51], v[152:155], v[204:207], v[48:51]
	v_mfma_f32_16x16x32_bf16 v[40:43], v[160:163], v[204:207], v[40:43]
	v_mfma_f32_16x16x32_bf16 v[32:35], v[152:155], v[212:215], v[32:35]
	v_mfma_f32_16x16x32_bf16 v[24:27], v[160:163], v[212:215], v[24:27]
	v_mfma_f32_16x16x32_bf16 v[16:19], v[152:155], v[220:223], v[16:19]
	v_mfma_f32_16x16x32_bf16 v[8:11], v[160:163], v[220:223], v[8:11]
	s_setprio 0
	s_setprio 1
	v_mfma_f32_16x16x32_bf16 v[60:63], v[164:167], v[180:183], v[60:63]
	v_mfma_f32_16x16x32_bf16 v[52:55], v[172:175], v[180:183], v[52:55]
	v_mfma_f32_16x16x32_bf16 v[44:47], v[164:167], v[188:191], v[44:47]
	v_mfma_f32_16x16x32_bf16 v[36:39], v[172:175], v[188:191], v[36:39]
	v_mfma_f32_16x16x32_bf16 v[28:31], v[164:167], v[208:211], v[28:31]
	v_mfma_f32_16x16x32_bf16 v[20:23], v[172:175], v[208:211], v[20:23]
	v_mfma_f32_16x16x32_bf16 v[12:15], v[164:167], v[216:219], v[12:15]
	v_mfma_f32_16x16x32_bf16 v[4:7], v[172:175], v[216:219], v[4:7]
	v_mfma_f32_16x16x32_bf16 v[60:63], v[168:171], v[184:187], v[60:63]
	v_mfma_f32_16x16x32_bf16 v[52:55], v[176:179], v[184:187], v[52:55]
	v_mfma_f32_16x16x32_bf16 v[44:47], v[168:171], v[204:207], v[44:47]
	v_mfma_f32_16x16x32_bf16 v[36:39], v[176:179], v[204:207], v[36:39]
	v_mfma_f32_16x16x32_bf16 v[28:31], v[168:171], v[212:215], v[28:31]
	v_mfma_f32_16x16x32_bf16 v[20:23], v[176:179], v[212:215], v[20:23]
	v_mfma_f32_16x16x32_bf16 v[12:15], v[168:171], v[220:223], v[12:15]
	v_mfma_f32_16x16x32_bf16 v[4:7], v[176:179], v[220:223], v[4:7]
	s_setprio 0
	s_barrier
	s_add_i32 s24, s53, 2
	s_add_u32 s51, s51, 0x100
	s_addc_u32 s52, s52, 0
	s_add_u32 s22, s22, 0x100
	s_addc_u32 s23, s23, 0
	s_cmp_ge_i32 s53, s43
	s_mov_b32 s53, s24
	s_cbranch_scc0 .LBB0_244

; #define PG8_STAGE(bufoff, gbase, voff) do { _Pragma("unroll") for (int _i = 0; _i < 2; ++_i) \
;         __builtin_amdgcn_global_load_lds((const unsigned*)((const char*)(gbase) + (voff)[_i]), (PG8_LAS unsigned*)(lds + (bufoff) + ldsw + _i * 8192), 16, 0, 0); } while (0)
; #define PG8_LDA(dst, b, h) do { _Pragma("unroll") for (int m = 0; m < 4; ++m) _Pragma("unroll") for (int k = 0; k < 2; ++k) dst[m][k] = *(const PG8_LAS bf16x8*)(lds + PG8_SA(b, h) + aoff + m * 2048 + k * 1024); } while (0)
; #define PG8_LDB(dst, b, h) do { _Pragma("unroll") for (int n = 0; n < 2; ++n) _Pragma("unroll") for (int k = 0; k < 2; ++k) dst[n][k] = *(const PG8_LAS bf16x8*)(lds + PG8_SB(b, h) + boff + n * 2048 + k * 1024); } while (0)
; #define PG8_MMA(ai, bj, At, Bt) do { __builtin_amdgcn_s_setprio(1); _Pragma("unroll") for (int m = 0; m < 4; ++m) _Pragma("unroll") for (int n = 0; n < 2; ++n) _Pragma("unroll") for (int k = 0; k < 2; ++k) \
;         acc[ai][bj][m][n] = __builtin_amdgcn_mfma_f32_16x16x32_bf16(Bt[n][k], At[m][k], acc[ai][bj][m][n], 0, 0, 0); __builtin_amdgcn_s_setprio(0); } while (0)
; #define PG8_WAIT_V(n) asm volatile("s_waitcnt vmcnt(" #n ")" ::: "memory")
; #define PG8_WAIT_L(n) asm volatile("s_waitcnt lgkmcnt(" #n ")" ::: "memory")
; template <class Epi, class Sched, bool ALIGN_EPI = false, bool SP2 = false>
; __device__ __forceinline__ void gemm_phase(PG8_LAS unsigned char* lds, const Gemm g, const Sched& S, const Epi& E, int tid_in) {
;     ...
;             const char* a1 = cA + (size_t)(t + 1) * kstep + (t >= jt ? jb : 0);
;             const char* a2 = last ? nA : cA + (size_t)(t + 2) * kstep + (t + 2 >= jt ? jb : 0); const char* b2 = last ? nB : cB + (size_t)(t + 2) * kstep;
;             const char* a3 = a2 + kstep; const char* b3 = b2 + kstep;
;             if (last && has_next) S.a_ready(nxt);
;             if constexpr (SP2) {
;             PG8_LDB(B0, 0, 0); PG8_LDB(B1, 0, 1); PG8_SCHED; PG8_LDA(At, 0, 0); PG8_STAGE(PG8_SA(1, 1), a1 + hsA, voffA);
;             PG8_WAIT_V(8); PG8_WAIT_L(0); PG8_BAR; PG8_MMA(0, 0, At, B0); PG8_MMA(0, 1, At, B1); PG8_BAR; PG8_SCHED;
;             PG8_LDA(At, 0, 1); PG8_STAGE(PG8_SB(0, 0), b2, voffB); PG8_STAGE(PG8_SB(0, 1), b2 + hsB, voffB); PG8_STAGE(PG8_SA(0, 0), a2, voffA);
;             PG8_WAIT_V(8); PG8_WAIT_L(0); PG8_BAR; PG8_MMA(1, 0, At, B0); PG8_MMA(1, 1, At, B1); PG8_BAR; PG8_SCHED;
.LBB0_321:
	s_add_i32 s40, s42, -2
	s_cmp_ge_i32 s40, s33
	s_cselect_b32 s78, s49, 0
	s_cselect_b32 s79, s65, 0
	s_cmp_ge_i32 s42, s33
	s_cselect_b32 s41, s49, 0
	s_cselect_b32 s40, s65, 0
	s_add_u32 s41, s4, s41
	s_addc_u32 s40, s5, s40
	s_add_u32 s43, s41, 0x80
	s_addc_u32 s40, s40, 0
	s_add_i32 s84, 0, 0x10000
	s_cmp_eq_u32 s64, s42
	s_cselect_b32 s41, s37, s40
	s_cselect_b32 s40, s36, s43
	s_cselect_b32 s83, s39, s77
	s_cselect_b32 s82, s38, s76
	s_add_i32 s43, 0, 0x14000
	v_add_u32_e32 v144, s84, v219
	v_add_u32_e32 v170, s43, v219
	ds_read_b128 v[132:135], v144
	ds_read_b128 v[136:139], v144 offset:1024
	ds_read_b128 v[140:143], v144 offset:2048
	ds_read_b128 v[144:147], v144 offset:3072
	ds_read_b128 v[148:151], v170
	ds_read_b128 v[162:165], v170 offset:1024
	ds_read_b128 v[166:169], v170 offset:2048
	ds_read_b128 v[170:173], v170 offset:3072
	v_lshl_add_u64 v[190:191], s[4:5], 0, v[160:161]
	v_lshl_add_u64 v[190:191], v[190:191], 0, s[78:79]
	s_add_i32 m0, s53, 0xc000
	ds_read_b128 v[174:177], v221
	ds_read_b128 v[178:181], v221 offset:1024
	ds_read_b128 v[182:185], v221 offset:2048
	ds_read_b128 v[186:189], v221 offset:3072
	ds_read_b128 v[204:207], v221 offset:4096
	ds_read_b128 v[208:211], v221 offset:5120
	ds_read_b128 v[212:215], v221 offset:6144
	ds_read_b128 v[238:241], v221 offset:7168
	global_load_lds_dwordx4 v[190:191], off
	v_lshl_add_u64 v[190:191], s[4:5], 0, v[158:159]
	v_lshl_add_u64 v[190:191], v[190:191], 0, s[78:79]
	s_add_i32 m0, s53, 0xe000
	s_nop 0
	global_load_lds_dwordx4 v[190:191], off
	s_waitcnt vmcnt(8)
	s_waitcnt lgkmcnt(0)
	s_barrier
	s_setprio 1
	v_mfma_f32_16x16x32_bf16 v[128:131], v[132:135], v[174:177], v[128:131]
	v_mfma_f32_16x16x32_bf16 v[124:127], v[140:143], v[174:177], v[124:127]
	v_mfma_f32_16x16x32_bf16 v[120:123], v[132:135], v[182:185], v[120:123]
	v_mfma_f32_16x16x32_bf16 v[116:119], v[140:143], v[182:185], v[116:119]
	v_mfma_f32_16x16x32_bf16 v[112:115], v[132:135], v[204:207], v[112:115]
	v_mfma_f32_16x16x32_bf16 v[108:111], v[140:143], v[204:207], v[108:111]
	v_mfma_f32_16x16x32_bf16 v[104:107], v[132:135], v[212:215], v[104:107]
	v_mfma_f32_16x16x32_bf16 v[100:103], v[140:143], v[212:215], v[100:103]
	v_mfma_f32_16x16x32_bf16 v[128:131], v[136:139], v[178:181], v[128:131]
	v_mfma_f32_16x16x32_bf16 v[124:127], v[144:147], v[178:181], v[124:127]
	v_mfma_f32_16x16x32_bf16 v[120:123], v[136:139], v[186:189], v[120:123]
	v_mfma_f32_16x16x32_bf16 v[116:119], v[144:147], v[186:189], v[116:119]
	v_mfma_f32_16x16x32_bf16 v[112:115], v[136:139], v[208:211], v[112:115]
	v_mfma_f32_16x16x32_bf16 v[108:111], v[144:147], v[208:211], v[108:111]
	v_mfma_f32_16x16x32_bf16 v[104:107], v[136:139], v[238:241], v[104:107]
	v_mfma_f32_16x16x32_bf16 v[100:103], v[144:147], v[238:241], v[100:103]
	s_setprio 0
	s_setprio 1
	v_mfma_f32_16x16x32_bf16 v[64:67], v[148:151], v[174:177], v[64:67]
	v_mfma_f32_16x16x32_bf16 v[56:59], v[166:169], v[174:177], v[56:59]
	v_mfma_f32_16x16x32_bf16 v[60:63], v[148:151], v[182:185], v[60:63]
	v_mfma_f32_16x16x32_bf16 v[52:55], v[166:169], v[182:185], v[52:55]
	v_mfma_f32_16x16x32_bf16 v[48:51], v[148:151], v[204:207], v[48:51]
	v_mfma_f32_16x16x32_bf16 v[40:43], v[166:169], v[204:207], v[40:43]
	v_mfma_f32_16x16x32_bf16 v[44:47], v[148:151], v[212:215], v[44:47]
	v_mfma_f32_16x16x32_bf16 v[36:39], v[166:169], v[212:215], v[36:39]
	v_mfma_f32_16x16x32_bf16 v[64:67], v[162:165], v[178:181], v[64:67]
	v_mfma_f32_16x16x32_bf16 v[56:59], v[170:173], v[178:181], v[56:59]
	v_mfma_f32_16x16x32_bf16 v[60:63], v[162:165], v[186:189], v[60:63]
	v_mfma_f32_16x16x32_bf16 v[52:55], v[170:173], v[186:189], v[52:55]
	v_mfma_f32_16x16x32_bf16 v[48:51], v[162:165], v[208:211], v[48:51]
	v_mfma_f32_16x16x32_bf16 v[40:43], v[170:173], v[208:211], v[40:43]
	v_mfma_f32_16x16x32_bf16 v[44:47], v[162:165], v[238:241], v[44:47]
	v_mfma_f32_16x16x32_bf16 v[36:39], v[170:173], v[238:241], v[36:39]
	s_setprio 0
	s_barrier
	s_add_i32 s78, s84, s52
	v_lshl_add_u64 v[190:191], s[82:83], 0, v[152:153]
	s_mov_b32 m0, s78
	ds_read_b128 v[174:177], v221 offset:16384
	ds_read_b128 v[178:181], v221 offset:17408
	ds_read_b128 v[182:185], v221 offset:18432
	ds_read_b128 v[186:189], v221 offset:19456
	ds_read_b128 v[204:207], v221 offset:20480
	ds_read_b128 v[208:211], v221 offset:21504
	ds_read_b128 v[212:215], v221 offset:22528
	ds_read_b128 v[238:241], v221 offset:23552
	global_load_lds_dwordx4 v[190:191], off
	s_add_i32 m0, s78, 0x2000
	s_add_u32 s78, s82, s12
	v_lshl_add_u64 v[216:217], s[82:83], 0, v[156:157]
	s_addc_u32 s79, s83, s13
	s_add_i32 s43, s43, s52
	global_load_lds_dwordx4 v[216:217], off
	v_lshl_add_u64 v[222:223], s[78:79], 0, v[152:153]
	s_mov_b32 m0, s43
	v_lshl_add_u64 v[230:231], s[78:79], 0, v[156:157]
	global_load_lds_dwordx4 v[222:223], off
	s_add_i32 m0, s43, 0x2000
	v_lshl_add_u64 v[232:233], s[40:41], 0, v[0:1]
	global_load_lds_dwordx4 v[230:231], off
	s_mov_b32 m0, s53
	v_lshl_add_u64 v[242:243], s[40:41], 0, v[154:155]
	global_load_lds_dwordx4 v[232:233], off
	s_mov_b32 m0, s54
	s_nop 0
	global_load_lds_dwordx4 v[242:243], off
	s_waitcnt vmcnt(8)
	s_waitcnt lgkmcnt(0)
	s_barrier
; #define PG8_STAGE(bufoff, gbase, voff) do { _Pragma("unroll") for (int _i = 0; _i < 2; ++_i) \
;         __builtin_amdgcn_global_load_lds((const unsigned*)((const char*)(gbase) + (voff)[_i]), (PG8_LAS unsigned*)(lds + (bufoff) + ldsw + _i * 8192), 16, 0, 0); } while (0)
; #define PG8_LDA(dst, b, h) do { _Pragma("unroll") for (int m = 0; m < 4; ++m) _Pragma("unroll") for (int k = 0; k < 2; ++k) dst[m][k] = *(const PG8_LAS bf16x8*)(lds + PG8_SA(b, h) + aoff + m * 2048 + k * 1024); } while (0)
; #define PG8_LDB(dst, b, h) do { _Pragma("unroll") for (int n = 0; n < 2; ++n) _Pragma("unroll") for (int k = 0; k < 2; ++k) dst[n][k] = *(const PG8_LAS bf16x8*)(lds + PG8_SB(b, h) + boff + n * 2048 + k * 1024); } while (0)
; #define PG8_MMA(ai, bj, At, Bt) do { __builtin_amdgcn_s_setprio(1); _Pragma("unroll") for (int m = 0; m < 4; ++m) _Pragma("unroll") for (int n = 0; n < 2; ++n) _Pragma("unroll") for (int k = 0; k < 2; ++k) \
;         acc[ai][bj][m][n] = __builtin_amdgcn_mfma_f32_16x16x32_bf16(Bt[n][k], At[m][k], acc[ai][bj][m][n], 0, 0, 0); __builtin_amdgcn_s_setprio(0); } while (0)
; #define PG8_WAIT_V(n) asm volatile("s_waitcnt vmcnt(" #n ")" ::: "memory")
; #define PG8_WAIT_L(n) asm volatile("s_waitcnt lgkmcnt(" #n ")" ::: "memory")
; #define PG8_BAR __builtin_amdgcn_s_barrier()
; #define PG8_SCHED __builtin_amdgcn_sched_barrier(0)
; template <class Epi, class Sched, bool ALIGN_EPI = false, bool SP2 = false>
; __device__ __forceinline__ void gemm_phase(PG8_LAS unsigned char* lds, const Gemm g, const Sched& S, const Epi& E, int tid_in) {
;     ...
;             PG8_WAIT_V(8); PG8_WAIT_L(0); PG8_BAR; PG8_MMA(1, 0, At, B0); PG8_MMA(1, 1, At, B1); PG8_BAR; PG8_SCHED;
;             PG8_LDB(B0, 1, 0); PG8_LDB(B1, 1, 1); PG8_SCHED; PG8_LDA(At, 1, 0); PG8_STAGE(PG8_SA(0, 1), a2 + hsA, voffA);
;             PG8_WAIT_V(8); PG8_WAIT_L(0); PG8_BAR; PG8_MMA(0, 0, At, B0); PG8_MMA(0, 1, At, B1); PG8_BAR; PG8_SCHED;
	s_setprio 1
	v_mfma_f32_16x16x32_bf16 v[96:99], v[132:135], v[174:177], v[96:99]
	v_mfma_f32_16x16x32_bf16 v[92:95], v[140:143], v[174:177], v[92:95]
	v_mfma_f32_16x16x32_bf16 v[88:91], v[132:135], v[182:185], v[88:91]
	v_mfma_f32_16x16x32_bf16 v[84:87], v[140:143], v[182:185], v[84:87]
	v_mfma_f32_16x16x32_bf16 v[80:83], v[132:135], v[204:207], v[80:83]
	v_mfma_f32_16x16x32_bf16 v[76:79], v[140:143], v[204:207], v[76:79]
	v_mfma_f32_16x16x32_bf16 v[72:75], v[132:135], v[212:215], v[72:75]
	v_mfma_f32_16x16x32_bf16 v[68:71], v[140:143], v[212:215], v[68:71]
	v_mfma_f32_16x16x32_bf16 v[96:99], v[136:139], v[178:181], v[96:99]
	v_mfma_f32_16x16x32_bf16 v[92:95], v[144:147], v[178:181], v[92:95]
	v_mfma_f32_16x16x32_bf16 v[88:91], v[136:139], v[186:189], v[88:91]
	v_mfma_f32_16x16x32_bf16 v[84:87], v[144:147], v[186:189], v[84:87]
	v_mfma_f32_16x16x32_bf16 v[80:83], v[136:139], v[208:211], v[80:83]
	v_mfma_f32_16x16x32_bf16 v[76:79], v[144:147], v[208:211], v[76:79]
	v_mfma_f32_16x16x32_bf16 v[72:75], v[136:139], v[238:241], v[72:75]
	v_mfma_f32_16x16x32_bf16 v[68:71], v[144:147], v[238:241], v[68:71]
	s_setprio 0
	s_setprio 1
	v_mfma_f32_16x16x32_bf16 v[32:35], v[148:151], v[174:177], v[32:35]
	v_mfma_f32_16x16x32_bf16 v[28:31], v[166:169], v[174:177], v[28:31]
	v_mfma_f32_16x16x32_bf16 v[24:27], v[148:151], v[182:185], v[24:27]
	v_mfma_f32_16x16x32_bf16 v[12:15], v[166:169], v[182:185], v[12:15]
	v_mfma_f32_16x16x32_bf16 v[20:23], v[148:151], v[204:207], v[20:23]
	v_mfma_f32_16x16x32_bf16 v[8:11], v[166:169], v[204:207], v[8:11]
	v_mfma_f32_16x16x32_bf16 v[16:19], v[148:151], v[212:215], v[16:19]
	v_mfma_f32_16x16x32_bf16 v[4:7], v[166:169], v[212:215], v[4:7]
	v_mfma_f32_16x16x32_bf16 v[32:35], v[162:165], v[178:181], v[32:35]
	v_mfma_f32_16x16x32_bf16 v[28:31], v[170:173], v[178:181], v[28:31]
	v_mfma_f32_16x16x32_bf16 v[24:27], v[162:165], v[186:189], v[24:27]
	v_mfma_f32_16x16x32_bf16 v[12:15], v[170:173], v[186:189], v[12:15]
	v_mfma_f32_16x16x32_bf16 v[20:23], v[162:165], v[208:211], v[20:23]
	v_mfma_f32_16x16x32_bf16 v[8:11], v[170:173], v[208:211], v[8:11]
	v_mfma_f32_16x16x32_bf16 v[16:19], v[162:165], v[238:241], v[16:19]
	v_mfma_f32_16x16x32_bf16 v[4:7], v[170:173], v[238:241], v[4:7]
	s_setprio 0
	s_barrier
	s_add_i32 s43, 0, 0x18000
	s_add_i32 s78, 0, 0x1c000
	v_add_u32_e32 v144, s43, v219
	v_add_u32_e32 v170, s78, v219
	ds_read_b128 v[132:135], v144
	ds_read_b128 v[136:139], v144 offset:1024
	ds_read_b128 v[140:143], v144 offset:2048
	ds_read_b128 v[144:147], v144 offset:3072
	ds_read_b128 v[148:151], v170
	ds_read_b128 v[162:165], v170 offset:1024
	ds_read_b128 v[166:169], v170 offset:2048
	ds_read_b128 v[170:173], v170 offset:3072
	s_add_u32 s40, s40, s10
	s_addc_u32 s41, s41, s11
	s_mov_b32 m0, s55
	v_lshl_add_u64 v[244:245], s[40:41], 0, v[0:1]
	ds_read_b128 v[174:177], v221 offset:32768
	ds_read_b128 v[178:181], v221 offset:33792
	ds_read_b128 v[182:185], v221 offset:34816
	ds_read_b128 v[186:189], v221 offset:35840
	ds_read_b128 v[204:207], v221 offset:36864
	ds_read_b128 v[208:211], v221 offset:37888
	ds_read_b128 v[212:215], v221 offset:38912
	ds_read_b128 v[238:241], v221 offset:39936
	global_load_lds_dwordx4 v[244:245], off
	v_lshl_add_u64 v[244:245], s[40:41], 0, v[154:155]
	s_mov_b32 m0, s58
	s_nop 0
	global_load_lds_dwordx4 v[244:245], off
	s_waitcnt vmcnt(8)
	s_waitcnt lgkmcnt(0)
	s_barrier
	s_setprio 1
	v_mfma_f32_16x16x32_bf16 v[128:131], v[132:135], v[174:177], v[128:131]
	v_mfma_f32_16x16x32_bf16 v[124:127], v[140:143], v[174:177], v[124:127]
	v_mfma_f32_16x16x32_bf16 v[120:123], v[132:135], v[182:185], v[120:123]
	v_mfma_f32_16x16x32_bf16 v[116:119], v[140:143], v[182:185], v[116:119]
	v_mfma_f32_16x16x32_bf16 v[112:115], v[132:135], v[204:207], v[112:115]
	v_mfma_f32_16x16x32_bf16 v[108:111], v[140:143], v[204:207], v[108:111]
	v_mfma_f32_16x16x32_bf16 v[104:107], v[132:135], v[212:215], v[104:107]
	v_mfma_f32_16x16x32_bf16 v[100:103], v[140:143], v[212:215], v[100:103]
	v_mfma_f32_16x16x32_bf16 v[128:131], v[136:139], v[178:181], v[128:131]
	v_mfma_f32_16x16x32_bf16 v[124:127], v[144:147], v[178:181], v[124:127]
	v_mfma_f32_16x16x32_bf16 v[120:123], v[136:139], v[186:189], v[120:123]
	v_mfma_f32_16x16x32_bf16 v[116:119], v[144:147], v[186:189], v[116:119]
	v_mfma_f32_16x16x32_bf16 v[112:115], v[136:139], v[208:211], v[112:115]
	v_mfma_f32_16x16x32_bf16 v[108:111], v[144:147], v[208:211], v[108:111]
	v_mfma_f32_16x16x32_bf16 v[104:107], v[136:139], v[238:241], v[104:107]
	v_mfma_f32_16x16x32_bf16 v[100:103], v[144:147], v[238:241], v[100:103]
	s_setprio 0
	s_setprio 1
	v_mfma_f32_16x16x32_bf16 v[64:67], v[148:151], v[174:177], v[64:67]
	v_mfma_f32_16x16x32_bf16 v[56:59], v[166:169], v[174:177], v[56:59]
	v_mfma_f32_16x16x32_bf16 v[60:63], v[148:151], v[182:185], v[60:63]
	v_mfma_f32_16x16x32_bf16 v[52:55], v[166:169], v[182:185], v[52:55]
	v_mfma_f32_16x16x32_bf16 v[48:51], v[148:151], v[204:207], v[48:51]
	v_mfma_f32_16x16x32_bf16 v[40:43], v[166:169], v[204:207], v[40:43]
	v_mfma_f32_16x16x32_bf16 v[44:47], v[148:151], v[212:215], v[44:47]
	v_mfma_f32_16x16x32_bf16 v[36:39], v[166:169], v[212:215], v[36:39]
	v_mfma_f32_16x16x32_bf16 v[64:67], v[162:165], v[178:181], v[64:67]
	v_mfma_f32_16x16x32_bf16 v[56:59], v[170:173], v[178:181], v[56:59]
	v_mfma_f32_16x16x32_bf16 v[60:63], v[162:165], v[186:189], v[60:63]
	v_mfma_f32_16x16x32_bf16 v[52:55], v[170:173], v[186:189], v[52:55]
	v_mfma_f32_16x16x32_bf16 v[48:51], v[162:165], v[208:211], v[48:51]
	v_mfma_f32_16x16x32_bf16 v[40:43], v[170:173], v[208:211], v[40:43]
	v_mfma_f32_16x16x32_bf16 v[44:47], v[162:165], v[238:241], v[44:47]
	v_mfma_f32_16x16x32_bf16 v[36:39], v[170:173], v[238:241], v[36:39]
	s_setprio 0
	s_barrier
; #define PG8_STAGE(bufoff, gbase, voff) do { _Pragma("unroll") for (int _i = 0; _i < 2; ++_i) \
;         __builtin_amdgcn_global_load_lds((const unsigned*)((const char*)(gbase) + (voff)[_i]), (PG8_LAS unsigned*)(lds + (bufoff) + ldsw + _i * 8192), 16, 0, 0); } while (0)
; #define PG8_LDA(dst, b, h) do { _Pragma("unroll") for (int m = 0; m < 4; ++m) _Pragma("unroll") for (int k = 0; k < 2; ++k) dst[m][k] = *(const PG8_LAS bf16x8*)(lds + PG8_SA(b, h) + aoff + m * 2048 + k * 1024); } while (0)
; #define PG8_MMA(ai, bj, At, Bt) do { __builtin_amdgcn_s_setprio(1); _Pragma("unroll") for (int m = 0; m < 4; ++m) _Pragma("unroll") for (int n = 0; n < 2; ++n) _Pragma("unroll") for (int k = 0; k < 2; ++k) \
;         acc[ai][bj][m][n] = __builtin_amdgcn_mfma_f32_16x16x32_bf16(Bt[n][k], At[m][k], acc[ai][bj][m][n], 0, 0, 0); __builtin_amdgcn_s_setprio(0); } while (0)
; #define PG8_WAIT_V(n) asm volatile("s_waitcnt vmcnt(" #n ")" ::: "memory")
; #define PG8_WAIT_L(n) asm volatile("s_waitcnt lgkmcnt(" #n ")" ::: "memory")
; #define PG8_BAR __builtin_amdgcn_s_barrier()
; #define PG8_SCHED __builtin_amdgcn_sched_barrier(0)
; template <class Epi, class Sched, bool ALIGN_EPI = false, bool SP2 = false>
; __device__ __forceinline__ void gemm_phase(PG8_LAS unsigned char* lds, const Gemm g, const Sched& S, const Epi& E, int tid_in) {
;     ...
;             PG8_LDA(At, 1, 1); PG8_STAGE(PG8_SB(1, 0), b3, voffB); PG8_STAGE(PG8_SB(1, 1), b3 + hsB, voffB); PG8_STAGE(PG8_SA(1, 0), a3, voffA);
;             PG8_WAIT_V(8); PG8_WAIT_L(0); PG8_BAR; PG8_MMA(1, 0, At, B0); PG8_MMA(1, 1, At, B1); PG8_BAR; PG8_SCHED;
	s_add_i32 s40, s43, s52
	v_lshl_add_u64 v[190:191], v[190:191], 0, s[80:81]
	s_mov_b32 m0, s40
	ds_read_b128 v[174:177], v221 offset:49152
	ds_read_b128 v[178:181], v221 offset:50176
	ds_read_b128 v[182:185], v221 offset:51200
	ds_read_b128 v[186:189], v221 offset:52224
	ds_read_b128 v[204:207], v221 offset:53248
	ds_read_b128 v[208:211], v221 offset:54272
	ds_read_b128 v[212:215], v221 offset:55296
	ds_read_b128 v[238:241], v221 offset:56320
	global_load_lds_dwordx4 v[190:191], off
	v_lshl_add_u64 v[190:191], v[216:217], 0, s[80:81]
	s_add_i32 m0, s40, 0x2000
	s_add_i32 s40, s78, s52
	global_load_lds_dwordx4 v[190:191], off
	v_lshl_add_u64 v[190:191], v[222:223], 0, s[80:81]
	s_mov_b32 m0, s40
	s_nop 0
	global_load_lds_dwordx4 v[190:191], off
	v_lshl_add_u64 v[190:191], v[230:231], 0, s[80:81]
	s_add_i32 m0, s40, 0x2000
	s_nop 0
	global_load_lds_dwordx4 v[190:191], off
	v_lshl_add_u64 v[190:191], v[232:233], 0, s[80:81]
	s_mov_b32 m0, s61
	s_nop 0
	global_load_lds_dwordx4 v[190:191], off
	v_lshl_add_u64 v[190:191], v[242:243], 0, s[80:81]
	s_mov_b32 m0, s62
	s_nop 0
	global_load_lds_dwordx4 v[190:191], off
	s_waitcnt vmcnt(8)
	s_waitcnt lgkmcnt(0)
	s_barrier
	s_setprio 1
	v_mfma_f32_16x16x32_bf16 v[96:99], v[132:135], v[174:177], v[96:99]
	v_mfma_f32_16x16x32_bf16 v[92:95], v[140:143], v[174:177], v[92:95]
	v_mfma_f32_16x16x32_bf16 v[88:91], v[132:135], v[182:185], v[88:91]
	v_mfma_f32_16x16x32_bf16 v[84:87], v[140:143], v[182:185], v[84:87]
	v_mfma_f32_16x16x32_bf16 v[80:83], v[132:135], v[204:207], v[80:83]
	v_mfma_f32_16x16x32_bf16 v[76:79], v[140:143], v[204:207], v[76:79]
	v_mfma_f32_16x16x32_bf16 v[72:75], v[132:135], v[212:215], v[72:75]
	v_mfma_f32_16x16x32_bf16 v[68:71], v[140:143], v[212:215], v[68:71]
	v_mfma_f32_16x16x32_bf16 v[96:99], v[136:139], v[178:181], v[96:99]
	v_mfma_f32_16x16x32_bf16 v[92:95], v[144:147], v[178:181], v[92:95]
	v_mfma_f32_16x16x32_bf16 v[88:91], v[136:139], v[186:189], v[88:91]
	v_mfma_f32_16x16x32_bf16 v[84:87], v[144:147], v[186:189], v[84:87]
	v_mfma_f32_16x16x32_bf16 v[80:83], v[136:139], v[208:211], v[80:83]
	v_mfma_f32_16x16x32_bf16 v[76:79], v[144:147], v[208:211], v[76:79]
	v_mfma_f32_16x16x32_bf16 v[72:75], v[136:139], v[238:241], v[72:75]
	v_mfma_f32_16x16x32_bf16 v[68:71], v[144:147], v[238:241], v[68:71]
	s_setprio 0
	s_setprio 1
	v_mfma_f32_16x16x32_bf16 v[32:35], v[148:151], v[174:177], v[32:35]
	v_mfma_f32_16x16x32_bf16 v[28:31], v[166:169], v[174:177], v[28:31]
	v_mfma_f32_16x16x32_bf16 v[24:27], v[148:151], v[182:185], v[24:27]
	v_mfma_f32_16x16x32_bf16 v[12:15], v[166:169], v[182:185], v[12:15]
	v_mfma_f32_16x16x32_bf16 v[20:23], v[148:151], v[204:207], v[20:23]
	v_mfma_f32_16x16x32_bf16 v[8:11], v[166:169], v[204:207], v[8:11]
	v_mfma_f32_16x16x32_bf16 v[16:19], v[148:151], v[212:215], v[16:19]
	v_mfma_f32_16x16x32_bf16 v[4:7], v[166:169], v[212:215], v[4:7]
	v_mfma_f32_16x16x32_bf16 v[32:35], v[162:165], v[178:181], v[32:35]
	v_mfma_f32_16x16x32_bf16 v[28:31], v[170:173], v[178:181], v[28:31]
	v_mfma_f32_16x16x32_bf16 v[24:27], v[162:165], v[186:189], v[24:27]
	v_mfma_f32_16x16x32_bf16 v[12:15], v[170:173], v[186:189], v[12:15]
	v_mfma_f32_16x16x32_bf16 v[20:23], v[162:165], v[208:211], v[20:23]
	v_mfma_f32_16x16x32_bf16 v[8:11], v[170:173], v[208:211], v[8:11]
	v_mfma_f32_16x16x32_bf16 v[16:19], v[162:165], v[238:241], v[16:19]
	v_mfma_f32_16x16x32_bf16 v[4:7], v[170:173], v[238:241], v[4:7]
	s_setprio 0
	s_barrier
	s_add_i32 s40, s42, 2
	s_add_u32 s76, s76, 0x100
	s_addc_u32 s77, s77, 0
	s_add_u32 s4, s4, 0x100
	s_addc_u32 s5, s5, 0
	s_cmp_ge_i32 s42, s64
	s_mov_b32 s42, s40
	s_cbranch_scc0 .LBB0_321
	s_movk_i32 s83, 0x3000

; #define PG8_STAGE(bufoff, gbase, voff) do { _Pragma("unroll") for (int _i = 0; _i < 2; ++_i) \
;         __builtin_amdgcn_global_load_lds((const unsigned*)((const char*)(gbase) + (voff)[_i]), (PG8_LAS unsigned*)(lds + (bufoff) + ldsw + _i * 8192), 16, 0, 0); } while (0)
; #define PG8_LDA(dst, b, h) do { _Pragma("unroll") for (int m = 0; m < 4; ++m) _Pragma("unroll") for (int k = 0; k < 2; ++k) dst[m][k] = *(const PG8_LAS bf16x8*)(lds + PG8_SA(b, h) + aoff + m * 2048 + k * 1024); } while (0)
; #define PG8_LDB(dst, b, h) do { _Pragma("unroll") for (int n = 0; n < 2; ++n) _Pragma("unroll") for (int k = 0; k < 2; ++k) dst[n][k] = *(const PG8_LAS bf16x8*)(lds + PG8_SB(b, h) + boff + n * 2048 + k * 1024); } while (0)
; #define PG8_MMA(ai, bj, At, Bt) do { __builtin_amdgcn_s_setprio(1); _Pragma("unroll") for (int m = 0; m < 4; ++m) _Pragma("unroll") for (int n = 0; n < 2; ++n) _Pragma("unroll") for (int k = 0; k < 2; ++k) \
;         acc[ai][bj][m][n] = __builtin_amdgcn_mfma_f32_16x16x32_bf16(Bt[n][k], At[m][k], acc[ai][bj][m][n], 0, 0, 0); __builtin_amdgcn_s_setprio(0); } while (0)
; #define PG8_WAIT_V(n) asm volatile("s_waitcnt vmcnt(" #n ")" ::: "memory")
; #define PG8_WAIT_L(n) asm volatile("s_waitcnt lgkmcnt(" #n ")" ::: "memory")
; template <class Epi, class Sched, bool ALIGN_EPI = false, bool SP2 = false>
; __device__ __forceinline__ void gemm_phase(PG8_LAS unsigned char* lds, const Gemm g, const Sched& S, const Epi& E, int tid_in) {
;     ...
;             const char* a1 = cA + (size_t)(t + 1) * kstep + (t >= jt ? jb : 0);
;             const char* a2 = last ? nA : cA + (size_t)(t + 2) * kstep + (t + 2 >= jt ? jb : 0); const char* b2 = last ? nB : cB + (size_t)(t + 2) * kstep;
;             const char* a3 = a2 + kstep; const char* b3 = b2 + kstep;
;             if (last && has_next) S.a_ready(nxt);
;             if constexpr (SP2) {
;             PG8_LDB(B0, 0, 0); PG8_LDB(B1, 0, 1); PG8_SCHED; PG8_LDA(At, 0, 0); PG8_STAGE(PG8_SA(1, 1), a1 + hsA, voffA);
;             PG8_WAIT_V(8); PG8_WAIT_L(0); PG8_BAR; PG8_MMA(0, 0, At, B0); PG8_MMA(0, 1, At, B1); PG8_BAR; PG8_SCHED;
;             PG8_LDA(At, 0, 1); PG8_STAGE(PG8_SB(0, 0), b2, voffB); PG8_STAGE(PG8_SB(0, 1), b2 + hsB, voffB); PG8_STAGE(PG8_SA(0, 0), a2, voffA);
;             PG8_WAIT_V(8); PG8_WAIT_L(0); PG8_BAR; PG8_MMA(1, 0, At, B0); PG8_MMA(1, 1, At, B1); PG8_BAR; PG8_SCHED;
.LBB0_352:
	s_add_i32 s24, s55, -2
	s_cmp_ge_i32 s24, s26
	s_cselect_b32 s58, s27, 0
	s_cselect_b32 s59, s42, 0
	s_cmp_ge_i32 s55, s26
	s_cselect_b32 s25, s27, 0
	s_cselect_b32 s24, s42, 0
	s_add_u32 s25, s22, s25
	s_addc_u32 s24, s23, s24
	s_add_u32 s60, s25, 0x80
	s_addc_u32 s24, s24, 0
	s_add_i32 s62, 0, 0x10000
	s_cmp_eq_u32 s41, s55
	s_cselect_b32 s25, s5, s24
	s_cselect_b32 s24, s4, s60
	s_cselect_b32 s61, s21, s54
	s_cselect_b32 s60, s20, s53
	s_add_i32 s63, 0, 0x14000
	v_add_u32_e32 v160, s62, v3
	v_add_u32_e32 v176, s63, v3
	ds_read_b128 v[148:151], v160
	ds_read_b128 v[152:155], v160 offset:1024
	ds_read_b128 v[156:159], v160 offset:2048
	ds_read_b128 v[160:163], v160 offset:3072
	ds_read_b128 v[164:167], v176
	ds_read_b128 v[168:171], v176 offset:1024
	ds_read_b128 v[172:175], v176 offset:2048
	ds_read_b128 v[176:179], v176 offset:3072
	v_lshl_add_u64 v[230:231], s[22:23], 0, v[140:141]
	v_lshl_add_u64 v[230:231], v[230:231], 0, s[58:59]
	s_add_i32 m0, s31, 0xc000
	ds_read_b128 v[180:183], v147
	ds_read_b128 v[184:187], v147 offset:1024
	ds_read_b128 v[188:191], v147 offset:2048
	ds_read_b128 v[204:207], v147 offset:3072
	ds_read_b128 v[208:211], v147 offset:4096
	ds_read_b128 v[212:215], v147 offset:5120
	ds_read_b128 v[216:219], v147 offset:6144
	ds_read_b128 v[220:223], v147 offset:7168
	global_load_lds_dwordx4 v[230:231], off
	v_lshl_add_u64 v[230:231], s[22:23], 0, v[138:139]
	v_lshl_add_u64 v[230:231], v[230:231], 0, s[58:59]
	s_add_i32 m0, s31, 0xe000
	s_nop 0
	global_load_lds_dwordx4 v[230:231], off
	s_waitcnt vmcnt(8)
	s_waitcnt lgkmcnt(0)
	s_barrier
	s_setprio 1
	v_mfma_f32_16x16x32_bf16 v[124:127], v[148:151], v[180:183], v[124:127]
	v_mfma_f32_16x16x32_bf16 v[128:131], v[156:159], v[180:183], v[128:131]
	v_mfma_f32_16x16x32_bf16 v[112:115], v[148:151], v[188:191], v[112:115]
	v_mfma_f32_16x16x32_bf16 v[108:111], v[156:159], v[188:191], v[108:111]
	v_mfma_f32_16x16x32_bf16 v[96:99], v[148:151], v[208:211], v[96:99]
	v_mfma_f32_16x16x32_bf16 v[92:95], v[156:159], v[208:211], v[92:95]
	v_mfma_f32_16x16x32_bf16 v[80:83], v[148:151], v[216:219], v[80:83]
	v_mfma_f32_16x16x32_bf16 v[76:79], v[156:159], v[216:219], v[76:79]
	v_mfma_f32_16x16x32_bf16 v[124:127], v[152:155], v[184:187], v[124:127]
	v_mfma_f32_16x16x32_bf16 v[128:131], v[160:163], v[184:187], v[128:131]
	v_mfma_f32_16x16x32_bf16 v[112:115], v[152:155], v[204:207], v[112:115]
	v_mfma_f32_16x16x32_bf16 v[108:111], v[160:163], v[204:207], v[108:111]
	v_mfma_f32_16x16x32_bf16 v[96:99], v[152:155], v[212:215], v[96:99]
	v_mfma_f32_16x16x32_bf16 v[92:95], v[160:163], v[212:215], v[92:95]
	v_mfma_f32_16x16x32_bf16 v[80:83], v[152:155], v[220:223], v[80:83]
	v_mfma_f32_16x16x32_bf16 v[76:79], v[160:163], v[220:223], v[76:79]
	s_setprio 0
	s_setprio 1
	v_mfma_f32_16x16x32_bf16 v[120:123], v[164:167], v[180:183], v[120:123]
	v_mfma_f32_16x16x32_bf16 v[116:119], v[172:175], v[180:183], v[116:119]
	v_mfma_f32_16x16x32_bf16 v[104:107], v[164:167], v[188:191], v[104:107]
	v_mfma_f32_16x16x32_bf16 v[100:103], v[172:175], v[188:191], v[100:103]
	v_mfma_f32_16x16x32_bf16 v[88:91], v[164:167], v[208:211], v[88:91]
	v_mfma_f32_16x16x32_bf16 v[84:87], v[172:175], v[208:211], v[84:87]
	v_mfma_f32_16x16x32_bf16 v[72:75], v[164:167], v[216:219], v[72:75]
	v_mfma_f32_16x16x32_bf16 v[68:71], v[172:175], v[216:219], v[68:71]
	v_mfma_f32_16x16x32_bf16 v[120:123], v[168:171], v[184:187], v[120:123]
	v_mfma_f32_16x16x32_bf16 v[116:119], v[176:179], v[184:187], v[116:119]
	v_mfma_f32_16x16x32_bf16 v[104:107], v[168:171], v[204:207], v[104:107]
	v_mfma_f32_16x16x32_bf16 v[100:103], v[176:179], v[204:207], v[100:103]
	v_mfma_f32_16x16x32_bf16 v[88:91], v[168:171], v[212:215], v[88:91]
	v_mfma_f32_16x16x32_bf16 v[84:87], v[176:179], v[212:215], v[84:87]
	v_mfma_f32_16x16x32_bf16 v[72:75], v[168:171], v[220:223], v[72:75]
	v_mfma_f32_16x16x32_bf16 v[68:71], v[176:179], v[220:223], v[68:71]
	s_setprio 0
	s_barrier
	s_add_i32 s58, s62, s30
	v_lshl_add_u64 v[230:231], s[60:61], 0, v[134:135]
	s_mov_b32 m0, s58
	ds_read_b128 v[180:183], v147 offset:16384
	ds_read_b128 v[184:187], v147 offset:17408
	ds_read_b128 v[188:191], v147 offset:18432
	ds_read_b128 v[204:207], v147 offset:19456
	ds_read_b128 v[208:211], v147 offset:20480
	ds_read_b128 v[212:215], v147 offset:21504
	ds_read_b128 v[216:219], v147 offset:22528
	ds_read_b128 v[220:223], v147 offset:23552
	global_load_lds_dwordx4 v[230:231], off
	s_add_i32 m0, s58, 0x2000
	s_add_u32 s58, s60, s8
	v_lshl_add_u64 v[232:233], s[60:61], 0, v[0:1]
	s_addc_u32 s59, s61, s9
	s_add_i32 s60, s63, s30
	global_load_lds_dwordx4 v[232:233], off
	v_lshl_add_u64 v[238:239], s[58:59], 0, v[134:135]
	s_mov_b32 m0, s60
	v_lshl_add_u64 v[240:241], s[58:59], 0, v[0:1]
	global_load_lds_dwordx4 v[238:239], off
	s_add_i32 m0, s60, 0x2000
	v_lshl_add_u64 v[242:243], s[24:25], 0, v[136:137]
	global_load_lds_dwordx4 v[240:241], off
	s_mov_b32 m0, s31
	v_lshl_add_u64 v[244:245], s[24:25], 0, v[132:133]
	global_load_lds_dwordx4 v[242:243], off
	s_mov_b32 m0, s33
	s_nop 0
	global_load_lds_dwordx4 v[244:245], off
	s_waitcnt vmcnt(8)
	s_waitcnt lgkmcnt(0)
	s_barrier
; #define PG8_STAGE(bufoff, gbase, voff) do { _Pragma("unroll") for (int _i = 0; _i < 2; ++_i) \
;         __builtin_amdgcn_global_load_lds((const unsigned*)((const char*)(gbase) + (voff)[_i]), (PG8_LAS unsigned*)(lds + (bufoff) + ldsw + _i * 8192), 16, 0, 0); } while (0)
; #define PG8_LDA(dst, b, h) do { _Pragma("unroll") for (int m = 0; m < 4; ++m) _Pragma("unroll") for (int k = 0; k < 2; ++k) dst[m][k] = *(const PG8_LAS bf16x8*)(lds + PG8_SA(b, h) + aoff + m * 2048 + k * 1024); } while (0)
; #define PG8_LDB(dst, b, h) do { _Pragma("unroll") for (int n = 0; n < 2; ++n) _Pragma("unroll") for (int k = 0; k < 2; ++k) dst[n][k] = *(const PG8_LAS bf16x8*)(lds + PG8_SB(b, h) + boff + n * 2048 + k * 1024); } while (0)
; #define PG8_MMA(ai, bj, At, Bt) do { __builtin_amdgcn_s_setprio(1); _Pragma("unroll") for (int m = 0; m < 4; ++m) _Pragma("unroll") for (int n = 0; n < 2; ++n) _Pragma("unroll") for (int k = 0; k < 2; ++k) \
;         acc[ai][bj][m][n] = __builtin_amdgcn_mfma_f32_16x16x32_bf16(Bt[n][k], At[m][k], acc[ai][bj][m][n], 0, 0, 0); __builtin_amdgcn_s_setprio(0); } while (0)
; #define PG8_WAIT_V(n) asm volatile("s_waitcnt vmcnt(" #n ")" ::: "memory")
; #define PG8_WAIT_L(n) asm volatile("s_waitcnt lgkmcnt(" #n ")" ::: "memory")
; #define PG8_BAR __builtin_amdgcn_s_barrier()
; #define PG8_SCHED __builtin_amdgcn_sched_barrier(0)
; template <class Epi, class Sched, bool ALIGN_EPI = false, bool SP2 = false>
; __device__ __forceinline__ void gemm_phase(PG8_LAS unsigned char* lds, const Gemm g, const Sched& S, const Epi& E, int tid_in) {
;     ...
;             PG8_WAIT_V(8); PG8_WAIT_L(0); PG8_BAR; PG8_MMA(1, 0, At, B0); PG8_MMA(1, 1, At, B1); PG8_BAR; PG8_SCHED;
;             PG8_LDB(B0, 1, 0); PG8_LDB(B1, 1, 1); PG8_SCHED; PG8_LDA(At, 1, 0); PG8_STAGE(PG8_SA(0, 1), a2 + hsA, voffA);
;             PG8_WAIT_V(8); PG8_WAIT_L(0); PG8_BAR; PG8_MMA(0, 0, At, B0); PG8_MMA(0, 1, At, B1); PG8_BAR; PG8_SCHED;
	s_setprio 1
	v_mfma_f32_16x16x32_bf16 v[64:67], v[148:151], v[180:183], v[64:67]
	v_mfma_f32_16x16x32_bf16 v[60:63], v[156:159], v[180:183], v[60:63]
	v_mfma_f32_16x16x32_bf16 v[48:51], v[148:151], v[188:191], v[48:51]
	v_mfma_f32_16x16x32_bf16 v[44:47], v[156:159], v[188:191], v[44:47]
	v_mfma_f32_16x16x32_bf16 v[32:35], v[148:151], v[208:211], v[32:35]
	v_mfma_f32_16x16x32_bf16 v[28:31], v[156:159], v[208:211], v[28:31]
	v_mfma_f32_16x16x32_bf16 v[16:19], v[148:151], v[216:219], v[16:19]
	v_mfma_f32_16x16x32_bf16 v[12:15], v[156:159], v[216:219], v[12:15]
	v_mfma_f32_16x16x32_bf16 v[64:67], v[152:155], v[184:187], v[64:67]
	v_mfma_f32_16x16x32_bf16 v[60:63], v[160:163], v[184:187], v[60:63]
	v_mfma_f32_16x16x32_bf16 v[48:51], v[152:155], v[204:207], v[48:51]
	v_mfma_f32_16x16x32_bf16 v[44:47], v[160:163], v[204:207], v[44:47]
	v_mfma_f32_16x16x32_bf16 v[32:35], v[152:155], v[212:215], v[32:35]
	v_mfma_f32_16x16x32_bf16 v[28:31], v[160:163], v[212:215], v[28:31]
	v_mfma_f32_16x16x32_bf16 v[16:19], v[152:155], v[220:223], v[16:19]
	v_mfma_f32_16x16x32_bf16 v[12:15], v[160:163], v[220:223], v[12:15]
	s_setprio 0
	s_setprio 1
	v_mfma_f32_16x16x32_bf16 v[56:59], v[164:167], v[180:183], v[56:59]
	v_mfma_f32_16x16x32_bf16 v[52:55], v[172:175], v[180:183], v[52:55]
	v_mfma_f32_16x16x32_bf16 v[40:43], v[164:167], v[188:191], v[40:43]
	v_mfma_f32_16x16x32_bf16 v[36:39], v[172:175], v[188:191], v[36:39]
	v_mfma_f32_16x16x32_bf16 v[24:27], v[164:167], v[208:211], v[24:27]
	v_mfma_f32_16x16x32_bf16 v[20:23], v[172:175], v[208:211], v[20:23]
	v_mfma_f32_16x16x32_bf16 v[8:11], v[164:167], v[216:219], v[8:11]
	v_mfma_f32_16x16x32_bf16 v[4:7], v[172:175], v[216:219], v[4:7]
	v_mfma_f32_16x16x32_bf16 v[56:59], v[168:171], v[184:187], v[56:59]
	v_mfma_f32_16x16x32_bf16 v[52:55], v[176:179], v[184:187], v[52:55]
	v_mfma_f32_16x16x32_bf16 v[40:43], v[168:171], v[204:207], v[40:43]
	v_mfma_f32_16x16x32_bf16 v[36:39], v[176:179], v[204:207], v[36:39]
	v_mfma_f32_16x16x32_bf16 v[24:27], v[168:171], v[212:215], v[24:27]
	v_mfma_f32_16x16x32_bf16 v[20:23], v[176:179], v[212:215], v[20:23]
	v_mfma_f32_16x16x32_bf16 v[8:11], v[168:171], v[220:223], v[8:11]
	v_mfma_f32_16x16x32_bf16 v[4:7], v[176:179], v[220:223], v[4:7]
	s_setprio 0
	s_barrier
	s_add_i32 s58, 0, 0x18000
	s_add_i32 s59, 0, 0x1c000
	v_add_u32_e32 v160, s58, v3
	v_add_u32_e32 v176, s59, v3
	ds_read_b128 v[148:151], v160
	ds_read_b128 v[152:155], v160 offset:1024
	ds_read_b128 v[156:159], v160 offset:2048
	ds_read_b128 v[160:163], v160 offset:3072
	ds_read_b128 v[164:167], v176
	ds_read_b128 v[168:171], v176 offset:1024
	ds_read_b128 v[172:175], v176 offset:2048
	ds_read_b128 v[176:179], v176 offset:3072
	s_add_u32 s24, s24, s6
	s_addc_u32 s25, s25, s7
	s_mov_b32 m0, s34
	v_lshl_add_u64 v[246:247], s[24:25], 0, v[136:137]
	ds_read_b128 v[180:183], v147 offset:32768
	ds_read_b128 v[184:187], v147 offset:33792
	ds_read_b128 v[188:191], v147 offset:34816
	ds_read_b128 v[204:207], v147 offset:35840
	ds_read_b128 v[208:211], v147 offset:36864
	ds_read_b128 v[212:215], v147 offset:37888
	ds_read_b128 v[216:219], v147 offset:38912
	ds_read_b128 v[220:223], v147 offset:39936
	global_load_lds_dwordx4 v[246:247], off
	v_lshl_add_u64 v[246:247], s[24:25], 0, v[132:133]
	s_mov_b32 m0, s35
	s_nop 0
	global_load_lds_dwordx4 v[246:247], off
	s_waitcnt vmcnt(8)
	s_waitcnt lgkmcnt(0)
	s_barrier
	s_setprio 1
	v_mfma_f32_16x16x32_bf16 v[124:127], v[148:151], v[180:183], v[124:127]
	v_mfma_f32_16x16x32_bf16 v[128:131], v[156:159], v[180:183], v[128:131]
	v_mfma_f32_16x16x32_bf16 v[112:115], v[148:151], v[188:191], v[112:115]
	v_mfma_f32_16x16x32_bf16 v[108:111], v[156:159], v[188:191], v[108:111]
	v_mfma_f32_16x16x32_bf16 v[96:99], v[148:151], v[208:211], v[96:99]
	v_mfma_f32_16x16x32_bf16 v[92:95], v[156:159], v[208:211], v[92:95]
	v_mfma_f32_16x16x32_bf16 v[80:83], v[148:151], v[216:219], v[80:83]
	v_mfma_f32_16x16x32_bf16 v[76:79], v[156:159], v[216:219], v[76:79]
	v_mfma_f32_16x16x32_bf16 v[124:127], v[152:155], v[184:187], v[124:127]
	v_mfma_f32_16x16x32_bf16 v[128:131], v[160:163], v[184:187], v[128:131]
	v_mfma_f32_16x16x32_bf16 v[112:115], v[152:155], v[204:207], v[112:115]
	v_mfma_f32_16x16x32_bf16 v[108:111], v[160:163], v[204:207], v[108:111]
	v_mfma_f32_16x16x32_bf16 v[96:99], v[152:155], v[212:215], v[96:99]
	v_mfma_f32_16x16x32_bf16 v[92:95], v[160:163], v[212:215], v[92:95]
	v_mfma_f32_16x16x32_bf16 v[80:83], v[152:155], v[220:223], v[80:83]
	v_mfma_f32_16x16x32_bf16 v[76:79], v[160:163], v[220:223], v[76:79]
	s_setprio 0
	s_setprio 1
	v_mfma_f32_16x16x32_bf16 v[120:123], v[164:167], v[180:183], v[120:123]
	v_mfma_f32_16x16x32_bf16 v[116:119], v[172:175], v[180:183], v[116:119]
	v_mfma_f32_16x16x32_bf16 v[104:107], v[164:167], v[188:191], v[104:107]
	v_mfma_f32_16x16x32_bf16 v[100:103], v[172:175], v[188:191], v[100:103]
	v_mfma_f32_16x16x32_bf16 v[88:91], v[164:167], v[208:211], v[88:91]
	v_mfma_f32_16x16x32_bf16 v[84:87], v[172:175], v[208:211], v[84:87]
	v_mfma_f32_16x16x32_bf16 v[72:75], v[164:167], v[216:219], v[72:75]
	v_mfma_f32_16x16x32_bf16 v[68:71], v[172:175], v[216:219], v[68:71]
	v_mfma_f32_16x16x32_bf16 v[120:123], v[168:171], v[184:187], v[120:123]
	v_mfma_f32_16x16x32_bf16 v[116:119], v[176:179], v[184:187], v[116:119]
	v_mfma_f32_16x16x32_bf16 v[104:107], v[168:171], v[204:207], v[104:107]
	v_mfma_f32_16x16x32_bf16 v[100:103], v[176:179], v[204:207], v[100:103]
	v_mfma_f32_16x16x32_bf16 v[88:91], v[168:171], v[212:215], v[88:91]
	v_mfma_f32_16x16x32_bf16 v[84:87], v[176:179], v[212:215], v[84:87]
	v_mfma_f32_16x16x32_bf16 v[72:75], v[168:171], v[220:223], v[72:75]
	v_mfma_f32_16x16x32_bf16 v[68:71], v[176:179], v[220:223], v[68:71]
	s_setprio 0
	s_barrier
; #define PG8_STAGE(bufoff, gbase, voff) do { _Pragma("unroll") for (int _i = 0; _i < 2; ++_i) \
;         __builtin_amdgcn_global_load_lds((const unsigned*)((const char*)(gbase) + (voff)[_i]), (PG8_LAS unsigned*)(lds + (bufoff) + ldsw + _i * 8192), 16, 0, 0); } while (0)
; #define PG8_LDA(dst, b, h) do { _Pragma("unroll") for (int m = 0; m < 4; ++m) _Pragma("unroll") for (int k = 0; k < 2; ++k) dst[m][k] = *(const PG8_LAS bf16x8*)(lds + PG8_SA(b, h) + aoff + m * 2048 + k * 1024); } while (0)
; #define PG8_MMA(ai, bj, At, Bt) do { __builtin_amdgcn_s_setprio(1); _Pragma("unroll") for (int m = 0; m < 4; ++m) _Pragma("unroll") for (int n = 0; n < 2; ++n) _Pragma("unroll") for (int k = 0; k < 2; ++k) \
;         acc[ai][bj][m][n] = __builtin_amdgcn_mfma_f32_16x16x32_bf16(Bt[n][k], At[m][k], acc[ai][bj][m][n], 0, 0, 0); __builtin_amdgcn_s_setprio(0); } while (0)
; #define PG8_WAIT_V(n) asm volatile("s_waitcnt vmcnt(" #n ")" ::: "memory")
; #define PG8_WAIT_L(n) asm volatile("s_waitcnt lgkmcnt(" #n ")" ::: "memory")
; #define PG8_BAR __builtin_amdgcn_s_barrier()
; #define PG8_SCHED __builtin_amdgcn_sched_barrier(0)
; template <class Epi, class Sched, bool ALIGN_EPI = false, bool SP2 = false>
; __device__ __forceinline__ void gemm_phase(PG8_LAS unsigned char* lds, const Gemm g, const Sched& S, const Epi& E, int tid_in) {
;     ...
;             PG8_LDA(At, 1, 1); PG8_STAGE(PG8_SB(1, 0), b3, voffB); PG8_STAGE(PG8_SB(1, 1), b3 + hsB, voffB); PG8_STAGE(PG8_SA(1, 0), a3, voffA);
;             PG8_WAIT_V(8); PG8_WAIT_L(0); PG8_BAR; PG8_MMA(1, 0, At, B0); PG8_MMA(1, 1, At, B1); PG8_BAR; PG8_SCHED;
	s_add_i32 s24, s58, s30
	v_lshl_add_u64 v[230:231], v[230:231], 0, s[80:81]
	s_mov_b32 m0, s24
	ds_read_b128 v[180:183], v147 offset:49152
	ds_read_b128 v[184:187], v147 offset:50176
	ds_read_b128 v[188:191], v147 offset:51200
	ds_read_b128 v[204:207], v147 offset:52224
	ds_read_b128 v[208:211], v147 offset:53248
	ds_read_b128 v[212:215], v147 offset:54272
	ds_read_b128 v[216:219], v147 offset:55296
	ds_read_b128 v[220:223], v147 offset:56320
	global_load_lds_dwordx4 v[230:231], off
	v_lshl_add_u64 v[230:231], v[232:233], 0, s[80:81]
	s_add_i32 m0, s24, 0x2000
	s_add_i32 s24, s59, s30
	global_load_lds_dwordx4 v[230:231], off
	v_lshl_add_u64 v[230:231], v[238:239], 0, s[80:81]
	s_mov_b32 m0, s24
	s_nop 0
	global_load_lds_dwordx4 v[230:231], off
	v_lshl_add_u64 v[230:231], v[240:241], 0, s[80:81]
	s_add_i32 m0, s24, 0x2000
	s_nop 0
	global_load_lds_dwordx4 v[230:231], off
	v_lshl_add_u64 v[230:231], v[242:243], 0, s[80:81]
	s_mov_b32 m0, s38
	s_nop 0
	global_load_lds_dwordx4 v[230:231], off
	v_lshl_add_u64 v[230:231], v[244:245], 0, s[80:81]
	s_mov_b32 m0, s39
	s_nop 0
	global_load_lds_dwordx4 v[230:231], off
	s_waitcnt vmcnt(8)
	s_waitcnt lgkmcnt(0)
	s_barrier
	s_setprio 1
	v_mfma_f32_16x16x32_bf16 v[64:67], v[148:151], v[180:183], v[64:67]
	v_mfma_f32_16x16x32_bf16 v[60:63], v[156:159], v[180:183], v[60:63]
	v_mfma_f32_16x16x32_bf16 v[48:51], v[148:151], v[188:191], v[48:51]
	v_mfma_f32_16x16x32_bf16 v[44:47], v[156:159], v[188:191], v[44:47]
	v_mfma_f32_16x16x32_bf16 v[32:35], v[148:151], v[208:211], v[32:35]
	v_mfma_f32_16x16x32_bf16 v[28:31], v[156:159], v[208:211], v[28:31]
	v_mfma_f32_16x16x32_bf16 v[16:19], v[148:151], v[216:219], v[16:19]
	v_mfma_f32_16x16x32_bf16 v[12:15], v[156:159], v[216:219], v[12:15]
	v_mfma_f32_16x16x32_bf16 v[64:67], v[152:155], v[184:187], v[64:67]
	v_mfma_f32_16x16x32_bf16 v[60:63], v[160:163], v[184:187], v[60:63]
	v_mfma_f32_16x16x32_bf16 v[48:51], v[152:155], v[204:207], v[48:51]
	v_mfma_f32_16x16x32_bf16 v[44:47], v[160:163], v[204:207], v[44:47]
	v_mfma_f32_16x16x32_bf16 v[32:35], v[152:155], v[212:215], v[32:35]
	v_mfma_f32_16x16x32_bf16 v[28:31], v[160:163], v[212:215], v[28:31]
	v_mfma_f32_16x16x32_bf16 v[16:19], v[152:155], v[220:223], v[16:19]
	v_mfma_f32_16x16x32_bf16 v[12:15], v[160:163], v[220:223], v[12:15]
	s_setprio 0
	s_setprio 1
	v_mfma_f32_16x16x32_bf16 v[56:59], v[164:167], v[180:183], v[56:59]
	v_mfma_f32_16x16x32_bf16 v[52:55], v[172:175], v[180:183], v[52:55]
	v_mfma_f32_16x16x32_bf16 v[40:43], v[164:167], v[188:191], v[40:43]
	v_mfma_f32_16x16x32_bf16 v[36:39], v[172:175], v[188:191], v[36:39]
	v_mfma_f32_16x16x32_bf16 v[24:27], v[164:167], v[208:211], v[24:27]
	v_mfma_f32_16x16x32_bf16 v[20:23], v[172:175], v[208:211], v[20:23]
	v_mfma_f32_16x16x32_bf16 v[8:11], v[164:167], v[216:219], v[8:11]
	v_mfma_f32_16x16x32_bf16 v[4:7], v[172:175], v[216:219], v[4:7]
	v_mfma_f32_16x16x32_bf16 v[56:59], v[168:171], v[184:187], v[56:59]
	v_mfma_f32_16x16x32_bf16 v[52:55], v[176:179], v[184:187], v[52:55]
	v_mfma_f32_16x16x32_bf16 v[40:43], v[168:171], v[204:207], v[40:43]
	v_mfma_f32_16x16x32_bf16 v[36:39], v[176:179], v[204:207], v[36:39]
	v_mfma_f32_16x16x32_bf16 v[24:27], v[168:171], v[212:215], v[24:27]
	v_mfma_f32_16x16x32_bf16 v[20:23], v[176:179], v[212:215], v[20:23]
	v_mfma_f32_16x16x32_bf16 v[8:11], v[168:171], v[220:223], v[8:11]
	v_mfma_f32_16x16x32_bf16 v[4:7], v[176:179], v[220:223], v[4:7]
	s_setprio 0
	s_barrier
	s_add_i32 s24, s55, 2
	s_add_u32 s53, s53, 0x100
	s_addc_u32 s54, s54, 0
	s_add_u32 s22, s22, 0x100
	s_addc_u32 s23, s23, 0
	s_cmp_ge_i32 s55, s41
	s_mov_b32 s55, s24
	s_cbranch_scc0 .LBB0_352

; #define PG8_STAGE(bufoff, gbase, voff) do { _Pragma("unroll") for (int _i = 0; _i < 2; ++_i) \
;         __builtin_amdgcn_global_load_lds((const unsigned*)((const char*)(gbase) + (voff)[_i]), (PG8_LAS unsigned*)(lds + (bufoff) + ldsw + _i * 8192), 16, 0, 0); } while (0)
; #define PG8_LDA(dst, b, h) do { _Pragma("unroll") for (int m = 0; m < 4; ++m) _Pragma("unroll") for (int k = 0; k < 2; ++k) dst[m][k] = *(const PG8_LAS bf16x8*)(lds + PG8_SA(b, h) + aoff + m * 2048 + k * 1024); } while (0)
; #define PG8_LDB(dst, b, h) do { _Pragma("unroll") for (int n = 0; n < 2; ++n) _Pragma("unroll") for (int k = 0; k < 2; ++k) dst[n][k] = *(const PG8_LAS bf16x8*)(lds + PG8_SB(b, h) + boff + n * 2048 + k * 1024); } while (0)
; #define PG8_MMA(ai, bj, At, Bt) do { __builtin_amdgcn_s_setprio(1); _Pragma("unroll") for (int m = 0; m < 4; ++m) _Pragma("unroll") for (int n = 0; n < 2; ++n) _Pragma("unroll") for (int k = 0; k < 2; ++k) \
;         acc[ai][bj][m][n] = __builtin_amdgcn_mfma_f32_16x16x32_bf16(Bt[n][k], At[m][k], acc[ai][bj][m][n], 0, 0, 0); __builtin_amdgcn_s_setprio(0); } while (0)
; #define PG8_WAIT_V(n) asm volatile("s_waitcnt vmcnt(" #n ")" ::: "memory")
; #define PG8_WAIT_L(n) asm volatile("s_waitcnt lgkmcnt(" #n ")" ::: "memory")
; template <class Epi, class Sched, bool ALIGN_EPI = false, bool SP2 = false>
; __device__ __forceinline__ void gemm_phase(PG8_LAS unsigned char* lds, const Gemm g, const Sched& S, const Epi& E, int tid_in) {
;     ...
;             const char* a1 = cA + (size_t)(t + 1) * kstep + (t >= jt ? jb : 0);
;             const char* a2 = last ? nA : cA + (size_t)(t + 2) * kstep + (t + 2 >= jt ? jb : 0); const char* b2 = last ? nB : cB + (size_t)(t + 2) * kstep;
;             const char* a3 = a2 + kstep; const char* b3 = b2 + kstep;
;             if (last && has_next) S.a_ready(nxt);
;             if constexpr (SP2) {
;             PG8_LDB(B0, 0, 0); PG8_LDB(B1, 0, 1); PG8_SCHED; PG8_LDA(At, 0, 0); PG8_STAGE(PG8_SA(1, 1), a1 + hsA, voffA);
;             PG8_WAIT_V(8); PG8_WAIT_L(0); PG8_BAR; PG8_MMA(0, 0, At, B0); PG8_MMA(0, 1, At, B1); PG8_BAR; PG8_SCHED;
;             PG8_LDA(At, 0, 1); PG8_STAGE(PG8_SB(0, 0), b2, voffB); PG8_STAGE(PG8_SB(0, 1), b2 + hsB, voffB); PG8_STAGE(PG8_SA(0, 0), a2, voffA);
;             PG8_WAIT_V(8); PG8_WAIT_L(0); PG8_BAR; PG8_MMA(1, 0, At, B0); PG8_MMA(1, 1, At, B1); PG8_BAR; PG8_SCHED;
.LBB0_485:
	s_add_i32 s24, s53, -2
	s_cmp_ge_i32 s24, s28
	s_cselect_b32 s54, s29, 0
	s_cselect_b32 s55, s45, 0
	s_cmp_ge_i32 s53, s28
	s_cselect_b32 s25, s29, 0
	s_cselect_b32 s24, s45, 0
	s_add_u32 s25, s22, s25
	s_addc_u32 s24, s23, s24
	s_add_u32 s58, s25, 0x80
	s_addc_u32 s24, s24, 0
	s_add_i32 s60, 0, 0x10000
	s_cmp_eq_u32 s44, s53
	s_cselect_b32 s25, s5, s24
	s_cselect_b32 s24, s4, s58
	v_add_u32_e32 v145, s60, v142
	s_cselect_b32 s59, s21, s52
	s_cselect_b32 s58, s20, s51
	s_add_i32 s61, 0, 0x14000
	ds_read_b128 v[146:149], v145
	ds_read_b128 v[150:153], v145 offset:1024
	ds_read_b128 v[154:157], v145 offset:2048
	ds_read_b128 v[158:161], v145 offset:3072
	v_add_u32_e32 v145, s61, v142
	ds_read_b128 v[162:165], v145
	ds_read_b128 v[166:169], v145 offset:1024
	ds_read_b128 v[170:173], v145 offset:2048
	ds_read_b128 v[174:177], v145 offset:3072
	v_lshl_add_u64 v[190:191], s[22:23], 0, v[140:141]
	v_lshl_add_u64 v[190:191], v[190:191], 0, s[54:55]
	s_add_i32 m0, s37, 0xc000
	ds_read_b128 v[178:181], v144
	ds_read_b128 v[182:185], v144 offset:1024
	ds_read_b128 v[186:189], v144 offset:2048
	ds_read_b128 v[204:207], v144 offset:3072
	ds_read_b128 v[208:211], v144 offset:4096
	ds_read_b128 v[212:215], v144 offset:5120
	ds_read_b128 v[216:219], v144 offset:6144
	ds_read_b128 v[220:223], v144 offset:7168
	global_load_lds_dwordx4 v[190:191], off
	v_lshl_add_u64 v[190:191], s[22:23], 0, v[138:139]
	v_lshl_add_u64 v[190:191], v[190:191], 0, s[54:55]
	s_add_i32 m0, s37, 0xe000
	s_nop 0
	global_load_lds_dwordx4 v[190:191], off
	s_waitcnt vmcnt(8)
	s_waitcnt lgkmcnt(0)
	s_barrier
	s_setprio 1
	v_mfma_f32_16x16x32_bf16 v[124:127], v[146:149], v[178:181], v[124:127]
	v_mfma_f32_16x16x32_bf16 v[128:131], v[154:157], v[178:181], v[128:131]
	v_mfma_f32_16x16x32_bf16 v[112:115], v[146:149], v[186:189], v[112:115]
	v_mfma_f32_16x16x32_bf16 v[108:111], v[154:157], v[186:189], v[108:111]
	v_mfma_f32_16x16x32_bf16 v[96:99], v[146:149], v[208:211], v[96:99]
	v_mfma_f32_16x16x32_bf16 v[92:95], v[154:157], v[208:211], v[92:95]
	v_mfma_f32_16x16x32_bf16 v[80:83], v[146:149], v[216:219], v[80:83]
	v_mfma_f32_16x16x32_bf16 v[76:79], v[154:157], v[216:219], v[76:79]
	v_mfma_f32_16x16x32_bf16 v[124:127], v[150:153], v[182:185], v[124:127]
	v_mfma_f32_16x16x32_bf16 v[128:131], v[158:161], v[182:185], v[128:131]
	v_mfma_f32_16x16x32_bf16 v[112:115], v[150:153], v[204:207], v[112:115]
	v_mfma_f32_16x16x32_bf16 v[108:111], v[158:161], v[204:207], v[108:111]
	v_mfma_f32_16x16x32_bf16 v[96:99], v[150:153], v[212:215], v[96:99]
	v_mfma_f32_16x16x32_bf16 v[92:95], v[158:161], v[212:215], v[92:95]
	v_mfma_f32_16x16x32_bf16 v[80:83], v[150:153], v[220:223], v[80:83]
	v_mfma_f32_16x16x32_bf16 v[76:79], v[158:161], v[220:223], v[76:79]
	s_setprio 0
	s_setprio 1
	v_mfma_f32_16x16x32_bf16 v[120:123], v[162:165], v[178:181], v[120:123]
	v_mfma_f32_16x16x32_bf16 v[116:119], v[170:173], v[178:181], v[116:119]
	v_mfma_f32_16x16x32_bf16 v[104:107], v[162:165], v[186:189], v[104:107]
	v_mfma_f32_16x16x32_bf16 v[100:103], v[170:173], v[186:189], v[100:103]
	v_mfma_f32_16x16x32_bf16 v[88:91], v[162:165], v[208:211], v[88:91]
	v_mfma_f32_16x16x32_bf16 v[84:87], v[170:173], v[208:211], v[84:87]
	v_mfma_f32_16x16x32_bf16 v[72:75], v[162:165], v[216:219], v[72:75]
	v_mfma_f32_16x16x32_bf16 v[68:71], v[170:173], v[216:219], v[68:71]
	v_mfma_f32_16x16x32_bf16 v[120:123], v[166:169], v[182:185], v[120:123]
	v_mfma_f32_16x16x32_bf16 v[116:119], v[174:177], v[182:185], v[116:119]
	v_mfma_f32_16x16x32_bf16 v[104:107], v[166:169], v[204:207], v[104:107]
	v_mfma_f32_16x16x32_bf16 v[100:103], v[174:177], v[204:207], v[100:103]
	v_mfma_f32_16x16x32_bf16 v[88:91], v[166:169], v[212:215], v[88:91]
	v_mfma_f32_16x16x32_bf16 v[84:87], v[174:177], v[212:215], v[84:87]
	v_mfma_f32_16x16x32_bf16 v[72:75], v[166:169], v[220:223], v[72:75]
	v_mfma_f32_16x16x32_bf16 v[68:71], v[174:177], v[220:223], v[68:71]
	s_setprio 0
	s_barrier
	s_add_i32 s54, s60, s35
	v_lshl_add_u64 v[190:191], s[58:59], 0, v[134:135]
	s_mov_b32 m0, s54
	ds_read_b128 v[178:181], v144 offset:16384
	ds_read_b128 v[182:185], v144 offset:17408
	ds_read_b128 v[186:189], v144 offset:18432
	ds_read_b128 v[204:207], v144 offset:19456
	ds_read_b128 v[208:211], v144 offset:20480
	ds_read_b128 v[212:215], v144 offset:21504
	ds_read_b128 v[216:219], v144 offset:22528
	ds_read_b128 v[220:223], v144 offset:23552
	global_load_lds_dwordx4 v[190:191], off
	s_add_i32 m0, s54, 0x2000
	s_add_u32 s54, s58, s8
	v_lshl_add_u64 v[230:231], s[58:59], 0, v[0:1]
	s_addc_u32 s55, s59, s9
	s_add_i32 s58, s61, s35
	global_load_lds_dwordx4 v[230:231], off
	v_lshl_add_u64 v[232:233], s[54:55], 0, v[134:135]
	s_mov_b32 m0, s58
	v_lshl_add_u64 v[238:239], s[54:55], 0, v[0:1]
	global_load_lds_dwordx4 v[232:233], off
	s_add_i32 m0, s58, 0x2000
	v_lshl_add_u64 v[240:241], s[24:25], 0, v[136:137]
	global_load_lds_dwordx4 v[238:239], off
	s_mov_b32 m0, s37
	v_lshl_add_u64 v[242:243], s[24:25], 0, v[132:133]
	global_load_lds_dwordx4 v[240:241], off
	s_mov_b32 m0, s38
	s_nop 0
	global_load_lds_dwordx4 v[242:243], off
	s_waitcnt vmcnt(8)
	s_waitcnt lgkmcnt(0)
	s_barrier
; #define PG8_STAGE(bufoff, gbase, voff) do { _Pragma("unroll") for (int _i = 0; _i < 2; ++_i) \
;         __builtin_amdgcn_global_load_lds((const unsigned*)((const char*)(gbase) + (voff)[_i]), (PG8_LAS unsigned*)(lds + (bufoff) + ldsw + _i * 8192), 16, 0, 0); } while (0)
; #define PG8_LDA(dst, b, h) do { _Pragma("unroll") for (int m = 0; m < 4; ++m) _Pragma("unroll") for (int k = 0; k < 2; ++k) dst[m][k] = *(const PG8_LAS bf16x8*)(lds + PG8_SA(b, h) + aoff + m * 2048 + k * 1024); } while (0)
; #define PG8_LDB(dst, b, h) do { _Pragma("unroll") for (int n = 0; n < 2; ++n) _Pragma("unroll") for (int k = 0; k < 2; ++k) dst[n][k] = *(const PG8_LAS bf16x8*)(lds + PG8_SB(b, h) + boff + n * 2048 + k * 1024); } while (0)
; #define PG8_MMA(ai, bj, At, Bt) do { __builtin_amdgcn_s_setprio(1); _Pragma("unroll") for (int m = 0; m < 4; ++m) _Pragma("unroll") for (int n = 0; n < 2; ++n) _Pragma("unroll") for (int k = 0; k < 2; ++k) \
;         acc[ai][bj][m][n] = __builtin_amdgcn_mfma_f32_16x16x32_bf16(Bt[n][k], At[m][k], acc[ai][bj][m][n], 0, 0, 0); __builtin_amdgcn_s_setprio(0); } while (0)
; #define PG8_WAIT_V(n) asm volatile("s_waitcnt vmcnt(" #n ")" ::: "memory")
; #define PG8_WAIT_L(n) asm volatile("s_waitcnt lgkmcnt(" #n ")" ::: "memory")
; #define PG8_BAR __builtin_amdgcn_s_barrier()
; #define PG8_SCHED __builtin_amdgcn_sched_barrier(0)
; template <class Epi, class Sched, bool ALIGN_EPI = false, bool SP2 = false>
; __device__ __forceinline__ void gemm_phase(PG8_LAS unsigned char* lds, const Gemm g, const Sched& S, const Epi& E, int tid_in) {
;     ...
;             PG8_WAIT_V(8); PG8_WAIT_L(0); PG8_BAR; PG8_MMA(1, 0, At, B0); PG8_MMA(1, 1, At, B1); PG8_BAR; PG8_SCHED;
;             PG8_LDB(B0, 1, 0); PG8_LDB(B1, 1, 1); PG8_SCHED; PG8_LDA(At, 1, 0); PG8_STAGE(PG8_SA(0, 1), a2 + hsA, voffA);
;             PG8_WAIT_V(8); PG8_WAIT_L(0); PG8_BAR; PG8_MMA(0, 0, At, B0); PG8_MMA(0, 1, At, B1); PG8_BAR; PG8_SCHED;
	s_setprio 1
	v_mfma_f32_16x16x32_bf16 v[64:67], v[146:149], v[178:181], v[64:67]
	v_mfma_f32_16x16x32_bf16 v[60:63], v[154:157], v[178:181], v[60:63]
	v_mfma_f32_16x16x32_bf16 v[48:51], v[146:149], v[186:189], v[48:51]
	v_mfma_f32_16x16x32_bf16 v[44:47], v[154:157], v[186:189], v[44:47]
	v_mfma_f32_16x16x32_bf16 v[32:35], v[146:149], v[208:211], v[32:35]
	v_mfma_f32_16x16x32_bf16 v[28:31], v[154:157], v[208:211], v[28:31]
	v_mfma_f32_16x16x32_bf16 v[16:19], v[146:149], v[216:219], v[16:19]
	v_mfma_f32_16x16x32_bf16 v[12:15], v[154:157], v[216:219], v[12:15]
	v_mfma_f32_16x16x32_bf16 v[64:67], v[150:153], v[182:185], v[64:67]
	v_mfma_f32_16x16x32_bf16 v[60:63], v[158:161], v[182:185], v[60:63]
	v_mfma_f32_16x16x32_bf16 v[48:51], v[150:153], v[204:207], v[48:51]
	v_mfma_f32_16x16x32_bf16 v[44:47], v[158:161], v[204:207], v[44:47]
	v_mfma_f32_16x16x32_bf16 v[32:35], v[150:153], v[212:215], v[32:35]
	v_mfma_f32_16x16x32_bf16 v[28:31], v[158:161], v[212:215], v[28:31]
	v_mfma_f32_16x16x32_bf16 v[16:19], v[150:153], v[220:223], v[16:19]
	v_mfma_f32_16x16x32_bf16 v[12:15], v[158:161], v[220:223], v[12:15]
	s_setprio 0
	s_setprio 1
	v_mfma_f32_16x16x32_bf16 v[56:59], v[162:165], v[178:181], v[56:59]
	v_mfma_f32_16x16x32_bf16 v[52:55], v[170:173], v[178:181], v[52:55]
	v_mfma_f32_16x16x32_bf16 v[40:43], v[162:165], v[186:189], v[40:43]
	v_mfma_f32_16x16x32_bf16 v[36:39], v[170:173], v[186:189], v[36:39]
	v_mfma_f32_16x16x32_bf16 v[24:27], v[162:165], v[208:211], v[24:27]
	v_mfma_f32_16x16x32_bf16 v[20:23], v[170:173], v[208:211], v[20:23]
	v_mfma_f32_16x16x32_bf16 v[8:11], v[162:165], v[216:219], v[8:11]
	v_mfma_f32_16x16x32_bf16 v[4:7], v[170:173], v[216:219], v[4:7]
	v_mfma_f32_16x16x32_bf16 v[56:59], v[166:169], v[182:185], v[56:59]
	v_mfma_f32_16x16x32_bf16 v[52:55], v[174:177], v[182:185], v[52:55]
	v_mfma_f32_16x16x32_bf16 v[40:43], v[166:169], v[204:207], v[40:43]
	v_mfma_f32_16x16x32_bf16 v[36:39], v[174:177], v[204:207], v[36:39]
	v_mfma_f32_16x16x32_bf16 v[24:27], v[166:169], v[212:215], v[24:27]
	v_mfma_f32_16x16x32_bf16 v[20:23], v[174:177], v[212:215], v[20:23]
	v_mfma_f32_16x16x32_bf16 v[8:11], v[166:169], v[220:223], v[8:11]
	v_mfma_f32_16x16x32_bf16 v[4:7], v[174:177], v[220:223], v[4:7]
	s_setprio 0
	s_barrier
	s_add_i32 s54, 0, 0x18000
	v_add_u32_e32 v145, s54, v142
	s_add_i32 s55, 0, 0x1c000
	ds_read_b128 v[146:149], v145
	ds_read_b128 v[150:153], v145 offset:1024
	ds_read_b128 v[154:157], v145 offset:2048
	ds_read_b128 v[158:161], v145 offset:3072
	v_add_u32_e32 v145, s55, v142
	ds_read_b128 v[162:165], v145
	ds_read_b128 v[166:169], v145 offset:1024
	ds_read_b128 v[170:173], v145 offset:2048
	ds_read_b128 v[174:177], v145 offset:3072
	s_add_u32 s24, s24, s6
	s_addc_u32 s25, s25, s7
	s_mov_b32 m0, s39
	v_lshl_add_u64 v[244:245], s[24:25], 0, v[136:137]
	ds_read_b128 v[178:181], v144 offset:32768
	ds_read_b128 v[182:185], v144 offset:33792
	ds_read_b128 v[186:189], v144 offset:34816
	ds_read_b128 v[204:207], v144 offset:35840
	ds_read_b128 v[208:211], v144 offset:36864
	ds_read_b128 v[212:215], v144 offset:37888
	ds_read_b128 v[216:219], v144 offset:38912
	ds_read_b128 v[220:223], v144 offset:39936
	global_load_lds_dwordx4 v[244:245], off
	v_lshl_add_u64 v[244:245], s[24:25], 0, v[132:133]
	s_mov_b32 m0, s40
	s_nop 0
	global_load_lds_dwordx4 v[244:245], off
	s_waitcnt vmcnt(8)
	s_waitcnt lgkmcnt(0)
	s_barrier
	s_setprio 1
	v_mfma_f32_16x16x32_bf16 v[124:127], v[146:149], v[178:181], v[124:127]
	v_mfma_f32_16x16x32_bf16 v[128:131], v[154:157], v[178:181], v[128:131]
	v_mfma_f32_16x16x32_bf16 v[112:115], v[146:149], v[186:189], v[112:115]
	v_mfma_f32_16x16x32_bf16 v[108:111], v[154:157], v[186:189], v[108:111]
	v_mfma_f32_16x16x32_bf16 v[96:99], v[146:149], v[208:211], v[96:99]
	v_mfma_f32_16x16x32_bf16 v[92:95], v[154:157], v[208:211], v[92:95]
	v_mfma_f32_16x16x32_bf16 v[80:83], v[146:149], v[216:219], v[80:83]
	v_mfma_f32_16x16x32_bf16 v[76:79], v[154:157], v[216:219], v[76:79]
	v_mfma_f32_16x16x32_bf16 v[124:127], v[150:153], v[182:185], v[124:127]
	v_mfma_f32_16x16x32_bf16 v[128:131], v[158:161], v[182:185], v[128:131]
	v_mfma_f32_16x16x32_bf16 v[112:115], v[150:153], v[204:207], v[112:115]
	v_mfma_f32_16x16x32_bf16 v[108:111], v[158:161], v[204:207], v[108:111]
	v_mfma_f32_16x16x32_bf16 v[96:99], v[150:153], v[212:215], v[96:99]
	v_mfma_f32_16x16x32_bf16 v[92:95], v[158:161], v[212:215], v[92:95]
	v_mfma_f32_16x16x32_bf16 v[80:83], v[150:153], v[220:223], v[80:83]
	v_mfma_f32_16x16x32_bf16 v[76:79], v[158:161], v[220:223], v[76:79]
	s_setprio 0
	s_setprio 1
	v_mfma_f32_16x16x32_bf16 v[120:123], v[162:165], v[178:181], v[120:123]
	v_mfma_f32_16x16x32_bf16 v[116:119], v[170:173], v[178:181], v[116:119]
	v_mfma_f32_16x16x32_bf16 v[104:107], v[162:165], v[186:189], v[104:107]
	v_mfma_f32_16x16x32_bf16 v[100:103], v[170:173], v[186:189], v[100:103]
	v_mfma_f32_16x16x32_bf16 v[88:91], v[162:165], v[208:211], v[88:91]
	v_mfma_f32_16x16x32_bf16 v[84:87], v[170:173], v[208:211], v[84:87]
	v_mfma_f32_16x16x32_bf16 v[72:75], v[162:165], v[216:219], v[72:75]
	v_mfma_f32_16x16x32_bf16 v[68:71], v[170:173], v[216:219], v[68:71]
	v_mfma_f32_16x16x32_bf16 v[120:123], v[166:169], v[182:185], v[120:123]
	v_mfma_f32_16x16x32_bf16 v[116:119], v[174:177], v[182:185], v[116:119]
	v_mfma_f32_16x16x32_bf16 v[104:107], v[166:169], v[204:207], v[104:107]
	v_mfma_f32_16x16x32_bf16 v[100:103], v[174:177], v[204:207], v[100:103]
	v_mfma_f32_16x16x32_bf16 v[88:91], v[166:169], v[212:215], v[88:91]
	v_mfma_f32_16x16x32_bf16 v[84:87], v[174:177], v[212:215], v[84:87]
	v_mfma_f32_16x16x32_bf16 v[72:75], v[166:169], v[220:223], v[72:75]
	v_mfma_f32_16x16x32_bf16 v[68:71], v[174:177], v[220:223], v[68:71]
	s_setprio 0
	s_barrier
; #define PG8_STAGE(bufoff, gbase, voff) do { _Pragma("unroll") for (int _i = 0; _i < 2; ++_i) \
;         __builtin_amdgcn_global_load_lds((const unsigned*)((const char*)(gbase) + (voff)[_i]), (PG8_LAS unsigned*)(lds + (bufoff) + ldsw + _i * 8192), 16, 0, 0); } while (0)
; #define PG8_LDA(dst, b, h) do { _Pragma("unroll") for (int m = 0; m < 4; ++m) _Pragma("unroll") for (int k = 0; k < 2; ++k) dst[m][k] = *(const PG8_LAS bf16x8*)(lds + PG8_SA(b, h) + aoff + m * 2048 + k * 1024); } while (0)
; #define PG8_MMA(ai, bj, At, Bt) do { __builtin_amdgcn_s_setprio(1); _Pragma("unroll") for (int m = 0; m < 4; ++m) _Pragma("unroll") for (int n = 0; n < 2; ++n) _Pragma("unroll") for (int k = 0; k < 2; ++k) \
;         acc[ai][bj][m][n] = __builtin_amdgcn_mfma_f32_16x16x32_bf16(Bt[n][k], At[m][k], acc[ai][bj][m][n], 0, 0, 0); __builtin_amdgcn_s_setprio(0); } while (0)
; #define PG8_WAIT_V(n) asm volatile("s_waitcnt vmcnt(" #n ")" ::: "memory")
; #define PG8_WAIT_L(n) asm volatile("s_waitcnt lgkmcnt(" #n ")" ::: "memory")
; #define PG8_BAR __builtin_amdgcn_s_barrier()
; #define PG8_SCHED __builtin_amdgcn_sched_barrier(0)
; template <class Epi, class Sched, bool ALIGN_EPI = false, bool SP2 = false>
; __device__ __forceinline__ void gemm_phase(PG8_LAS unsigned char* lds, const Gemm g, const Sched& S, const Epi& E, int tid_in) {
;     ...
;             PG8_LDA(At, 1, 1); PG8_STAGE(PG8_SB(1, 0), b3, voffB); PG8_STAGE(PG8_SB(1, 1), b3 + hsB, voffB); PG8_STAGE(PG8_SA(1, 0), a3, voffA);
;             PG8_WAIT_V(8); PG8_WAIT_L(0); PG8_BAR; PG8_MMA(1, 0, At, B0); PG8_MMA(1, 1, At, B1); PG8_BAR; PG8_SCHED;
	s_add_i32 s24, s54, s35
	v_lshl_add_u64 v[190:191], v[190:191], 0, s[80:81]
	s_mov_b32 m0, s24
	ds_read_b128 v[178:181], v144 offset:49152
	ds_read_b128 v[182:185], v144 offset:50176
	ds_read_b128 v[186:189], v144 offset:51200
	ds_read_b128 v[204:207], v144 offset:52224
	ds_read_b128 v[208:211], v144 offset:53248
	ds_read_b128 v[212:215], v144 offset:54272
	ds_read_b128 v[216:219], v144 offset:55296
	ds_read_b128 v[220:223], v144 offset:56320
	global_load_lds_dwordx4 v[190:191], off
	v_lshl_add_u64 v[190:191], v[230:231], 0, s[80:81]
	s_add_i32 m0, s24, 0x2000
	s_add_i32 s24, s55, s35
	global_load_lds_dwordx4 v[190:191], off
	v_lshl_add_u64 v[190:191], v[232:233], 0, s[80:81]
	s_mov_b32 m0, s24
	s_nop 0
	global_load_lds_dwordx4 v[190:191], off
	v_lshl_add_u64 v[190:191], v[238:239], 0, s[80:81]
	s_add_i32 m0, s24, 0x2000
	s_nop 0
	global_load_lds_dwordx4 v[190:191], off
	v_lshl_add_u64 v[190:191], v[240:241], 0, s[80:81]
	s_mov_b32 m0, s41
	s_nop 0
	global_load_lds_dwordx4 v[190:191], off
	v_lshl_add_u64 v[190:191], v[242:243], 0, s[80:81]
	s_mov_b32 m0, s42
	s_nop 0
	global_load_lds_dwordx4 v[190:191], off
	s_waitcnt vmcnt(8)
	s_waitcnt lgkmcnt(0)
	s_barrier
	s_setprio 1
	v_mfma_f32_16x16x32_bf16 v[64:67], v[146:149], v[178:181], v[64:67]
	v_mfma_f32_16x16x32_bf16 v[60:63], v[154:157], v[178:181], v[60:63]
	v_mfma_f32_16x16x32_bf16 v[48:51], v[146:149], v[186:189], v[48:51]
	v_mfma_f32_16x16x32_bf16 v[44:47], v[154:157], v[186:189], v[44:47]
	v_mfma_f32_16x16x32_bf16 v[32:35], v[146:149], v[208:211], v[32:35]
	v_mfma_f32_16x16x32_bf16 v[28:31], v[154:157], v[208:211], v[28:31]
	v_mfma_f32_16x16x32_bf16 v[16:19], v[146:149], v[216:219], v[16:19]
	v_mfma_f32_16x16x32_bf16 v[12:15], v[154:157], v[216:219], v[12:15]
	v_mfma_f32_16x16x32_bf16 v[64:67], v[150:153], v[182:185], v[64:67]
	v_mfma_f32_16x16x32_bf16 v[60:63], v[158:161], v[182:185], v[60:63]
	v_mfma_f32_16x16x32_bf16 v[48:51], v[150:153], v[204:207], v[48:51]
	v_mfma_f32_16x16x32_bf16 v[44:47], v[158:161], v[204:207], v[44:47]
	v_mfma_f32_16x16x32_bf16 v[32:35], v[150:153], v[212:215], v[32:35]
	v_mfma_f32_16x16x32_bf16 v[28:31], v[158:161], v[212:215], v[28:31]
	v_mfma_f32_16x16x32_bf16 v[16:19], v[150:153], v[220:223], v[16:19]
	v_mfma_f32_16x16x32_bf16 v[12:15], v[158:161], v[220:223], v[12:15]
	s_setprio 0
	s_setprio 1
	v_mfma_f32_16x16x32_bf16 v[56:59], v[162:165], v[178:181], v[56:59]
	v_mfma_f32_16x16x32_bf16 v[52:55], v[170:173], v[178:181], v[52:55]
	v_mfma_f32_16x16x32_bf16 v[40:43], v[162:165], v[186:189], v[40:43]
	v_mfma_f32_16x16x32_bf16 v[36:39], v[170:173], v[186:189], v[36:39]
	v_mfma_f32_16x16x32_bf16 v[24:27], v[162:165], v[208:211], v[24:27]
	v_mfma_f32_16x16x32_bf16 v[20:23], v[170:173], v[208:211], v[20:23]
	v_mfma_f32_16x16x32_bf16 v[8:11], v[162:165], v[216:219], v[8:11]
	v_mfma_f32_16x16x32_bf16 v[4:7], v[170:173], v[216:219], v[4:7]
	v_mfma_f32_16x16x32_bf16 v[56:59], v[166:169], v[182:185], v[56:59]
	v_mfma_f32_16x16x32_bf16 v[52:55], v[174:177], v[182:185], v[52:55]
	v_mfma_f32_16x16x32_bf16 v[40:43], v[166:169], v[204:207], v[40:43]
	v_mfma_f32_16x16x32_bf16 v[36:39], v[174:177], v[204:207], v[36:39]
	v_mfma_f32_16x16x32_bf16 v[24:27], v[166:169], v[212:215], v[24:27]
	v_mfma_f32_16x16x32_bf16 v[20:23], v[174:177], v[212:215], v[20:23]
	v_mfma_f32_16x16x32_bf16 v[8:11], v[166:169], v[220:223], v[8:11]
	v_mfma_f32_16x16x32_bf16 v[4:7], v[174:177], v[220:223], v[4:7]
	s_setprio 0
	s_barrier
	s_add_i32 s24, s53, 2
	s_add_u32 s51, s51, 0x100
	s_addc_u32 s52, s52, 0
	s_add_u32 s22, s22, 0x100
	s_addc_u32 s23, s23, 0
	s_cmp_ge_i32 s53, s44
	s_mov_b32 s53, s24
	s_cbranch_scc0 .LBB0_485

; #define PG8_STAGE(bufoff, gbase, voff) do { _Pragma("unroll") for (int _i = 0; _i < 2; ++_i) \
;         __builtin_amdgcn_global_load_lds((const unsigned*)((const char*)(gbase) + (voff)[_i]), (PG8_LAS unsigned*)(lds + (bufoff) + ldsw + _i * 8192), 16, 0, 0); } while (0)
; #define PG8_LDA(dst, b, h) do { _Pragma("unroll") for (int m = 0; m < 4; ++m) _Pragma("unroll") for (int k = 0; k < 2; ++k) dst[m][k] = *(const PG8_LAS bf16x8*)(lds + PG8_SA(b, h) + aoff + m * 2048 + k * 1024); } while (0)
; #define PG8_LDB(dst, b, h) do { _Pragma("unroll") for (int n = 0; n < 2; ++n) _Pragma("unroll") for (int k = 0; k < 2; ++k) dst[n][k] = *(const PG8_LAS bf16x8*)(lds + PG8_SB(b, h) + boff + n * 2048 + k * 1024); } while (0)
; #define PG8_MMA(ai, bj, At, Bt) do { __builtin_amdgcn_s_setprio(1); _Pragma("unroll") for (int m = 0; m < 4; ++m) _Pragma("unroll") for (int n = 0; n < 2; ++n) _Pragma("unroll") for (int k = 0; k < 2; ++k) \
;         acc[ai][bj][m][n] = __builtin_amdgcn_mfma_f32_16x16x32_bf16(Bt[n][k], At[m][k], acc[ai][bj][m][n], 0, 0, 0); __builtin_amdgcn_s_setprio(0); } while (0)
; #define PG8_WAIT_V(n) asm volatile("s_waitcnt vmcnt(" #n ")" ::: "memory")
; #define PG8_WAIT_L(n) asm volatile("s_waitcnt lgkmcnt(" #n ")" ::: "memory")
; template <class Epi, class Sched, bool ALIGN_EPI = false, bool SP2 = false>
; __device__ __forceinline__ void gemm_phase(PG8_LAS unsigned char* lds, const Gemm g, const Sched& S, const Epi& E, int tid_in) {
;     ...
;             const char* a1 = cA + (size_t)(t + 1) * kstep + (t >= jt ? jb : 0);
;             const char* a2 = last ? nA : cA + (size_t)(t + 2) * kstep + (t + 2 >= jt ? jb : 0); const char* b2 = last ? nB : cB + (size_t)(t + 2) * kstep;
;             const char* a3 = a2 + kstep; const char* b3 = b2 + kstep;
;             if (last && has_next) S.a_ready(nxt);
;             if constexpr (SP2) {
;             PG8_LDB(B0, 0, 0); PG8_LDB(B1, 0, 1); PG8_SCHED; PG8_LDA(At, 0, 0); PG8_STAGE(PG8_SA(1, 1), a1 + hsA, voffA);
;             PG8_WAIT_V(8); PG8_WAIT_L(0); PG8_BAR; PG8_MMA(0, 0, At, B0); PG8_MMA(0, 1, At, B1); PG8_BAR; PG8_SCHED;
;             PG8_LDA(At, 0, 1); PG8_STAGE(PG8_SB(0, 0), b2, voffB); PG8_STAGE(PG8_SB(0, 1), b2 + hsB, voffB); PG8_STAGE(PG8_SA(0, 0), a2, voffA);
;             PG8_WAIT_V(8); PG8_WAIT_L(0); PG8_BAR; PG8_MMA(1, 0, At, B0); PG8_MMA(1, 1, At, B1); PG8_BAR; PG8_SCHED;
.LBB0_667:
	s_add_i32 s24, s55, -2
	s_cmp_ge_i32 s24, s28
	s_cselect_b32 s58, s29, 0
	s_cselect_b32 s59, s47, 0
	s_cmp_ge_i32 s55, s28
	s_cselect_b32 s25, s29, 0
	s_cselect_b32 s24, s47, 0
	s_add_u32 s25, s22, s25
	s_addc_u32 s24, s23, s24
	s_add_u32 s60, s25, 0x80
	s_addc_u32 s24, s24, 0
	s_add_i32 s62, 0, 0x10000
	s_cmp_eq_u32 s46, s55
	s_cselect_b32 s25, s1, s24
	s_cselect_b32 s24, s0, s60
	s_cselect_b32 s61, s5, s54
	s_cselect_b32 s60, s4, s53
	s_add_i32 s63, 0, 0x14000
	v_add_u32_e32 v48, s62, v162
	v_add_u32_e32 v165, s63, v162
	ds_read_b128 v[28:31], v48
	ds_read_b128 v[32:35], v48 offset:1024
	ds_read_b128 v[44:47], v48 offset:2048
	ds_read_b128 v[48:51], v48 offset:3072
	ds_read_b128 v[158:161], v165
	ds_read_b128 v[166:169], v165 offset:1024
	ds_read_b128 v[170:173], v165 offset:2048
	ds_read_b128 v[174:177], v165 offset:3072
	v_lshl_add_u64 v[190:191], s[22:23], 0, v[156:157]
	v_lshl_add_u64 v[190:191], v[190:191], 0, s[58:59]
	s_add_i32 m0, s38, 0xc000
	ds_read_b128 v[178:181], v164
	ds_read_b128 v[182:185], v164 offset:1024
	ds_read_b128 v[186:189], v164 offset:2048
	ds_read_b128 v[204:207], v164 offset:3072
	ds_read_b128 v[208:211], v164 offset:4096
	ds_read_b128 v[212:215], v164 offset:5120
	ds_read_b128 v[216:219], v164 offset:6144
	ds_read_b128 v[220:223], v164 offset:7168
	global_load_lds_dwordx4 v[190:191], off
	v_lshl_add_u64 v[190:191], s[22:23], 0, v[154:155]
	v_lshl_add_u64 v[190:191], v[190:191], 0, s[58:59]
	s_add_i32 m0, s38, 0xe000
	s_nop 0
	global_load_lds_dwordx4 v[190:191], off
	s_waitcnt vmcnt(8)
	s_waitcnt lgkmcnt(0)
	s_barrier
	s_setprio 1
	v_mfma_f32_16x16x32_bf16 v[140:143], v[28:31], v[178:181], v[140:143]
	v_mfma_f32_16x16x32_bf16 v[144:147], v[44:47], v[178:181], v[144:147]
	v_mfma_f32_16x16x32_bf16 v[128:131], v[28:31], v[186:189], v[128:131]
	v_mfma_f32_16x16x32_bf16 v[124:127], v[44:47], v[186:189], v[124:127]
	v_mfma_f32_16x16x32_bf16 v[112:115], v[28:31], v[208:211], v[112:115]
	v_mfma_f32_16x16x32_bf16 v[108:111], v[44:47], v[208:211], v[108:111]
	v_mfma_f32_16x16x32_bf16 v[96:99], v[28:31], v[216:219], v[96:99]
	v_mfma_f32_16x16x32_bf16 v[92:95], v[44:47], v[216:219], v[92:95]
	v_mfma_f32_16x16x32_bf16 v[140:143], v[32:35], v[182:185], v[140:143]
	v_mfma_f32_16x16x32_bf16 v[144:147], v[48:51], v[182:185], v[144:147]
	v_mfma_f32_16x16x32_bf16 v[128:131], v[32:35], v[204:207], v[128:131]
	v_mfma_f32_16x16x32_bf16 v[124:127], v[48:51], v[204:207], v[124:127]
	v_mfma_f32_16x16x32_bf16 v[112:115], v[32:35], v[212:215], v[112:115]
	v_mfma_f32_16x16x32_bf16 v[108:111], v[48:51], v[212:215], v[108:111]
	v_mfma_f32_16x16x32_bf16 v[96:99], v[32:35], v[220:223], v[96:99]
	v_mfma_f32_16x16x32_bf16 v[92:95], v[48:51], v[220:223], v[92:95]
	s_setprio 0
	s_setprio 1
	v_mfma_f32_16x16x32_bf16 v[136:139], v[158:161], v[178:181], v[136:139]
	v_mfma_f32_16x16x32_bf16 v[132:135], v[170:173], v[178:181], v[132:135]
	v_mfma_f32_16x16x32_bf16 v[120:123], v[158:161], v[186:189], v[120:123]
	v_mfma_f32_16x16x32_bf16 v[116:119], v[170:173], v[186:189], v[116:119]
	v_mfma_f32_16x16x32_bf16 v[104:107], v[158:161], v[208:211], v[104:107]
	v_mfma_f32_16x16x32_bf16 v[100:103], v[170:173], v[208:211], v[100:103]
	v_mfma_f32_16x16x32_bf16 v[88:91], v[158:161], v[216:219], v[88:91]
	v_mfma_f32_16x16x32_bf16 v[84:87], v[170:173], v[216:219], v[84:87]
	v_mfma_f32_16x16x32_bf16 v[136:139], v[166:169], v[182:185], v[136:139]
	v_mfma_f32_16x16x32_bf16 v[132:135], v[174:177], v[182:185], v[132:135]
	v_mfma_f32_16x16x32_bf16 v[120:123], v[166:169], v[204:207], v[120:123]
	v_mfma_f32_16x16x32_bf16 v[116:119], v[174:177], v[204:207], v[116:119]
	v_mfma_f32_16x16x32_bf16 v[104:107], v[166:169], v[212:215], v[104:107]
	v_mfma_f32_16x16x32_bf16 v[100:103], v[174:177], v[212:215], v[100:103]
	v_mfma_f32_16x16x32_bf16 v[88:91], v[166:169], v[220:223], v[88:91]
	v_mfma_f32_16x16x32_bf16 v[84:87], v[174:177], v[220:223], v[84:87]
	s_setprio 0
	s_barrier
	s_add_i32 s58, s62, s36
	v_lshl_add_u64 v[190:191], s[60:61], 0, v[150:151]
	s_mov_b32 m0, s58
	ds_read_b128 v[178:181], v164 offset:16384
	ds_read_b128 v[182:185], v164 offset:17408
	ds_read_b128 v[186:189], v164 offset:18432
	ds_read_b128 v[204:207], v164 offset:19456
	ds_read_b128 v[208:211], v164 offset:20480
	ds_read_b128 v[212:215], v164 offset:21504
	ds_read_b128 v[216:219], v164 offset:22528
	ds_read_b128 v[220:223], v164 offset:23552
	global_load_lds_dwordx4 v[190:191], off
	s_add_i32 m0, s58, 0x2000
	s_add_u32 s58, s60, s8
	v_lshl_add_u64 v[230:231], s[60:61], 0, v[0:1]
	s_addc_u32 s59, s61, s9
	s_add_i32 s60, s63, s36
	global_load_lds_dwordx4 v[230:231], off
	v_lshl_add_u64 v[232:233], s[58:59], 0, v[150:151]
	s_mov_b32 m0, s60
	v_lshl_add_u64 v[238:239], s[58:59], 0, v[0:1]
	global_load_lds_dwordx4 v[232:233], off
	s_add_i32 m0, s60, 0x2000
	v_lshl_add_u64 v[240:241], s[24:25], 0, v[152:153]
	global_load_lds_dwordx4 v[238:239], off
	s_mov_b32 m0, s38
	v_lshl_add_u64 v[242:243], s[24:25], 0, v[148:149]
	global_load_lds_dwordx4 v[240:241], off
	s_mov_b32 m0, s39
	s_nop 0
	global_load_lds_dwordx4 v[242:243], off
	s_waitcnt vmcnt(8)
	s_waitcnt lgkmcnt(0)
	s_barrier
; #define PG8_STAGE(bufoff, gbase, voff) do { _Pragma("unroll") for (int _i = 0; _i < 2; ++_i) \
;         __builtin_amdgcn_global_load_lds((const unsigned*)((const char*)(gbase) + (voff)[_i]), (PG8_LAS unsigned*)(lds + (bufoff) + ldsw + _i * 8192), 16, 0, 0); } while (0)
; #define PG8_LDA(dst, b, h) do { _Pragma("unroll") for (int m = 0; m < 4; ++m) _Pragma("unroll") for (int k = 0; k < 2; ++k) dst[m][k] = *(const PG8_LAS bf16x8*)(lds + PG8_SA(b, h) + aoff + m * 2048 + k * 1024); } while (0)
; #define PG8_LDB(dst, b, h) do { _Pragma("unroll") for (int n = 0; n < 2; ++n) _Pragma("unroll") for (int k = 0; k < 2; ++k) dst[n][k] = *(const PG8_LAS bf16x8*)(lds + PG8_SB(b, h) + boff + n * 2048 + k * 1024); } while (0)
; #define PG8_MMA(ai, bj, At, Bt) do { __builtin_amdgcn_s_setprio(1); _Pragma("unroll") for (int m = 0; m < 4; ++m) _Pragma("unroll") for (int n = 0; n < 2; ++n) _Pragma("unroll") for (int k = 0; k < 2; ++k) \
;         acc[ai][bj][m][n] = __builtin_amdgcn_mfma_f32_16x16x32_bf16(Bt[n][k], At[m][k], acc[ai][bj][m][n], 0, 0, 0); __builtin_amdgcn_s_setprio(0); } while (0)
; #define PG8_WAIT_V(n) asm volatile("s_waitcnt vmcnt(" #n ")" ::: "memory")
; #define PG8_WAIT_L(n) asm volatile("s_waitcnt lgkmcnt(" #n ")" ::: "memory")
; #define PG8_BAR __builtin_amdgcn_s_barrier()
; #define PG8_SCHED __builtin_amdgcn_sched_barrier(0)
; template <class Epi, class Sched, bool ALIGN_EPI = false, bool SP2 = false>
; __device__ __forceinline__ void gemm_phase(PG8_LAS unsigned char* lds, const Gemm g, const Sched& S, const Epi& E, int tid_in) {
;     ...
;             PG8_WAIT_V(8); PG8_WAIT_L(0); PG8_BAR; PG8_MMA(1, 0, At, B0); PG8_MMA(1, 1, At, B1); PG8_BAR; PG8_SCHED;
;             PG8_LDB(B0, 1, 0); PG8_LDB(B1, 1, 1); PG8_SCHED; PG8_LDA(At, 1, 0); PG8_STAGE(PG8_SA(0, 1), a2 + hsA, voffA);
;             PG8_WAIT_V(8); PG8_WAIT_L(0); PG8_BAR; PG8_MMA(0, 0, At, B0); PG8_MMA(0, 1, At, B1); PG8_BAR; PG8_SCHED;
	s_setprio 1
	v_mfma_f32_16x16x32_bf16 v[80:83], v[28:31], v[178:181], v[80:83]
	v_mfma_f32_16x16x32_bf16 v[76:79], v[44:47], v[178:181], v[76:79]
	v_mfma_f32_16x16x32_bf16 v[64:67], v[28:31], v[186:189], v[64:67]
	v_mfma_f32_16x16x32_bf16 v[60:63], v[44:47], v[186:189], v[60:63]
	v_mfma_f32_16x16x32_bf16 v[40:43], v[28:31], v[208:211], v[40:43]
	v_mfma_f32_16x16x32_bf16 v[36:39], v[44:47], v[208:211], v[36:39]
	v_mfma_f32_16x16x32_bf16 v[16:19], v[28:31], v[216:219], v[16:19]
	v_mfma_f32_16x16x32_bf16 v[12:15], v[44:47], v[216:219], v[12:15]
	v_mfma_f32_16x16x32_bf16 v[80:83], v[32:35], v[182:185], v[80:83]
	v_mfma_f32_16x16x32_bf16 v[76:79], v[48:51], v[182:185], v[76:79]
	v_mfma_f32_16x16x32_bf16 v[64:67], v[32:35], v[204:207], v[64:67]
	v_mfma_f32_16x16x32_bf16 v[60:63], v[48:51], v[204:207], v[60:63]
	v_mfma_f32_16x16x32_bf16 v[40:43], v[32:35], v[212:215], v[40:43]
	v_mfma_f32_16x16x32_bf16 v[36:39], v[48:51], v[212:215], v[36:39]
	v_mfma_f32_16x16x32_bf16 v[16:19], v[32:35], v[220:223], v[16:19]
	v_mfma_f32_16x16x32_bf16 v[12:15], v[48:51], v[220:223], v[12:15]
	s_setprio 0
	s_setprio 1
	v_mfma_f32_16x16x32_bf16 v[24:27], v[158:161], v[208:211], v[24:27]
	v_mfma_f32_16x16x32_bf16 v[20:23], v[170:173], v[208:211], v[20:23]
	v_mfma_f32_16x16x32_bf16 v[8:11], v[158:161], v[216:219], v[8:11]
	v_mfma_f32_16x16x32_bf16 v[4:7], v[170:173], v[216:219], v[4:7]
	v_mfma_f32_16x16x32_bf16 v[28:31], v[158:161], v[178:181], v[72:75]
	v_mfma_f32_16x16x32_bf16 v[32:35], v[170:173], v[178:181], v[68:71]
	v_mfma_f32_16x16x32_bf16 v[44:47], v[158:161], v[186:189], v[56:59]
	v_mfma_f32_16x16x32_bf16 v[48:51], v[170:173], v[186:189], v[52:55]
	v_mfma_f32_16x16x32_bf16 v[24:27], v[166:169], v[212:215], v[24:27]
	v_mfma_f32_16x16x32_bf16 v[20:23], v[174:177], v[212:215], v[20:23]
	v_mfma_f32_16x16x32_bf16 v[8:11], v[166:169], v[220:223], v[8:11]
	v_mfma_f32_16x16x32_bf16 v[4:7], v[174:177], v[220:223], v[4:7]
	v_mfma_f32_16x16x32_bf16 v[28:31], v[166:169], v[182:185], v[28:31]
	v_mfma_f32_16x16x32_bf16 v[32:35], v[174:177], v[182:185], v[32:35]
	v_mfma_f32_16x16x32_bf16 v[44:47], v[166:169], v[204:207], v[44:47]
	v_mfma_f32_16x16x32_bf16 v[48:51], v[174:177], v[204:207], v[48:51]
	s_setprio 0
	s_barrier
	s_add_i32 s58, 0, 0x18000
	s_add_i32 s59, 0, 0x1c000
	v_add_u32_e32 v72, s58, v162
	v_add_u32_e32 v165, s59, v162
	ds_read_b128 v[52:55], v72
	ds_read_b128 v[56:59], v72 offset:1024
	ds_read_b128 v[68:71], v72 offset:2048
	ds_read_b128 v[72:75], v72 offset:3072
	ds_read_b128 v[158:161], v165
	ds_read_b128 v[166:169], v165 offset:1024
	ds_read_b128 v[170:173], v165 offset:2048
	ds_read_b128 v[174:177], v165 offset:3072
	s_add_u32 s24, s24, s6
	s_addc_u32 s25, s25, s7
	s_mov_b32 m0, s40
	v_lshl_add_u64 v[244:245], s[24:25], 0, v[152:153]
	ds_read_b128 v[178:181], v164 offset:32768
	ds_read_b128 v[182:185], v164 offset:33792
	ds_read_b128 v[186:189], v164 offset:34816
	ds_read_b128 v[204:207], v164 offset:35840
	ds_read_b128 v[208:211], v164 offset:36864
	ds_read_b128 v[212:215], v164 offset:37888
	ds_read_b128 v[216:219], v164 offset:38912
	ds_read_b128 v[220:223], v164 offset:39936
	global_load_lds_dwordx4 v[244:245], off
	v_lshl_add_u64 v[244:245], s[24:25], 0, v[148:149]
	s_mov_b32 m0, s41
	s_nop 0
	global_load_lds_dwordx4 v[244:245], off
	s_waitcnt vmcnt(8)
	s_waitcnt lgkmcnt(0)
	s_barrier
	s_setprio 1
	v_mfma_f32_16x16x32_bf16 v[140:143], v[52:55], v[178:181], v[140:143]
	v_mfma_f32_16x16x32_bf16 v[144:147], v[68:71], v[178:181], v[144:147]
	v_mfma_f32_16x16x32_bf16 v[128:131], v[52:55], v[186:189], v[128:131]
	v_mfma_f32_16x16x32_bf16 v[124:127], v[68:71], v[186:189], v[124:127]
	v_mfma_f32_16x16x32_bf16 v[112:115], v[52:55], v[208:211], v[112:115]
	v_mfma_f32_16x16x32_bf16 v[108:111], v[68:71], v[208:211], v[108:111]
	v_mfma_f32_16x16x32_bf16 v[96:99], v[52:55], v[216:219], v[96:99]
	v_mfma_f32_16x16x32_bf16 v[92:95], v[68:71], v[216:219], v[92:95]
	v_mfma_f32_16x16x32_bf16 v[140:143], v[56:59], v[182:185], v[140:143]
	v_mfma_f32_16x16x32_bf16 v[144:147], v[72:75], v[182:185], v[144:147]
	v_mfma_f32_16x16x32_bf16 v[128:131], v[56:59], v[204:207], v[128:131]
	v_mfma_f32_16x16x32_bf16 v[124:127], v[72:75], v[204:207], v[124:127]
	v_mfma_f32_16x16x32_bf16 v[112:115], v[56:59], v[212:215], v[112:115]
	v_mfma_f32_16x16x32_bf16 v[108:111], v[72:75], v[212:215], v[108:111]
	v_mfma_f32_16x16x32_bf16 v[96:99], v[56:59], v[220:223], v[96:99]
	v_mfma_f32_16x16x32_bf16 v[92:95], v[72:75], v[220:223], v[92:95]
	s_setprio 0
	s_setprio 1
	v_mfma_f32_16x16x32_bf16 v[136:139], v[158:161], v[178:181], v[136:139]
	v_mfma_f32_16x16x32_bf16 v[132:135], v[170:173], v[178:181], v[132:135]
	v_mfma_f32_16x16x32_bf16 v[120:123], v[158:161], v[186:189], v[120:123]
	v_mfma_f32_16x16x32_bf16 v[116:119], v[170:173], v[186:189], v[116:119]
	v_mfma_f32_16x16x32_bf16 v[104:107], v[158:161], v[208:211], v[104:107]
	v_mfma_f32_16x16x32_bf16 v[100:103], v[170:173], v[208:211], v[100:103]
	v_mfma_f32_16x16x32_bf16 v[88:91], v[158:161], v[216:219], v[88:91]
	v_mfma_f32_16x16x32_bf16 v[84:87], v[170:173], v[216:219], v[84:87]
	v_mfma_f32_16x16x32_bf16 v[136:139], v[166:169], v[182:185], v[136:139]
	v_mfma_f32_16x16x32_bf16 v[132:135], v[174:177], v[182:185], v[132:135]
	v_mfma_f32_16x16x32_bf16 v[120:123], v[166:169], v[204:207], v[120:123]
	v_mfma_f32_16x16x32_bf16 v[116:119], v[174:177], v[204:207], v[116:119]
	v_mfma_f32_16x16x32_bf16 v[104:107], v[166:169], v[212:215], v[104:107]
	v_mfma_f32_16x16x32_bf16 v[100:103], v[174:177], v[212:215], v[100:103]
	v_mfma_f32_16x16x32_bf16 v[88:91], v[166:169], v[220:223], v[88:91]
	v_mfma_f32_16x16x32_bf16 v[84:87], v[174:177], v[220:223], v[84:87]
	s_setprio 0
	s_barrier
; #define PG8_STAGE(bufoff, gbase, voff) do { _Pragma("unroll") for (int _i = 0; _i < 2; ++_i) \
;         __builtin_amdgcn_global_load_lds((const unsigned*)((const char*)(gbase) + (voff)[_i]), (PG8_LAS unsigned*)(lds + (bufoff) + ldsw + _i * 8192), 16, 0, 0); } while (0)
; #define PG8_LDA(dst, b, h) do { _Pragma("unroll") for (int m = 0; m < 4; ++m) _Pragma("unroll") for (int k = 0; k < 2; ++k) dst[m][k] = *(const PG8_LAS bf16x8*)(lds + PG8_SA(b, h) + aoff + m * 2048 + k * 1024); } while (0)
; #define PG8_MMA(ai, bj, At, Bt) do { __builtin_amdgcn_s_setprio(1); _Pragma("unroll") for (int m = 0; m < 4; ++m) _Pragma("unroll") for (int n = 0; n < 2; ++n) _Pragma("unroll") for (int k = 0; k < 2; ++k) \
;         acc[ai][bj][m][n] = __builtin_amdgcn_mfma_f32_16x16x32_bf16(Bt[n][k], At[m][k], acc[ai][bj][m][n], 0, 0, 0); __builtin_amdgcn_s_setprio(0); } while (0)
; #define PG8_WAIT_V(n) asm volatile("s_waitcnt vmcnt(" #n ")" ::: "memory")
; #define PG8_WAIT_L(n) asm volatile("s_waitcnt lgkmcnt(" #n ")" ::: "memory")
; #define PG8_BAR __builtin_amdgcn_s_barrier()
; #define PG8_SCHED __builtin_amdgcn_sched_barrier(0)
; template <class Epi, class Sched, bool ALIGN_EPI = false, bool SP2 = false>
; __device__ __forceinline__ void gemm_phase(PG8_LAS unsigned char* lds, const Gemm g, const Sched& S, const Epi& E, int tid_in) {
;     ...
;             PG8_LDA(At, 1, 1); PG8_STAGE(PG8_SB(1, 0), b3, voffB); PG8_STAGE(PG8_SB(1, 1), b3 + hsB, voffB); PG8_STAGE(PG8_SA(1, 0), a3, voffA);
;             PG8_WAIT_V(8); PG8_WAIT_L(0); PG8_BAR; PG8_MMA(1, 0, At, B0); PG8_MMA(1, 1, At, B1); PG8_BAR; PG8_SCHED;
	s_add_i32 s24, s58, s36
	v_lshl_add_u64 v[190:191], v[190:191], 0, s[80:81]
	s_mov_b32 m0, s24
	ds_read_b128 v[178:181], v164 offset:49152
	ds_read_b128 v[182:185], v164 offset:50176
	ds_read_b128 v[186:189], v164 offset:51200
	ds_read_b128 v[204:207], v164 offset:52224
	ds_read_b128 v[208:211], v164 offset:53248
	ds_read_b128 v[212:215], v164 offset:54272
	ds_read_b128 v[216:219], v164 offset:55296
	ds_read_b128 v[220:223], v164 offset:56320
	global_load_lds_dwordx4 v[190:191], off
	v_lshl_add_u64 v[190:191], v[230:231], 0, s[80:81]
	s_add_i32 m0, s24, 0x2000
	s_add_i32 s24, s59, s36
	global_load_lds_dwordx4 v[190:191], off
	v_lshl_add_u64 v[190:191], v[232:233], 0, s[80:81]
	s_mov_b32 m0, s24
	s_nop 0
	global_load_lds_dwordx4 v[190:191], off
	v_lshl_add_u64 v[190:191], v[238:239], 0, s[80:81]
	s_add_i32 m0, s24, 0x2000
	s_nop 0
	global_load_lds_dwordx4 v[190:191], off
	v_lshl_add_u64 v[190:191], v[240:241], 0, s[80:81]
	s_mov_b32 m0, s44
	s_nop 0
	global_load_lds_dwordx4 v[190:191], off
	v_lshl_add_u64 v[190:191], v[242:243], 0, s[80:81]
	s_mov_b32 m0, s45
	s_nop 0
	global_load_lds_dwordx4 v[190:191], off
	s_waitcnt vmcnt(8)
	s_waitcnt lgkmcnt(0)
	s_barrier
	s_setprio 1
	v_mfma_f32_16x16x32_bf16 v[80:83], v[52:55], v[178:181], v[80:83]
	v_mfma_f32_16x16x32_bf16 v[76:79], v[68:71], v[178:181], v[76:79]
	v_mfma_f32_16x16x32_bf16 v[64:67], v[52:55], v[186:189], v[64:67]
	v_mfma_f32_16x16x32_bf16 v[60:63], v[68:71], v[186:189], v[60:63]
	v_mfma_f32_16x16x32_bf16 v[40:43], v[52:55], v[208:211], v[40:43]
	v_mfma_f32_16x16x32_bf16 v[36:39], v[68:71], v[208:211], v[36:39]
	v_mfma_f32_16x16x32_bf16 v[16:19], v[52:55], v[216:219], v[16:19]
	v_mfma_f32_16x16x32_bf16 v[12:15], v[68:71], v[216:219], v[12:15]
	v_mfma_f32_16x16x32_bf16 v[80:83], v[56:59], v[182:185], v[80:83]
	v_mfma_f32_16x16x32_bf16 v[76:79], v[72:75], v[182:185], v[76:79]
	v_mfma_f32_16x16x32_bf16 v[64:67], v[56:59], v[204:207], v[64:67]
	v_mfma_f32_16x16x32_bf16 v[60:63], v[72:75], v[204:207], v[60:63]
	v_mfma_f32_16x16x32_bf16 v[40:43], v[56:59], v[212:215], v[40:43]
	v_mfma_f32_16x16x32_bf16 v[36:39], v[72:75], v[212:215], v[36:39]
	v_mfma_f32_16x16x32_bf16 v[16:19], v[56:59], v[220:223], v[16:19]
	v_mfma_f32_16x16x32_bf16 v[12:15], v[72:75], v[220:223], v[12:15]
	s_setprio 0
	s_setprio 1
	v_mfma_f32_16x16x32_bf16 v[28:31], v[158:161], v[178:181], v[28:31]
	v_mfma_f32_16x16x32_bf16 v[72:75], v[166:169], v[182:185], v[28:31]
	v_mfma_f32_16x16x32_bf16 v[28:31], v[170:173], v[178:181], v[32:35]
	v_mfma_f32_16x16x32_bf16 v[68:71], v[174:177], v[182:185], v[28:31]
	v_mfma_f32_16x16x32_bf16 v[28:31], v[158:161], v[186:189], v[44:47]
	v_mfma_f32_16x16x32_bf16 v[56:59], v[166:169], v[204:207], v[28:31]
	v_mfma_f32_16x16x32_bf16 v[28:31], v[170:173], v[186:189], v[48:51]
	v_mfma_f32_16x16x32_bf16 v[24:27], v[158:161], v[208:211], v[24:27]
	v_mfma_f32_16x16x32_bf16 v[20:23], v[170:173], v[208:211], v[20:23]
	v_mfma_f32_16x16x32_bf16 v[8:11], v[158:161], v[216:219], v[8:11]
	v_mfma_f32_16x16x32_bf16 v[4:7], v[170:173], v[216:219], v[4:7]
	v_mfma_f32_16x16x32_bf16 v[52:55], v[174:177], v[204:207], v[28:31]
	v_mfma_f32_16x16x32_bf16 v[24:27], v[166:169], v[212:215], v[24:27]
	v_mfma_f32_16x16x32_bf16 v[20:23], v[174:177], v[212:215], v[20:23]
	v_mfma_f32_16x16x32_bf16 v[8:11], v[166:169], v[220:223], v[8:11]
	v_mfma_f32_16x16x32_bf16 v[4:7], v[174:177], v[220:223], v[4:7]
	s_setprio 0
	s_barrier
	s_add_i32 s24, s55, 2
	s_add_u32 s53, s53, 0x100
	s_addc_u32 s54, s54, 0
	s_add_u32 s22, s22, 0x100
	s_addc_u32 s23, s23, 0
	s_cmp_ge_i32 s55, s46
	s_mov_b32 s55, s24
	s_cbranch_scc0 .LBB0_667

; #define PG8_STAGE(bufoff, gbase, voff) do { _Pragma("unroll") for (int _i = 0; _i < 2; ++_i) \
;         __builtin_amdgcn_global_load_lds((const unsigned*)((const char*)(gbase) + (voff)[_i]), (PG8_LAS unsigned*)(lds + (bufoff) + ldsw + _i * 8192), 16, 0, 0); } while (0)
; #define PG8_LDA(dst, b, h) do { _Pragma("unroll") for (int m = 0; m < 4; ++m) _Pragma("unroll") for (int k = 0; k < 2; ++k) dst[m][k] = *(const PG8_LAS bf16x8*)(lds + PG8_SA(b, h) + aoff + m * 2048 + k * 1024); } while (0)
; #define PG8_LDB(dst, b, h) do { _Pragma("unroll") for (int n = 0; n < 2; ++n) _Pragma("unroll") for (int k = 0; k < 2; ++k) dst[n][k] = *(const PG8_LAS bf16x8*)(lds + PG8_SB(b, h) + boff + n * 2048 + k * 1024); } while (0)
; #define PG8_MMA(ai, bj, At, Bt) do { __builtin_amdgcn_s_setprio(1); _Pragma("unroll") for (int m = 0; m < 4; ++m) _Pragma("unroll") for (int n = 0; n < 2; ++n) _Pragma("unroll") for (int k = 0; k < 2; ++k) \
;         acc[ai][bj][m][n] = __builtin_amdgcn_mfma_f32_16x16x32_bf16(Bt[n][k], At[m][k], acc[ai][bj][m][n], 0, 0, 0); __builtin_amdgcn_s_setprio(0); } while (0)
; #define PG8_WAIT_V(n) asm volatile("s_waitcnt vmcnt(" #n ")" ::: "memory")
; #define PG8_WAIT_L(n) asm volatile("s_waitcnt lgkmcnt(" #n ")" ::: "memory")
; template <class Epi, class Sched, bool ALIGN_EPI = false, bool SP2 = false>
; __device__ __forceinline__ void gemm_phase(PG8_LAS unsigned char* lds, const Gemm g, const Sched& S, const Epi& E, int tid_in) {
;     ...
;             const char* a1 = cA + (size_t)(t + 1) * kstep + (t >= jt ? jb : 0);
;             const char* a2 = last ? nA : cA + (size_t)(t + 2) * kstep + (t + 2 >= jt ? jb : 0); const char* b2 = last ? nB : cB + (size_t)(t + 2) * kstep;
;             const char* a3 = a2 + kstep; const char* b3 = b2 + kstep;
;             if (last && has_next) S.a_ready(nxt);
;             if constexpr (SP2) {
;             PG8_LDB(B0, 0, 0); PG8_LDB(B1, 0, 1); PG8_SCHED; PG8_LDA(At, 0, 0); PG8_STAGE(PG8_SA(1, 1), a1 + hsA, voffA);
;             PG8_WAIT_V(8); PG8_WAIT_L(0); PG8_BAR; PG8_MMA(0, 0, At, B0); PG8_MMA(0, 1, At, B1); PG8_BAR; PG8_SCHED;
;             PG8_LDA(At, 0, 1); PG8_STAGE(PG8_SB(0, 0), b2, voffB); PG8_STAGE(PG8_SB(0, 1), b2 + hsB, voffB); PG8_STAGE(PG8_SA(0, 0), a2, voffA);
;             PG8_WAIT_V(8); PG8_WAIT_L(0); PG8_BAR; PG8_MMA(1, 0, At, B0); PG8_MMA(1, 1, At, B1); PG8_BAR; PG8_SCHED;
.LBB0_688:
	s_add_i32 s24, s55, -2
	s_cmp_ge_i32 s24, s28
	s_cselect_b32 s58, s29, 0
	s_cselect_b32 s59, s46, 0
	s_cmp_ge_i32 s55, s28
	s_cselect_b32 s25, s29, 0
	s_cselect_b32 s24, s46, 0
	s_add_u32 s25, s22, s25
	s_addc_u32 s24, s23, s24
	s_add_u32 s60, s25, 0x80
	s_addc_u32 s24, s24, 0
	s_add_i32 s62, 0, 0x10000
	s_cmp_eq_u32 s45, s55
	s_cselect_b32 s25, s5, s24
	s_cselect_b32 s24, s4, s60
	s_cselect_b32 s61, s21, s54
	s_cselect_b32 s60, s20, s53
	s_add_i32 s63, 0, 0x14000
	v_add_u32_e32 v88, s62, v160
	v_add_u32_e32 v158, s63, v160
	ds_read_b128 v[68:71], v88
	ds_read_b128 v[72:75], v88 offset:1024
	ds_read_b128 v[84:87], v88 offset:2048
	ds_read_b128 v[88:91], v88 offset:3072
	ds_read_b128 v[164:167], v158
	ds_read_b128 v[168:171], v158 offset:1024
	ds_read_b128 v[172:175], v158 offset:2048
	ds_read_b128 v[176:179], v158 offset:3072
	v_lshl_add_u64 v[158:159], s[22:23], 0, v[156:157]
	v_lshl_add_u64 v[158:159], v[158:159], 0, s[58:59]
	s_add_i32 m0, s37, 0xc000
	ds_read_b128 v[180:183], v162
	ds_read_b128 v[184:187], v162 offset:1024
	ds_read_b128 v[188:191], v162 offset:2048
	ds_read_b128 v[204:207], v162 offset:3072
	ds_read_b128 v[208:211], v162 offset:4096
	ds_read_b128 v[212:215], v162 offset:5120
	ds_read_b128 v[216:219], v162 offset:6144
	ds_read_b128 v[220:223], v162 offset:7168
	global_load_lds_dwordx4 v[158:159], off
	v_lshl_add_u64 v[158:159], s[22:23], 0, v[154:155]
	v_lshl_add_u64 v[158:159], v[158:159], 0, s[58:59]
	s_add_i32 m0, s37, 0xe000
	s_nop 0
	global_load_lds_dwordx4 v[158:159], off
	s_waitcnt vmcnt(8)
	s_waitcnt lgkmcnt(0)
	s_barrier
	s_setprio 1
	v_mfma_f32_16x16x32_bf16 v[140:143], v[68:71], v[180:183], v[140:143]
	v_mfma_f32_16x16x32_bf16 v[144:147], v[84:87], v[180:183], v[144:147]
	v_mfma_f32_16x16x32_bf16 v[128:131], v[68:71], v[188:191], v[128:131]
	v_mfma_f32_16x16x32_bf16 v[124:127], v[84:87], v[188:191], v[124:127]
	v_mfma_f32_16x16x32_bf16 v[112:115], v[68:71], v[208:211], v[112:115]
	v_mfma_f32_16x16x32_bf16 v[108:111], v[84:87], v[208:211], v[108:111]
	v_mfma_f32_16x16x32_bf16 v[96:99], v[68:71], v[216:219], v[96:99]
	v_mfma_f32_16x16x32_bf16 v[92:95], v[84:87], v[216:219], v[92:95]
	v_mfma_f32_16x16x32_bf16 v[140:143], v[72:75], v[184:187], v[140:143]
	v_mfma_f32_16x16x32_bf16 v[144:147], v[88:91], v[184:187], v[144:147]
	v_mfma_f32_16x16x32_bf16 v[128:131], v[72:75], v[204:207], v[128:131]
	v_mfma_f32_16x16x32_bf16 v[124:127], v[88:91], v[204:207], v[124:127]
	v_mfma_f32_16x16x32_bf16 v[112:115], v[72:75], v[212:215], v[112:115]
	v_mfma_f32_16x16x32_bf16 v[108:111], v[88:91], v[212:215], v[108:111]
	v_mfma_f32_16x16x32_bf16 v[96:99], v[72:75], v[220:223], v[96:99]
	v_mfma_f32_16x16x32_bf16 v[92:95], v[88:91], v[220:223], v[92:95]
	s_setprio 0
	s_setprio 1
	v_mfma_f32_16x16x32_bf16 v[136:139], v[164:167], v[180:183], v[136:139]
	v_mfma_f32_16x16x32_bf16 v[132:135], v[172:175], v[180:183], v[132:135]
	v_mfma_f32_16x16x32_bf16 v[120:123], v[164:167], v[188:191], v[120:123]
	v_mfma_f32_16x16x32_bf16 v[116:119], v[172:175], v[188:191], v[116:119]
	v_mfma_f32_16x16x32_bf16 v[104:107], v[164:167], v[208:211], v[104:107]
	v_mfma_f32_16x16x32_bf16 v[100:103], v[172:175], v[208:211], v[100:103]
	v_mfma_f32_16x16x32_bf16 v[80:83], v[164:167], v[216:219], v[80:83]
	v_mfma_f32_16x16x32_bf16 v[76:79], v[172:175], v[216:219], v[76:79]
	v_mfma_f32_16x16x32_bf16 v[136:139], v[168:171], v[184:187], v[136:139]
	v_mfma_f32_16x16x32_bf16 v[132:135], v[176:179], v[184:187], v[132:135]
	v_mfma_f32_16x16x32_bf16 v[120:123], v[168:171], v[204:207], v[120:123]
	v_mfma_f32_16x16x32_bf16 v[116:119], v[176:179], v[204:207], v[116:119]
	v_mfma_f32_16x16x32_bf16 v[104:107], v[168:171], v[212:215], v[104:107]
	v_mfma_f32_16x16x32_bf16 v[100:103], v[176:179], v[212:215], v[100:103]
	v_mfma_f32_16x16x32_bf16 v[80:83], v[168:171], v[220:223], v[80:83]
	v_mfma_f32_16x16x32_bf16 v[76:79], v[176:179], v[220:223], v[76:79]
	s_setprio 0
	s_barrier
	s_add_i32 s58, s62, s35
	v_lshl_add_u64 v[158:159], s[60:61], 0, v[150:151]
	s_mov_b32 m0, s58
	ds_read_b128 v[180:183], v162 offset:16384
	ds_read_b128 v[184:187], v162 offset:17408
	ds_read_b128 v[188:191], v162 offset:18432
	ds_read_b128 v[204:207], v162 offset:19456
	ds_read_b128 v[208:211], v162 offset:20480
	ds_read_b128 v[212:215], v162 offset:21504
	ds_read_b128 v[216:219], v162 offset:22528
	ds_read_b128 v[220:223], v162 offset:23552
	global_load_lds_dwordx4 v[158:159], off
	s_add_i32 m0, s58, 0x2000
	s_add_u32 s58, s60, s6
	v_lshl_add_u64 v[230:231], s[60:61], 0, v[0:1]
	s_addc_u32 s59, s61, s7
	s_add_i32 s60, s63, s35
	global_load_lds_dwordx4 v[230:231], off
	v_lshl_add_u64 v[232:233], s[58:59], 0, v[150:151]
	s_mov_b32 m0, s60
	v_lshl_add_u64 v[238:239], s[58:59], 0, v[0:1]
	global_load_lds_dwordx4 v[232:233], off
	s_add_i32 m0, s60, 0x2000
	v_lshl_add_u64 v[240:241], s[24:25], 0, v[152:153]
	global_load_lds_dwordx4 v[238:239], off
	s_mov_b32 m0, s37
	v_lshl_add_u64 v[242:243], s[24:25], 0, v[148:149]
	global_load_lds_dwordx4 v[240:241], off
	s_mov_b32 m0, s38
	s_nop 0
	global_load_lds_dwordx4 v[242:243], off
	s_waitcnt vmcnt(8)
	s_waitcnt lgkmcnt(0)
	s_barrier
; #define PG8_STAGE(bufoff, gbase, voff) do { _Pragma("unroll") for (int _i = 0; _i < 2; ++_i) \
;         __builtin_amdgcn_global_load_lds((const unsigned*)((const char*)(gbase) + (voff)[_i]), (PG8_LAS unsigned*)(lds + (bufoff) + ldsw + _i * 8192), 16, 0, 0); } while (0)
; #define PG8_LDA(dst, b, h) do { _Pragma("unroll") for (int m = 0; m < 4; ++m) _Pragma("unroll") for (int k = 0; k < 2; ++k) dst[m][k] = *(const PG8_LAS bf16x8*)(lds + PG8_SA(b, h) + aoff + m * 2048 + k * 1024); } while (0)
; #define PG8_LDB(dst, b, h) do { _Pragma("unroll") for (int n = 0; n < 2; ++n) _Pragma("unroll") for (int k = 0; k < 2; ++k) dst[n][k] = *(const PG8_LAS bf16x8*)(lds + PG8_SB(b, h) + boff + n * 2048 + k * 1024); } while (0)
; #define PG8_MMA(ai, bj, At, Bt) do { __builtin_amdgcn_s_setprio(1); _Pragma("unroll") for (int m = 0; m < 4; ++m) _Pragma("unroll") for (int n = 0; n < 2; ++n) _Pragma("unroll") for (int k = 0; k < 2; ++k) \
;         acc[ai][bj][m][n] = __builtin_amdgcn_mfma_f32_16x16x32_bf16(Bt[n][k], At[m][k], acc[ai][bj][m][n], 0, 0, 0); __builtin_amdgcn_s_setprio(0); } while (0)
; #define PG8_WAIT_V(n) asm volatile("s_waitcnt vmcnt(" #n ")" ::: "memory")
; #define PG8_WAIT_L(n) asm volatile("s_waitcnt lgkmcnt(" #n ")" ::: "memory")
; #define PG8_BAR __builtin_amdgcn_s_barrier()
; #define PG8_SCHED __builtin_amdgcn_sched_barrier(0)
; template <class Epi, class Sched, bool ALIGN_EPI = false, bool SP2 = false>
; __device__ __forceinline__ void gemm_phase(PG8_LAS unsigned char* lds, const Gemm g, const Sched& S, const Epi& E, int tid_in) {
;     ...
;             PG8_WAIT_V(8); PG8_WAIT_L(0); PG8_BAR; PG8_MMA(1, 0, At, B0); PG8_MMA(1, 1, At, B1); PG8_BAR; PG8_SCHED;
;             PG8_LDB(B0, 1, 0); PG8_LDB(B1, 1, 1); PG8_SCHED; PG8_LDA(At, 1, 0); PG8_STAGE(PG8_SA(0, 1), a2 + hsA, voffA);
;             PG8_WAIT_V(8); PG8_WAIT_L(0); PG8_BAR; PG8_MMA(0, 0, At, B0); PG8_MMA(0, 1, At, B1); PG8_BAR; PG8_SCHED;
	s_setprio 1
	v_mfma_f32_16x16x32_bf16 v[64:67], v[68:71], v[180:183], v[64:67]
	v_mfma_f32_16x16x32_bf16 v[60:63], v[84:87], v[180:183], v[60:63]
	v_mfma_f32_16x16x32_bf16 v[48:51], v[68:71], v[188:191], v[48:51]
	v_mfma_f32_16x16x32_bf16 v[44:47], v[84:87], v[188:191], v[44:47]
	v_mfma_f32_16x16x32_bf16 v[32:35], v[68:71], v[208:211], v[32:35]
	v_mfma_f32_16x16x32_bf16 v[28:31], v[84:87], v[208:211], v[28:31]
	v_mfma_f32_16x16x32_bf16 v[16:19], v[68:71], v[216:219], v[16:19]
	v_mfma_f32_16x16x32_bf16 v[12:15], v[84:87], v[216:219], v[12:15]
	v_mfma_f32_16x16x32_bf16 v[64:67], v[72:75], v[184:187], v[64:67]
	v_mfma_f32_16x16x32_bf16 v[60:63], v[88:91], v[184:187], v[60:63]
	v_mfma_f32_16x16x32_bf16 v[48:51], v[72:75], v[204:207], v[48:51]
	v_mfma_f32_16x16x32_bf16 v[44:47], v[88:91], v[204:207], v[44:47]
	v_mfma_f32_16x16x32_bf16 v[32:35], v[72:75], v[212:215], v[32:35]
	v_mfma_f32_16x16x32_bf16 v[28:31], v[88:91], v[212:215], v[28:31]
	v_mfma_f32_16x16x32_bf16 v[16:19], v[72:75], v[220:223], v[16:19]
	v_mfma_f32_16x16x32_bf16 v[12:15], v[88:91], v[220:223], v[12:15]
	s_setprio 0
	s_setprio 1
	v_mfma_f32_16x16x32_bf16 v[56:59], v[164:167], v[180:183], v[56:59]
	v_mfma_f32_16x16x32_bf16 v[52:55], v[172:175], v[180:183], v[52:55]
	v_mfma_f32_16x16x32_bf16 v[40:43], v[164:167], v[188:191], v[40:43]
	v_mfma_f32_16x16x32_bf16 v[36:39], v[172:175], v[188:191], v[36:39]
	v_mfma_f32_16x16x32_bf16 v[24:27], v[164:167], v[208:211], v[24:27]
	v_mfma_f32_16x16x32_bf16 v[20:23], v[172:175], v[208:211], v[20:23]
	v_mfma_f32_16x16x32_bf16 v[8:11], v[164:167], v[216:219], v[8:11]
	v_mfma_f32_16x16x32_bf16 v[4:7], v[172:175], v[216:219], v[4:7]
	v_mfma_f32_16x16x32_bf16 v[56:59], v[168:171], v[184:187], v[56:59]
	v_mfma_f32_16x16x32_bf16 v[52:55], v[176:179], v[184:187], v[52:55]
	v_mfma_f32_16x16x32_bf16 v[40:43], v[168:171], v[204:207], v[40:43]
	v_mfma_f32_16x16x32_bf16 v[36:39], v[176:179], v[204:207], v[36:39]
	v_mfma_f32_16x16x32_bf16 v[24:27], v[168:171], v[212:215], v[24:27]
	v_mfma_f32_16x16x32_bf16 v[20:23], v[176:179], v[212:215], v[20:23]
	v_mfma_f32_16x16x32_bf16 v[8:11], v[168:171], v[220:223], v[8:11]
	v_mfma_f32_16x16x32_bf16 v[4:7], v[176:179], v[220:223], v[4:7]
	s_setprio 0
	s_barrier
	s_add_i32 s58, 0, 0x18000
	s_add_i32 s59, 0, 0x1c000
	v_add_u32_e32 v88, s58, v160
	v_add_u32_e32 v163, s59, v160
	ds_read_b128 v[68:71], v88
	ds_read_b128 v[72:75], v88 offset:1024
	ds_read_b128 v[84:87], v88 offset:2048
	ds_read_b128 v[88:91], v88 offset:3072
	ds_read_b128 v[164:167], v163
	ds_read_b128 v[168:171], v163 offset:1024
	ds_read_b128 v[172:175], v163 offset:2048
	ds_read_b128 v[176:179], v163 offset:3072
	s_add_u32 s24, s24, s0
	s_addc_u32 s25, s25, s1
	s_mov_b32 m0, s39
	v_lshl_add_u64 v[244:245], s[24:25], 0, v[152:153]
	ds_read_b128 v[180:183], v162 offset:32768
	ds_read_b128 v[184:187], v162 offset:33792
	ds_read_b128 v[188:191], v162 offset:34816
	ds_read_b128 v[204:207], v162 offset:35840
	ds_read_b128 v[208:211], v162 offset:36864
	ds_read_b128 v[212:215], v162 offset:37888
	ds_read_b128 v[216:219], v162 offset:38912
	ds_read_b128 v[220:223], v162 offset:39936
	global_load_lds_dwordx4 v[244:245], off
	v_lshl_add_u64 v[244:245], s[24:25], 0, v[148:149]
	s_mov_b32 m0, s40
	s_nop 0
	global_load_lds_dwordx4 v[244:245], off
	s_waitcnt vmcnt(8)
	s_waitcnt lgkmcnt(0)
	s_barrier
	s_setprio 1
	v_mfma_f32_16x16x32_bf16 v[140:143], v[68:71], v[180:183], v[140:143]
	v_mfma_f32_16x16x32_bf16 v[144:147], v[84:87], v[180:183], v[144:147]
	v_mfma_f32_16x16x32_bf16 v[128:131], v[68:71], v[188:191], v[128:131]
	v_mfma_f32_16x16x32_bf16 v[124:127], v[84:87], v[188:191], v[124:127]
	v_mfma_f32_16x16x32_bf16 v[112:115], v[68:71], v[208:211], v[112:115]
	v_mfma_f32_16x16x32_bf16 v[108:111], v[84:87], v[208:211], v[108:111]
	v_mfma_f32_16x16x32_bf16 v[96:99], v[68:71], v[216:219], v[96:99]
	v_mfma_f32_16x16x32_bf16 v[92:95], v[84:87], v[216:219], v[92:95]
	v_mfma_f32_16x16x32_bf16 v[140:143], v[72:75], v[184:187], v[140:143]
	v_mfma_f32_16x16x32_bf16 v[144:147], v[88:91], v[184:187], v[144:147]
	v_mfma_f32_16x16x32_bf16 v[128:131], v[72:75], v[204:207], v[128:131]
	v_mfma_f32_16x16x32_bf16 v[124:127], v[88:91], v[204:207], v[124:127]
	v_mfma_f32_16x16x32_bf16 v[112:115], v[72:75], v[212:215], v[112:115]
	v_mfma_f32_16x16x32_bf16 v[108:111], v[88:91], v[212:215], v[108:111]
	v_mfma_f32_16x16x32_bf16 v[96:99], v[72:75], v[220:223], v[96:99]
	v_mfma_f32_16x16x32_bf16 v[92:95], v[88:91], v[220:223], v[92:95]
	s_setprio 0
	s_setprio 1
	v_mfma_f32_16x16x32_bf16 v[136:139], v[164:167], v[180:183], v[136:139]
	v_mfma_f32_16x16x32_bf16 v[132:135], v[172:175], v[180:183], v[132:135]
	v_mfma_f32_16x16x32_bf16 v[120:123], v[164:167], v[188:191], v[120:123]
	v_mfma_f32_16x16x32_bf16 v[116:119], v[172:175], v[188:191], v[116:119]
	v_mfma_f32_16x16x32_bf16 v[104:107], v[164:167], v[208:211], v[104:107]
	v_mfma_f32_16x16x32_bf16 v[100:103], v[172:175], v[208:211], v[100:103]
	v_mfma_f32_16x16x32_bf16 v[80:83], v[164:167], v[216:219], v[80:83]
	v_mfma_f32_16x16x32_bf16 v[76:79], v[172:175], v[216:219], v[76:79]
	v_mfma_f32_16x16x32_bf16 v[136:139], v[168:171], v[184:187], v[136:139]
	v_mfma_f32_16x16x32_bf16 v[132:135], v[176:179], v[184:187], v[132:135]
	v_mfma_f32_16x16x32_bf16 v[120:123], v[168:171], v[204:207], v[120:123]
	v_mfma_f32_16x16x32_bf16 v[116:119], v[176:179], v[204:207], v[116:119]
	v_mfma_f32_16x16x32_bf16 v[104:107], v[168:171], v[212:215], v[104:107]
	v_mfma_f32_16x16x32_bf16 v[100:103], v[176:179], v[212:215], v[100:103]
	v_mfma_f32_16x16x32_bf16 v[80:83], v[168:171], v[220:223], v[80:83]
	v_mfma_f32_16x16x32_bf16 v[76:79], v[176:179], v[220:223], v[76:79]
	s_setprio 0
	s_barrier
; #define PG8_STAGE(bufoff, gbase, voff) do { _Pragma("unroll") for (int _i = 0; _i < 2; ++_i) \
;         __builtin_amdgcn_global_load_lds((const unsigned*)((const char*)(gbase) + (voff)[_i]), (PG8_LAS unsigned*)(lds + (bufoff) + ldsw + _i * 8192), 16, 0, 0); } while (0)
; #define PG8_LDA(dst, b, h) do { _Pragma("unroll") for (int m = 0; m < 4; ++m) _Pragma("unroll") for (int k = 0; k < 2; ++k) dst[m][k] = *(const PG8_LAS bf16x8*)(lds + PG8_SA(b, h) + aoff + m * 2048 + k * 1024); } while (0)
; #define PG8_MMA(ai, bj, At, Bt) do { __builtin_amdgcn_s_setprio(1); _Pragma("unroll") for (int m = 0; m < 4; ++m) _Pragma("unroll") for (int n = 0; n < 2; ++n) _Pragma("unroll") for (int k = 0; k < 2; ++k) \
;         acc[ai][bj][m][n] = __builtin_amdgcn_mfma_f32_16x16x32_bf16(Bt[n][k], At[m][k], acc[ai][bj][m][n], 0, 0, 0); __builtin_amdgcn_s_setprio(0); } while (0)
; #define PG8_WAIT_V(n) asm volatile("s_waitcnt vmcnt(" #n ")" ::: "memory")
; #define PG8_WAIT_L(n) asm volatile("s_waitcnt lgkmcnt(" #n ")" ::: "memory")
; #define PG8_BAR __builtin_amdgcn_s_barrier()
; #define PG8_SCHED __builtin_amdgcn_sched_barrier(0)
; template <class Epi, class Sched, bool ALIGN_EPI = false, bool SP2 = false>
; __device__ __forceinline__ void gemm_phase(PG8_LAS unsigned char* lds, const Gemm g, const Sched& S, const Epi& E, int tid_in) {
;     ...
;             PG8_LDA(At, 1, 1); PG8_STAGE(PG8_SB(1, 0), b3, voffB); PG8_STAGE(PG8_SB(1, 1), b3 + hsB, voffB); PG8_STAGE(PG8_SA(1, 0), a3, voffA);
;             PG8_WAIT_V(8); PG8_WAIT_L(0); PG8_BAR; PG8_MMA(1, 0, At, B0); PG8_MMA(1, 1, At, B1); PG8_BAR; PG8_SCHED;
	s_add_i32 s24, s58, s35
	v_lshl_add_u64 v[158:159], v[158:159], 0, s[80:81]
	s_mov_b32 m0, s24
	ds_read_b128 v[180:183], v162 offset:49152
	ds_read_b128 v[184:187], v162 offset:50176
	ds_read_b128 v[188:191], v162 offset:51200
	ds_read_b128 v[204:207], v162 offset:52224
	ds_read_b128 v[208:211], v162 offset:53248
	ds_read_b128 v[212:215], v162 offset:54272
	ds_read_b128 v[216:219], v162 offset:55296
	ds_read_b128 v[220:223], v162 offset:56320
	global_load_lds_dwordx4 v[158:159], off
	v_lshl_add_u64 v[158:159], v[230:231], 0, s[80:81]
	s_add_i32 m0, s24, 0x2000
	s_add_i32 s24, s59, s35
	global_load_lds_dwordx4 v[158:159], off
	v_lshl_add_u64 v[158:159], v[232:233], 0, s[80:81]
	s_mov_b32 m0, s24
	s_nop 0
	global_load_lds_dwordx4 v[158:159], off
	v_lshl_add_u64 v[158:159], v[238:239], 0, s[80:81]
	s_add_i32 m0, s24, 0x2000
	s_nop 0
	global_load_lds_dwordx4 v[158:159], off
	v_lshl_add_u64 v[158:159], v[240:241], 0, s[80:81]
	s_mov_b32 m0, s43
	s_nop 0
	global_load_lds_dwordx4 v[158:159], off
	v_lshl_add_u64 v[158:159], v[242:243], 0, s[80:81]
	s_mov_b32 m0, s44
	s_nop 0
	global_load_lds_dwordx4 v[158:159], off
	s_waitcnt vmcnt(8)
	s_waitcnt lgkmcnt(0)
	s_barrier
	s_setprio 1
	v_mfma_f32_16x16x32_bf16 v[64:67], v[68:71], v[180:183], v[64:67]
	v_mfma_f32_16x16x32_bf16 v[60:63], v[84:87], v[180:183], v[60:63]
	v_mfma_f32_16x16x32_bf16 v[48:51], v[68:71], v[188:191], v[48:51]
	v_mfma_f32_16x16x32_bf16 v[44:47], v[84:87], v[188:191], v[44:47]
	v_mfma_f32_16x16x32_bf16 v[32:35], v[68:71], v[208:211], v[32:35]
	v_mfma_f32_16x16x32_bf16 v[28:31], v[84:87], v[208:211], v[28:31]
	v_mfma_f32_16x16x32_bf16 v[16:19], v[68:71], v[216:219], v[16:19]
	v_mfma_f32_16x16x32_bf16 v[12:15], v[84:87], v[216:219], v[12:15]
	v_mfma_f32_16x16x32_bf16 v[64:67], v[72:75], v[184:187], v[64:67]
	v_mfma_f32_16x16x32_bf16 v[60:63], v[88:91], v[184:187], v[60:63]
	v_mfma_f32_16x16x32_bf16 v[48:51], v[72:75], v[204:207], v[48:51]
	v_mfma_f32_16x16x32_bf16 v[44:47], v[88:91], v[204:207], v[44:47]
	v_mfma_f32_16x16x32_bf16 v[32:35], v[72:75], v[212:215], v[32:35]
	v_mfma_f32_16x16x32_bf16 v[28:31], v[88:91], v[212:215], v[28:31]
	v_mfma_f32_16x16x32_bf16 v[16:19], v[72:75], v[220:223], v[16:19]
	v_mfma_f32_16x16x32_bf16 v[12:15], v[88:91], v[220:223], v[12:15]
	s_setprio 0
	s_setprio 1
	v_mfma_f32_16x16x32_bf16 v[56:59], v[164:167], v[180:183], v[56:59]
	v_mfma_f32_16x16x32_bf16 v[52:55], v[172:175], v[180:183], v[52:55]
	v_mfma_f32_16x16x32_bf16 v[40:43], v[164:167], v[188:191], v[40:43]
	v_mfma_f32_16x16x32_bf16 v[36:39], v[172:175], v[188:191], v[36:39]
	v_mfma_f32_16x16x32_bf16 v[24:27], v[164:167], v[208:211], v[24:27]
	v_mfma_f32_16x16x32_bf16 v[20:23], v[172:175], v[208:211], v[20:23]
	v_mfma_f32_16x16x32_bf16 v[8:11], v[164:167], v[216:219], v[8:11]
	v_mfma_f32_16x16x32_bf16 v[4:7], v[172:175], v[216:219], v[4:7]
	v_mfma_f32_16x16x32_bf16 v[56:59], v[168:171], v[184:187], v[56:59]
	v_mfma_f32_16x16x32_bf16 v[52:55], v[176:179], v[184:187], v[52:55]
	v_mfma_f32_16x16x32_bf16 v[40:43], v[168:171], v[204:207], v[40:43]
	v_mfma_f32_16x16x32_bf16 v[36:39], v[176:179], v[204:207], v[36:39]
	v_mfma_f32_16x16x32_bf16 v[24:27], v[168:171], v[212:215], v[24:27]
	v_mfma_f32_16x16x32_bf16 v[20:23], v[176:179], v[212:215], v[20:23]
	v_mfma_f32_16x16x32_bf16 v[8:11], v[168:171], v[220:223], v[8:11]
	v_mfma_f32_16x16x32_bf16 v[4:7], v[176:179], v[220:223], v[4:7]
	s_setprio 0
	s_barrier
	s_add_i32 s24, s55, 2
	s_add_u32 s53, s53, 0x100
	s_addc_u32 s54, s54, 0
	s_add_u32 s22, s22, 0x100
	s_addc_u32 s23, s23, 0
	s_cmp_ge_i32 s55, s45
	s_mov_b32 s55, s24
	s_cbranch_scc0 .LBB0_688

; #define PG8_STAGE(bufoff, gbase, voff) do { _Pragma("unroll") for (int _i = 0; _i < 2; ++_i) \
;         __builtin_amdgcn_global_load_lds((const unsigned*)((const char*)(gbase) + (voff)[_i]), (PG8_LAS unsigned*)(lds + (bufoff) + ldsw + _i * 8192), 16, 0, 0); } while (0)
; #define PG8_LDA(dst, b, h) do { _Pragma("unroll") for (int m = 0; m < 4; ++m) _Pragma("unroll") for (int k = 0; k < 2; ++k) dst[m][k] = *(const PG8_LAS bf16x8*)(lds + PG8_SA(b, h) + aoff + m * 2048 + k * 1024); } while (0)
; #define PG8_LDB(dst, b, h) do { _Pragma("unroll") for (int n = 0; n < 2; ++n) _Pragma("unroll") for (int k = 0; k < 2; ++k) dst[n][k] = *(const PG8_LAS bf16x8*)(lds + PG8_SB(b, h) + boff + n * 2048 + k * 1024); } while (0)
; #define PG8_MMA(ai, bj, At, Bt) do { __builtin_amdgcn_s_setprio(1); _Pragma("unroll") for (int m = 0; m < 4; ++m) _Pragma("unroll") for (int n = 0; n < 2; ++n) _Pragma("unroll") for (int k = 0; k < 2; ++k) \
;         acc[ai][bj][m][n] = __builtin_amdgcn_mfma_f32_16x16x32_bf16(Bt[n][k], At[m][k], acc[ai][bj][m][n], 0, 0, 0); __builtin_amdgcn_s_setprio(0); } while (0)
; #define PG8_WAIT_V(n) asm volatile("s_waitcnt vmcnt(" #n ")" ::: "memory")
; #define PG8_WAIT_L(n) asm volatile("s_waitcnt lgkmcnt(" #n ")" ::: "memory")
; template <class Epi, class Sched, bool ALIGN_EPI = false, bool SP2 = false>
; __device__ __forceinline__ void gemm_phase(PG8_LAS unsigned char* lds, const Gemm g, const Sched& S, const Epi& E, int tid_in) {
;     ...
;             const char* a1 = cA + (size_t)(t + 1) * kstep + (t >= jt ? jb : 0);
;             const char* a2 = last ? nA : cA + (size_t)(t + 2) * kstep + (t + 2 >= jt ? jb : 0); const char* b2 = last ? nB : cB + (size_t)(t + 2) * kstep;
;             const char* a3 = a2 + kstep; const char* b3 = b2 + kstep;
;             if (last && has_next) S.a_ready(nxt);
;             if constexpr (SP2) {
;             PG8_LDB(B0, 0, 0); PG8_LDB(B1, 0, 1); PG8_SCHED; PG8_LDA(At, 0, 0); PG8_STAGE(PG8_SA(1, 1), a1 + hsA, voffA);
;             PG8_WAIT_V(8); PG8_WAIT_L(0); PG8_BAR; PG8_MMA(0, 0, At, B0); PG8_MMA(0, 1, At, B1); PG8_BAR; PG8_SCHED;
;             PG8_LDA(At, 0, 1); PG8_STAGE(PG8_SB(0, 0), b2, voffB); PG8_STAGE(PG8_SB(0, 1), b2 + hsB, voffB); PG8_STAGE(PG8_SA(0, 0), a2, voffA);
;             PG8_WAIT_V(8); PG8_WAIT_L(0); PG8_BAR; PG8_MMA(1, 0, At, B0); PG8_MMA(1, 1, At, B1); PG8_BAR; PG8_SCHED;
.LBB0_709:
	s_add_i32 s24, s53, -2
	s_cmp_ge_i32 s24, s28
	s_cselect_b32 s54, s29, 0
	s_cselect_b32 s55, s44, 0
	s_cmp_ge_i32 s53, s28
	s_cselect_b32 s25, s29, 0
	s_cselect_b32 s24, s44, 0
	s_add_u32 s25, s22, s25
	s_addc_u32 s24, s23, s24
	s_add_u32 s58, s25, 0x80
	s_addc_u32 s24, s24, 0
	s_add_i32 s60, 0, 0x10000
	s_cmp_eq_u32 s43, s53
	s_cselect_b32 s25, s5, s24
	s_cselect_b32 s24, s4, s58
	v_add_u32_e32 v145, s60, v142
	s_cselect_b32 s59, s21, s52
	s_cselect_b32 s58, s20, s51
	s_add_i32 s61, 0, 0x14000
	ds_read_b128 v[146:149], v145
	ds_read_b128 v[150:153], v145 offset:1024
	ds_read_b128 v[154:157], v145 offset:2048
	ds_read_b128 v[158:161], v145 offset:3072
	v_add_u32_e32 v145, s61, v142
	ds_read_b128 v[162:165], v145
	ds_read_b128 v[166:169], v145 offset:1024
	ds_read_b128 v[170:173], v145 offset:2048
	ds_read_b128 v[174:177], v145 offset:3072
	v_lshl_add_u64 v[190:191], s[22:23], 0, v[140:141]
	v_lshl_add_u64 v[190:191], v[190:191], 0, s[54:55]
	s_add_i32 m0, s37, 0xc000
	ds_read_b128 v[178:181], v144
	ds_read_b128 v[182:185], v144 offset:1024
	ds_read_b128 v[186:189], v144 offset:2048
	ds_read_b128 v[204:207], v144 offset:3072
	ds_read_b128 v[208:211], v144 offset:4096
	ds_read_b128 v[212:215], v144 offset:5120
	ds_read_b128 v[216:219], v144 offset:6144
	ds_read_b128 v[220:223], v144 offset:7168
	global_load_lds_dwordx4 v[190:191], off
	v_lshl_add_u64 v[190:191], s[22:23], 0, v[138:139]
	v_lshl_add_u64 v[190:191], v[190:191], 0, s[54:55]
	s_add_i32 m0, s37, 0xe000
	s_nop 0
	global_load_lds_dwordx4 v[190:191], off
	s_waitcnt vmcnt(8)
	s_waitcnt lgkmcnt(0)
	s_barrier
	s_setprio 1
	v_mfma_f32_16x16x32_bf16 v[124:127], v[146:149], v[178:181], v[124:127]
	v_mfma_f32_16x16x32_bf16 v[128:131], v[154:157], v[178:181], v[128:131]
	v_mfma_f32_16x16x32_bf16 v[112:115], v[146:149], v[186:189], v[112:115]
	v_mfma_f32_16x16x32_bf16 v[108:111], v[154:157], v[186:189], v[108:111]
	v_mfma_f32_16x16x32_bf16 v[96:99], v[146:149], v[208:211], v[96:99]
	v_mfma_f32_16x16x32_bf16 v[92:95], v[154:157], v[208:211], v[92:95]
	v_mfma_f32_16x16x32_bf16 v[80:83], v[146:149], v[216:219], v[80:83]
	v_mfma_f32_16x16x32_bf16 v[76:79], v[154:157], v[216:219], v[76:79]
	v_mfma_f32_16x16x32_bf16 v[124:127], v[150:153], v[182:185], v[124:127]
	v_mfma_f32_16x16x32_bf16 v[128:131], v[158:161], v[182:185], v[128:131]
	v_mfma_f32_16x16x32_bf16 v[112:115], v[150:153], v[204:207], v[112:115]
	v_mfma_f32_16x16x32_bf16 v[108:111], v[158:161], v[204:207], v[108:111]
	v_mfma_f32_16x16x32_bf16 v[96:99], v[150:153], v[212:215], v[96:99]
	v_mfma_f32_16x16x32_bf16 v[92:95], v[158:161], v[212:215], v[92:95]
	v_mfma_f32_16x16x32_bf16 v[80:83], v[150:153], v[220:223], v[80:83]
	v_mfma_f32_16x16x32_bf16 v[76:79], v[158:161], v[220:223], v[76:79]
	s_setprio 0
	s_setprio 1
	v_mfma_f32_16x16x32_bf16 v[120:123], v[162:165], v[178:181], v[120:123]
	v_mfma_f32_16x16x32_bf16 v[116:119], v[170:173], v[178:181], v[116:119]
	v_mfma_f32_16x16x32_bf16 v[104:107], v[162:165], v[186:189], v[104:107]
	v_mfma_f32_16x16x32_bf16 v[100:103], v[170:173], v[186:189], v[100:103]
	v_mfma_f32_16x16x32_bf16 v[88:91], v[162:165], v[208:211], v[88:91]
	v_mfma_f32_16x16x32_bf16 v[84:87], v[170:173], v[208:211], v[84:87]
	v_mfma_f32_16x16x32_bf16 v[72:75], v[162:165], v[216:219], v[72:75]
	v_mfma_f32_16x16x32_bf16 v[68:71], v[170:173], v[216:219], v[68:71]
	v_mfma_f32_16x16x32_bf16 v[120:123], v[166:169], v[182:185], v[120:123]
	v_mfma_f32_16x16x32_bf16 v[116:119], v[174:177], v[182:185], v[116:119]
	v_mfma_f32_16x16x32_bf16 v[104:107], v[166:169], v[204:207], v[104:107]
	v_mfma_f32_16x16x32_bf16 v[100:103], v[174:177], v[204:207], v[100:103]
	v_mfma_f32_16x16x32_bf16 v[88:91], v[166:169], v[212:215], v[88:91]
	v_mfma_f32_16x16x32_bf16 v[84:87], v[174:177], v[212:215], v[84:87]
	v_mfma_f32_16x16x32_bf16 v[72:75], v[166:169], v[220:223], v[72:75]
	v_mfma_f32_16x16x32_bf16 v[68:71], v[174:177], v[220:223], v[68:71]
	s_setprio 0
	s_barrier
	s_add_i32 s54, s60, s35
	v_lshl_add_u64 v[190:191], s[58:59], 0, v[134:135]
	s_mov_b32 m0, s54
	ds_read_b128 v[178:181], v144 offset:16384
	ds_read_b128 v[182:185], v144 offset:17408
	ds_read_b128 v[186:189], v144 offset:18432
	ds_read_b128 v[204:207], v144 offset:19456
	ds_read_b128 v[208:211], v144 offset:20480
	ds_read_b128 v[212:215], v144 offset:21504
	ds_read_b128 v[216:219], v144 offset:22528
	ds_read_b128 v[220:223], v144 offset:23552
	global_load_lds_dwordx4 v[190:191], off
	s_add_i32 m0, s54, 0x2000
	s_add_u32 s54, s58, s6
	v_lshl_add_u64 v[230:231], s[58:59], 0, v[0:1]
	s_addc_u32 s55, s59, s7
	s_add_i32 s58, s61, s35
	global_load_lds_dwordx4 v[230:231], off
	v_lshl_add_u64 v[232:233], s[54:55], 0, v[134:135]
	s_mov_b32 m0, s58
	v_lshl_add_u64 v[238:239], s[54:55], 0, v[0:1]
	global_load_lds_dwordx4 v[232:233], off
	s_add_i32 m0, s58, 0x2000
	v_lshl_add_u64 v[240:241], s[24:25], 0, v[136:137]
	global_load_lds_dwordx4 v[238:239], off
	s_mov_b32 m0, s37
	v_lshl_add_u64 v[242:243], s[24:25], 0, v[132:133]
	global_load_lds_dwordx4 v[240:241], off
	s_mov_b32 m0, s38
	s_nop 0
	global_load_lds_dwordx4 v[242:243], off
	s_waitcnt vmcnt(8)
	s_waitcnt lgkmcnt(0)
	s_barrier
; #define PG8_STAGE(bufoff, gbase, voff) do { _Pragma("unroll") for (int _i = 0; _i < 2; ++_i) \
;         __builtin_amdgcn_global_load_lds((const unsigned*)((const char*)(gbase) + (voff)[_i]), (PG8_LAS unsigned*)(lds + (bufoff) + ldsw + _i * 8192), 16, 0, 0); } while (0)
; #define PG8_LDA(dst, b, h) do { _Pragma("unroll") for (int m = 0; m < 4; ++m) _Pragma("unroll") for (int k = 0; k < 2; ++k) dst[m][k] = *(const PG8_LAS bf16x8*)(lds + PG8_SA(b, h) + aoff + m * 2048 + k * 1024); } while (0)
; #define PG8_LDB(dst, b, h) do { _Pragma("unroll") for (int n = 0; n < 2; ++n) _Pragma("unroll") for (int k = 0; k < 2; ++k) dst[n][k] = *(const PG8_LAS bf16x8*)(lds + PG8_SB(b, h) + boff + n * 2048 + k * 1024); } while (0)
; #define PG8_MMA(ai, bj, At, Bt) do { __builtin_amdgcn_s_setprio(1); _Pragma("unroll") for (int m = 0; m < 4; ++m) _Pragma("unroll") for (int n = 0; n < 2; ++n) _Pragma("unroll") for (int k = 0; k < 2; ++k) \
;         acc[ai][bj][m][n] = __builtin_amdgcn_mfma_f32_16x16x32_bf16(Bt[n][k], At[m][k], acc[ai][bj][m][n], 0, 0, 0); __builtin_amdgcn_s_setprio(0); } while (0)
; #define PG8_WAIT_V(n) asm volatile("s_waitcnt vmcnt(" #n ")" ::: "memory")
; #define PG8_WAIT_L(n) asm volatile("s_waitcnt lgkmcnt(" #n ")" ::: "memory")
; #define PG8_BAR __builtin_amdgcn_s_barrier()
; #define PG8_SCHED __builtin_amdgcn_sched_barrier(0)
; template <class Epi, class Sched, bool ALIGN_EPI = false, bool SP2 = false>
; __device__ __forceinline__ void gemm_phase(PG8_LAS unsigned char* lds, const Gemm g, const Sched& S, const Epi& E, int tid_in) {
;     ...
;             PG8_WAIT_V(8); PG8_WAIT_L(0); PG8_BAR; PG8_MMA(1, 0, At, B0); PG8_MMA(1, 1, At, B1); PG8_BAR; PG8_SCHED;
;             PG8_LDB(B0, 1, 0); PG8_LDB(B1, 1, 1); PG8_SCHED; PG8_LDA(At, 1, 0); PG8_STAGE(PG8_SA(0, 1), a2 + hsA, voffA);
;             PG8_WAIT_V(8); PG8_WAIT_L(0); PG8_BAR; PG8_MMA(0, 0, At, B0); PG8_MMA(0, 1, At, B1); PG8_BAR; PG8_SCHED;
	s_setprio 1
	v_mfma_f32_16x16x32_bf16 v[64:67], v[146:149], v[178:181], v[64:67]
	v_mfma_f32_16x16x32_bf16 v[60:63], v[154:157], v[178:181], v[60:63]
	v_mfma_f32_16x16x32_bf16 v[48:51], v[146:149], v[186:189], v[48:51]
	v_mfma_f32_16x16x32_bf16 v[44:47], v[154:157], v[186:189], v[44:47]
	v_mfma_f32_16x16x32_bf16 v[32:35], v[146:149], v[208:211], v[32:35]
	v_mfma_f32_16x16x32_bf16 v[28:31], v[154:157], v[208:211], v[28:31]
	v_mfma_f32_16x16x32_bf16 v[16:19], v[146:149], v[216:219], v[16:19]
	v_mfma_f32_16x16x32_bf16 v[12:15], v[154:157], v[216:219], v[12:15]
	v_mfma_f32_16x16x32_bf16 v[64:67], v[150:153], v[182:185], v[64:67]
	v_mfma_f32_16x16x32_bf16 v[60:63], v[158:161], v[182:185], v[60:63]
	v_mfma_f32_16x16x32_bf16 v[48:51], v[150:153], v[204:207], v[48:51]
	v_mfma_f32_16x16x32_bf16 v[44:47], v[158:161], v[204:207], v[44:47]
	v_mfma_f32_16x16x32_bf16 v[32:35], v[150:153], v[212:215], v[32:35]
	v_mfma_f32_16x16x32_bf16 v[28:31], v[158:161], v[212:215], v[28:31]
	v_mfma_f32_16x16x32_bf16 v[16:19], v[150:153], v[220:223], v[16:19]
	v_mfma_f32_16x16x32_bf16 v[12:15], v[158:161], v[220:223], v[12:15]
	s_setprio 0
	s_setprio 1
	v_mfma_f32_16x16x32_bf16 v[56:59], v[162:165], v[178:181], v[56:59]
	v_mfma_f32_16x16x32_bf16 v[52:55], v[170:173], v[178:181], v[52:55]
	v_mfma_f32_16x16x32_bf16 v[40:43], v[162:165], v[186:189], v[40:43]
	v_mfma_f32_16x16x32_bf16 v[36:39], v[170:173], v[186:189], v[36:39]
	v_mfma_f32_16x16x32_bf16 v[24:27], v[162:165], v[208:211], v[24:27]
	v_mfma_f32_16x16x32_bf16 v[20:23], v[170:173], v[208:211], v[20:23]
	v_mfma_f32_16x16x32_bf16 v[8:11], v[162:165], v[216:219], v[8:11]
	v_mfma_f32_16x16x32_bf16 v[4:7], v[170:173], v[216:219], v[4:7]
	v_mfma_f32_16x16x32_bf16 v[56:59], v[166:169], v[182:185], v[56:59]
	v_mfma_f32_16x16x32_bf16 v[52:55], v[174:177], v[182:185], v[52:55]
	v_mfma_f32_16x16x32_bf16 v[40:43], v[166:169], v[204:207], v[40:43]
	v_mfma_f32_16x16x32_bf16 v[36:39], v[174:177], v[204:207], v[36:39]
	v_mfma_f32_16x16x32_bf16 v[24:27], v[166:169], v[212:215], v[24:27]
	v_mfma_f32_16x16x32_bf16 v[20:23], v[174:177], v[212:215], v[20:23]
	v_mfma_f32_16x16x32_bf16 v[8:11], v[166:169], v[220:223], v[8:11]
	v_mfma_f32_16x16x32_bf16 v[4:7], v[174:177], v[220:223], v[4:7]
	s_setprio 0
	s_barrier
	s_add_i32 s54, 0, 0x18000
	v_add_u32_e32 v145, s54, v142
	s_add_i32 s55, 0, 0x1c000
	ds_read_b128 v[146:149], v145
	ds_read_b128 v[150:153], v145 offset:1024
	ds_read_b128 v[154:157], v145 offset:2048
	ds_read_b128 v[158:161], v145 offset:3072
	v_add_u32_e32 v145, s55, v142
	ds_read_b128 v[162:165], v145
	ds_read_b128 v[166:169], v145 offset:1024
	ds_read_b128 v[170:173], v145 offset:2048
	ds_read_b128 v[174:177], v145 offset:3072
	s_add_u32 s24, s24, s0
	s_addc_u32 s25, s25, s1
	s_mov_b32 m0, s39
	v_lshl_add_u64 v[244:245], s[24:25], 0, v[136:137]
	ds_read_b128 v[178:181], v144 offset:32768
	ds_read_b128 v[182:185], v144 offset:33792
	ds_read_b128 v[186:189], v144 offset:34816
	ds_read_b128 v[204:207], v144 offset:35840
	ds_read_b128 v[208:211], v144 offset:36864
	ds_read_b128 v[212:215], v144 offset:37888
	ds_read_b128 v[216:219], v144 offset:38912
	ds_read_b128 v[220:223], v144 offset:39936
	global_load_lds_dwordx4 v[244:245], off
	v_lshl_add_u64 v[244:245], s[24:25], 0, v[132:133]
	s_mov_b32 m0, s40
	s_nop 0
	global_load_lds_dwordx4 v[244:245], off
	s_waitcnt vmcnt(8)
	s_waitcnt lgkmcnt(0)
	s_barrier
	s_setprio 1
	v_mfma_f32_16x16x32_bf16 v[124:127], v[146:149], v[178:181], v[124:127]
	v_mfma_f32_16x16x32_bf16 v[128:131], v[154:157], v[178:181], v[128:131]
	v_mfma_f32_16x16x32_bf16 v[112:115], v[146:149], v[186:189], v[112:115]
	v_mfma_f32_16x16x32_bf16 v[108:111], v[154:157], v[186:189], v[108:111]
	v_mfma_f32_16x16x32_bf16 v[96:99], v[146:149], v[208:211], v[96:99]
	v_mfma_f32_16x16x32_bf16 v[92:95], v[154:157], v[208:211], v[92:95]
	v_mfma_f32_16x16x32_bf16 v[80:83], v[146:149], v[216:219], v[80:83]
	v_mfma_f32_16x16x32_bf16 v[76:79], v[154:157], v[216:219], v[76:79]
	v_mfma_f32_16x16x32_bf16 v[124:127], v[150:153], v[182:185], v[124:127]
	v_mfma_f32_16x16x32_bf16 v[128:131], v[158:161], v[182:185], v[128:131]
	v_mfma_f32_16x16x32_bf16 v[112:115], v[150:153], v[204:207], v[112:115]
	v_mfma_f32_16x16x32_bf16 v[108:111], v[158:161], v[204:207], v[108:111]
	v_mfma_f32_16x16x32_bf16 v[96:99], v[150:153], v[212:215], v[96:99]
	v_mfma_f32_16x16x32_bf16 v[92:95], v[158:161], v[212:215], v[92:95]
	v_mfma_f32_16x16x32_bf16 v[80:83], v[150:153], v[220:223], v[80:83]
	v_mfma_f32_16x16x32_bf16 v[76:79], v[158:161], v[220:223], v[76:79]
	s_setprio 0
	s_setprio 1
	v_mfma_f32_16x16x32_bf16 v[120:123], v[162:165], v[178:181], v[120:123]
	v_mfma_f32_16x16x32_bf16 v[116:119], v[170:173], v[178:181], v[116:119]
	v_mfma_f32_16x16x32_bf16 v[104:107], v[162:165], v[186:189], v[104:107]
	v_mfma_f32_16x16x32_bf16 v[100:103], v[170:173], v[186:189], v[100:103]
	v_mfma_f32_16x16x32_bf16 v[88:91], v[162:165], v[208:211], v[88:91]
	v_mfma_f32_16x16x32_bf16 v[84:87], v[170:173], v[208:211], v[84:87]
	v_mfma_f32_16x16x32_bf16 v[72:75], v[162:165], v[216:219], v[72:75]
	v_mfma_f32_16x16x32_bf16 v[68:71], v[170:173], v[216:219], v[68:71]
	v_mfma_f32_16x16x32_bf16 v[120:123], v[166:169], v[182:185], v[120:123]
	v_mfma_f32_16x16x32_bf16 v[116:119], v[174:177], v[182:185], v[116:119]
	v_mfma_f32_16x16x32_bf16 v[104:107], v[166:169], v[204:207], v[104:107]
	v_mfma_f32_16x16x32_bf16 v[100:103], v[174:177], v[204:207], v[100:103]
	v_mfma_f32_16x16x32_bf16 v[88:91], v[166:169], v[212:215], v[88:91]
	v_mfma_f32_16x16x32_bf16 v[84:87], v[174:177], v[212:215], v[84:87]
	v_mfma_f32_16x16x32_bf16 v[72:75], v[166:169], v[220:223], v[72:75]
	v_mfma_f32_16x16x32_bf16 v[68:71], v[174:177], v[220:223], v[68:71]
	s_setprio 0
	s_barrier
; #define PG8_STAGE(bufoff, gbase, voff) do { _Pragma("unroll") for (int _i = 0; _i < 2; ++_i) \
;         __builtin_amdgcn_global_load_lds((const unsigned*)((const char*)(gbase) + (voff)[_i]), (PG8_LAS unsigned*)(lds + (bufoff) + ldsw + _i * 8192), 16, 0, 0); } while (0)
; #define PG8_LDA(dst, b, h) do { _Pragma("unroll") for (int m = 0; m < 4; ++m) _Pragma("unroll") for (int k = 0; k < 2; ++k) dst[m][k] = *(const PG8_LAS bf16x8*)(lds + PG8_SA(b, h) + aoff + m * 2048 + k * 1024); } while (0)
; #define PG8_MMA(ai, bj, At, Bt) do { __builtin_amdgcn_s_setprio(1); _Pragma("unroll") for (int m = 0; m < 4; ++m) _Pragma("unroll") for (int n = 0; n < 2; ++n) _Pragma("unroll") for (int k = 0; k < 2; ++k) \
;         acc[ai][bj][m][n] = __builtin_amdgcn_mfma_f32_16x16x32_bf16(Bt[n][k], At[m][k], acc[ai][bj][m][n], 0, 0, 0); __builtin_amdgcn_s_setprio(0); } while (0)
; #define PG8_WAIT_V(n) asm volatile("s_waitcnt vmcnt(" #n ")" ::: "memory")
; #define PG8_WAIT_L(n) asm volatile("s_waitcnt lgkmcnt(" #n ")" ::: "memory")
; #define PG8_BAR __builtin_amdgcn_s_barrier()
; #define PG8_SCHED __builtin_amdgcn_sched_barrier(0)
; template <class Epi, class Sched, bool ALIGN_EPI = false, bool SP2 = false>
; __device__ __forceinline__ void gemm_phase(PG8_LAS unsigned char* lds, const Gemm g, const Sched& S, const Epi& E, int tid_in) {
;     ...
;             PG8_LDA(At, 1, 1); PG8_STAGE(PG8_SB(1, 0), b3, voffB); PG8_STAGE(PG8_SB(1, 1), b3 + hsB, voffB); PG8_STAGE(PG8_SA(1, 0), a3, voffA);
;             PG8_WAIT_V(8); PG8_WAIT_L(0); PG8_BAR; PG8_MMA(1, 0, At, B0); PG8_MMA(1, 1, At, B1); PG8_BAR; PG8_SCHED;
	s_add_i32 s24, s54, s35
	v_lshl_add_u64 v[190:191], v[190:191], 0, s[80:81]
	s_mov_b32 m0, s24
	ds_read_b128 v[178:181], v144 offset:49152
	ds_read_b128 v[182:185], v144 offset:50176
	ds_read_b128 v[186:189], v144 offset:51200
	ds_read_b128 v[204:207], v144 offset:52224
	ds_read_b128 v[208:211], v144 offset:53248
	ds_read_b128 v[212:215], v144 offset:54272
	ds_read_b128 v[216:219], v144 offset:55296
	ds_read_b128 v[220:223], v144 offset:56320
	global_load_lds_dwordx4 v[190:191], off
	v_lshl_add_u64 v[190:191], v[230:231], 0, s[80:81]
	s_add_i32 m0, s24, 0x2000
	s_add_i32 s24, s55, s35
	global_load_lds_dwordx4 v[190:191], off
	v_lshl_add_u64 v[190:191], v[232:233], 0, s[80:81]
	s_mov_b32 m0, s24
	s_nop 0
	global_load_lds_dwordx4 v[190:191], off
	v_lshl_add_u64 v[190:191], v[238:239], 0, s[80:81]
	s_add_i32 m0, s24, 0x2000
	s_nop 0
	global_load_lds_dwordx4 v[190:191], off
	v_lshl_add_u64 v[190:191], v[240:241], 0, s[80:81]
	s_mov_b32 m0, s41
	s_nop 0
	global_load_lds_dwordx4 v[190:191], off
	v_lshl_add_u64 v[190:191], v[242:243], 0, s[80:81]
	s_mov_b32 m0, s42
	s_nop 0
	global_load_lds_dwordx4 v[190:191], off
	s_waitcnt vmcnt(8)
	s_waitcnt lgkmcnt(0)
	s_barrier
	s_setprio 1
	v_mfma_f32_16x16x32_bf16 v[64:67], v[146:149], v[178:181], v[64:67]
	v_mfma_f32_16x16x32_bf16 v[60:63], v[154:157], v[178:181], v[60:63]
	v_mfma_f32_16x16x32_bf16 v[48:51], v[146:149], v[186:189], v[48:51]
	v_mfma_f32_16x16x32_bf16 v[44:47], v[154:157], v[186:189], v[44:47]
	v_mfma_f32_16x16x32_bf16 v[32:35], v[146:149], v[208:211], v[32:35]
	v_mfma_f32_16x16x32_bf16 v[28:31], v[154:157], v[208:211], v[28:31]
	v_mfma_f32_16x16x32_bf16 v[16:19], v[146:149], v[216:219], v[16:19]
	v_mfma_f32_16x16x32_bf16 v[12:15], v[154:157], v[216:219], v[12:15]
	v_mfma_f32_16x16x32_bf16 v[64:67], v[150:153], v[182:185], v[64:67]
	v_mfma_f32_16x16x32_bf16 v[60:63], v[158:161], v[182:185], v[60:63]
	v_mfma_f32_16x16x32_bf16 v[48:51], v[150:153], v[204:207], v[48:51]
	v_mfma_f32_16x16x32_bf16 v[44:47], v[158:161], v[204:207], v[44:47]
	v_mfma_f32_16x16x32_bf16 v[32:35], v[150:153], v[212:215], v[32:35]
	v_mfma_f32_16x16x32_bf16 v[28:31], v[158:161], v[212:215], v[28:31]
	v_mfma_f32_16x16x32_bf16 v[16:19], v[150:153], v[220:223], v[16:19]
	v_mfma_f32_16x16x32_bf16 v[12:15], v[158:161], v[220:223], v[12:15]
	s_setprio 0
	s_setprio 1
	v_mfma_f32_16x16x32_bf16 v[56:59], v[162:165], v[178:181], v[56:59]
	v_mfma_f32_16x16x32_bf16 v[52:55], v[170:173], v[178:181], v[52:55]
	v_mfma_f32_16x16x32_bf16 v[40:43], v[162:165], v[186:189], v[40:43]
	v_mfma_f32_16x16x32_bf16 v[36:39], v[170:173], v[186:189], v[36:39]
	v_mfma_f32_16x16x32_bf16 v[24:27], v[162:165], v[208:211], v[24:27]
	v_mfma_f32_16x16x32_bf16 v[20:23], v[170:173], v[208:211], v[20:23]
	v_mfma_f32_16x16x32_bf16 v[8:11], v[162:165], v[216:219], v[8:11]
	v_mfma_f32_16x16x32_bf16 v[4:7], v[170:173], v[216:219], v[4:7]
	v_mfma_f32_16x16x32_bf16 v[56:59], v[166:169], v[182:185], v[56:59]
	v_mfma_f32_16x16x32_bf16 v[52:55], v[174:177], v[182:185], v[52:55]
	v_mfma_f32_16x16x32_bf16 v[40:43], v[166:169], v[204:207], v[40:43]
	v_mfma_f32_16x16x32_bf16 v[36:39], v[174:177], v[204:207], v[36:39]
	v_mfma_f32_16x16x32_bf16 v[24:27], v[166:169], v[212:215], v[24:27]
	v_mfma_f32_16x16x32_bf16 v[20:23], v[174:177], v[212:215], v[20:23]
	v_mfma_f32_16x16x32_bf16 v[8:11], v[166:169], v[220:223], v[8:11]
	v_mfma_f32_16x16x32_bf16 v[4:7], v[174:177], v[220:223], v[4:7]
	s_setprio 0
	s_barrier
	s_add_i32 s24, s53, 2
	s_add_u32 s51, s51, 0x100
	s_addc_u32 s52, s52, 0
	s_add_u32 s22, s22, 0x100
	s_addc_u32 s23, s23, 0
	s_cmp_ge_i32 s53, s43
	s_mov_b32 s53, s24
	s_cbranch_scc0 .LBB0_709

; #define PG8_STAGE(bufoff, gbase, voff) do { _Pragma("unroll") for (int _i = 0; _i < 2; ++_i) \
;         __builtin_amdgcn_global_load_lds((const unsigned*)((const char*)(gbase) + (voff)[_i]), (PG8_LAS unsigned*)(lds + (bufoff) + ldsw + _i * 8192), 16, 0, 0); } while (0)
; #define PG8_LDA(dst, b, h) do { _Pragma("unroll") for (int m = 0; m < 4; ++m) _Pragma("unroll") for (int k = 0; k < 2; ++k) dst[m][k] = *(const PG8_LAS bf16x8*)(lds + PG8_SA(b, h) + aoff + m * 2048 + k * 1024); } while (0)
; #define PG8_LDB(dst, b, h) do { _Pragma("unroll") for (int n = 0; n < 2; ++n) _Pragma("unroll") for (int k = 0; k < 2; ++k) dst[n][k] = *(const PG8_LAS bf16x8*)(lds + PG8_SB(b, h) + boff + n * 2048 + k * 1024); } while (0)
; #define PG8_MMA(ai, bj, At, Bt) do { __builtin_amdgcn_s_setprio(1); _Pragma("unroll") for (int m = 0; m < 4; ++m) _Pragma("unroll") for (int n = 0; n < 2; ++n) _Pragma("unroll") for (int k = 0; k < 2; ++k) \
;         acc[ai][bj][m][n] = __builtin_amdgcn_mfma_f32_16x16x32_bf16(Bt[n][k], At[m][k], acc[ai][bj][m][n], 0, 0, 0); __builtin_amdgcn_s_setprio(0); } while (0)
; #define PG8_WAIT_V(n) asm volatile("s_waitcnt vmcnt(" #n ")" ::: "memory")
; #define PG8_WAIT_L(n) asm volatile("s_waitcnt lgkmcnt(" #n ")" ::: "memory")
; template <class Epi, class Sched, bool ALIGN_EPI = false, bool SP2 = false>
; __device__ __forceinline__ void gemm_phase(PG8_LAS unsigned char* lds, const Gemm g, const Sched& S, const Epi& E, int tid_in) {
;     ...
;             const char* a1 = cA + (size_t)(t + 1) * kstep + (t >= jt ? jb : 0);
;             const char* a2 = last ? nA : cA + (size_t)(t + 2) * kstep + (t + 2 >= jt ? jb : 0); const char* b2 = last ? nB : cB + (size_t)(t + 2) * kstep;
;             const char* a3 = a2 + kstep; const char* b3 = b2 + kstep;
;             if (last && has_next) S.a_ready(nxt);
;             if constexpr (SP2) {
;             PG8_LDB(B0, 0, 0); PG8_LDB(B1, 0, 1); PG8_SCHED; PG8_LDA(At, 0, 0); PG8_STAGE(PG8_SA(1, 1), a1 + hsA, voffA);
;             PG8_WAIT_V(8); PG8_WAIT_L(0); PG8_BAR; PG8_MMA(0, 0, At, B0); PG8_MMA(0, 1, At, B1); PG8_BAR; PG8_SCHED;
;             PG8_LDA(At, 0, 1); PG8_STAGE(PG8_SB(0, 0), b2, voffB); PG8_STAGE(PG8_SB(0, 1), b2 + hsB, voffB); PG8_STAGE(PG8_SA(0, 0), a2, voffA);
;             PG8_WAIT_V(8); PG8_WAIT_L(0); PG8_BAR; PG8_MMA(1, 0, At, B0); PG8_MMA(1, 1, At, B1); PG8_BAR; PG8_SCHED;
.LBB0_924:
	s_add_i32 s24, s58, -2
	s_cmp_ge_i32 s24, s29
	s_cselect_b32 s60, s30, 0
	s_cselect_b32 s61, s47, 0
	s_cmp_ge_i32 s58, s29
	s_cselect_b32 s25, s30, 0
	s_cselect_b32 s24, s47, 0
	s_add_u32 s25, s22, s25
	s_addc_u32 s24, s23, s24
	s_add_u32 s59, s25, 0x80
	s_addc_u32 s24, s24, 0
	s_add_i32 s64, 0, 0x10000
	s_cmp_eq_u32 s46, s58
	s_cselect_b32 s25, s5, s24
	s_cselect_b32 s24, s4, s59
	v_add_u32_e32 v142, s64, v144
	s_cselect_b32 s63, s21, s55
	s_cselect_b32 s62, s20, s54
	s_add_i32 s59, 0, 0x14000
	ds_read_b128 v[148:151], v142
	ds_read_b128 v[152:155], v142 offset:1024
	ds_read_b128 v[156:159], v142 offset:2048
	ds_read_b128 v[160:163], v142 offset:3072
	v_add_u32_e32 v142, s59, v144
	ds_read_b128 v[164:167], v142
	ds_read_b128 v[168:171], v142 offset:1024
	ds_read_b128 v[172:175], v142 offset:2048
	ds_read_b128 v[176:179], v142 offset:3072
	v_lshl_add_u64 v[142:143], s[22:23], 0, v[140:141]
	v_lshl_add_u64 v[142:143], v[142:143], 0, s[60:61]
	s_add_i32 m0, s40, 0xc000
	ds_read_b128 v[180:183], v146
	ds_read_b128 v[184:187], v146 offset:1024
	ds_read_b128 v[188:191], v146 offset:2048
	ds_read_b128 v[204:207], v146 offset:3072
	ds_read_b128 v[208:211], v146 offset:4096
	ds_read_b128 v[212:215], v146 offset:5120
	ds_read_b128 v[216:219], v146 offset:6144
	ds_read_b128 v[220:223], v146 offset:7168
	global_load_lds_dwordx4 v[142:143], off
	v_lshl_add_u64 v[142:143], s[22:23], 0, v[138:139]
	v_lshl_add_u64 v[142:143], v[142:143], 0, s[60:61]
	s_add_i32 m0, s40, 0xe000
	s_nop 0
	global_load_lds_dwordx4 v[142:143], off
	s_waitcnt vmcnt(8)
	s_waitcnt lgkmcnt(0)
	s_barrier
	s_setprio 1
	v_mfma_f32_16x16x32_bf16 v[128:131], v[148:151], v[180:183], v[128:131]
	v_mfma_f32_16x16x32_bf16 v[124:127], v[156:159], v[180:183], v[124:127]
	v_mfma_f32_16x16x32_bf16 v[112:115], v[148:151], v[188:191], v[112:115]
	v_mfma_f32_16x16x32_bf16 v[108:111], v[156:159], v[188:191], v[108:111]
	v_mfma_f32_16x16x32_bf16 v[96:99], v[148:151], v[208:211], v[96:99]
	v_mfma_f32_16x16x32_bf16 v[92:95], v[156:159], v[208:211], v[92:95]
	v_mfma_f32_16x16x32_bf16 v[80:83], v[148:151], v[216:219], v[80:83]
	v_mfma_f32_16x16x32_bf16 v[76:79], v[156:159], v[216:219], v[76:79]
	v_mfma_f32_16x16x32_bf16 v[128:131], v[152:155], v[184:187], v[128:131]
	v_mfma_f32_16x16x32_bf16 v[124:127], v[160:163], v[184:187], v[124:127]
	v_mfma_f32_16x16x32_bf16 v[112:115], v[152:155], v[204:207], v[112:115]
	v_mfma_f32_16x16x32_bf16 v[108:111], v[160:163], v[204:207], v[108:111]
	v_mfma_f32_16x16x32_bf16 v[96:99], v[152:155], v[212:215], v[96:99]
	v_mfma_f32_16x16x32_bf16 v[92:95], v[160:163], v[212:215], v[92:95]
	v_mfma_f32_16x16x32_bf16 v[80:83], v[152:155], v[220:223], v[80:83]
	v_mfma_f32_16x16x32_bf16 v[76:79], v[160:163], v[220:223], v[76:79]
	s_setprio 0
	s_setprio 1
	v_mfma_f32_16x16x32_bf16 v[120:123], v[164:167], v[180:183], v[120:123]
	v_mfma_f32_16x16x32_bf16 v[116:119], v[172:175], v[180:183], v[116:119]
	v_mfma_f32_16x16x32_bf16 v[104:107], v[164:167], v[188:191], v[104:107]
	v_mfma_f32_16x16x32_bf16 v[100:103], v[172:175], v[188:191], v[100:103]
	v_mfma_f32_16x16x32_bf16 v[88:91], v[164:167], v[208:211], v[88:91]
	v_mfma_f32_16x16x32_bf16 v[84:87], v[172:175], v[208:211], v[84:87]
	v_mfma_f32_16x16x32_bf16 v[72:75], v[164:167], v[216:219], v[72:75]
	v_mfma_f32_16x16x32_bf16 v[68:71], v[172:175], v[216:219], v[68:71]
	v_mfma_f32_16x16x32_bf16 v[120:123], v[168:171], v[184:187], v[120:123]
	v_mfma_f32_16x16x32_bf16 v[116:119], v[176:179], v[184:187], v[116:119]
	v_mfma_f32_16x16x32_bf16 v[104:107], v[168:171], v[204:207], v[104:107]
	v_mfma_f32_16x16x32_bf16 v[100:103], v[176:179], v[204:207], v[100:103]
	v_mfma_f32_16x16x32_bf16 v[88:91], v[168:171], v[212:215], v[88:91]
	v_mfma_f32_16x16x32_bf16 v[84:87], v[176:179], v[212:215], v[84:87]
	v_mfma_f32_16x16x32_bf16 v[72:75], v[168:171], v[220:223], v[72:75]
	v_mfma_f32_16x16x32_bf16 v[68:71], v[176:179], v[220:223], v[68:71]
	s_setprio 0
	s_barrier
	s_add_i32 s60, s64, s34
	v_lshl_add_u64 v[142:143], s[62:63], 0, v[134:135]
	s_mov_b32 m0, s60
	ds_read_b128 v[180:183], v146 offset:16384
	ds_read_b128 v[184:187], v146 offset:17408
	ds_read_b128 v[188:191], v146 offset:18432
	ds_read_b128 v[204:207], v146 offset:19456
	ds_read_b128 v[208:211], v146 offset:20480
	ds_read_b128 v[212:215], v146 offset:21504
	ds_read_b128 v[216:219], v146 offset:22528
	ds_read_b128 v[220:223], v146 offset:23552
	global_load_lds_dwordx4 v[142:143], off
	s_add_i32 m0, s60, 0x2000
	s_add_u32 s60, s62, s8
	v_lshl_add_u64 v[196:197], s[62:63], 0, v[0:1]
	s_addc_u32 s61, s63, s9
	s_add_i32 s59, s59, s34
	global_load_lds_dwordx4 v[196:197], off
	v_lshl_add_u64 v[198:199], s[60:61], 0, v[134:135]
	s_mov_b32 m0, s59
	v_lshl_add_u64 v[200:201], s[60:61], 0, v[0:1]
	global_load_lds_dwordx4 v[198:199], off
	s_add_i32 m0, s59, 0x2000
	v_lshl_add_u64 v[228:229], s[24:25], 0, v[136:137]
	global_load_lds_dwordx4 v[200:201], off
	s_mov_b32 m0, s40
	v_lshl_add_u64 v[230:231], s[24:25], 0, v[132:133]
	global_load_lds_dwordx4 v[228:229], off
	s_mov_b32 m0, s41
	s_nop 0
	global_load_lds_dwordx4 v[230:231], off
	s_waitcnt vmcnt(8)
	s_waitcnt lgkmcnt(0)
	s_barrier
; #define PG8_STAGE(bufoff, gbase, voff) do { _Pragma("unroll") for (int _i = 0; _i < 2; ++_i) \
;         __builtin_amdgcn_global_load_lds((const unsigned*)((const char*)(gbase) + (voff)[_i]), (PG8_LAS unsigned*)(lds + (bufoff) + ldsw + _i * 8192), 16, 0, 0); } while (0)
; #define PG8_LDA(dst, b, h) do { _Pragma("unroll") for (int m = 0; m < 4; ++m) _Pragma("unroll") for (int k = 0; k < 2; ++k) dst[m][k] = *(const PG8_LAS bf16x8*)(lds + PG8_SA(b, h) + aoff + m * 2048 + k * 1024); } while (0)
; #define PG8_LDB(dst, b, h) do { _Pragma("unroll") for (int n = 0; n < 2; ++n) _Pragma("unroll") for (int k = 0; k < 2; ++k) dst[n][k] = *(const PG8_LAS bf16x8*)(lds + PG8_SB(b, h) + boff + n * 2048 + k * 1024); } while (0)
; #define PG8_MMA(ai, bj, At, Bt) do { __builtin_amdgcn_s_setprio(1); _Pragma("unroll") for (int m = 0; m < 4; ++m) _Pragma("unroll") for (int n = 0; n < 2; ++n) _Pragma("unroll") for (int k = 0; k < 2; ++k) \
;         acc[ai][bj][m][n] = __builtin_amdgcn_mfma_f32_16x16x32_bf16(Bt[n][k], At[m][k], acc[ai][bj][m][n], 0, 0, 0); __builtin_amdgcn_s_setprio(0); } while (0)
; #define PG8_WAIT_V(n) asm volatile("s_waitcnt vmcnt(" #n ")" ::: "memory")
; #define PG8_WAIT_L(n) asm volatile("s_waitcnt lgkmcnt(" #n ")" ::: "memory")
; #define PG8_BAR __builtin_amdgcn_s_barrier()
; #define PG8_SCHED __builtin_amdgcn_sched_barrier(0)
; template <class Epi, class Sched, bool ALIGN_EPI = false, bool SP2 = false>
; __device__ __forceinline__ void gemm_phase(PG8_LAS unsigned char* lds, const Gemm g, const Sched& S, const Epi& E, int tid_in) {
;     ...
;             PG8_WAIT_V(8); PG8_WAIT_L(0); PG8_BAR; PG8_MMA(1, 0, At, B0); PG8_MMA(1, 1, At, B1); PG8_BAR; PG8_SCHED;
;             PG8_LDB(B0, 1, 0); PG8_LDB(B1, 1, 1); PG8_SCHED; PG8_LDA(At, 1, 0); PG8_STAGE(PG8_SA(0, 1), a2 + hsA, voffA);
;             PG8_WAIT_V(8); PG8_WAIT_L(0); PG8_BAR; PG8_MMA(0, 0, At, B0); PG8_MMA(0, 1, At, B1); PG8_BAR; PG8_SCHED;
	s_setprio 1
	v_mfma_f32_16x16x32_bf16 v[64:67], v[148:151], v[180:183], v[64:67]
	v_mfma_f32_16x16x32_bf16 v[60:63], v[156:159], v[180:183], v[60:63]
	v_mfma_f32_16x16x32_bf16 v[48:51], v[148:151], v[188:191], v[48:51]
	v_mfma_f32_16x16x32_bf16 v[44:47], v[156:159], v[188:191], v[44:47]
	v_mfma_f32_16x16x32_bf16 v[32:35], v[148:151], v[208:211], v[32:35]
	v_mfma_f32_16x16x32_bf16 v[28:31], v[156:159], v[208:211], v[28:31]
	v_mfma_f32_16x16x32_bf16 v[16:19], v[148:151], v[216:219], v[16:19]
	v_mfma_f32_16x16x32_bf16 v[12:15], v[156:159], v[216:219], v[12:15]
	v_mfma_f32_16x16x32_bf16 v[64:67], v[152:155], v[184:187], v[64:67]
	v_mfma_f32_16x16x32_bf16 v[60:63], v[160:163], v[184:187], v[60:63]
	v_mfma_f32_16x16x32_bf16 v[48:51], v[152:155], v[204:207], v[48:51]
	v_mfma_f32_16x16x32_bf16 v[44:47], v[160:163], v[204:207], v[44:47]
	v_mfma_f32_16x16x32_bf16 v[32:35], v[152:155], v[212:215], v[32:35]
	v_mfma_f32_16x16x32_bf16 v[28:31], v[160:163], v[212:215], v[28:31]
	v_mfma_f32_16x16x32_bf16 v[16:19], v[152:155], v[220:223], v[16:19]
	v_mfma_f32_16x16x32_bf16 v[12:15], v[160:163], v[220:223], v[12:15]
	s_setprio 0
	s_setprio 1
	v_mfma_f32_16x16x32_bf16 v[56:59], v[164:167], v[180:183], v[56:59]
	v_mfma_f32_16x16x32_bf16 v[52:55], v[172:175], v[180:183], v[52:55]
	v_mfma_f32_16x16x32_bf16 v[40:43], v[164:167], v[188:191], v[40:43]
	v_mfma_f32_16x16x32_bf16 v[36:39], v[172:175], v[188:191], v[36:39]
	v_mfma_f32_16x16x32_bf16 v[24:27], v[164:167], v[208:211], v[24:27]
	v_mfma_f32_16x16x32_bf16 v[20:23], v[172:175], v[208:211], v[20:23]
	v_mfma_f32_16x16x32_bf16 v[8:11], v[164:167], v[216:219], v[8:11]
	v_mfma_f32_16x16x32_bf16 v[4:7], v[172:175], v[216:219], v[4:7]
	v_mfma_f32_16x16x32_bf16 v[56:59], v[168:171], v[184:187], v[56:59]
	v_mfma_f32_16x16x32_bf16 v[52:55], v[176:179], v[184:187], v[52:55]
	v_mfma_f32_16x16x32_bf16 v[40:43], v[168:171], v[204:207], v[40:43]
	v_mfma_f32_16x16x32_bf16 v[36:39], v[176:179], v[204:207], v[36:39]
	v_mfma_f32_16x16x32_bf16 v[24:27], v[168:171], v[212:215], v[24:27]
	v_mfma_f32_16x16x32_bf16 v[20:23], v[176:179], v[212:215], v[20:23]
	v_mfma_f32_16x16x32_bf16 v[8:11], v[168:171], v[220:223], v[8:11]
	v_mfma_f32_16x16x32_bf16 v[4:7], v[176:179], v[220:223], v[4:7]
	s_setprio 0
	s_barrier
	s_add_i32 s59, 0, 0x18000
	v_add_u32_e32 v147, s59, v144
	s_add_i32 s60, 0, 0x1c000
	ds_read_b128 v[148:151], v147
	ds_read_b128 v[152:155], v147 offset:1024
	ds_read_b128 v[156:159], v147 offset:2048
	ds_read_b128 v[160:163], v147 offset:3072
	v_add_u32_e32 v147, s60, v144
	ds_read_b128 v[164:167], v147
	ds_read_b128 v[168:171], v147 offset:1024
	ds_read_b128 v[172:175], v147 offset:2048
	ds_read_b128 v[176:179], v147 offset:3072
	s_add_u32 s24, s24, s6
	s_addc_u32 s25, s25, s7
	s_mov_b32 m0, s42
	v_lshl_add_u64 v[232:233], s[24:25], 0, v[136:137]
	ds_read_b128 v[180:183], v146 offset:32768
	ds_read_b128 v[184:187], v146 offset:33792
	ds_read_b128 v[188:191], v146 offset:34816
	ds_read_b128 v[204:207], v146 offset:35840
	ds_read_b128 v[208:211], v146 offset:36864
	ds_read_b128 v[212:215], v146 offset:37888
	ds_read_b128 v[216:219], v146 offset:38912
	ds_read_b128 v[220:223], v146 offset:39936
	global_load_lds_dwordx4 v[232:233], off
	v_lshl_add_u64 v[232:233], s[24:25], 0, v[132:133]
	s_mov_b32 m0, s43
	s_nop 0
	global_load_lds_dwordx4 v[232:233], off
	s_waitcnt vmcnt(8)
	s_waitcnt lgkmcnt(0)
	s_barrier
	s_setprio 1
	v_mfma_f32_16x16x32_bf16 v[128:131], v[148:151], v[180:183], v[128:131]
	v_mfma_f32_16x16x32_bf16 v[124:127], v[156:159], v[180:183], v[124:127]
	v_mfma_f32_16x16x32_bf16 v[112:115], v[148:151], v[188:191], v[112:115]
	v_mfma_f32_16x16x32_bf16 v[108:111], v[156:159], v[188:191], v[108:111]
	v_mfma_f32_16x16x32_bf16 v[96:99], v[148:151], v[208:211], v[96:99]
	v_mfma_f32_16x16x32_bf16 v[92:95], v[156:159], v[208:211], v[92:95]
	v_mfma_f32_16x16x32_bf16 v[80:83], v[148:151], v[216:219], v[80:83]
	v_mfma_f32_16x16x32_bf16 v[76:79], v[156:159], v[216:219], v[76:79]
	v_mfma_f32_16x16x32_bf16 v[128:131], v[152:155], v[184:187], v[128:131]
	v_mfma_f32_16x16x32_bf16 v[124:127], v[160:163], v[184:187], v[124:127]
	v_mfma_f32_16x16x32_bf16 v[112:115], v[152:155], v[204:207], v[112:115]
	v_mfma_f32_16x16x32_bf16 v[108:111], v[160:163], v[204:207], v[108:111]
	v_mfma_f32_16x16x32_bf16 v[96:99], v[152:155], v[212:215], v[96:99]
	v_mfma_f32_16x16x32_bf16 v[92:95], v[160:163], v[212:215], v[92:95]
	v_mfma_f32_16x16x32_bf16 v[80:83], v[152:155], v[220:223], v[80:83]
	v_mfma_f32_16x16x32_bf16 v[76:79], v[160:163], v[220:223], v[76:79]
	s_setprio 0
	s_setprio 1
	v_mfma_f32_16x16x32_bf16 v[120:123], v[164:167], v[180:183], v[120:123]
	v_mfma_f32_16x16x32_bf16 v[116:119], v[172:175], v[180:183], v[116:119]
	v_mfma_f32_16x16x32_bf16 v[104:107], v[164:167], v[188:191], v[104:107]
	v_mfma_f32_16x16x32_bf16 v[100:103], v[172:175], v[188:191], v[100:103]
	v_mfma_f32_16x16x32_bf16 v[88:91], v[164:167], v[208:211], v[88:91]
	v_mfma_f32_16x16x32_bf16 v[84:87], v[172:175], v[208:211], v[84:87]
	v_mfma_f32_16x16x32_bf16 v[72:75], v[164:167], v[216:219], v[72:75]
	v_mfma_f32_16x16x32_bf16 v[68:71], v[172:175], v[216:219], v[68:71]
	v_mfma_f32_16x16x32_bf16 v[120:123], v[168:171], v[184:187], v[120:123]
	v_mfma_f32_16x16x32_bf16 v[116:119], v[176:179], v[184:187], v[116:119]
	v_mfma_f32_16x16x32_bf16 v[104:107], v[168:171], v[204:207], v[104:107]
	v_mfma_f32_16x16x32_bf16 v[100:103], v[176:179], v[204:207], v[100:103]
	v_mfma_f32_16x16x32_bf16 v[88:91], v[168:171], v[212:215], v[88:91]
	v_mfma_f32_16x16x32_bf16 v[84:87], v[176:179], v[212:215], v[84:87]
	v_mfma_f32_16x16x32_bf16 v[72:75], v[168:171], v[220:223], v[72:75]
	v_mfma_f32_16x16x32_bf16 v[68:71], v[176:179], v[220:223], v[68:71]
	s_setprio 0
	s_barrier
; #define PG8_STAGE(bufoff, gbase, voff) do { _Pragma("unroll") for (int _i = 0; _i < 2; ++_i) \
;         __builtin_amdgcn_global_load_lds((const unsigned*)((const char*)(gbase) + (voff)[_i]), (PG8_LAS unsigned*)(lds + (bufoff) + ldsw + _i * 8192), 16, 0, 0); } while (0)
; #define PG8_LDA(dst, b, h) do { _Pragma("unroll") for (int m = 0; m < 4; ++m) _Pragma("unroll") for (int k = 0; k < 2; ++k) dst[m][k] = *(const PG8_LAS bf16x8*)(lds + PG8_SA(b, h) + aoff + m * 2048 + k * 1024); } while (0)
; #define PG8_MMA(ai, bj, At, Bt) do { __builtin_amdgcn_s_setprio(1); _Pragma("unroll") for (int m = 0; m < 4; ++m) _Pragma("unroll") for (int n = 0; n < 2; ++n) _Pragma("unroll") for (int k = 0; k < 2; ++k) \
;         acc[ai][bj][m][n] = __builtin_amdgcn_mfma_f32_16x16x32_bf16(Bt[n][k], At[m][k], acc[ai][bj][m][n], 0, 0, 0); __builtin_amdgcn_s_setprio(0); } while (0)
; #define PG8_WAIT_V(n) asm volatile("s_waitcnt vmcnt(" #n ")" ::: "memory")
; #define PG8_WAIT_L(n) asm volatile("s_waitcnt lgkmcnt(" #n ")" ::: "memory")
; #define PG8_BAR __builtin_amdgcn_s_barrier()
; #define PG8_SCHED __builtin_amdgcn_sched_barrier(0)
; template <class Epi, class Sched, bool ALIGN_EPI = false, bool SP2 = false>
; __device__ __forceinline__ void gemm_phase(PG8_LAS unsigned char* lds, const Gemm g, const Sched& S, const Epi& E, int tid_in) {
;     ...
;             PG8_LDA(At, 1, 1); PG8_STAGE(PG8_SB(1, 0), b3, voffB); PG8_STAGE(PG8_SB(1, 1), b3 + hsB, voffB); PG8_STAGE(PG8_SA(1, 0), a3, voffA);
;             PG8_WAIT_V(8); PG8_WAIT_L(0); PG8_BAR; PG8_MMA(1, 0, At, B0); PG8_MMA(1, 1, At, B1); PG8_BAR; PG8_SCHED;
	s_add_i32 s24, s59, s34
	v_lshl_add_u64 v[142:143], v[142:143], 0, s[80:81]
	s_mov_b32 m0, s24
	ds_read_b128 v[180:183], v146 offset:49152
	ds_read_b128 v[184:187], v146 offset:50176
	ds_read_b128 v[188:191], v146 offset:51200
	ds_read_b128 v[204:207], v146 offset:52224
	ds_read_b128 v[208:211], v146 offset:53248
	ds_read_b128 v[212:215], v146 offset:54272
	ds_read_b128 v[216:219], v146 offset:55296
	ds_read_b128 v[220:223], v146 offset:56320
	global_load_lds_dwordx4 v[142:143], off
	v_lshl_add_u64 v[142:143], v[196:197], 0, s[80:81]
	s_add_i32 m0, s24, 0x2000
	s_add_i32 s24, s60, s34
	global_load_lds_dwordx4 v[142:143], off
	v_lshl_add_u64 v[142:143], v[198:199], 0, s[80:81]
	s_mov_b32 m0, s24
	s_nop 0
	global_load_lds_dwordx4 v[142:143], off
	v_lshl_add_u64 v[142:143], v[200:201], 0, s[80:81]
	s_add_i32 m0, s24, 0x2000
	s_nop 0
	global_load_lds_dwordx4 v[142:143], off
	v_lshl_add_u64 v[142:143], v[228:229], 0, s[80:81]
	s_mov_b32 m0, s44
	s_nop 0
	global_load_lds_dwordx4 v[142:143], off
	v_lshl_add_u64 v[142:143], v[230:231], 0, s[80:81]
	s_mov_b32 m0, s45
	s_nop 0
	global_load_lds_dwordx4 v[142:143], off
	s_waitcnt vmcnt(8)
	s_waitcnt lgkmcnt(0)
	s_barrier
	s_setprio 1
	v_mfma_f32_16x16x32_bf16 v[64:67], v[148:151], v[180:183], v[64:67]
	v_mfma_f32_16x16x32_bf16 v[60:63], v[156:159], v[180:183], v[60:63]
	v_mfma_f32_16x16x32_bf16 v[48:51], v[148:151], v[188:191], v[48:51]
	v_mfma_f32_16x16x32_bf16 v[44:47], v[156:159], v[188:191], v[44:47]
	v_mfma_f32_16x16x32_bf16 v[32:35], v[148:151], v[208:211], v[32:35]
	v_mfma_f32_16x16x32_bf16 v[28:31], v[156:159], v[208:211], v[28:31]
	v_mfma_f32_16x16x32_bf16 v[16:19], v[148:151], v[216:219], v[16:19]
	v_mfma_f32_16x16x32_bf16 v[12:15], v[156:159], v[216:219], v[12:15]
	v_mfma_f32_16x16x32_bf16 v[64:67], v[152:155], v[184:187], v[64:67]
	v_mfma_f32_16x16x32_bf16 v[60:63], v[160:163], v[184:187], v[60:63]
	v_mfma_f32_16x16x32_bf16 v[48:51], v[152:155], v[204:207], v[48:51]
	v_mfma_f32_16x16x32_bf16 v[44:47], v[160:163], v[204:207], v[44:47]
	v_mfma_f32_16x16x32_bf16 v[32:35], v[152:155], v[212:215], v[32:35]
	v_mfma_f32_16x16x32_bf16 v[28:31], v[160:163], v[212:215], v[28:31]
	v_mfma_f32_16x16x32_bf16 v[16:19], v[152:155], v[220:223], v[16:19]
	v_mfma_f32_16x16x32_bf16 v[12:15], v[160:163], v[220:223], v[12:15]
	s_setprio 0
	s_setprio 1
	v_mfma_f32_16x16x32_bf16 v[56:59], v[164:167], v[180:183], v[56:59]
	v_mfma_f32_16x16x32_bf16 v[52:55], v[172:175], v[180:183], v[52:55]
	v_mfma_f32_16x16x32_bf16 v[40:43], v[164:167], v[188:191], v[40:43]
	v_mfma_f32_16x16x32_bf16 v[36:39], v[172:175], v[188:191], v[36:39]
	v_mfma_f32_16x16x32_bf16 v[24:27], v[164:167], v[208:211], v[24:27]
	v_mfma_f32_16x16x32_bf16 v[20:23], v[172:175], v[208:211], v[20:23]
	v_mfma_f32_16x16x32_bf16 v[8:11], v[164:167], v[216:219], v[8:11]
	v_mfma_f32_16x16x32_bf16 v[4:7], v[172:175], v[216:219], v[4:7]
	v_mfma_f32_16x16x32_bf16 v[56:59], v[168:171], v[184:187], v[56:59]
	v_mfma_f32_16x16x32_bf16 v[52:55], v[176:179], v[184:187], v[52:55]
	v_mfma_f32_16x16x32_bf16 v[40:43], v[168:171], v[204:207], v[40:43]
	v_mfma_f32_16x16x32_bf16 v[36:39], v[176:179], v[204:207], v[36:39]
	v_mfma_f32_16x16x32_bf16 v[24:27], v[168:171], v[212:215], v[24:27]
	v_mfma_f32_16x16x32_bf16 v[20:23], v[176:179], v[212:215], v[20:23]
	v_mfma_f32_16x16x32_bf16 v[8:11], v[168:171], v[220:223], v[8:11]
	v_mfma_f32_16x16x32_bf16 v[4:7], v[176:179], v[220:223], v[4:7]
	s_setprio 0
	s_barrier
	s_add_i32 s24, s58, 2
	s_add_u32 s54, s54, 0x100
	s_addc_u32 s55, s55, 0
	s_add_u32 s22, s22, 0x100
	s_addc_u32 s23, s23, 0
	s_cmp_ge_i32 s58, s46
	s_mov_b32 s58, s24
	s_cbranch_scc0 .LBB0_924

; #define PG8_STAGE(bufoff, gbase, voff) do { _Pragma("unroll") for (int _i = 0; _i < 2; ++_i) \
;         __builtin_amdgcn_global_load_lds((const unsigned*)((const char*)(gbase) + (voff)[_i]), (PG8_LAS unsigned*)(lds + (bufoff) + ldsw + _i * 8192), 16, 0, 0); } while (0)
; #define PG8_LDA(dst, b, h) do { _Pragma("unroll") for (int m = 0; m < 4; ++m) _Pragma("unroll") for (int k = 0; k < 2; ++k) dst[m][k] = *(const PG8_LAS bf16x8*)(lds + PG8_SA(b, h) + aoff + m * 2048 + k * 1024); } while (0)
; #define PG8_LDB(dst, b, h) do { _Pragma("unroll") for (int n = 0; n < 2; ++n) _Pragma("unroll") for (int k = 0; k < 2; ++k) dst[n][k] = *(const PG8_LAS bf16x8*)(lds + PG8_SB(b, h) + boff + n * 2048 + k * 1024); } while (0)
; #define PG8_WAIT_V(n) asm volatile("s_waitcnt vmcnt(" #n ")" ::: "memory")
; #define PG8_WAIT_L(n) asm volatile("s_waitcnt lgkmcnt(" #n ")" ::: "memory")
; #define PG8_BAR __builtin_amdgcn_s_barrier()
; #define PG8_SCHED __builtin_amdgcn_sched_barrier(0)
; template <class Epi, class Sched, bool ALIGN_EPI = false, bool SP2 = false>
; __device__ __forceinline__ void gemm_phase(PG8_LAS unsigned char* lds, const Gemm g, const Sched& S, const Epi& E, int tid_in) {
;     ...
;         for (int t = 0; t < nt; t += 2) {
;             const bool last = (t == nt - 2);
;             if constexpr (mid_hook<Epi>::value) { if (t == Epi::H1 || t == Epi::H2) E.mid(acc, cur, wr, wc, fr, fq, t == Epi::H2); }
;             const char* a1 = cA + (size_t)(t + 1) * kstep + (t >= jt ? jb : 0);
;             const char* a2 = last ? nA : cA + (size_t)(t + 2) * kstep + (t + 2 >= jt ? jb : 0); const char* b2 = last ? nB : cB + (size_t)(t + 2) * kstep;
;             const char* a3 = a2 + kstep; const char* b3 = b2 + kstep;
;             if (last && has_next) S.a_ready(nxt);
;             if constexpr (SP2) {
;             PG8_LDB(B0, 0, 0); PG8_LDB(B1, 0, 1); PG8_SCHED; PG8_LDA(At, 0, 0); PG8_STAGE(PG8_SA(1, 1), a1 + hsA, voffA);
;             PG8_WAIT_V(8); PG8_WAIT_L(0); PG8_BAR; PG8_MMA(0, 0, At, B0); PG8_MMA(0, 1, At, B1); PG8_BAR; PG8_SCHED;
;             PG8_LDA(At, 0, 1); PG8_STAGE(PG8_SB(0, 0), b2, voffB); PG8_STAGE(PG8_SB(0, 1), b2 + hsB, voffB); PG8_STAGE(PG8_SA(0, 0), a2, voffA);
;             PG8_WAIT_V(8); PG8_WAIT_L(0); PG8_BAR; PG8_MMA(1, 0, At, B0); PG8_MMA(1, 1, At, B1); PG8_BAR; PG8_SCHED;
.LBB0_994:
	s_cmp_ge_i32 s62, s37
	s_cselect_b32 s64, s38, 0
	s_cselect_b32 s65, s52, 0
	s_add_i32 s30, s62, 2
	s_cmp_ge_i32 s30, s37
	s_cselect_b32 s29, s38, 0
	s_cselect_b32 s28, s52, 0
	s_add_u32 s29, s26, s29
	s_addc_u32 s28, s27, s28
	s_add_u32 s31, s29, 0x80
	s_addc_u32 s28, s28, 0
	s_add_i32 s66, 0, 0x10000
	s_cmp_eq_u32 s53, s62
	s_cselect_b32 s29, s5, s28
	s_cselect_b32 s28, s4, s31
	v_add_u32_e32 v3, s66, v217
	s_cselect_b32 s63, s25, s61
	s_cselect_b32 s62, s24, s60
	s_add_i32 s31, 0, 0x14000
	ds_read_b128 v[134:137], v3
	ds_read_b128 v[138:141], v3 offset:1024
	ds_read_b128 v[142:145], v3 offset:2048
	ds_read_b128 v[146:149], v3 offset:3072
	v_add_u32_e32 v3, s31, v217
	ds_read_b128 v[150:153], v3
	ds_read_b128 v[154:157], v3 offset:1024
	ds_read_b128 v[158:161], v3 offset:2048
	ds_read_b128 v[162:165], v3 offset:3072
	v_lshl_add_u64 v[4:5], s[26:27], 0, v[182:183]
	v_lshl_add_u64 v[4:5], v[4:5], 0, s[64:65]
	s_add_i32 m0, s33, 0xc000
	ds_read_b128 v[166:169], v219
	ds_read_b128 v[170:173], v219 offset:1024
	ds_read_b128 v[220:223], v219 offset:2048
	ds_read_b128 v[238:241], v219 offset:3072
	ds_read_b128 v[242:245], v219 offset:4096
	ds_read_b128 v[246:249], v219 offset:5120
	ds_read_b128 v[250:253], v219 offset:6144
	ds_read_b128 v[230:233], v219 offset:7168
	global_load_lds_dwordx4 v[4:5], off
	v_lshl_add_u64 v[4:5], s[26:27], 0, v[180:181]
	v_lshl_add_u64 v[4:5], v[4:5], 0, s[64:65]
	s_add_i32 m0, s33, 0xe000
	s_nop 0
	global_load_lds_dwordx4 v[4:5], off
	s_waitcnt vmcnt(8)
	s_waitcnt lgkmcnt(0)
	s_barrier
	s_setprio 1
	v_mfma_f32_16x16x32_bf16 v[126:129], v[134:137], v[166:169], v[126:129]
	v_mfma_f32_16x16x32_bf16 v[130:133], v[142:145], v[166:169], v[130:133]
	v_mfma_f32_16x16x32_bf16 v[114:117], v[134:137], v[220:223], v[114:117]
	v_mfma_f32_16x16x32_bf16 v[110:113], v[142:145], v[220:223], v[110:113]
	v_mfma_f32_16x16x32_bf16 v[98:101], v[134:137], v[242:245], v[98:101]
	v_mfma_f32_16x16x32_bf16 v[94:97], v[142:145], v[242:245], v[94:97]
	v_mfma_f32_16x16x32_bf16 v[82:85], v[134:137], v[250:253], v[82:85]
	v_mfma_f32_16x16x32_bf16 v[78:81], v[142:145], v[250:253], v[78:81]
	v_mfma_f32_16x16x32_bf16 v[126:129], v[138:141], v[170:173], v[126:129]
	v_mfma_f32_16x16x32_bf16 v[130:133], v[146:149], v[170:173], v[130:133]
	v_mfma_f32_16x16x32_bf16 v[114:117], v[138:141], v[238:241], v[114:117]
	v_mfma_f32_16x16x32_bf16 v[110:113], v[146:149], v[238:241], v[110:113]
	v_mfma_f32_16x16x32_bf16 v[98:101], v[138:141], v[246:249], v[98:101]
	v_mfma_f32_16x16x32_bf16 v[94:97], v[146:149], v[246:249], v[94:97]
	v_mfma_f32_16x16x32_bf16 v[82:85], v[138:141], v[230:233], v[82:85]
	v_mfma_f32_16x16x32_bf16 v[78:81], v[146:149], v[230:233], v[78:81]
	s_setprio 0
	s_setprio 1
	v_mfma_f32_16x16x32_bf16 v[122:125], v[150:153], v[166:169], v[122:125]
	v_mfma_f32_16x16x32_bf16 v[118:121], v[158:161], v[166:169], v[118:121]
	v_mfma_f32_16x16x32_bf16 v[106:109], v[150:153], v[220:223], v[106:109]
	v_mfma_f32_16x16x32_bf16 v[102:105], v[158:161], v[220:223], v[102:105]
	v_mfma_f32_16x16x32_bf16 v[90:93], v[150:153], v[242:245], v[90:93]
	v_mfma_f32_16x16x32_bf16 v[86:89], v[158:161], v[242:245], v[86:89]
	v_mfma_f32_16x16x32_bf16 v[74:77], v[150:153], v[250:253], v[74:77]
	v_mfma_f32_16x16x32_bf16 v[70:73], v[158:161], v[250:253], v[70:73]
	v_mfma_f32_16x16x32_bf16 v[122:125], v[154:157], v[170:173], v[122:125]
	v_mfma_f32_16x16x32_bf16 v[118:121], v[162:165], v[170:173], v[118:121]
	v_mfma_f32_16x16x32_bf16 v[106:109], v[154:157], v[238:241], v[106:109]
	v_mfma_f32_16x16x32_bf16 v[102:105], v[162:165], v[238:241], v[102:105]
	v_mfma_f32_16x16x32_bf16 v[90:93], v[154:157], v[246:249], v[90:93]
	v_mfma_f32_16x16x32_bf16 v[86:89], v[162:165], v[246:249], v[86:89]
	v_mfma_f32_16x16x32_bf16 v[74:77], v[154:157], v[230:233], v[74:77]
	v_mfma_f32_16x16x32_bf16 v[70:73], v[162:165], v[230:233], v[70:73]
	s_setprio 0
	s_barrier
	s_add_i32 s64, s66, s43
	v_lshl_add_u64 v[196:197], s[62:63], 0, v[176:177]
	s_mov_b32 m0, s64
	ds_read_b128 v[166:169], v219 offset:16384
	ds_read_b128 v[170:173], v219 offset:17408
	ds_read_b128 v[220:223], v219 offset:18432
	ds_read_b128 v[230:233], v219 offset:19456
	ds_read_b128 v[238:241], v219 offset:20480
	ds_read_b128 v[242:245], v219 offset:21504
	ds_read_b128 v[246:249], v219 offset:22528
	ds_read_b128 v[250:253], v219 offset:23552
	global_load_lds_dwordx4 v[196:197], off
	s_add_i32 m0, s64, 0x2000
	v_lshl_add_u64 v[198:199], s[62:63], 0, v[0:1]
	s_add_u32 s62, s62, s8
	s_addc_u32 s63, s63, s9
	s_add_i32 s31, s31, s43
	global_load_lds_dwordx4 v[198:199], off
	v_lshl_add_u64 v[200:201], s[62:63], 0, v[176:177]
	s_mov_b32 m0, s31
	v_lshl_add_u64 v[228:229], s[62:63], 0, v[0:1]
	global_load_lds_dwordx4 v[200:201], off
	s_add_i32 m0, s31, 0x2000
	v_lshl_add_u64 v[202:203], s[28:29], 0, v[178:179]
	global_load_lds_dwordx4 v[228:229], off
	s_mov_b32 m0, s33
	v_lshl_add_u64 v[192:193], s[28:29], 0, v[174:175]
	global_load_lds_dwordx4 v[202:203], off
	s_mov_b32 m0, s46
	s_nop 0
	global_load_lds_dwordx4 v[192:193], off
	s_waitcnt vmcnt(8)
	s_waitcnt lgkmcnt(0)
	s_barrier
; #define PG8_STAGE(bufoff, gbase, voff) do { _Pragma("unroll") for (int _i = 0; _i < 2; ++_i) \
;         __builtin_amdgcn_global_load_lds((const unsigned*)((const char*)(gbase) + (voff)[_i]), (PG8_LAS unsigned*)(lds + (bufoff) + ldsw + _i * 8192), 16, 0, 0); } while (0)
; #define PG8_LDA(dst, b, h) do { _Pragma("unroll") for (int m = 0; m < 4; ++m) _Pragma("unroll") for (int k = 0; k < 2; ++k) dst[m][k] = *(const PG8_LAS bf16x8*)(lds + PG8_SA(b, h) + aoff + m * 2048 + k * 1024); } while (0)
; #define PG8_LDB(dst, b, h) do { _Pragma("unroll") for (int n = 0; n < 2; ++n) _Pragma("unroll") for (int k = 0; k < 2; ++k) dst[n][k] = *(const PG8_LAS bf16x8*)(lds + PG8_SB(b, h) + boff + n * 2048 + k * 1024); } while (0)
; #define PG8_MMA(ai, bj, At, Bt) do { __builtin_amdgcn_s_setprio(1); _Pragma("unroll") for (int m = 0; m < 4; ++m) _Pragma("unroll") for (int n = 0; n < 2; ++n) _Pragma("unroll") for (int k = 0; k < 2; ++k) \
;         acc[ai][bj][m][n] = __builtin_amdgcn_mfma_f32_16x16x32_bf16(Bt[n][k], At[m][k], acc[ai][bj][m][n], 0, 0, 0); __builtin_amdgcn_s_setprio(0); } while (0)
; #define PG8_WAIT_V(n) asm volatile("s_waitcnt vmcnt(" #n ")" ::: "memory")
; #define PG8_WAIT_L(n) asm volatile("s_waitcnt lgkmcnt(" #n ")" ::: "memory")
; #define PG8_BAR __builtin_amdgcn_s_barrier()
; #define PG8_SCHED __builtin_amdgcn_sched_barrier(0)
; template <class Epi, class Sched, bool ALIGN_EPI = false, bool SP2 = false>
; __device__ __forceinline__ void gemm_phase(PG8_LAS unsigned char* lds, const Gemm g, const Sched& S, const Epi& E, int tid_in) {
;     ...
;             PG8_WAIT_V(8); PG8_WAIT_L(0); PG8_BAR; PG8_MMA(1, 0, At, B0); PG8_MMA(1, 1, At, B1); PG8_BAR; PG8_SCHED;
;             PG8_LDB(B0, 1, 0); PG8_LDB(B1, 1, 1); PG8_SCHED; PG8_LDA(At, 1, 0); PG8_STAGE(PG8_SA(0, 1), a2 + hsA, voffA);
;             PG8_WAIT_V(8); PG8_WAIT_L(0); PG8_BAR; PG8_MMA(0, 0, At, B0); PG8_MMA(0, 1, At, B1); PG8_BAR; PG8_SCHED;
	s_setprio 1
	v_mfma_f32_16x16x32_bf16 v[66:69], v[134:137], v[166:169], v[66:69]
	v_mfma_f32_16x16x32_bf16 v[62:65], v[142:145], v[166:169], v[62:65]
	v_mfma_f32_16x16x32_bf16 v[50:53], v[134:137], v[220:223], v[50:53]
	v_mfma_f32_16x16x32_bf16 v[46:49], v[142:145], v[220:223], v[46:49]
	v_mfma_f32_16x16x32_bf16 v[34:37], v[134:137], v[238:241], v[34:37]
	v_mfma_f32_16x16x32_bf16 v[30:33], v[142:145], v[238:241], v[30:33]
	v_mfma_f32_16x16x32_bf16 v[18:21], v[134:137], v[246:249], v[18:21]
	v_mfma_f32_16x16x32_bf16 v[14:17], v[142:145], v[246:249], v[14:17]
	v_mfma_f32_16x16x32_bf16 v[66:69], v[138:141], v[170:173], v[66:69]
	v_mfma_f32_16x16x32_bf16 v[62:65], v[146:149], v[170:173], v[62:65]
	v_mfma_f32_16x16x32_bf16 v[50:53], v[138:141], v[230:233], v[50:53]
	v_mfma_f32_16x16x32_bf16 v[46:49], v[146:149], v[230:233], v[46:49]
	v_mfma_f32_16x16x32_bf16 v[34:37], v[138:141], v[242:245], v[34:37]
	v_mfma_f32_16x16x32_bf16 v[30:33], v[146:149], v[242:245], v[30:33]
	v_mfma_f32_16x16x32_bf16 v[18:21], v[138:141], v[250:253], v[18:21]
	v_mfma_f32_16x16x32_bf16 v[14:17], v[146:149], v[250:253], v[14:17]
	s_setprio 0
	s_setprio 1
	v_mfma_f32_16x16x32_bf16 v[58:61], v[150:153], v[166:169], v[58:61]
	v_mfma_f32_16x16x32_bf16 v[54:57], v[158:161], v[166:169], v[54:57]
	v_mfma_f32_16x16x32_bf16 v[42:45], v[150:153], v[220:223], v[42:45]
	v_mfma_f32_16x16x32_bf16 v[38:41], v[158:161], v[220:223], v[38:41]
	v_mfma_f32_16x16x32_bf16 v[26:29], v[150:153], v[238:241], v[26:29]
	v_mfma_f32_16x16x32_bf16 v[22:25], v[158:161], v[238:241], v[22:25]
	v_mfma_f32_16x16x32_bf16 v[10:13], v[150:153], v[246:249], v[10:13]
	v_mfma_f32_16x16x32_bf16 v[4:7], v[158:161], v[246:249], v[6:9]
	v_mfma_f32_16x16x32_bf16 v[58:61], v[154:157], v[170:173], v[58:61]
	v_mfma_f32_16x16x32_bf16 v[54:57], v[162:165], v[170:173], v[54:57]
	v_mfma_f32_16x16x32_bf16 v[42:45], v[154:157], v[230:233], v[42:45]
	v_mfma_f32_16x16x32_bf16 v[38:41], v[162:165], v[230:233], v[38:41]
	v_mfma_f32_16x16x32_bf16 v[26:29], v[154:157], v[242:245], v[26:29]
	v_mfma_f32_16x16x32_bf16 v[22:25], v[162:165], v[242:245], v[22:25]
	v_mfma_f32_16x16x32_bf16 v[10:13], v[154:157], v[250:253], v[10:13]
	v_mfma_f32_16x16x32_bf16 v[4:7], v[162:165], v[250:253], v[4:7]
	s_setprio 0
	s_barrier
	s_add_i32 s31, 0, 0x18000
	v_add_u32_e32 v3, s31, v217
	s_add_i32 s62, 0, 0x1c000
	ds_read_b128 v[134:137], v3
	ds_read_b128 v[138:141], v3 offset:1024
	ds_read_b128 v[142:145], v3 offset:2048
	ds_read_b128 v[146:149], v3 offset:3072
	v_add_u32_e32 v3, s62, v217
	ds_read_b128 v[150:153], v3
	ds_read_b128 v[154:157], v3 offset:1024
	ds_read_b128 v[158:161], v3 offset:2048
	ds_read_b128 v[162:165], v3 offset:3072
	s_add_u32 s28, s28, s6
	s_addc_u32 s29, s29, s7
	s_mov_b32 m0, s47
	v_lshl_add_u64 v[8:9], s[28:29], 0, v[178:179]
	ds_read_b128 v[166:169], v219 offset:32768
	ds_read_b128 v[170:173], v219 offset:33792
	ds_read_b128 v[220:223], v219 offset:34816
	ds_read_b128 v[230:233], v219 offset:35840
	ds_read_b128 v[238:241], v219 offset:36864
	ds_read_b128 v[242:245], v219 offset:37888
	ds_read_b128 v[246:249], v219 offset:38912
	ds_read_b128 v[250:253], v219 offset:39936
	global_load_lds_dwordx4 v[8:9], off
	v_lshl_add_u64 v[8:9], s[28:29], 0, v[174:175]
	s_mov_b32 m0, s48
	s_nop 0
	global_load_lds_dwordx4 v[8:9], off
	s_waitcnt vmcnt(8)
	s_waitcnt lgkmcnt(0)
	s_barrier
	s_setprio 1
	v_mfma_f32_16x16x32_bf16 v[126:129], v[134:137], v[166:169], v[126:129]
	v_mfma_f32_16x16x32_bf16 v[130:133], v[142:145], v[166:169], v[130:133]
	v_mfma_f32_16x16x32_bf16 v[114:117], v[134:137], v[220:223], v[114:117]
	v_mfma_f32_16x16x32_bf16 v[110:113], v[142:145], v[220:223], v[110:113]
	v_mfma_f32_16x16x32_bf16 v[98:101], v[134:137], v[238:241], v[98:101]
	v_mfma_f32_16x16x32_bf16 v[94:97], v[142:145], v[238:241], v[94:97]
	v_mfma_f32_16x16x32_bf16 v[82:85], v[134:137], v[246:249], v[82:85]
	v_mfma_f32_16x16x32_bf16 v[78:81], v[142:145], v[246:249], v[78:81]
	v_mfma_f32_16x16x32_bf16 v[126:129], v[138:141], v[170:173], v[126:129]
	v_mfma_f32_16x16x32_bf16 v[130:133], v[146:149], v[170:173], v[130:133]
	v_mfma_f32_16x16x32_bf16 v[114:117], v[138:141], v[230:233], v[114:117]
	v_mfma_f32_16x16x32_bf16 v[110:113], v[146:149], v[230:233], v[110:113]
	v_mfma_f32_16x16x32_bf16 v[98:101], v[138:141], v[242:245], v[98:101]
	v_mfma_f32_16x16x32_bf16 v[94:97], v[146:149], v[242:245], v[94:97]
	v_mfma_f32_16x16x32_bf16 v[82:85], v[138:141], v[250:253], v[82:85]
	v_mfma_f32_16x16x32_bf16 v[78:81], v[146:149], v[250:253], v[78:81]
	s_setprio 0
	s_setprio 1
	v_mfma_f32_16x16x32_bf16 v[122:125], v[150:153], v[166:169], v[122:125]
	v_mfma_f32_16x16x32_bf16 v[118:121], v[158:161], v[166:169], v[118:121]
	v_mfma_f32_16x16x32_bf16 v[106:109], v[150:153], v[220:223], v[106:109]
	v_mfma_f32_16x16x32_bf16 v[102:105], v[158:161], v[220:223], v[102:105]
	v_mfma_f32_16x16x32_bf16 v[90:93], v[150:153], v[238:241], v[90:93]
	v_mfma_f32_16x16x32_bf16 v[86:89], v[158:161], v[238:241], v[86:89]
	v_mfma_f32_16x16x32_bf16 v[74:77], v[150:153], v[246:249], v[74:77]
	v_mfma_f32_16x16x32_bf16 v[70:73], v[158:161], v[246:249], v[70:73]
	v_mfma_f32_16x16x32_bf16 v[122:125], v[154:157], v[170:173], v[122:125]
	v_mfma_f32_16x16x32_bf16 v[118:121], v[162:165], v[170:173], v[118:121]
	v_mfma_f32_16x16x32_bf16 v[106:109], v[154:157], v[230:233], v[106:109]
	v_mfma_f32_16x16x32_bf16 v[102:105], v[162:165], v[230:233], v[102:105]
	v_mfma_f32_16x16x32_bf16 v[90:93], v[154:157], v[242:245], v[90:93]
	v_mfma_f32_16x16x32_bf16 v[86:89], v[162:165], v[242:245], v[86:89]
	v_mfma_f32_16x16x32_bf16 v[74:77], v[154:157], v[250:253], v[74:77]
	v_mfma_f32_16x16x32_bf16 v[70:73], v[162:165], v[250:253], v[70:73]
	s_setprio 0
	s_barrier
; #define PG8_STAGE(bufoff, gbase, voff) do { _Pragma("unroll") for (int _i = 0; _i < 2; ++_i) \
;         __builtin_amdgcn_global_load_lds((const unsigned*)((const char*)(gbase) + (voff)[_i]), (PG8_LAS unsigned*)(lds + (bufoff) + ldsw + _i * 8192), 16, 0, 0); } while (0)
; #define PG8_LDA(dst, b, h) do { _Pragma("unroll") for (int m = 0; m < 4; ++m) _Pragma("unroll") for (int k = 0; k < 2; ++k) dst[m][k] = *(const PG8_LAS bf16x8*)(lds + PG8_SA(b, h) + aoff + m * 2048 + k * 1024); } while (0)
; #define PG8_MMA(ai, bj, At, Bt) do { __builtin_amdgcn_s_setprio(1); _Pragma("unroll") for (int m = 0; m < 4; ++m) _Pragma("unroll") for (int n = 0; n < 2; ++n) _Pragma("unroll") for (int k = 0; k < 2; ++k) \
;         acc[ai][bj][m][n] = __builtin_amdgcn_mfma_f32_16x16x32_bf16(Bt[n][k], At[m][k], acc[ai][bj][m][n], 0, 0, 0); __builtin_amdgcn_s_setprio(0); } while (0)
; #define PG8_WAIT_V(n) asm volatile("s_waitcnt vmcnt(" #n ")" ::: "memory")
; #define PG8_WAIT_L(n) asm volatile("s_waitcnt lgkmcnt(" #n ")" ::: "memory")
; #define PG8_BAR __builtin_amdgcn_s_barrier()
; #define PG8_SCHED __builtin_amdgcn_sched_barrier(0)
; template <class Epi, class Sched, bool ALIGN_EPI = false, bool SP2 = false>
; __device__ __forceinline__ void gemm_phase(PG8_LAS unsigned char* lds, const Gemm g, const Sched& S, const Epi& E, int tid_in) {
;     ...
;         for (int t = 0; t < nt; t += 2) {
;     ...
;             PG8_LDA(At, 1, 1); PG8_STAGE(PG8_SB(1, 0), b3, voffB); PG8_STAGE(PG8_SB(1, 1), b3 + hsB, voffB); PG8_STAGE(PG8_SA(1, 0), a3, voffA);
;             PG8_WAIT_V(8); PG8_WAIT_L(0); PG8_BAR; PG8_MMA(1, 0, At, B0); PG8_MMA(1, 1, At, B1); PG8_BAR; PG8_SCHED;
	s_add_i32 s28, s31, s43
	v_lshl_add_u64 v[8:9], v[196:197], 0, s[80:81]
	s_mov_b32 m0, s28
	ds_read_b128 v[166:169], v219 offset:49152
	ds_read_b128 v[170:173], v219 offset:50176
	ds_read_b128 v[220:223], v219 offset:51200
	ds_read_b128 v[230:233], v219 offset:52224
	ds_read_b128 v[238:241], v219 offset:53248
	ds_read_b128 v[242:245], v219 offset:54272
	ds_read_b128 v[246:249], v219 offset:55296
	ds_read_b128 v[250:253], v219 offset:56320
	global_load_lds_dwordx4 v[8:9], off
	v_lshl_add_u64 v[8:9], v[198:199], 0, s[80:81]
	s_add_i32 m0, s28, 0x2000
	s_add_i32 s28, s62, s43
	global_load_lds_dwordx4 v[8:9], off
	v_lshl_add_u64 v[8:9], v[200:201], 0, s[80:81]
	s_mov_b32 m0, s28
	s_nop 0
	global_load_lds_dwordx4 v[8:9], off
	v_lshl_add_u64 v[8:9], v[228:229], 0, s[80:81]
	s_add_i32 m0, s28, 0x2000
	s_nop 0
	global_load_lds_dwordx4 v[8:9], off
	v_lshl_add_u64 v[8:9], v[202:203], 0, s[80:81]
	s_mov_b32 m0, s49
	s_nop 0
	global_load_lds_dwordx4 v[8:9], off
	v_lshl_add_u64 v[8:9], v[192:193], 0, s[80:81]
	s_mov_b32 m0, s50
	s_nop 0
	global_load_lds_dwordx4 v[8:9], off
	s_waitcnt vmcnt(8)
	s_waitcnt lgkmcnt(0)
	s_barrier
	s_setprio 1
	v_mfma_f32_16x16x32_bf16 v[66:69], v[134:137], v[166:169], v[66:69]
	v_mfma_f32_16x16x32_bf16 v[62:65], v[142:145], v[166:169], v[62:65]
	v_mfma_f32_16x16x32_bf16 v[50:53], v[134:137], v[220:223], v[50:53]
	v_mfma_f32_16x16x32_bf16 v[46:49], v[142:145], v[220:223], v[46:49]
	v_mfma_f32_16x16x32_bf16 v[34:37], v[134:137], v[238:241], v[34:37]
	v_mfma_f32_16x16x32_bf16 v[30:33], v[142:145], v[238:241], v[30:33]
	v_mfma_f32_16x16x32_bf16 v[18:21], v[134:137], v[246:249], v[18:21]
	v_mfma_f32_16x16x32_bf16 v[14:17], v[142:145], v[246:249], v[14:17]
	v_mfma_f32_16x16x32_bf16 v[66:69], v[138:141], v[170:173], v[66:69]
	v_mfma_f32_16x16x32_bf16 v[62:65], v[146:149], v[170:173], v[62:65]
	v_mfma_f32_16x16x32_bf16 v[50:53], v[138:141], v[230:233], v[50:53]
	v_mfma_f32_16x16x32_bf16 v[46:49], v[146:149], v[230:233], v[46:49]
	v_mfma_f32_16x16x32_bf16 v[34:37], v[138:141], v[242:245], v[34:37]
	v_mfma_f32_16x16x32_bf16 v[30:33], v[146:149], v[242:245], v[30:33]
	v_mfma_f32_16x16x32_bf16 v[18:21], v[138:141], v[250:253], v[18:21]
	v_mfma_f32_16x16x32_bf16 v[14:17], v[146:149], v[250:253], v[14:17]
	s_setprio 0
	s_setprio 1
	v_mfma_f32_16x16x32_bf16 v[58:61], v[150:153], v[166:169], v[58:61]
	v_mfma_f32_16x16x32_bf16 v[54:57], v[158:161], v[166:169], v[54:57]
	v_mfma_f32_16x16x32_bf16 v[42:45], v[150:153], v[220:223], v[42:45]
	v_mfma_f32_16x16x32_bf16 v[38:41], v[158:161], v[220:223], v[38:41]
	v_mfma_f32_16x16x32_bf16 v[26:29], v[150:153], v[238:241], v[26:29]
	v_mfma_f32_16x16x32_bf16 v[22:25], v[158:161], v[238:241], v[22:25]
	v_mfma_f32_16x16x32_bf16 v[8:11], v[150:153], v[246:249], v[10:13]
	v_mfma_f32_16x16x32_bf16 v[4:7], v[158:161], v[246:249], v[4:7]
	v_mfma_f32_16x16x32_bf16 v[58:61], v[154:157], v[170:173], v[58:61]
	v_mfma_f32_16x16x32_bf16 v[54:57], v[162:165], v[170:173], v[54:57]
	v_mfma_f32_16x16x32_bf16 v[42:45], v[154:157], v[230:233], v[42:45]
	v_mfma_f32_16x16x32_bf16 v[38:41], v[162:165], v[230:233], v[38:41]
	v_mfma_f32_16x16x32_bf16 v[26:29], v[154:157], v[242:245], v[26:29]
	v_mfma_f32_16x16x32_bf16 v[22:25], v[162:165], v[242:245], v[22:25]
	v_mfma_f32_16x16x32_bf16 v[10:13], v[154:157], v[250:253], v[8:11]
	v_mfma_f32_16x16x32_bf16 v[6:9], v[162:165], v[250:253], v[4:7]
	s_setprio 0
	s_barrier
	s_add_u32 s60, s60, 0x100
	s_addc_u32 s61, s61, 0
	s_add_u32 s26, s26, 0x100
	s_addc_u32 s27, s27, 0
	s_cmp_ge_i32 s30, s51
	s_cbranch_scc1 .LBB0_996
	s_mov_b32 s62, s30
	s_cmp_lt_i32 s62, 32
	s_cbranch_scc1 .LBB0_990
	s_branch .LBB0_989

; #define PG8_STAGE(bufoff, gbase, voff) do { _Pragma("unroll") for (int _i = 0; _i < 2; ++_i) \
;         __builtin_amdgcn_global_load_lds((const unsigned*)((const char*)(gbase) + (voff)[_i]), (PG8_LAS unsigned*)(lds + (bufoff) + ldsw + _i * 8192), 16, 0, 0); } while (0)
; #define PG8_LDA(dst, b, h) do { _Pragma("unroll") for (int m = 0; m < 4; ++m) _Pragma("unroll") for (int k = 0; k < 2; ++k) dst[m][k] = *(const PG8_LAS bf16x8*)(lds + PG8_SA(b, h) + aoff + m * 2048 + k * 1024); } while (0)
; #define PG8_LDB(dst, b, h) do { _Pragma("unroll") for (int n = 0; n < 2; ++n) _Pragma("unroll") for (int k = 0; k < 2; ++k) dst[n][k] = *(const PG8_LAS bf16x8*)(lds + PG8_SB(b, h) + boff + n * 2048 + k * 1024); } while (0)
; #define PG8_WAIT_V(n) asm volatile("s_waitcnt vmcnt(" #n ")" ::: "memory")
; #define PG8_WAIT_L(n) asm volatile("s_waitcnt lgkmcnt(" #n ")" ::: "memory")
; #define PG8_BAR __builtin_amdgcn_s_barrier()
; #define PG8_SCHED __builtin_amdgcn_sched_barrier(0)
; template <class Epi, class Sched, bool ALIGN_EPI = false, bool SP2 = false>
; __device__ __forceinline__ void gemm_phase(PG8_LAS unsigned char* lds, const Gemm g, const Sched& S, const Epi& E, int tid_in) {
;     ...
;         for (int t = 0; t < nt; t += 2) {
;             const bool last = (t == nt - 2);
;             if constexpr (mid_hook<Epi>::value) { if (t == Epi::H1 || t == Epi::H2) E.mid(acc, cur, wr, wc, fr, fq, t == Epi::H2); }
;             const char* a1 = cA + (size_t)(t + 1) * kstep + (t >= jt ? jb : 0);
;             const char* a2 = last ? nA : cA + (size_t)(t + 2) * kstep + (t + 2 >= jt ? jb : 0); const char* b2 = last ? nB : cB + (size_t)(t + 2) * kstep;
;             const char* a3 = a2 + kstep; const char* b3 = b2 + kstep;
;             if (last && has_next) S.a_ready(nxt);
;             if constexpr (SP2) {
;             PG8_LDB(B0, 0, 0); PG8_LDB(B1, 0, 1); PG8_SCHED; PG8_LDA(At, 0, 0); PG8_STAGE(PG8_SA(1, 1), a1 + hsA, voffA);
;             PG8_WAIT_V(8); PG8_WAIT_L(0); PG8_BAR; PG8_MMA(0, 0, At, B0); PG8_MMA(0, 1, At, B1); PG8_BAR; PG8_SCHED;
;             PG8_LDA(At, 0, 1); PG8_STAGE(PG8_SB(0, 0), b2, voffB); PG8_STAGE(PG8_SB(0, 1), b2 + hsB, voffB); PG8_STAGE(PG8_SA(0, 0), a2, voffA);
;             PG8_WAIT_V(8); PG8_WAIT_L(0); PG8_BAR; PG8_MMA(1, 0, At, B0); PG8_MMA(1, 1, At, B1); PG8_BAR; PG8_SCHED;
.LBB0_1070:
	s_add_i32 s38, s40, -2
	s_cmp_ge_i32 s38, s46
	s_cselect_b32 s78, s47, 0
	s_cselect_b32 s79, s62, 0
	s_cmp_ge_i32 s40, s46
	s_cselect_b32 s39, s47, 0
	s_cselect_b32 s38, s62, 0
	s_add_u32 s39, s4, s39
	s_addc_u32 s38, s5, s38
	s_add_u32 s41, s39, 0x80
	s_addc_u32 s38, s38, 0
	s_add_i32 s77, 0, 0x10000
	s_cmp_eq_u32 s61, s40
	s_cselect_b32 s39, s35, s38
	s_cselect_b32 s38, s34, s41
	s_cselect_b32 s83, s37, s76
	s_cselect_b32 s82, s36, s75
	s_add_i32 s41, 0, 0x14000
	v_add_u32_e32 v144, s77, v217
	v_add_u32_e32 v170, s41, v217
	ds_read_b128 v[116:119], v144
	ds_read_b128 v[120:123], v144 offset:1024
	ds_read_b128 v[140:143], v144 offset:2048
	ds_read_b128 v[144:147], v144 offset:3072
	ds_read_b128 v[148:151], v170
	ds_read_b128 v[152:155], v170 offset:1024
	ds_read_b128 v[156:159], v170 offset:2048
	ds_read_b128 v[170:173], v170 offset:3072
	v_lshl_add_u64 v[190:191], s[4:5], 0, v[168:169]
	v_lshl_add_u64 v[190:191], v[190:191], 0, s[78:79]
	s_add_i32 m0, s51, 0xc000
	ds_read_b128 v[174:177], v219
	ds_read_b128 v[178:181], v219 offset:1024
	ds_read_b128 v[182:185], v219 offset:2048
	ds_read_b128 v[186:189], v219 offset:3072
	ds_read_b128 v[204:207], v219 offset:4096
	ds_read_b128 v[208:211], v219 offset:5120
	ds_read_b128 v[212:215], v219 offset:6144
	ds_read_b128 v[220:223], v219 offset:7168
	global_load_lds_dwordx4 v[190:191], off
	v_lshl_add_u64 v[190:191], s[4:5], 0, v[166:167]
	v_lshl_add_u64 v[190:191], v[190:191], 0, s[78:79]
	s_add_i32 m0, s51, 0xe000
	s_nop 0
	global_load_lds_dwordx4 v[190:191], off
	s_waitcnt vmcnt(8)
	s_waitcnt lgkmcnt(0)
	s_barrier
	s_setprio 1
	v_mfma_f32_16x16x32_bf16 v[136:139], v[116:119], v[174:177], v[136:139]
	v_mfma_f32_16x16x32_bf16 v[132:135], v[140:143], v[174:177], v[132:135]
	v_mfma_f32_16x16x32_bf16 v[128:131], v[116:119], v[182:185], v[128:131]
	v_mfma_f32_16x16x32_bf16 v[124:127], v[140:143], v[182:185], v[124:127]
	v_mfma_f32_16x16x32_bf16 v[112:115], v[116:119], v[204:207], v[112:115]
	v_mfma_f32_16x16x32_bf16 v[108:111], v[140:143], v[204:207], v[108:111]
	v_mfma_f32_16x16x32_bf16 v[104:107], v[116:119], v[212:215], v[104:107]
	v_mfma_f32_16x16x32_bf16 v[100:103], v[140:143], v[212:215], v[100:103]
	v_mfma_f32_16x16x32_bf16 v[136:139], v[120:123], v[178:181], v[136:139]
	v_mfma_f32_16x16x32_bf16 v[132:135], v[144:147], v[178:181], v[132:135]
	v_mfma_f32_16x16x32_bf16 v[128:131], v[120:123], v[186:189], v[128:131]
	v_mfma_f32_16x16x32_bf16 v[124:127], v[144:147], v[186:189], v[124:127]
	v_mfma_f32_16x16x32_bf16 v[112:115], v[120:123], v[208:211], v[112:115]
	v_mfma_f32_16x16x32_bf16 v[108:111], v[144:147], v[208:211], v[108:111]
	v_mfma_f32_16x16x32_bf16 v[104:107], v[120:123], v[220:223], v[104:107]
	v_mfma_f32_16x16x32_bf16 v[100:103], v[144:147], v[220:223], v[100:103]
	s_setprio 0
	s_setprio 1
	v_mfma_f32_16x16x32_bf16 v[64:67], v[148:151], v[174:177], v[64:67]
	v_mfma_f32_16x16x32_bf16 v[56:59], v[156:159], v[174:177], v[56:59]
	v_mfma_f32_16x16x32_bf16 v[60:63], v[148:151], v[182:185], v[60:63]
	v_mfma_f32_16x16x32_bf16 v[52:55], v[156:159], v[182:185], v[52:55]
	v_mfma_f32_16x16x32_bf16 v[48:51], v[148:151], v[204:207], v[48:51]
	v_mfma_f32_16x16x32_bf16 v[40:43], v[156:159], v[204:207], v[40:43]
	v_mfma_f32_16x16x32_bf16 v[44:47], v[148:151], v[212:215], v[44:47]
	v_mfma_f32_16x16x32_bf16 v[36:39], v[156:159], v[212:215], v[36:39]
	v_mfma_f32_16x16x32_bf16 v[64:67], v[152:155], v[178:181], v[64:67]
	v_mfma_f32_16x16x32_bf16 v[56:59], v[170:173], v[178:181], v[56:59]
	v_mfma_f32_16x16x32_bf16 v[60:63], v[152:155], v[186:189], v[60:63]
	v_mfma_f32_16x16x32_bf16 v[52:55], v[170:173], v[186:189], v[52:55]
	v_mfma_f32_16x16x32_bf16 v[48:51], v[152:155], v[208:211], v[48:51]
	v_mfma_f32_16x16x32_bf16 v[40:43], v[170:173], v[208:211], v[40:43]
	v_mfma_f32_16x16x32_bf16 v[44:47], v[152:155], v[220:223], v[44:47]
	v_mfma_f32_16x16x32_bf16 v[36:39], v[170:173], v[220:223], v[36:39]
	s_setprio 0
	s_barrier
	s_add_i32 s77, s77, s50
	v_lshl_add_u64 v[190:191], s[82:83], 0, v[160:161]
	s_mov_b32 m0, s77
	ds_read_b128 v[174:177], v219 offset:16384
	ds_read_b128 v[178:181], v219 offset:17408
	ds_read_b128 v[182:185], v219 offset:18432
	ds_read_b128 v[186:189], v219 offset:19456
	ds_read_b128 v[204:207], v219 offset:20480
	ds_read_b128 v[208:211], v219 offset:21504
	ds_read_b128 v[212:215], v219 offset:22528
	ds_read_b128 v[220:223], v219 offset:23552
	global_load_lds_dwordx4 v[190:191], off
	s_add_i32 m0, s77, 0x2000
	s_add_u32 s78, s82, s12
	v_lshl_add_u64 v[192:193], s[82:83], 0, v[164:165]
	s_addc_u32 s79, s83, s13
	s_add_i32 s41, s41, s50
	global_load_lds_dwordx4 v[192:193], off
	v_lshl_add_u64 v[196:197], s[78:79], 0, v[160:161]
	s_mov_b32 m0, s41
	v_lshl_add_u64 v[198:199], s[78:79], 0, v[164:165]
	global_load_lds_dwordx4 v[196:197], off
	s_add_i32 m0, s41, 0x2000
	v_lshl_add_u64 v[200:201], s[38:39], 0, v[0:1]
	global_load_lds_dwordx4 v[198:199], off
	s_mov_b32 m0, s51
	v_lshl_add_u64 v[202:203], s[38:39], 0, v[162:163]
	global_load_lds_dwordx4 v[200:201], off
	s_mov_b32 m0, s52
	s_nop 0
	global_load_lds_dwordx4 v[202:203], off
	s_waitcnt vmcnt(8)
	s_waitcnt lgkmcnt(0)
	s_barrier
; #define PG8_STAGE(bufoff, gbase, voff) do { _Pragma("unroll") for (int _i = 0; _i < 2; ++_i) \
;         __builtin_amdgcn_global_load_lds((const unsigned*)((const char*)(gbase) + (voff)[_i]), (PG8_LAS unsigned*)(lds + (bufoff) + ldsw + _i * 8192), 16, 0, 0); } while (0)
; #define PG8_LDA(dst, b, h) do { _Pragma("unroll") for (int m = 0; m < 4; ++m) _Pragma("unroll") for (int k = 0; k < 2; ++k) dst[m][k] = *(const PG8_LAS bf16x8*)(lds + PG8_SA(b, h) + aoff + m * 2048 + k * 1024); } while (0)
; #define PG8_LDB(dst, b, h) do { _Pragma("unroll") for (int n = 0; n < 2; ++n) _Pragma("unroll") for (int k = 0; k < 2; ++k) dst[n][k] = *(const PG8_LAS bf16x8*)(lds + PG8_SB(b, h) + boff + n * 2048 + k * 1024); } while (0)
; #define PG8_MMA(ai, bj, At, Bt) do { __builtin_amdgcn_s_setprio(1); _Pragma("unroll") for (int m = 0; m < 4; ++m) _Pragma("unroll") for (int n = 0; n < 2; ++n) _Pragma("unroll") for (int k = 0; k < 2; ++k) \
;         acc[ai][bj][m][n] = __builtin_amdgcn_mfma_f32_16x16x32_bf16(Bt[n][k], At[m][k], acc[ai][bj][m][n], 0, 0, 0); __builtin_amdgcn_s_setprio(0); } while (0)
; #define PG8_WAIT_V(n) asm volatile("s_waitcnt vmcnt(" #n ")" ::: "memory")
; #define PG8_WAIT_L(n) asm volatile("s_waitcnt lgkmcnt(" #n ")" ::: "memory")
; #define PG8_BAR __builtin_amdgcn_s_barrier()
; #define PG8_SCHED __builtin_amdgcn_sched_barrier(0)
; template <class Epi, class Sched, bool ALIGN_EPI = false, bool SP2 = false>
; __device__ __forceinline__ void gemm_phase(PG8_LAS unsigned char* lds, const Gemm g, const Sched& S, const Epi& E, int tid_in) {
;     ...
;             PG8_WAIT_V(8); PG8_WAIT_L(0); PG8_BAR; PG8_MMA(1, 0, At, B0); PG8_MMA(1, 1, At, B1); PG8_BAR; PG8_SCHED;
;             PG8_LDB(B0, 1, 0); PG8_LDB(B1, 1, 1); PG8_SCHED; PG8_LDA(At, 1, 0); PG8_STAGE(PG8_SA(0, 1), a2 + hsA, voffA);
;             PG8_WAIT_V(8); PG8_WAIT_L(0); PG8_BAR; PG8_MMA(0, 0, At, B0); PG8_MMA(0, 1, At, B1); PG8_BAR; PG8_SCHED;
	s_setprio 1
	v_mfma_f32_16x16x32_bf16 v[96:99], v[116:119], v[174:177], v[96:99]
	v_mfma_f32_16x16x32_bf16 v[92:95], v[140:143], v[174:177], v[92:95]
	v_mfma_f32_16x16x32_bf16 v[88:91], v[116:119], v[182:185], v[88:91]
	v_mfma_f32_16x16x32_bf16 v[84:87], v[140:143], v[182:185], v[84:87]
	v_mfma_f32_16x16x32_bf16 v[80:83], v[116:119], v[204:207], v[80:83]
	v_mfma_f32_16x16x32_bf16 v[76:79], v[140:143], v[204:207], v[76:79]
	v_mfma_f32_16x16x32_bf16 v[72:75], v[116:119], v[212:215], v[72:75]
	v_mfma_f32_16x16x32_bf16 v[68:71], v[140:143], v[212:215], v[68:71]
	v_mfma_f32_16x16x32_bf16 v[96:99], v[120:123], v[178:181], v[96:99]
	v_mfma_f32_16x16x32_bf16 v[92:95], v[144:147], v[178:181], v[92:95]
	v_mfma_f32_16x16x32_bf16 v[88:91], v[120:123], v[186:189], v[88:91]
	v_mfma_f32_16x16x32_bf16 v[84:87], v[144:147], v[186:189], v[84:87]
	v_mfma_f32_16x16x32_bf16 v[80:83], v[120:123], v[208:211], v[80:83]
	v_mfma_f32_16x16x32_bf16 v[76:79], v[144:147], v[208:211], v[76:79]
	v_mfma_f32_16x16x32_bf16 v[72:75], v[120:123], v[220:223], v[72:75]
	v_mfma_f32_16x16x32_bf16 v[68:71], v[144:147], v[220:223], v[68:71]
	s_setprio 0
	s_setprio 1
	v_mfma_f32_16x16x32_bf16 v[32:35], v[148:151], v[174:177], v[32:35]
	v_mfma_f32_16x16x32_bf16 v[28:31], v[156:159], v[174:177], v[28:31]
	v_mfma_f32_16x16x32_bf16 v[24:27], v[148:151], v[182:185], v[24:27]
	v_mfma_f32_16x16x32_bf16 v[12:15], v[156:159], v[182:185], v[12:15]
	v_mfma_f32_16x16x32_bf16 v[20:23], v[148:151], v[204:207], v[20:23]
	v_mfma_f32_16x16x32_bf16 v[8:11], v[156:159], v[204:207], v[8:11]
	v_mfma_f32_16x16x32_bf16 v[16:19], v[148:151], v[212:215], v[16:19]
	v_mfma_f32_16x16x32_bf16 v[4:7], v[156:159], v[212:215], v[4:7]
	v_mfma_f32_16x16x32_bf16 v[32:35], v[152:155], v[178:181], v[32:35]
	v_mfma_f32_16x16x32_bf16 v[28:31], v[170:173], v[178:181], v[28:31]
	v_mfma_f32_16x16x32_bf16 v[24:27], v[152:155], v[186:189], v[24:27]
	v_mfma_f32_16x16x32_bf16 v[12:15], v[170:173], v[186:189], v[12:15]
	v_mfma_f32_16x16x32_bf16 v[20:23], v[152:155], v[208:211], v[20:23]
	v_mfma_f32_16x16x32_bf16 v[8:11], v[170:173], v[208:211], v[8:11]
	v_mfma_f32_16x16x32_bf16 v[16:19], v[152:155], v[220:223], v[16:19]
	v_mfma_f32_16x16x32_bf16 v[4:7], v[170:173], v[220:223], v[4:7]
	s_setprio 0
	s_barrier
	s_add_i32 s41, 0, 0x18000
	s_add_i32 s77, 0, 0x1c000
	v_add_u32_e32 v144, s41, v217
	v_add_u32_e32 v170, s77, v217
	ds_read_b128 v[116:119], v144
	ds_read_b128 v[120:123], v144 offset:1024
	ds_read_b128 v[140:143], v144 offset:2048
	ds_read_b128 v[144:147], v144 offset:3072
	ds_read_b128 v[148:151], v170
	ds_read_b128 v[152:155], v170 offset:1024
	ds_read_b128 v[156:159], v170 offset:2048
	ds_read_b128 v[170:173], v170 offset:3072
	s_add_u32 s38, s38, s10
	s_addc_u32 s39, s39, s11
	s_mov_b32 m0, s53
	v_lshl_add_u64 v[228:229], s[38:39], 0, v[0:1]
	ds_read_b128 v[174:177], v219 offset:32768
	ds_read_b128 v[178:181], v219 offset:33792
	ds_read_b128 v[182:185], v219 offset:34816
	ds_read_b128 v[186:189], v219 offset:35840
	ds_read_b128 v[204:207], v219 offset:36864
	ds_read_b128 v[208:211], v219 offset:37888
	ds_read_b128 v[212:215], v219 offset:38912
	ds_read_b128 v[220:223], v219 offset:39936
	global_load_lds_dwordx4 v[228:229], off
	v_lshl_add_u64 v[228:229], s[38:39], 0, v[162:163]
	s_mov_b32 m0, s54
	s_nop 0
	global_load_lds_dwordx4 v[228:229], off
	s_waitcnt vmcnt(8)
	s_waitcnt lgkmcnt(0)
	s_barrier
	s_setprio 1
	v_mfma_f32_16x16x32_bf16 v[136:139], v[116:119], v[174:177], v[136:139]
	v_mfma_f32_16x16x32_bf16 v[132:135], v[140:143], v[174:177], v[132:135]
	v_mfma_f32_16x16x32_bf16 v[128:131], v[116:119], v[182:185], v[128:131]
	v_mfma_f32_16x16x32_bf16 v[124:127], v[140:143], v[182:185], v[124:127]
	v_mfma_f32_16x16x32_bf16 v[112:115], v[116:119], v[204:207], v[112:115]
	v_mfma_f32_16x16x32_bf16 v[108:111], v[140:143], v[204:207], v[108:111]
	v_mfma_f32_16x16x32_bf16 v[104:107], v[116:119], v[212:215], v[104:107]
	v_mfma_f32_16x16x32_bf16 v[100:103], v[140:143], v[212:215], v[100:103]
	v_mfma_f32_16x16x32_bf16 v[136:139], v[120:123], v[178:181], v[136:139]
	v_mfma_f32_16x16x32_bf16 v[132:135], v[144:147], v[178:181], v[132:135]
	v_mfma_f32_16x16x32_bf16 v[128:131], v[120:123], v[186:189], v[128:131]
	v_mfma_f32_16x16x32_bf16 v[124:127], v[144:147], v[186:189], v[124:127]
	v_mfma_f32_16x16x32_bf16 v[112:115], v[120:123], v[208:211], v[112:115]
	v_mfma_f32_16x16x32_bf16 v[108:111], v[144:147], v[208:211], v[108:111]
	v_mfma_f32_16x16x32_bf16 v[104:107], v[120:123], v[220:223], v[104:107]
	v_mfma_f32_16x16x32_bf16 v[100:103], v[144:147], v[220:223], v[100:103]
	s_setprio 0
	s_setprio 1
	v_mfma_f32_16x16x32_bf16 v[64:67], v[148:151], v[174:177], v[64:67]
	v_mfma_f32_16x16x32_bf16 v[56:59], v[156:159], v[174:177], v[56:59]
	v_mfma_f32_16x16x32_bf16 v[60:63], v[148:151], v[182:185], v[60:63]
	v_mfma_f32_16x16x32_bf16 v[52:55], v[156:159], v[182:185], v[52:55]
	v_mfma_f32_16x16x32_bf16 v[48:51], v[148:151], v[204:207], v[48:51]
	v_mfma_f32_16x16x32_bf16 v[40:43], v[156:159], v[204:207], v[40:43]
	v_mfma_f32_16x16x32_bf16 v[44:47], v[148:151], v[212:215], v[44:47]
	v_mfma_f32_16x16x32_bf16 v[36:39], v[156:159], v[212:215], v[36:39]
	v_mfma_f32_16x16x32_bf16 v[64:67], v[152:155], v[178:181], v[64:67]
	v_mfma_f32_16x16x32_bf16 v[56:59], v[170:173], v[178:181], v[56:59]
	v_mfma_f32_16x16x32_bf16 v[60:63], v[152:155], v[186:189], v[60:63]
	v_mfma_f32_16x16x32_bf16 v[52:55], v[170:173], v[186:189], v[52:55]
	v_mfma_f32_16x16x32_bf16 v[48:51], v[152:155], v[208:211], v[48:51]
	v_mfma_f32_16x16x32_bf16 v[40:43], v[170:173], v[208:211], v[40:43]
	v_mfma_f32_16x16x32_bf16 v[44:47], v[152:155], v[220:223], v[44:47]
	v_mfma_f32_16x16x32_bf16 v[36:39], v[170:173], v[220:223], v[36:39]
	s_setprio 0
	s_barrier
; #define PG8_STAGE(bufoff, gbase, voff) do { _Pragma("unroll") for (int _i = 0; _i < 2; ++_i) \
;         __builtin_amdgcn_global_load_lds((const unsigned*)((const char*)(gbase) + (voff)[_i]), (PG8_LAS unsigned*)(lds + (bufoff) + ldsw + _i * 8192), 16, 0, 0); } while (0)
; #define PG8_LDA(dst, b, h) do { _Pragma("unroll") for (int m = 0; m < 4; ++m) _Pragma("unroll") for (int k = 0; k < 2; ++k) dst[m][k] = *(const PG8_LAS bf16x8*)(lds + PG8_SA(b, h) + aoff + m * 2048 + k * 1024); } while (0)
; #define PG8_MMA(ai, bj, At, Bt) do { __builtin_amdgcn_s_setprio(1); _Pragma("unroll") for (int m = 0; m < 4; ++m) _Pragma("unroll") for (int n = 0; n < 2; ++n) _Pragma("unroll") for (int k = 0; k < 2; ++k) \
;         acc[ai][bj][m][n] = __builtin_amdgcn_mfma_f32_16x16x32_bf16(Bt[n][k], At[m][k], acc[ai][bj][m][n], 0, 0, 0); __builtin_amdgcn_s_setprio(0); } while (0)
; #define PG8_WAIT_V(n) asm volatile("s_waitcnt vmcnt(" #n ")" ::: "memory")
; #define PG8_WAIT_L(n) asm volatile("s_waitcnt lgkmcnt(" #n ")" ::: "memory")
; #define PG8_BAR __builtin_amdgcn_s_barrier()
; #define PG8_SCHED __builtin_amdgcn_sched_barrier(0)
; template <class Epi, class Sched, bool ALIGN_EPI = false, bool SP2 = false>
; __device__ __forceinline__ void gemm_phase(PG8_LAS unsigned char* lds, const Gemm g, const Sched& S, const Epi& E, int tid_in) {
;     ...
;         for (int t = 0; t < nt; t += 2) {
;     ...
;             PG8_LDA(At, 1, 1); PG8_STAGE(PG8_SB(1, 0), b3, voffB); PG8_STAGE(PG8_SB(1, 1), b3 + hsB, voffB); PG8_STAGE(PG8_SA(1, 0), a3, voffA);
;             PG8_WAIT_V(8); PG8_WAIT_L(0); PG8_BAR; PG8_MMA(1, 0, At, B0); PG8_MMA(1, 1, At, B1); PG8_BAR; PG8_SCHED;
	s_add_i32 s38, s41, s50
	v_lshl_add_u64 v[190:191], v[190:191], 0, s[80:81]
	s_mov_b32 m0, s38
	ds_read_b128 v[174:177], v219 offset:49152
	ds_read_b128 v[178:181], v219 offset:50176
	ds_read_b128 v[182:185], v219 offset:51200
	ds_read_b128 v[186:189], v219 offset:52224
	ds_read_b128 v[204:207], v219 offset:53248
	ds_read_b128 v[208:211], v219 offset:54272
	ds_read_b128 v[212:215], v219 offset:55296
	ds_read_b128 v[220:223], v219 offset:56320
	global_load_lds_dwordx4 v[190:191], off
	v_lshl_add_u64 v[190:191], v[192:193], 0, s[80:81]
	s_add_i32 m0, s38, 0x2000
	s_add_i32 s38, s77, s50
	global_load_lds_dwordx4 v[190:191], off
	v_lshl_add_u64 v[190:191], v[196:197], 0, s[80:81]
	s_mov_b32 m0, s38
	s_nop 0
	global_load_lds_dwordx4 v[190:191], off
	v_lshl_add_u64 v[190:191], v[198:199], 0, s[80:81]
	s_add_i32 m0, s38, 0x2000
	s_nop 0
	global_load_lds_dwordx4 v[190:191], off
	v_lshl_add_u64 v[190:191], v[200:201], 0, s[80:81]
	s_mov_b32 m0, s59
	s_nop 0
	global_load_lds_dwordx4 v[190:191], off
	v_lshl_add_u64 v[190:191], v[202:203], 0, s[80:81]
	s_mov_b32 m0, s60
	s_nop 0
	global_load_lds_dwordx4 v[190:191], off
	s_waitcnt vmcnt(8)
	s_waitcnt lgkmcnt(0)
	s_barrier
	s_setprio 1
	v_mfma_f32_16x16x32_bf16 v[96:99], v[116:119], v[174:177], v[96:99]
	v_mfma_f32_16x16x32_bf16 v[92:95], v[140:143], v[174:177], v[92:95]
	v_mfma_f32_16x16x32_bf16 v[88:91], v[116:119], v[182:185], v[88:91]
	v_mfma_f32_16x16x32_bf16 v[84:87], v[140:143], v[182:185], v[84:87]
	v_mfma_f32_16x16x32_bf16 v[80:83], v[116:119], v[204:207], v[80:83]
	v_mfma_f32_16x16x32_bf16 v[76:79], v[140:143], v[204:207], v[76:79]
	v_mfma_f32_16x16x32_bf16 v[72:75], v[116:119], v[212:215], v[72:75]
	v_mfma_f32_16x16x32_bf16 v[68:71], v[140:143], v[212:215], v[68:71]
	v_mfma_f32_16x16x32_bf16 v[96:99], v[120:123], v[178:181], v[96:99]
	v_mfma_f32_16x16x32_bf16 v[92:95], v[144:147], v[178:181], v[92:95]
	v_mfma_f32_16x16x32_bf16 v[88:91], v[120:123], v[186:189], v[88:91]
	v_mfma_f32_16x16x32_bf16 v[84:87], v[144:147], v[186:189], v[84:87]
	v_mfma_f32_16x16x32_bf16 v[80:83], v[120:123], v[208:211], v[80:83]
	v_mfma_f32_16x16x32_bf16 v[76:79], v[144:147], v[208:211], v[76:79]
	v_mfma_f32_16x16x32_bf16 v[72:75], v[120:123], v[220:223], v[72:75]
	v_mfma_f32_16x16x32_bf16 v[68:71], v[144:147], v[220:223], v[68:71]
	s_setprio 0
	s_setprio 1
	v_mfma_f32_16x16x32_bf16 v[32:35], v[148:151], v[174:177], v[32:35]
	v_mfma_f32_16x16x32_bf16 v[28:31], v[156:159], v[174:177], v[28:31]
	v_mfma_f32_16x16x32_bf16 v[24:27], v[148:151], v[182:185], v[24:27]
	v_mfma_f32_16x16x32_bf16 v[12:15], v[156:159], v[182:185], v[12:15]
	v_mfma_f32_16x16x32_bf16 v[20:23], v[148:151], v[204:207], v[20:23]
	v_mfma_f32_16x16x32_bf16 v[8:11], v[156:159], v[204:207], v[8:11]
	v_mfma_f32_16x16x32_bf16 v[16:19], v[148:151], v[212:215], v[16:19]
	v_mfma_f32_16x16x32_bf16 v[4:7], v[156:159], v[212:215], v[4:7]
	v_mfma_f32_16x16x32_bf16 v[32:35], v[152:155], v[178:181], v[32:35]
	v_mfma_f32_16x16x32_bf16 v[28:31], v[170:173], v[178:181], v[28:31]
	v_mfma_f32_16x16x32_bf16 v[24:27], v[152:155], v[186:189], v[24:27]
	v_mfma_f32_16x16x32_bf16 v[12:15], v[170:173], v[186:189], v[12:15]
	v_mfma_f32_16x16x32_bf16 v[20:23], v[152:155], v[208:211], v[20:23]
	v_mfma_f32_16x16x32_bf16 v[8:11], v[170:173], v[208:211], v[8:11]
	v_mfma_f32_16x16x32_bf16 v[16:19], v[152:155], v[220:223], v[16:19]
	v_mfma_f32_16x16x32_bf16 v[4:7], v[170:173], v[220:223], v[4:7]
	s_setprio 0
	s_barrier
	s_add_i32 s38, s40, 2
	s_add_u32 s75, s75, 0x100
	s_addc_u32 s76, s76, 0
	s_add_u32 s4, s4, 0x100
	s_addc_u32 s5, s5, 0
	s_cmp_ge_i32 s40, s61
	s_mov_b32 s40, s38
	s_cbranch_scc0 .LBB0_1070
	s_movk_i32 s83, 0x3000

; #define PG8_STAGE(bufoff, gbase, voff) do { _Pragma("unroll") for (int _i = 0; _i < 2; ++_i) \
;         __builtin_amdgcn_global_load_lds((const unsigned*)((const char*)(gbase) + (voff)[_i]), (PG8_LAS unsigned*)(lds + (bufoff) + ldsw + _i * 8192), 16, 0, 0); } while (0)
; #define PG8_LDA(dst, b, h) do { _Pragma("unroll") for (int m = 0; m < 4; ++m) _Pragma("unroll") for (int k = 0; k < 2; ++k) dst[m][k] = *(const PG8_LAS bf16x8*)(lds + PG8_SA(b, h) + aoff + m * 2048 + k * 1024); } while (0)
; #define PG8_LDB(dst, b, h) do { _Pragma("unroll") for (int n = 0; n < 2; ++n) _Pragma("unroll") for (int k = 0; k < 2; ++k) dst[n][k] = *(const PG8_LAS bf16x8*)(lds + PG8_SB(b, h) + boff + n * 2048 + k * 1024); } while (0)
; #define PG8_WAIT_V(n) asm volatile("s_waitcnt vmcnt(" #n ")" ::: "memory")
; #define PG8_WAIT_L(n) asm volatile("s_waitcnt lgkmcnt(" #n ")" ::: "memory")
; #define PG8_BAR __builtin_amdgcn_s_barrier()
; #define PG8_SCHED __builtin_amdgcn_sched_barrier(0)
; template <class Epi, class Sched, bool ALIGN_EPI = false, bool SP2 = false>
; __device__ __forceinline__ void gemm_phase(PG8_LAS unsigned char* lds, const Gemm g, const Sched& S, const Epi& E, int tid_in) {
;     ...
;         for (int t = 0; t < nt; t += 2) {
;             const bool last = (t == nt - 2);
;             if constexpr (mid_hook<Epi>::value) { if (t == Epi::H1 || t == Epi::H2) E.mid(acc, cur, wr, wc, fr, fq, t == Epi::H2); }
;             const char* a1 = cA + (size_t)(t + 1) * kstep + (t >= jt ? jb : 0);
;             const char* a2 = last ? nA : cA + (size_t)(t + 2) * kstep + (t + 2 >= jt ? jb : 0); const char* b2 = last ? nB : cB + (size_t)(t + 2) * kstep;
;             const char* a3 = a2 + kstep; const char* b3 = b2 + kstep;
;             if (last && has_next) S.a_ready(nxt);
;             if constexpr (SP2) {
;             PG8_LDB(B0, 0, 0); PG8_LDB(B1, 0, 1); PG8_SCHED; PG8_LDA(At, 0, 0); PG8_STAGE(PG8_SA(1, 1), a1 + hsA, voffA);
;             PG8_WAIT_V(8); PG8_WAIT_L(0); PG8_BAR; PG8_MMA(0, 0, At, B0); PG8_MMA(0, 1, At, B1); PG8_BAR; PG8_SCHED;
;             PG8_LDA(At, 0, 1); PG8_STAGE(PG8_SB(0, 0), b2, voffB); PG8_STAGE(PG8_SB(0, 1), b2 + hsB, voffB); PG8_STAGE(PG8_SA(0, 0), a2, voffA);
;             PG8_WAIT_V(8); PG8_WAIT_L(0); PG8_BAR; PG8_MMA(1, 0, At, B0); PG8_MMA(1, 1, At, B1); PG8_BAR; PG8_SCHED;
.LBB0_1102:
	s_add_i32 s26, s55, -2
	s_cmp_ge_i32 s26, s28
	s_cselect_b32 s58, s29, 0
	s_cselect_b32 s59, s49, 0
	s_cmp_ge_i32 s55, s28
	s_cselect_b32 s27, s29, 0
	s_cselect_b32 s26, s49, 0
	s_add_u32 s27, s24, s27
	s_addc_u32 s26, s25, s26
	s_add_u32 s60, s27, 0x80
	s_addc_u32 s26, s26, 0
	s_add_i32 s62, 0, 0x10000
	s_cmp_eq_u32 s48, s55
	s_cselect_b32 s27, s5, s26
	s_cselect_b32 s26, s4, s60
	s_cselect_b32 s61, s23, s21
	s_cselect_b32 s60, s22, s17
	s_add_i32 s63, 0, 0x14000
	v_add_u32_e32 v160, s62, v3
	v_add_u32_e32 v176, s63, v3
	ds_read_b128 v[148:151], v160
	ds_read_b128 v[152:155], v160 offset:1024
	ds_read_b128 v[156:159], v160 offset:2048
	ds_read_b128 v[160:163], v160 offset:3072
	ds_read_b128 v[164:167], v176
	ds_read_b128 v[168:171], v176 offset:1024
	ds_read_b128 v[172:175], v176 offset:2048
	ds_read_b128 v[176:179], v176 offset:3072
	v_lshl_add_u64 v[192:193], s[24:25], 0, v[140:141]
	v_lshl_add_u64 v[192:193], v[192:193], 0, s[58:59]
	s_add_i32 m0, s35, 0xc000
	ds_read_b128 v[180:183], v147
	ds_read_b128 v[184:187], v147 offset:1024
	ds_read_b128 v[188:191], v147 offset:2048
	ds_read_b128 v[204:207], v147 offset:3072
	ds_read_b128 v[208:211], v147 offset:4096
	ds_read_b128 v[212:215], v147 offset:5120
	ds_read_b128 v[216:219], v147 offset:6144
	ds_read_b128 v[220:223], v147 offset:7168
	global_load_lds_dwordx4 v[192:193], off
	v_lshl_add_u64 v[192:193], s[24:25], 0, v[138:139]
	v_lshl_add_u64 v[192:193], v[192:193], 0, s[58:59]
	s_add_i32 m0, s35, 0xe000
	s_nop 0
	global_load_lds_dwordx4 v[192:193], off
	s_waitcnt vmcnt(8)
	s_waitcnt lgkmcnt(0)
	s_barrier
	s_setprio 1
	v_mfma_f32_16x16x32_bf16 v[124:127], v[148:151], v[180:183], v[124:127]
	v_mfma_f32_16x16x32_bf16 v[128:131], v[156:159], v[180:183], v[128:131]
	v_mfma_f32_16x16x32_bf16 v[112:115], v[148:151], v[188:191], v[112:115]
	v_mfma_f32_16x16x32_bf16 v[108:111], v[156:159], v[188:191], v[108:111]
	v_mfma_f32_16x16x32_bf16 v[96:99], v[148:151], v[208:211], v[96:99]
	v_mfma_f32_16x16x32_bf16 v[92:95], v[156:159], v[208:211], v[92:95]
	v_mfma_f32_16x16x32_bf16 v[80:83], v[148:151], v[216:219], v[80:83]
	v_mfma_f32_16x16x32_bf16 v[76:79], v[156:159], v[216:219], v[76:79]
	v_mfma_f32_16x16x32_bf16 v[124:127], v[152:155], v[184:187], v[124:127]
	v_mfma_f32_16x16x32_bf16 v[128:131], v[160:163], v[184:187], v[128:131]
	v_mfma_f32_16x16x32_bf16 v[112:115], v[152:155], v[204:207], v[112:115]
	v_mfma_f32_16x16x32_bf16 v[108:111], v[160:163], v[204:207], v[108:111]
	v_mfma_f32_16x16x32_bf16 v[96:99], v[152:155], v[212:215], v[96:99]
	v_mfma_f32_16x16x32_bf16 v[92:95], v[160:163], v[212:215], v[92:95]
	v_mfma_f32_16x16x32_bf16 v[80:83], v[152:155], v[220:223], v[80:83]
	v_mfma_f32_16x16x32_bf16 v[76:79], v[160:163], v[220:223], v[76:79]
	s_setprio 0
	s_setprio 1
	v_mfma_f32_16x16x32_bf16 v[120:123], v[164:167], v[180:183], v[120:123]
	v_mfma_f32_16x16x32_bf16 v[116:119], v[172:175], v[180:183], v[116:119]
	v_mfma_f32_16x16x32_bf16 v[104:107], v[164:167], v[188:191], v[104:107]
	v_mfma_f32_16x16x32_bf16 v[100:103], v[172:175], v[188:191], v[100:103]
	v_mfma_f32_16x16x32_bf16 v[88:91], v[164:167], v[208:211], v[88:91]
	v_mfma_f32_16x16x32_bf16 v[84:87], v[172:175], v[208:211], v[84:87]
	v_mfma_f32_16x16x32_bf16 v[72:75], v[164:167], v[216:219], v[72:75]
	v_mfma_f32_16x16x32_bf16 v[68:71], v[172:175], v[216:219], v[68:71]
	v_mfma_f32_16x16x32_bf16 v[120:123], v[168:171], v[184:187], v[120:123]
	v_mfma_f32_16x16x32_bf16 v[116:119], v[176:179], v[184:187], v[116:119]
	v_mfma_f32_16x16x32_bf16 v[104:107], v[168:171], v[204:207], v[104:107]
	v_mfma_f32_16x16x32_bf16 v[100:103], v[176:179], v[204:207], v[100:103]
	v_mfma_f32_16x16x32_bf16 v[88:91], v[168:171], v[212:215], v[88:91]
	v_mfma_f32_16x16x32_bf16 v[84:87], v[176:179], v[212:215], v[84:87]
	v_mfma_f32_16x16x32_bf16 v[72:75], v[168:171], v[220:223], v[72:75]
	v_mfma_f32_16x16x32_bf16 v[68:71], v[176:179], v[220:223], v[68:71]
	s_setprio 0
	s_barrier
	s_add_i32 s58, s62, s33
	v_lshl_add_u64 v[192:193], s[60:61], 0, v[134:135]
	s_mov_b32 m0, s58
	ds_read_b128 v[180:183], v147 offset:16384
	ds_read_b128 v[184:187], v147 offset:17408
	ds_read_b128 v[188:191], v147 offset:18432
	ds_read_b128 v[204:207], v147 offset:19456
	ds_read_b128 v[208:211], v147 offset:20480
	ds_read_b128 v[212:215], v147 offset:21504
	ds_read_b128 v[216:219], v147 offset:22528
	ds_read_b128 v[220:223], v147 offset:23552
	global_load_lds_dwordx4 v[192:193], off
	s_add_i32 m0, s58, 0x2000
	s_add_u32 s58, s60, s8
	v_lshl_add_u64 v[196:197], s[60:61], 0, v[0:1]
	s_addc_u32 s59, s61, s9
	s_add_i32 s60, s63, s33
	global_load_lds_dwordx4 v[196:197], off
	v_lshl_add_u64 v[198:199], s[58:59], 0, v[134:135]
	s_mov_b32 m0, s60
	v_lshl_add_u64 v[200:201], s[58:59], 0, v[0:1]
	global_load_lds_dwordx4 v[198:199], off
	s_add_i32 m0, s60, 0x2000
	v_lshl_add_u64 v[202:203], s[26:27], 0, v[136:137]
	global_load_lds_dwordx4 v[200:201], off
	s_mov_b32 m0, s35
	v_lshl_add_u64 v[228:229], s[26:27], 0, v[132:133]
	global_load_lds_dwordx4 v[202:203], off
	s_mov_b32 m0, s36
	s_nop 0
	global_load_lds_dwordx4 v[228:229], off
	s_waitcnt vmcnt(8)
	s_waitcnt lgkmcnt(0)
	s_barrier
; #define PG8_STAGE(bufoff, gbase, voff) do { _Pragma("unroll") for (int _i = 0; _i < 2; ++_i) \
;         __builtin_amdgcn_global_load_lds((const unsigned*)((const char*)(gbase) + (voff)[_i]), (PG8_LAS unsigned*)(lds + (bufoff) + ldsw + _i * 8192), 16, 0, 0); } while (0)
; #define PG8_LDA(dst, b, h) do { _Pragma("unroll") for (int m = 0; m < 4; ++m) _Pragma("unroll") for (int k = 0; k < 2; ++k) dst[m][k] = *(const PG8_LAS bf16x8*)(lds + PG8_SA(b, h) + aoff + m * 2048 + k * 1024); } while (0)
; #define PG8_LDB(dst, b, h) do { _Pragma("unroll") for (int n = 0; n < 2; ++n) _Pragma("unroll") for (int k = 0; k < 2; ++k) dst[n][k] = *(const PG8_LAS bf16x8*)(lds + PG8_SB(b, h) + boff + n * 2048 + k * 1024); } while (0)
; #define PG8_MMA(ai, bj, At, Bt) do { __builtin_amdgcn_s_setprio(1); _Pragma("unroll") for (int m = 0; m < 4; ++m) _Pragma("unroll") for (int n = 0; n < 2; ++n) _Pragma("unroll") for (int k = 0; k < 2; ++k) \
;         acc[ai][bj][m][n] = __builtin_amdgcn_mfma_f32_16x16x32_bf16(Bt[n][k], At[m][k], acc[ai][bj][m][n], 0, 0, 0); __builtin_amdgcn_s_setprio(0); } while (0)
; #define PG8_WAIT_V(n) asm volatile("s_waitcnt vmcnt(" #n ")" ::: "memory")
; #define PG8_WAIT_L(n) asm volatile("s_waitcnt lgkmcnt(" #n ")" ::: "memory")
; #define PG8_BAR __builtin_amdgcn_s_barrier()
; #define PG8_SCHED __builtin_amdgcn_sched_barrier(0)
; template <class Epi, class Sched, bool ALIGN_EPI = false, bool SP2 = false>
; __device__ __forceinline__ void gemm_phase(PG8_LAS unsigned char* lds, const Gemm g, const Sched& S, const Epi& E, int tid_in) {
;     ...
;             PG8_WAIT_V(8); PG8_WAIT_L(0); PG8_BAR; PG8_MMA(1, 0, At, B0); PG8_MMA(1, 1, At, B1); PG8_BAR; PG8_SCHED;
;             PG8_LDB(B0, 1, 0); PG8_LDB(B1, 1, 1); PG8_SCHED; PG8_LDA(At, 1, 0); PG8_STAGE(PG8_SA(0, 1), a2 + hsA, voffA);
;             PG8_WAIT_V(8); PG8_WAIT_L(0); PG8_BAR; PG8_MMA(0, 0, At, B0); PG8_MMA(0, 1, At, B1); PG8_BAR; PG8_SCHED;
	s_setprio 1
	v_mfma_f32_16x16x32_bf16 v[64:67], v[148:151], v[180:183], v[64:67]
	v_mfma_f32_16x16x32_bf16 v[60:63], v[156:159], v[180:183], v[60:63]
	v_mfma_f32_16x16x32_bf16 v[48:51], v[148:151], v[188:191], v[48:51]
	v_mfma_f32_16x16x32_bf16 v[44:47], v[156:159], v[188:191], v[44:47]
	v_mfma_f32_16x16x32_bf16 v[32:35], v[148:151], v[208:211], v[32:35]
	v_mfma_f32_16x16x32_bf16 v[28:31], v[156:159], v[208:211], v[28:31]
	v_mfma_f32_16x16x32_bf16 v[16:19], v[148:151], v[216:219], v[16:19]
	v_mfma_f32_16x16x32_bf16 v[12:15], v[156:159], v[216:219], v[12:15]
	v_mfma_f32_16x16x32_bf16 v[64:67], v[152:155], v[184:187], v[64:67]
	v_mfma_f32_16x16x32_bf16 v[60:63], v[160:163], v[184:187], v[60:63]
	v_mfma_f32_16x16x32_bf16 v[48:51], v[152:155], v[204:207], v[48:51]
	v_mfma_f32_16x16x32_bf16 v[44:47], v[160:163], v[204:207], v[44:47]
	v_mfma_f32_16x16x32_bf16 v[32:35], v[152:155], v[212:215], v[32:35]
	v_mfma_f32_16x16x32_bf16 v[28:31], v[160:163], v[212:215], v[28:31]
	v_mfma_f32_16x16x32_bf16 v[16:19], v[152:155], v[220:223], v[16:19]
	v_mfma_f32_16x16x32_bf16 v[12:15], v[160:163], v[220:223], v[12:15]
	s_setprio 0
	s_setprio 1
	v_mfma_f32_16x16x32_bf16 v[56:59], v[164:167], v[180:183], v[56:59]
	v_mfma_f32_16x16x32_bf16 v[52:55], v[172:175], v[180:183], v[52:55]
	v_mfma_f32_16x16x32_bf16 v[40:43], v[164:167], v[188:191], v[40:43]
	v_mfma_f32_16x16x32_bf16 v[36:39], v[172:175], v[188:191], v[36:39]
	v_mfma_f32_16x16x32_bf16 v[24:27], v[164:167], v[208:211], v[24:27]
	v_mfma_f32_16x16x32_bf16 v[20:23], v[172:175], v[208:211], v[20:23]
	v_mfma_f32_16x16x32_bf16 v[8:11], v[164:167], v[216:219], v[8:11]
	v_mfma_f32_16x16x32_bf16 v[4:7], v[172:175], v[216:219], v[4:7]
	v_mfma_f32_16x16x32_bf16 v[56:59], v[168:171], v[184:187], v[56:59]
	v_mfma_f32_16x16x32_bf16 v[52:55], v[176:179], v[184:187], v[52:55]
	v_mfma_f32_16x16x32_bf16 v[40:43], v[168:171], v[204:207], v[40:43]
	v_mfma_f32_16x16x32_bf16 v[36:39], v[176:179], v[204:207], v[36:39]
	v_mfma_f32_16x16x32_bf16 v[24:27], v[168:171], v[212:215], v[24:27]
	v_mfma_f32_16x16x32_bf16 v[20:23], v[176:179], v[212:215], v[20:23]
	v_mfma_f32_16x16x32_bf16 v[8:11], v[168:171], v[220:223], v[8:11]
	v_mfma_f32_16x16x32_bf16 v[4:7], v[176:179], v[220:223], v[4:7]
	s_setprio 0
	s_barrier
	s_add_i32 s58, 0, 0x18000
	s_add_i32 s59, 0, 0x1c000
	v_add_u32_e32 v160, s58, v3
	v_add_u32_e32 v176, s59, v3
	ds_read_b128 v[148:151], v160
	ds_read_b128 v[152:155], v160 offset:1024
	ds_read_b128 v[156:159], v160 offset:2048
	ds_read_b128 v[160:163], v160 offset:3072
	ds_read_b128 v[164:167], v176
	ds_read_b128 v[168:171], v176 offset:1024
	ds_read_b128 v[172:175], v176 offset:2048
	ds_read_b128 v[176:179], v176 offset:3072
	s_add_u32 s26, s26, s6
	s_addc_u32 s27, s27, s7
	s_mov_b32 m0, s37
	v_lshl_add_u64 v[230:231], s[26:27], 0, v[136:137]
	ds_read_b128 v[180:183], v147 offset:32768
	ds_read_b128 v[184:187], v147 offset:33792
	ds_read_b128 v[188:191], v147 offset:34816
	ds_read_b128 v[204:207], v147 offset:35840
	ds_read_b128 v[208:211], v147 offset:36864
	ds_read_b128 v[212:215], v147 offset:37888
	ds_read_b128 v[216:219], v147 offset:38912
	ds_read_b128 v[220:223], v147 offset:39936
	global_load_lds_dwordx4 v[230:231], off
	v_lshl_add_u64 v[230:231], s[26:27], 0, v[132:133]
	s_mov_b32 m0, s38
	s_nop 0
	global_load_lds_dwordx4 v[230:231], off
	s_waitcnt vmcnt(8)
	s_waitcnt lgkmcnt(0)
	s_barrier
	s_setprio 1
	v_mfma_f32_16x16x32_bf16 v[124:127], v[148:151], v[180:183], v[124:127]
	v_mfma_f32_16x16x32_bf16 v[128:131], v[156:159], v[180:183], v[128:131]
	v_mfma_f32_16x16x32_bf16 v[112:115], v[148:151], v[188:191], v[112:115]
	v_mfma_f32_16x16x32_bf16 v[108:111], v[156:159], v[188:191], v[108:111]
	v_mfma_f32_16x16x32_bf16 v[96:99], v[148:151], v[208:211], v[96:99]
	v_mfma_f32_16x16x32_bf16 v[92:95], v[156:159], v[208:211], v[92:95]
	v_mfma_f32_16x16x32_bf16 v[80:83], v[148:151], v[216:219], v[80:83]
	v_mfma_f32_16x16x32_bf16 v[76:79], v[156:159], v[216:219], v[76:79]
	v_mfma_f32_16x16x32_bf16 v[124:127], v[152:155], v[184:187], v[124:127]
	v_mfma_f32_16x16x32_bf16 v[128:131], v[160:163], v[184:187], v[128:131]
	v_mfma_f32_16x16x32_bf16 v[112:115], v[152:155], v[204:207], v[112:115]
	v_mfma_f32_16x16x32_bf16 v[108:111], v[160:163], v[204:207], v[108:111]
	v_mfma_f32_16x16x32_bf16 v[96:99], v[152:155], v[212:215], v[96:99]
	v_mfma_f32_16x16x32_bf16 v[92:95], v[160:163], v[212:215], v[92:95]
	v_mfma_f32_16x16x32_bf16 v[80:83], v[152:155], v[220:223], v[80:83]
	v_mfma_f32_16x16x32_bf16 v[76:79], v[160:163], v[220:223], v[76:79]
	s_setprio 0
	s_setprio 1
	v_mfma_f32_16x16x32_bf16 v[120:123], v[164:167], v[180:183], v[120:123]
	v_mfma_f32_16x16x32_bf16 v[116:119], v[172:175], v[180:183], v[116:119]
	v_mfma_f32_16x16x32_bf16 v[104:107], v[164:167], v[188:191], v[104:107]
	v_mfma_f32_16x16x32_bf16 v[100:103], v[172:175], v[188:191], v[100:103]
	v_mfma_f32_16x16x32_bf16 v[88:91], v[164:167], v[208:211], v[88:91]
	v_mfma_f32_16x16x32_bf16 v[84:87], v[172:175], v[208:211], v[84:87]
	v_mfma_f32_16x16x32_bf16 v[72:75], v[164:167], v[216:219], v[72:75]
	v_mfma_f32_16x16x32_bf16 v[68:71], v[172:175], v[216:219], v[68:71]
	v_mfma_f32_16x16x32_bf16 v[120:123], v[168:171], v[184:187], v[120:123]
	v_mfma_f32_16x16x32_bf16 v[116:119], v[176:179], v[184:187], v[116:119]
	v_mfma_f32_16x16x32_bf16 v[104:107], v[168:171], v[204:207], v[104:107]
	v_mfma_f32_16x16x32_bf16 v[100:103], v[176:179], v[204:207], v[100:103]
	v_mfma_f32_16x16x32_bf16 v[88:91], v[168:171], v[212:215], v[88:91]
	v_mfma_f32_16x16x32_bf16 v[84:87], v[176:179], v[212:215], v[84:87]
	v_mfma_f32_16x16x32_bf16 v[72:75], v[168:171], v[220:223], v[72:75]
	v_mfma_f32_16x16x32_bf16 v[68:71], v[176:179], v[220:223], v[68:71]
	s_setprio 0
	s_barrier
; #define PG8_STAGE(bufoff, gbase, voff) do { _Pragma("unroll") for (int _i = 0; _i < 2; ++_i) \
;         __builtin_amdgcn_global_load_lds((const unsigned*)((const char*)(gbase) + (voff)[_i]), (PG8_LAS unsigned*)(lds + (bufoff) + ldsw + _i * 8192), 16, 0, 0); } while (0)
; #define PG8_LDA(dst, b, h) do { _Pragma("unroll") for (int m = 0; m < 4; ++m) _Pragma("unroll") for (int k = 0; k < 2; ++k) dst[m][k] = *(const PG8_LAS bf16x8*)(lds + PG8_SA(b, h) + aoff + m * 2048 + k * 1024); } while (0)
; #define PG8_MMA(ai, bj, At, Bt) do { __builtin_amdgcn_s_setprio(1); _Pragma("unroll") for (int m = 0; m < 4; ++m) _Pragma("unroll") for (int n = 0; n < 2; ++n) _Pragma("unroll") for (int k = 0; k < 2; ++k) \
;         acc[ai][bj][m][n] = __builtin_amdgcn_mfma_f32_16x16x32_bf16(Bt[n][k], At[m][k], acc[ai][bj][m][n], 0, 0, 0); __builtin_amdgcn_s_setprio(0); } while (0)
; #define PG8_WAIT_V(n) asm volatile("s_waitcnt vmcnt(" #n ")" ::: "memory")
; #define PG8_WAIT_L(n) asm volatile("s_waitcnt lgkmcnt(" #n ")" ::: "memory")
; #define PG8_BAR __builtin_amdgcn_s_barrier()
; #define PG8_SCHED __builtin_amdgcn_sched_barrier(0)
; template <class Epi, class Sched, bool ALIGN_EPI = false, bool SP2 = false>
; __device__ __forceinline__ void gemm_phase(PG8_LAS unsigned char* lds, const Gemm g, const Sched& S, const Epi& E, int tid_in) {
;     ...
;         for (int t = 0; t < nt; t += 2) {
;     ...
;             PG8_LDA(At, 1, 1); PG8_STAGE(PG8_SB(1, 0), b3, voffB); PG8_STAGE(PG8_SB(1, 1), b3 + hsB, voffB); PG8_STAGE(PG8_SA(1, 0), a3, voffA);
;             PG8_WAIT_V(8); PG8_WAIT_L(0); PG8_BAR; PG8_MMA(1, 0, At, B0); PG8_MMA(1, 1, At, B1); PG8_BAR; PG8_SCHED;
	s_add_i32 s26, s58, s33
	v_lshl_add_u64 v[192:193], v[192:193], 0, s[80:81]
	s_mov_b32 m0, s26
	ds_read_b128 v[180:183], v147 offset:49152
	ds_read_b128 v[184:187], v147 offset:50176
	ds_read_b128 v[188:191], v147 offset:51200
	ds_read_b128 v[204:207], v147 offset:52224
	ds_read_b128 v[208:211], v147 offset:53248
	ds_read_b128 v[212:215], v147 offset:54272
	ds_read_b128 v[216:219], v147 offset:55296
	ds_read_b128 v[220:223], v147 offset:56320
	global_load_lds_dwordx4 v[192:193], off
	v_lshl_add_u64 v[192:193], v[196:197], 0, s[80:81]
	s_add_i32 m0, s26, 0x2000
	s_add_i32 s26, s59, s33
	global_load_lds_dwordx4 v[192:193], off
	v_lshl_add_u64 v[192:193], v[198:199], 0, s[80:81]
	s_mov_b32 m0, s26
	s_nop 0
	global_load_lds_dwordx4 v[192:193], off
	v_lshl_add_u64 v[192:193], v[200:201], 0, s[80:81]
	s_add_i32 m0, s26, 0x2000
	s_nop 0
	global_load_lds_dwordx4 v[192:193], off
	v_lshl_add_u64 v[192:193], v[202:203], 0, s[80:81]
	s_mov_b32 m0, s41
	s_nop 0
	global_load_lds_dwordx4 v[192:193], off
	v_lshl_add_u64 v[192:193], v[228:229], 0, s[80:81]
	s_mov_b32 m0, s46
	s_nop 0
	global_load_lds_dwordx4 v[192:193], off
	s_waitcnt vmcnt(8)
	s_waitcnt lgkmcnt(0)
	s_barrier
	s_setprio 1
	v_mfma_f32_16x16x32_bf16 v[64:67], v[148:151], v[180:183], v[64:67]
	v_mfma_f32_16x16x32_bf16 v[60:63], v[156:159], v[180:183], v[60:63]
	v_mfma_f32_16x16x32_bf16 v[48:51], v[148:151], v[188:191], v[48:51]
	v_mfma_f32_16x16x32_bf16 v[44:47], v[156:159], v[188:191], v[44:47]
	v_mfma_f32_16x16x32_bf16 v[32:35], v[148:151], v[208:211], v[32:35]
	v_mfma_f32_16x16x32_bf16 v[28:31], v[156:159], v[208:211], v[28:31]
	v_mfma_f32_16x16x32_bf16 v[16:19], v[148:151], v[216:219], v[16:19]
	v_mfma_f32_16x16x32_bf16 v[12:15], v[156:159], v[216:219], v[12:15]
	v_mfma_f32_16x16x32_bf16 v[64:67], v[152:155], v[184:187], v[64:67]
	v_mfma_f32_16x16x32_bf16 v[60:63], v[160:163], v[184:187], v[60:63]
	v_mfma_f32_16x16x32_bf16 v[48:51], v[152:155], v[204:207], v[48:51]
	v_mfma_f32_16x16x32_bf16 v[44:47], v[160:163], v[204:207], v[44:47]
	v_mfma_f32_16x16x32_bf16 v[32:35], v[152:155], v[212:215], v[32:35]
	v_mfma_f32_16x16x32_bf16 v[28:31], v[160:163], v[212:215], v[28:31]
	v_mfma_f32_16x16x32_bf16 v[16:19], v[152:155], v[220:223], v[16:19]
	v_mfma_f32_16x16x32_bf16 v[12:15], v[160:163], v[220:223], v[12:15]
	s_setprio 0
	s_setprio 1
	v_mfma_f32_16x16x32_bf16 v[56:59], v[164:167], v[180:183], v[56:59]
	v_mfma_f32_16x16x32_bf16 v[52:55], v[172:175], v[180:183], v[52:55]
	v_mfma_f32_16x16x32_bf16 v[40:43], v[164:167], v[188:191], v[40:43]
	v_mfma_f32_16x16x32_bf16 v[36:39], v[172:175], v[188:191], v[36:39]
	v_mfma_f32_16x16x32_bf16 v[24:27], v[164:167], v[208:211], v[24:27]
	v_mfma_f32_16x16x32_bf16 v[20:23], v[172:175], v[208:211], v[20:23]
	v_mfma_f32_16x16x32_bf16 v[8:11], v[164:167], v[216:219], v[8:11]
	v_mfma_f32_16x16x32_bf16 v[4:7], v[172:175], v[216:219], v[4:7]
	v_mfma_f32_16x16x32_bf16 v[56:59], v[168:171], v[184:187], v[56:59]
	v_mfma_f32_16x16x32_bf16 v[52:55], v[176:179], v[184:187], v[52:55]
	v_mfma_f32_16x16x32_bf16 v[40:43], v[168:171], v[204:207], v[40:43]
	v_mfma_f32_16x16x32_bf16 v[36:39], v[176:179], v[204:207], v[36:39]
	v_mfma_f32_16x16x32_bf16 v[24:27], v[168:171], v[212:215], v[24:27]
	v_mfma_f32_16x16x32_bf16 v[20:23], v[176:179], v[212:215], v[20:23]
	v_mfma_f32_16x16x32_bf16 v[8:11], v[168:171], v[220:223], v[8:11]
	v_mfma_f32_16x16x32_bf16 v[4:7], v[176:179], v[220:223], v[4:7]
	s_setprio 0
	s_barrier
	s_add_i32 s26, s55, 2
	s_add_u32 s17, s17, 0x100
	s_addc_u32 s21, s21, 0
	s_add_u32 s24, s24, 0x100
	s_addc_u32 s25, s25, 0
	s_cmp_ge_i32 s55, s48
	s_mov_b32 s55, s26
	s_cbranch_scc0 .LBB0_1102

; #define PG8_STAGE(bufoff, gbase, voff) do { _Pragma("unroll") for (int _i = 0; _i < 2; ++_i) \
;         __builtin_amdgcn_global_load_lds((const unsigned*)((const char*)(gbase) + (voff)[_i]), (PG8_LAS unsigned*)(lds + (bufoff) + ldsw + _i * 8192), 16, 0, 0); } while (0)
; #define PG8_LDA(dst, b, h) do { _Pragma("unroll") for (int m = 0; m < 4; ++m) _Pragma("unroll") for (int k = 0; k < 2; ++k) dst[m][k] = *(const PG8_LAS bf16x8*)(lds + PG8_SA(b, h) + aoff + m * 2048 + k * 1024); } while (0)
; #define PG8_LDB(dst, b, h) do { _Pragma("unroll") for (int n = 0; n < 2; ++n) _Pragma("unroll") for (int k = 0; k < 2; ++k) dst[n][k] = *(const PG8_LAS bf16x8*)(lds + PG8_SB(b, h) + boff + n * 2048 + k * 1024); } while (0)
; #define PG8_WAIT_V(n) asm volatile("s_waitcnt vmcnt(" #n ")" ::: "memory")
; #define PG8_WAIT_L(n) asm volatile("s_waitcnt lgkmcnt(" #n ")" ::: "memory")
; #define PG8_BAR __builtin_amdgcn_s_barrier()
; #define PG8_SCHED __builtin_amdgcn_sched_barrier(0)
; template <class Epi, class Sched, bool ALIGN_EPI = false, bool SP2 = false>
; __device__ __forceinline__ void gemm_phase(PG8_LAS unsigned char* lds, const Gemm g, const Sched& S, const Epi& E, int tid_in) {
;     ...
;         for (int t = 0; t < nt; t += 2) {
;             const bool last = (t == nt - 2);
;             if constexpr (mid_hook<Epi>::value) { if (t == Epi::H1 || t == Epi::H2) E.mid(acc, cur, wr, wc, fr, fq, t == Epi::H2); }
;             const char* a1 = cA + (size_t)(t + 1) * kstep + (t >= jt ? jb : 0);
;             const char* a2 = last ? nA : cA + (size_t)(t + 2) * kstep + (t + 2 >= jt ? jb : 0); const char* b2 = last ? nB : cB + (size_t)(t + 2) * kstep;
;             const char* a3 = a2 + kstep; const char* b3 = b2 + kstep;
;             if (last && has_next) S.a_ready(nxt);
;             if constexpr (SP2) {
;             PG8_LDB(B0, 0, 0); PG8_LDB(B1, 0, 1); PG8_SCHED; PG8_LDA(At, 0, 0); PG8_STAGE(PG8_SA(1, 1), a1 + hsA, voffA);
;             PG8_WAIT_V(8); PG8_WAIT_L(0); PG8_BAR; PG8_MMA(0, 0, At, B0); PG8_MMA(0, 1, At, B1); PG8_BAR; PG8_SCHED;
;             PG8_LDA(At, 0, 1); PG8_STAGE(PG8_SB(0, 0), b2, voffB); PG8_STAGE(PG8_SB(0, 1), b2 + hsB, voffB); PG8_STAGE(PG8_SA(0, 0), a2, voffA);
;             PG8_WAIT_V(8); PG8_WAIT_L(0); PG8_BAR; PG8_MMA(1, 0, At, B0); PG8_MMA(1, 1, At, B1); PG8_BAR; PG8_SCHED;
.LBB0_1255:
	s_add_i32 s24, s58, -2
	s_cmp_ge_i32 s24, s29
	s_cselect_b32 s60, s30, 0
	s_cselect_b32 s61, s47, 0
	s_cmp_ge_i32 s58, s29
	s_cselect_b32 s25, s30, 0
	s_cselect_b32 s24, s47, 0
	s_add_u32 s25, s22, s25
	s_addc_u32 s24, s23, s24
	s_add_u32 s59, s25, 0x80
	s_addc_u32 s24, s24, 0
	s_add_i32 s64, 0, 0x10000
	s_cmp_eq_u32 s46, s58
	s_cselect_b32 s25, s5, s24
	s_cselect_b32 s24, s4, s59
	s_cselect_b32 s63, s21, s55
	s_cselect_b32 s62, s20, s54
	s_add_i32 s59, 0, 0x14000
	v_add_u32_e32 v160, s64, v142
	v_add_u32_e32 v176, s59, v142
	ds_read_b128 v[148:151], v160
	ds_read_b128 v[152:155], v160 offset:1024
	ds_read_b128 v[156:159], v160 offset:2048
	ds_read_b128 v[160:163], v160 offset:3072
	ds_read_b128 v[164:167], v176
	ds_read_b128 v[168:171], v176 offset:1024
	ds_read_b128 v[172:175], v176 offset:2048
	ds_read_b128 v[176:179], v176 offset:3072
	v_lshl_add_u64 v[192:193], s[22:23], 0, v[140:141]
	v_lshl_add_u64 v[192:193], v[192:193], 0, s[60:61]
	s_add_i32 m0, s40, 0xc000
	ds_read_b128 v[180:183], v147
	ds_read_b128 v[184:187], v147 offset:1024
	ds_read_b128 v[188:191], v147 offset:2048
	ds_read_b128 v[204:207], v147 offset:3072
	ds_read_b128 v[208:211], v147 offset:4096
	ds_read_b128 v[212:215], v147 offset:5120
	ds_read_b128 v[216:219], v147 offset:6144
	ds_read_b128 v[220:223], v147 offset:7168
	global_load_lds_dwordx4 v[192:193], off
	v_lshl_add_u64 v[192:193], s[22:23], 0, v[138:139]
	v_lshl_add_u64 v[192:193], v[192:193], 0, s[60:61]
	s_add_i32 m0, s40, 0xe000
	s_nop 0
	global_load_lds_dwordx4 v[192:193], off
	s_waitcnt vmcnt(8)
	s_waitcnt lgkmcnt(0)
	s_barrier
	s_setprio 1
	v_mfma_f32_16x16x32_bf16 v[124:127], v[148:151], v[180:183], v[124:127]
	v_mfma_f32_16x16x32_bf16 v[120:123], v[156:159], v[180:183], v[120:123]
	v_mfma_f32_16x16x32_bf16 v[112:115], v[148:151], v[188:191], v[112:115]
	v_mfma_f32_16x16x32_bf16 v[104:107], v[156:159], v[188:191], v[104:107]
	v_mfma_f32_16x16x32_bf16 v[96:99], v[148:151], v[208:211], v[96:99]
	v_mfma_f32_16x16x32_bf16 v[88:91], v[156:159], v[208:211], v[88:91]
	v_mfma_f32_16x16x32_bf16 v[80:83], v[148:151], v[216:219], v[80:83]
	v_mfma_f32_16x16x32_bf16 v[72:75], v[156:159], v[216:219], v[72:75]
	v_mfma_f32_16x16x32_bf16 v[124:127], v[152:155], v[184:187], v[124:127]
	v_mfma_f32_16x16x32_bf16 v[120:123], v[160:163], v[184:187], v[120:123]
	v_mfma_f32_16x16x32_bf16 v[112:115], v[152:155], v[204:207], v[112:115]
	v_mfma_f32_16x16x32_bf16 v[104:107], v[160:163], v[204:207], v[104:107]
	v_mfma_f32_16x16x32_bf16 v[96:99], v[152:155], v[212:215], v[96:99]
	v_mfma_f32_16x16x32_bf16 v[88:91], v[160:163], v[212:215], v[88:91]
	v_mfma_f32_16x16x32_bf16 v[80:83], v[152:155], v[220:223], v[80:83]
	v_mfma_f32_16x16x32_bf16 v[72:75], v[160:163], v[220:223], v[72:75]
	s_setprio 0
	s_setprio 1
	v_mfma_f32_16x16x32_bf16 v[128:131], v[164:167], v[180:183], v[128:131]
	v_mfma_f32_16x16x32_bf16 v[116:119], v[172:175], v[180:183], v[116:119]
	v_mfma_f32_16x16x32_bf16 v[108:111], v[164:167], v[188:191], v[108:111]
	v_mfma_f32_16x16x32_bf16 v[100:103], v[172:175], v[188:191], v[100:103]
	v_mfma_f32_16x16x32_bf16 v[92:95], v[164:167], v[208:211], v[92:95]
	v_mfma_f32_16x16x32_bf16 v[84:87], v[172:175], v[208:211], v[84:87]
	v_mfma_f32_16x16x32_bf16 v[76:79], v[164:167], v[216:219], v[76:79]
	v_mfma_f32_16x16x32_bf16 v[68:71], v[172:175], v[216:219], v[68:71]
	v_mfma_f32_16x16x32_bf16 v[128:131], v[168:171], v[184:187], v[128:131]
	v_mfma_f32_16x16x32_bf16 v[116:119], v[176:179], v[184:187], v[116:119]
	v_mfma_f32_16x16x32_bf16 v[108:111], v[168:171], v[204:207], v[108:111]
	v_mfma_f32_16x16x32_bf16 v[100:103], v[176:179], v[204:207], v[100:103]
	v_mfma_f32_16x16x32_bf16 v[92:95], v[168:171], v[212:215], v[92:95]
	v_mfma_f32_16x16x32_bf16 v[84:87], v[176:179], v[212:215], v[84:87]
	v_mfma_f32_16x16x32_bf16 v[76:79], v[168:171], v[220:223], v[76:79]
	v_mfma_f32_16x16x32_bf16 v[68:71], v[176:179], v[220:223], v[68:71]
	s_setprio 0
	s_barrier
	s_add_i32 s60, s64, s36
	v_lshl_add_u64 v[192:193], s[62:63], 0, v[134:135]
	s_mov_b32 m0, s60
	ds_read_b128 v[180:183], v147 offset:16384
	ds_read_b128 v[184:187], v147 offset:17408
	ds_read_b128 v[188:191], v147 offset:18432
	ds_read_b128 v[204:207], v147 offset:19456
	ds_read_b128 v[208:211], v147 offset:20480
	ds_read_b128 v[212:215], v147 offset:21504
	ds_read_b128 v[216:219], v147 offset:22528
	ds_read_b128 v[220:223], v147 offset:23552
	global_load_lds_dwordx4 v[192:193], off
	s_add_i32 m0, s60, 0x2000
	s_add_u32 s60, s62, s6
	v_lshl_add_u64 v[196:197], s[62:63], 0, v[0:1]
	s_addc_u32 s61, s63, s7
	s_add_i32 s59, s59, s36
	global_load_lds_dwordx4 v[196:197], off
	v_lshl_add_u64 v[198:199], s[60:61], 0, v[134:135]
	s_mov_b32 m0, s59
	v_lshl_add_u64 v[200:201], s[60:61], 0, v[0:1]
	global_load_lds_dwordx4 v[198:199], off
	s_add_i32 m0, s59, 0x2000
	v_lshl_add_u64 v[202:203], s[24:25], 0, v[136:137]
	global_load_lds_dwordx4 v[200:201], off
	s_mov_b32 m0, s40
	v_lshl_add_u64 v[228:229], s[24:25], 0, v[132:133]
	global_load_lds_dwordx4 v[202:203], off
	s_mov_b32 m0, s41
	s_nop 0
	global_load_lds_dwordx4 v[228:229], off
	s_waitcnt vmcnt(8)
	s_waitcnt lgkmcnt(0)
	s_barrier
; #define PG8_STAGE(bufoff, gbase, voff) do { _Pragma("unroll") for (int _i = 0; _i < 2; ++_i) \
;         __builtin_amdgcn_global_load_lds((const unsigned*)((const char*)(gbase) + (voff)[_i]), (PG8_LAS unsigned*)(lds + (bufoff) + ldsw + _i * 8192), 16, 0, 0); } while (0)
; #define PG8_LDA(dst, b, h) do { _Pragma("unroll") for (int m = 0; m < 4; ++m) _Pragma("unroll") for (int k = 0; k < 2; ++k) dst[m][k] = *(const PG8_LAS bf16x8*)(lds + PG8_SA(b, h) + aoff + m * 2048 + k * 1024); } while (0)
; #define PG8_LDB(dst, b, h) do { _Pragma("unroll") for (int n = 0; n < 2; ++n) _Pragma("unroll") for (int k = 0; k < 2; ++k) dst[n][k] = *(const PG8_LAS bf16x8*)(lds + PG8_SB(b, h) + boff + n * 2048 + k * 1024); } while (0)
; #define PG8_MMA(ai, bj, At, Bt) do { __builtin_amdgcn_s_setprio(1); _Pragma("unroll") for (int m = 0; m < 4; ++m) _Pragma("unroll") for (int n = 0; n < 2; ++n) _Pragma("unroll") for (int k = 0; k < 2; ++k) \
;         acc[ai][bj][m][n] = __builtin_amdgcn_mfma_f32_16x16x32_bf16(Bt[n][k], At[m][k], acc[ai][bj][m][n], 0, 0, 0); __builtin_amdgcn_s_setprio(0); } while (0)
; #define PG8_WAIT_V(n) asm volatile("s_waitcnt vmcnt(" #n ")" ::: "memory")
; #define PG8_WAIT_L(n) asm volatile("s_waitcnt lgkmcnt(" #n ")" ::: "memory")
; #define PG8_BAR __builtin_amdgcn_s_barrier()
; #define PG8_SCHED __builtin_amdgcn_sched_barrier(0)
; template <class Epi, class Sched, bool ALIGN_EPI = false, bool SP2 = false>
; __device__ __forceinline__ void gemm_phase(PG8_LAS unsigned char* lds, const Gemm g, const Sched& S, const Epi& E, int tid_in) {
;     ...
;             PG8_WAIT_V(8); PG8_WAIT_L(0); PG8_BAR; PG8_MMA(1, 0, At, B0); PG8_MMA(1, 1, At, B1); PG8_BAR; PG8_SCHED;
;             PG8_LDB(B0, 1, 0); PG8_LDB(B1, 1, 1); PG8_SCHED; PG8_LDA(At, 1, 0); PG8_STAGE(PG8_SA(0, 1), a2 + hsA, voffA);
;             PG8_WAIT_V(8); PG8_WAIT_L(0); PG8_BAR; PG8_MMA(0, 0, At, B0); PG8_MMA(0, 1, At, B1); PG8_BAR; PG8_SCHED;
	s_setprio 1
	v_mfma_f32_16x16x32_bf16 v[64:67], v[148:151], v[180:183], v[64:67]
	v_mfma_f32_16x16x32_bf16 v[56:59], v[156:159], v[180:183], v[56:59]
	v_mfma_f32_16x16x32_bf16 v[48:51], v[148:151], v[188:191], v[48:51]
	v_mfma_f32_16x16x32_bf16 v[40:43], v[156:159], v[188:191], v[40:43]
	v_mfma_f32_16x16x32_bf16 v[32:35], v[148:151], v[208:211], v[32:35]
	v_mfma_f32_16x16x32_bf16 v[24:27], v[156:159], v[208:211], v[24:27]
	v_mfma_f32_16x16x32_bf16 v[16:19], v[148:151], v[216:219], v[16:19]
	v_mfma_f32_16x16x32_bf16 v[8:11], v[156:159], v[216:219], v[8:11]
	v_mfma_f32_16x16x32_bf16 v[64:67], v[152:155], v[184:187], v[64:67]
	v_mfma_f32_16x16x32_bf16 v[56:59], v[160:163], v[184:187], v[56:59]
	v_mfma_f32_16x16x32_bf16 v[48:51], v[152:155], v[204:207], v[48:51]
	v_mfma_f32_16x16x32_bf16 v[40:43], v[160:163], v[204:207], v[40:43]
	v_mfma_f32_16x16x32_bf16 v[32:35], v[152:155], v[212:215], v[32:35]
	v_mfma_f32_16x16x32_bf16 v[24:27], v[160:163], v[212:215], v[24:27]
	v_mfma_f32_16x16x32_bf16 v[16:19], v[152:155], v[220:223], v[16:19]
	v_mfma_f32_16x16x32_bf16 v[8:11], v[160:163], v[220:223], v[8:11]
	s_setprio 0
	s_setprio 1
	v_mfma_f32_16x16x32_bf16 v[60:63], v[164:167], v[180:183], v[60:63]
	v_mfma_f32_16x16x32_bf16 v[52:55], v[172:175], v[180:183], v[52:55]
	v_mfma_f32_16x16x32_bf16 v[44:47], v[164:167], v[188:191], v[44:47]
	v_mfma_f32_16x16x32_bf16 v[36:39], v[172:175], v[188:191], v[36:39]
	v_mfma_f32_16x16x32_bf16 v[28:31], v[164:167], v[208:211], v[28:31]
	v_mfma_f32_16x16x32_bf16 v[20:23], v[172:175], v[208:211], v[20:23]
	v_mfma_f32_16x16x32_bf16 v[12:15], v[164:167], v[216:219], v[12:15]
	v_mfma_f32_16x16x32_bf16 v[4:7], v[172:175], v[216:219], v[4:7]
	v_mfma_f32_16x16x32_bf16 v[60:63], v[168:171], v[184:187], v[60:63]
	v_mfma_f32_16x16x32_bf16 v[52:55], v[176:179], v[184:187], v[52:55]
	v_mfma_f32_16x16x32_bf16 v[44:47], v[168:171], v[204:207], v[44:47]
	v_mfma_f32_16x16x32_bf16 v[36:39], v[176:179], v[204:207], v[36:39]
	v_mfma_f32_16x16x32_bf16 v[28:31], v[168:171], v[212:215], v[28:31]
	v_mfma_f32_16x16x32_bf16 v[20:23], v[176:179], v[212:215], v[20:23]
	v_mfma_f32_16x16x32_bf16 v[12:15], v[168:171], v[220:223], v[12:15]
	v_mfma_f32_16x16x32_bf16 v[4:7], v[176:179], v[220:223], v[4:7]
	s_setprio 0
	s_barrier
	s_add_i32 s59, 0, 0x18000
	s_add_i32 s60, 0, 0x1c000
	v_add_u32_e32 v160, s59, v142
	v_add_u32_e32 v176, s60, v142
	ds_read_b128 v[148:151], v160
	ds_read_b128 v[152:155], v160 offset:1024
	ds_read_b128 v[156:159], v160 offset:2048
	ds_read_b128 v[160:163], v160 offset:3072
	ds_read_b128 v[164:167], v176
	ds_read_b128 v[168:171], v176 offset:1024
	ds_read_b128 v[172:175], v176 offset:2048
	ds_read_b128 v[176:179], v176 offset:3072
	s_add_u32 s24, s24, s0
	s_addc_u32 s25, s25, s1
	s_mov_b32 m0, s42
	v_lshl_add_u64 v[230:231], s[24:25], 0, v[136:137]
	ds_read_b128 v[180:183], v147 offset:32768
	ds_read_b128 v[184:187], v147 offset:33792
	ds_read_b128 v[188:191], v147 offset:34816
	ds_read_b128 v[204:207], v147 offset:35840
	ds_read_b128 v[208:211], v147 offset:36864
	ds_read_b128 v[212:215], v147 offset:37888
	ds_read_b128 v[216:219], v147 offset:38912
	ds_read_b128 v[220:223], v147 offset:39936
	global_load_lds_dwordx4 v[230:231], off
	v_lshl_add_u64 v[230:231], s[24:25], 0, v[132:133]
	s_mov_b32 m0, s43
	s_nop 0
	global_load_lds_dwordx4 v[230:231], off
	s_waitcnt vmcnt(8)
	s_waitcnt lgkmcnt(0)
	s_barrier
	s_setprio 1
	v_mfma_f32_16x16x32_bf16 v[124:127], v[148:151], v[180:183], v[124:127]
	v_mfma_f32_16x16x32_bf16 v[120:123], v[156:159], v[180:183], v[120:123]
	v_mfma_f32_16x16x32_bf16 v[112:115], v[148:151], v[188:191], v[112:115]
	v_mfma_f32_16x16x32_bf16 v[104:107], v[156:159], v[188:191], v[104:107]
	v_mfma_f32_16x16x32_bf16 v[96:99], v[148:151], v[208:211], v[96:99]
	v_mfma_f32_16x16x32_bf16 v[88:91], v[156:159], v[208:211], v[88:91]
	v_mfma_f32_16x16x32_bf16 v[80:83], v[148:151], v[216:219], v[80:83]
	v_mfma_f32_16x16x32_bf16 v[72:75], v[156:159], v[216:219], v[72:75]
	v_mfma_f32_16x16x32_bf16 v[124:127], v[152:155], v[184:187], v[124:127]
	v_mfma_f32_16x16x32_bf16 v[120:123], v[160:163], v[184:187], v[120:123]
	v_mfma_f32_16x16x32_bf16 v[112:115], v[152:155], v[204:207], v[112:115]
	v_mfma_f32_16x16x32_bf16 v[104:107], v[160:163], v[204:207], v[104:107]
	v_mfma_f32_16x16x32_bf16 v[96:99], v[152:155], v[212:215], v[96:99]
	v_mfma_f32_16x16x32_bf16 v[88:91], v[160:163], v[212:215], v[88:91]
	v_mfma_f32_16x16x32_bf16 v[80:83], v[152:155], v[220:223], v[80:83]
	v_mfma_f32_16x16x32_bf16 v[72:75], v[160:163], v[220:223], v[72:75]
	s_setprio 0
	s_setprio 1
	v_mfma_f32_16x16x32_bf16 v[128:131], v[164:167], v[180:183], v[128:131]
	v_mfma_f32_16x16x32_bf16 v[116:119], v[172:175], v[180:183], v[116:119]
	v_mfma_f32_16x16x32_bf16 v[108:111], v[164:167], v[188:191], v[108:111]
	v_mfma_f32_16x16x32_bf16 v[100:103], v[172:175], v[188:191], v[100:103]
	v_mfma_f32_16x16x32_bf16 v[92:95], v[164:167], v[208:211], v[92:95]
	v_mfma_f32_16x16x32_bf16 v[84:87], v[172:175], v[208:211], v[84:87]
	v_mfma_f32_16x16x32_bf16 v[76:79], v[164:167], v[216:219], v[76:79]
	v_mfma_f32_16x16x32_bf16 v[68:71], v[172:175], v[216:219], v[68:71]
	v_mfma_f32_16x16x32_bf16 v[128:131], v[168:171], v[184:187], v[128:131]
	v_mfma_f32_16x16x32_bf16 v[116:119], v[176:179], v[184:187], v[116:119]
	v_mfma_f32_16x16x32_bf16 v[108:111], v[168:171], v[204:207], v[108:111]
	v_mfma_f32_16x16x32_bf16 v[100:103], v[176:179], v[204:207], v[100:103]
	v_mfma_f32_16x16x32_bf16 v[92:95], v[168:171], v[212:215], v[92:95]
	v_mfma_f32_16x16x32_bf16 v[84:87], v[176:179], v[212:215], v[84:87]
	v_mfma_f32_16x16x32_bf16 v[76:79], v[168:171], v[220:223], v[76:79]
	v_mfma_f32_16x16x32_bf16 v[68:71], v[176:179], v[220:223], v[68:71]
	s_setprio 0
	s_barrier
; #define PG8_STAGE(bufoff, gbase, voff) do { _Pragma("unroll") for (int _i = 0; _i < 2; ++_i) \
;         __builtin_amdgcn_global_load_lds((const unsigned*)((const char*)(gbase) + (voff)[_i]), (PG8_LAS unsigned*)(lds + (bufoff) + ldsw + _i * 8192), 16, 0, 0); } while (0)
; #define PG8_LDA(dst, b, h) do { _Pragma("unroll") for (int m = 0; m < 4; ++m) _Pragma("unroll") for (int k = 0; k < 2; ++k) dst[m][k] = *(const PG8_LAS bf16x8*)(lds + PG8_SA(b, h) + aoff + m * 2048 + k * 1024); } while (0)
; #define PG8_MMA(ai, bj, At, Bt) do { __builtin_amdgcn_s_setprio(1); _Pragma("unroll") for (int m = 0; m < 4; ++m) _Pragma("unroll") for (int n = 0; n < 2; ++n) _Pragma("unroll") for (int k = 0; k < 2; ++k) \
;         acc[ai][bj][m][n] = __builtin_amdgcn_mfma_f32_16x16x32_bf16(Bt[n][k], At[m][k], acc[ai][bj][m][n], 0, 0, 0); __builtin_amdgcn_s_setprio(0); } while (0)
; #define PG8_WAIT_V(n) asm volatile("s_waitcnt vmcnt(" #n ")" ::: "memory")
; #define PG8_WAIT_L(n) asm volatile("s_waitcnt lgkmcnt(" #n ")" ::: "memory")
; #define PG8_BAR __builtin_amdgcn_s_barrier()
; #define PG8_SCHED __builtin_amdgcn_sched_barrier(0)
; template <class Epi, class Sched, bool ALIGN_EPI = false, bool SP2 = false>
; __device__ __forceinline__ void gemm_phase(PG8_LAS unsigned char* lds, const Gemm g, const Sched& S, const Epi& E, int tid_in) {
;     ...
;         for (int t = 0; t < nt; t += 2) {
;     ...
;             PG8_LDA(At, 1, 1); PG8_STAGE(PG8_SB(1, 0), b3, voffB); PG8_STAGE(PG8_SB(1, 1), b3 + hsB, voffB); PG8_STAGE(PG8_SA(1, 0), a3, voffA);
;             PG8_WAIT_V(8); PG8_WAIT_L(0); PG8_BAR; PG8_MMA(1, 0, At, B0); PG8_MMA(1, 1, At, B1); PG8_BAR; PG8_SCHED;
	s_add_i32 s24, s59, s36
	v_lshl_add_u64 v[192:193], v[192:193], 0, s[80:81]
	s_mov_b32 m0, s24
	ds_read_b128 v[180:183], v147 offset:49152
	ds_read_b128 v[184:187], v147 offset:50176
	ds_read_b128 v[188:191], v147 offset:51200
	ds_read_b128 v[204:207], v147 offset:52224
	ds_read_b128 v[208:211], v147 offset:53248
	ds_read_b128 v[212:215], v147 offset:54272
	ds_read_b128 v[216:219], v147 offset:55296
	ds_read_b128 v[220:223], v147 offset:56320
	global_load_lds_dwordx4 v[192:193], off
	v_lshl_add_u64 v[192:193], v[196:197], 0, s[80:81]
	s_add_i32 m0, s24, 0x2000
	s_add_i32 s24, s60, s36
	global_load_lds_dwordx4 v[192:193], off
	v_lshl_add_u64 v[192:193], v[198:199], 0, s[80:81]
	s_mov_b32 m0, s24
	s_nop 0
	global_load_lds_dwordx4 v[192:193], off
	v_lshl_add_u64 v[192:193], v[200:201], 0, s[80:81]
	s_add_i32 m0, s24, 0x2000
	s_nop 0
	global_load_lds_dwordx4 v[192:193], off
	v_lshl_add_u64 v[192:193], v[202:203], 0, s[80:81]
	s_mov_b32 m0, s44
	s_nop 0
	global_load_lds_dwordx4 v[192:193], off
	v_lshl_add_u64 v[192:193], v[228:229], 0, s[80:81]
	s_mov_b32 m0, s45
	s_nop 0
	global_load_lds_dwordx4 v[192:193], off
	s_waitcnt vmcnt(8)
	s_waitcnt lgkmcnt(0)
	s_barrier
	s_setprio 1
	v_mfma_f32_16x16x32_bf16 v[64:67], v[148:151], v[180:183], v[64:67]
	v_mfma_f32_16x16x32_bf16 v[56:59], v[156:159], v[180:183], v[56:59]
	v_mfma_f32_16x16x32_bf16 v[48:51], v[148:151], v[188:191], v[48:51]
	v_mfma_f32_16x16x32_bf16 v[40:43], v[156:159], v[188:191], v[40:43]
	v_mfma_f32_16x16x32_bf16 v[32:35], v[148:151], v[208:211], v[32:35]
	v_mfma_f32_16x16x32_bf16 v[24:27], v[156:159], v[208:211], v[24:27]
	v_mfma_f32_16x16x32_bf16 v[16:19], v[148:151], v[216:219], v[16:19]
	v_mfma_f32_16x16x32_bf16 v[8:11], v[156:159], v[216:219], v[8:11]
	v_mfma_f32_16x16x32_bf16 v[64:67], v[152:155], v[184:187], v[64:67]
	v_mfma_f32_16x16x32_bf16 v[56:59], v[160:163], v[184:187], v[56:59]
	v_mfma_f32_16x16x32_bf16 v[48:51], v[152:155], v[204:207], v[48:51]
	v_mfma_f32_16x16x32_bf16 v[40:43], v[160:163], v[204:207], v[40:43]
	v_mfma_f32_16x16x32_bf16 v[32:35], v[152:155], v[212:215], v[32:35]
	v_mfma_f32_16x16x32_bf16 v[24:27], v[160:163], v[212:215], v[24:27]
	v_mfma_f32_16x16x32_bf16 v[16:19], v[152:155], v[220:223], v[16:19]
	v_mfma_f32_16x16x32_bf16 v[8:11], v[160:163], v[220:223], v[8:11]
	s_setprio 0
	s_setprio 1
	v_mfma_f32_16x16x32_bf16 v[60:63], v[164:167], v[180:183], v[60:63]
	v_mfma_f32_16x16x32_bf16 v[52:55], v[172:175], v[180:183], v[52:55]
	v_mfma_f32_16x16x32_bf16 v[44:47], v[164:167], v[188:191], v[44:47]
	v_mfma_f32_16x16x32_bf16 v[36:39], v[172:175], v[188:191], v[36:39]
	v_mfma_f32_16x16x32_bf16 v[28:31], v[164:167], v[208:211], v[28:31]
	v_mfma_f32_16x16x32_bf16 v[20:23], v[172:175], v[208:211], v[20:23]
	v_mfma_f32_16x16x32_bf16 v[12:15], v[164:167], v[216:219], v[12:15]
	v_mfma_f32_16x16x32_bf16 v[4:7], v[172:175], v[216:219], v[4:7]
	v_mfma_f32_16x16x32_bf16 v[60:63], v[168:171], v[184:187], v[60:63]
	v_mfma_f32_16x16x32_bf16 v[52:55], v[176:179], v[184:187], v[52:55]
	v_mfma_f32_16x16x32_bf16 v[44:47], v[168:171], v[204:207], v[44:47]
	v_mfma_f32_16x16x32_bf16 v[36:39], v[176:179], v[204:207], v[36:39]
	v_mfma_f32_16x16x32_bf16 v[28:31], v[168:171], v[212:215], v[28:31]
	v_mfma_f32_16x16x32_bf16 v[20:23], v[176:179], v[212:215], v[20:23]
	v_mfma_f32_16x16x32_bf16 v[12:15], v[168:171], v[220:223], v[12:15]
	v_mfma_f32_16x16x32_bf16 v[4:7], v[176:179], v[220:223], v[4:7]
	s_setprio 0
	s_barrier
	s_add_i32 s24, s58, 2
	s_add_u32 s54, s54, 0x100
	s_addc_u32 s55, s55, 0
	s_add_u32 s22, s22, 0x100
	s_addc_u32 s23, s23, 0
	s_cmp_ge_i32 s58, s46
	s_mov_b32 s58, s24
	s_cbranch_scc0 .LBB0_1255

; #define PG8_STAGE(bufoff, gbase, voff) do { _Pragma("unroll") for (int _i = 0; _i < 2; ++_i) \
;         __builtin_amdgcn_global_load_lds((const unsigned*)((const char*)(gbase) + (voff)[_i]), (PG8_LAS unsigned*)(lds + (bufoff) + ldsw + _i * 8192), 16, 0, 0); } while (0)
; #define PG8_LDA(dst, b, h) do { _Pragma("unroll") for (int m = 0; m < 4; ++m) _Pragma("unroll") for (int k = 0; k < 2; ++k) dst[m][k] = *(const PG8_LAS bf16x8*)(lds + PG8_SA(b, h) + aoff + m * 2048 + k * 1024); } while (0)
; #define PG8_LDB(dst, b, h) do { _Pragma("unroll") for (int n = 0; n < 2; ++n) _Pragma("unroll") for (int k = 0; k < 2; ++k) dst[n][k] = *(const PG8_LAS bf16x8*)(lds + PG8_SB(b, h) + boff + n * 2048 + k * 1024); } while (0)
; #define PG8_WAIT_V(n) asm volatile("s_waitcnt vmcnt(" #n ")" ::: "memory")
; #define PG8_WAIT_L(n) asm volatile("s_waitcnt lgkmcnt(" #n ")" ::: "memory")
; #define PG8_BAR __builtin_amdgcn_s_barrier()
; #define PG8_SCHED __builtin_amdgcn_sched_barrier(0)
; template <class Epi, class Sched, bool ALIGN_EPI = false, bool SP2 = false>
; __device__ __forceinline__ void gemm_phase(PG8_LAS unsigned char* lds, const Gemm g, const Sched& S, const Epi& E, int tid_in) {
;     ...
;         for (int t = 0; t < nt; t += 2) {
;             const bool last = (t == nt - 2);
;             if constexpr (mid_hook<Epi>::value) { if (t == Epi::H1 || t == Epi::H2) E.mid(acc, cur, wr, wc, fr, fq, t == Epi::H2); }
;             const char* a1 = cA + (size_t)(t + 1) * kstep + (t >= jt ? jb : 0);
;             const char* a2 = last ? nA : cA + (size_t)(t + 2) * kstep + (t + 2 >= jt ? jb : 0); const char* b2 = last ? nB : cB + (size_t)(t + 2) * kstep;
;             const char* a3 = a2 + kstep; const char* b3 = b2 + kstep;
;             if (last && has_next) S.a_ready(nxt);
;             if constexpr (SP2) {
;             PG8_LDB(B0, 0, 0); PG8_LDB(B1, 0, 1); PG8_SCHED; PG8_LDA(At, 0, 0); PG8_STAGE(PG8_SA(1, 1), a1 + hsA, voffA);
;             PG8_WAIT_V(8); PG8_WAIT_L(0); PG8_BAR; PG8_MMA(0, 0, At, B0); PG8_MMA(0, 1, At, B1); PG8_BAR; PG8_SCHED;
;             PG8_LDA(At, 0, 1); PG8_STAGE(PG8_SB(0, 0), b2, voffB); PG8_STAGE(PG8_SB(0, 1), b2 + hsB, voffB); PG8_STAGE(PG8_SA(0, 0), a2, voffA);
;             PG8_WAIT_V(8); PG8_WAIT_L(0); PG8_BAR; PG8_MMA(1, 0, At, B0); PG8_MMA(1, 1, At, B1); PG8_BAR; PG8_SCHED;
.LBB0_1331:
	s_add_i32 s38, s40, -2
	s_cmp_ge_i32 s38, s33
	s_cselect_b32 s76, s46, 0
	s_cselect_b32 s77, s61, 0
	s_cmp_ge_i32 s40, s33
	s_cselect_b32 s39, s46, 0
	s_cselect_b32 s38, s61, 0
	s_add_u32 s39, s4, s39
	s_addc_u32 s38, s5, s38
	s_add_u32 s41, s39, 0x80
	s_addc_u32 s38, s38, 0
	s_add_i32 s82, 0, 0x10000
	s_cmp_eq_u32 s60, s40
	s_cselect_b32 s39, s35, s38
	s_cselect_b32 s38, s34, s41
	s_cselect_b32 s79, s37, s75
	s_cselect_b32 s78, s36, s74
	s_add_i32 s41, 0, 0x14000
	v_add_u32_e32 v144, s82, v217
	v_add_u32_e32 v170, s41, v217
	ds_read_b128 v[132:135], v144
	ds_read_b128 v[136:139], v144 offset:1024
	ds_read_b128 v[140:143], v144 offset:2048
	ds_read_b128 v[144:147], v144 offset:3072
	ds_read_b128 v[148:151], v170
	ds_read_b128 v[162:165], v170 offset:1024
	ds_read_b128 v[166:169], v170 offset:2048
	ds_read_b128 v[170:173], v170 offset:3072
	v_lshl_add_u64 v[190:191], s[4:5], 0, v[160:161]
	v_lshl_add_u64 v[190:191], v[190:191], 0, s[76:77]
	s_add_i32 m0, s50, 0xc000
	ds_read_b128 v[174:177], v219
	ds_read_b128 v[178:181], v219 offset:1024
	ds_read_b128 v[182:185], v219 offset:2048
	ds_read_b128 v[186:189], v219 offset:3072
	ds_read_b128 v[204:207], v219 offset:4096
	ds_read_b128 v[208:211], v219 offset:5120
	ds_read_b128 v[212:215], v219 offset:6144
	ds_read_b128 v[220:223], v219 offset:7168
	global_load_lds_dwordx4 v[190:191], off
	v_lshl_add_u64 v[190:191], s[4:5], 0, v[158:159]
	v_lshl_add_u64 v[190:191], v[190:191], 0, s[76:77]
	s_add_i32 m0, s50, 0xe000
	s_nop 0
	global_load_lds_dwordx4 v[190:191], off
	s_waitcnt vmcnt(8)
	s_waitcnt lgkmcnt(0)
	s_barrier
	s_setprio 1
	v_mfma_f32_16x16x32_bf16 v[128:131], v[132:135], v[174:177], v[128:131]
	v_mfma_f32_16x16x32_bf16 v[124:127], v[140:143], v[174:177], v[124:127]
	v_mfma_f32_16x16x32_bf16 v[120:123], v[132:135], v[182:185], v[120:123]
	v_mfma_f32_16x16x32_bf16 v[116:119], v[140:143], v[182:185], v[116:119]
	v_mfma_f32_16x16x32_bf16 v[112:115], v[132:135], v[204:207], v[112:115]
	v_mfma_f32_16x16x32_bf16 v[108:111], v[140:143], v[204:207], v[108:111]
	v_mfma_f32_16x16x32_bf16 v[104:107], v[132:135], v[212:215], v[104:107]
	v_mfma_f32_16x16x32_bf16 v[100:103], v[140:143], v[212:215], v[100:103]
	v_mfma_f32_16x16x32_bf16 v[128:131], v[136:139], v[178:181], v[128:131]
	v_mfma_f32_16x16x32_bf16 v[124:127], v[144:147], v[178:181], v[124:127]
	v_mfma_f32_16x16x32_bf16 v[120:123], v[136:139], v[186:189], v[120:123]
	v_mfma_f32_16x16x32_bf16 v[116:119], v[144:147], v[186:189], v[116:119]
	v_mfma_f32_16x16x32_bf16 v[112:115], v[136:139], v[208:211], v[112:115]
	v_mfma_f32_16x16x32_bf16 v[108:111], v[144:147], v[208:211], v[108:111]
	v_mfma_f32_16x16x32_bf16 v[104:107], v[136:139], v[220:223], v[104:107]
	v_mfma_f32_16x16x32_bf16 v[100:103], v[144:147], v[220:223], v[100:103]
	s_setprio 0
	s_setprio 1
	v_mfma_f32_16x16x32_bf16 v[64:67], v[148:151], v[174:177], v[64:67]
	v_mfma_f32_16x16x32_bf16 v[56:59], v[166:169], v[174:177], v[56:59]
	v_mfma_f32_16x16x32_bf16 v[60:63], v[148:151], v[182:185], v[60:63]
	v_mfma_f32_16x16x32_bf16 v[52:55], v[166:169], v[182:185], v[52:55]
	v_mfma_f32_16x16x32_bf16 v[48:51], v[148:151], v[204:207], v[48:51]
	v_mfma_f32_16x16x32_bf16 v[40:43], v[166:169], v[204:207], v[40:43]
	v_mfma_f32_16x16x32_bf16 v[44:47], v[148:151], v[212:215], v[44:47]
	v_mfma_f32_16x16x32_bf16 v[36:39], v[166:169], v[212:215], v[36:39]
	v_mfma_f32_16x16x32_bf16 v[64:67], v[162:165], v[178:181], v[64:67]
	v_mfma_f32_16x16x32_bf16 v[56:59], v[170:173], v[178:181], v[56:59]
	v_mfma_f32_16x16x32_bf16 v[60:63], v[162:165], v[186:189], v[60:63]
	v_mfma_f32_16x16x32_bf16 v[52:55], v[170:173], v[186:189], v[52:55]
	v_mfma_f32_16x16x32_bf16 v[48:51], v[162:165], v[208:211], v[48:51]
	v_mfma_f32_16x16x32_bf16 v[40:43], v[170:173], v[208:211], v[40:43]
	v_mfma_f32_16x16x32_bf16 v[44:47], v[162:165], v[220:223], v[44:47]
	v_mfma_f32_16x16x32_bf16 v[36:39], v[170:173], v[220:223], v[36:39]
	s_setprio 0
	s_barrier
	s_add_i32 s76, s82, s49
	v_lshl_add_u64 v[190:191], s[78:79], 0, v[152:153]
	s_mov_b32 m0, s76
	ds_read_b128 v[174:177], v219 offset:16384
	ds_read_b128 v[178:181], v219 offset:17408
	ds_read_b128 v[182:185], v219 offset:18432
	ds_read_b128 v[186:189], v219 offset:19456
	ds_read_b128 v[204:207], v219 offset:20480
	ds_read_b128 v[208:211], v219 offset:21504
	ds_read_b128 v[212:215], v219 offset:22528
	ds_read_b128 v[220:223], v219 offset:23552
	global_load_lds_dwordx4 v[190:191], off
	s_add_i32 m0, s76, 0x2000
	s_add_u32 s76, s78, s12
	v_lshl_add_u64 v[192:193], s[78:79], 0, v[156:157]
	s_addc_u32 s77, s79, s13
	s_add_i32 s41, s41, s49
	global_load_lds_dwordx4 v[192:193], off
	v_lshl_add_u64 v[196:197], s[76:77], 0, v[152:153]
	s_mov_b32 m0, s41
	v_lshl_add_u64 v[198:199], s[76:77], 0, v[156:157]
	global_load_lds_dwordx4 v[196:197], off
	s_add_i32 m0, s41, 0x2000
	v_lshl_add_u64 v[200:201], s[38:39], 0, v[0:1]
	global_load_lds_dwordx4 v[198:199], off
	s_mov_b32 m0, s50
	v_lshl_add_u64 v[202:203], s[38:39], 0, v[154:155]
	global_load_lds_dwordx4 v[200:201], off
	s_mov_b32 m0, s51
	s_nop 0
	global_load_lds_dwordx4 v[202:203], off
	s_waitcnt vmcnt(8)
	s_waitcnt lgkmcnt(0)
	s_barrier
; #define PG8_STAGE(bufoff, gbase, voff) do { _Pragma("unroll") for (int _i = 0; _i < 2; ++_i) \
;         __builtin_amdgcn_global_load_lds((const unsigned*)((const char*)(gbase) + (voff)[_i]), (PG8_LAS unsigned*)(lds + (bufoff) + ldsw + _i * 8192), 16, 0, 0); } while (0)
; #define PG8_LDA(dst, b, h) do { _Pragma("unroll") for (int m = 0; m < 4; ++m) _Pragma("unroll") for (int k = 0; k < 2; ++k) dst[m][k] = *(const PG8_LAS bf16x8*)(lds + PG8_SA(b, h) + aoff + m * 2048 + k * 1024); } while (0)
; #define PG8_LDB(dst, b, h) do { _Pragma("unroll") for (int n = 0; n < 2; ++n) _Pragma("unroll") for (int k = 0; k < 2; ++k) dst[n][k] = *(const PG8_LAS bf16x8*)(lds + PG8_SB(b, h) + boff + n * 2048 + k * 1024); } while (0)
; #define PG8_MMA(ai, bj, At, Bt) do { __builtin_amdgcn_s_setprio(1); _Pragma("unroll") for (int m = 0; m < 4; ++m) _Pragma("unroll") for (int n = 0; n < 2; ++n) _Pragma("unroll") for (int k = 0; k < 2; ++k) \
;         acc[ai][bj][m][n] = __builtin_amdgcn_mfma_f32_16x16x32_bf16(Bt[n][k], At[m][k], acc[ai][bj][m][n], 0, 0, 0); __builtin_amdgcn_s_setprio(0); } while (0)
; #define PG8_WAIT_V(n) asm volatile("s_waitcnt vmcnt(" #n ")" ::: "memory")
; #define PG8_WAIT_L(n) asm volatile("s_waitcnt lgkmcnt(" #n ")" ::: "memory")
; #define PG8_BAR __builtin_amdgcn_s_barrier()
; #define PG8_SCHED __builtin_amdgcn_sched_barrier(0)
; template <class Epi, class Sched, bool ALIGN_EPI = false, bool SP2 = false>
; __device__ __forceinline__ void gemm_phase(PG8_LAS unsigned char* lds, const Gemm g, const Sched& S, const Epi& E, int tid_in) {
;     ...
;             PG8_WAIT_V(8); PG8_WAIT_L(0); PG8_BAR; PG8_MMA(1, 0, At, B0); PG8_MMA(1, 1, At, B1); PG8_BAR; PG8_SCHED;
;             PG8_LDB(B0, 1, 0); PG8_LDB(B1, 1, 1); PG8_SCHED; PG8_LDA(At, 1, 0); PG8_STAGE(PG8_SA(0, 1), a2 + hsA, voffA);
;             PG8_WAIT_V(8); PG8_WAIT_L(0); PG8_BAR; PG8_MMA(0, 0, At, B0); PG8_MMA(0, 1, At, B1); PG8_BAR; PG8_SCHED;
	s_setprio 1
	v_mfma_f32_16x16x32_bf16 v[96:99], v[132:135], v[174:177], v[96:99]
	v_mfma_f32_16x16x32_bf16 v[92:95], v[140:143], v[174:177], v[92:95]
	v_mfma_f32_16x16x32_bf16 v[88:91], v[132:135], v[182:185], v[88:91]
	v_mfma_f32_16x16x32_bf16 v[84:87], v[140:143], v[182:185], v[84:87]
	v_mfma_f32_16x16x32_bf16 v[80:83], v[132:135], v[204:207], v[80:83]
	v_mfma_f32_16x16x32_bf16 v[76:79], v[140:143], v[204:207], v[76:79]
	v_mfma_f32_16x16x32_bf16 v[72:75], v[132:135], v[212:215], v[72:75]
	v_mfma_f32_16x16x32_bf16 v[68:71], v[140:143], v[212:215], v[68:71]
	v_mfma_f32_16x16x32_bf16 v[96:99], v[136:139], v[178:181], v[96:99]
	v_mfma_f32_16x16x32_bf16 v[92:95], v[144:147], v[178:181], v[92:95]
	v_mfma_f32_16x16x32_bf16 v[88:91], v[136:139], v[186:189], v[88:91]
	v_mfma_f32_16x16x32_bf16 v[84:87], v[144:147], v[186:189], v[84:87]
	v_mfma_f32_16x16x32_bf16 v[80:83], v[136:139], v[208:211], v[80:83]
	v_mfma_f32_16x16x32_bf16 v[76:79], v[144:147], v[208:211], v[76:79]
	v_mfma_f32_16x16x32_bf16 v[72:75], v[136:139], v[220:223], v[72:75]
	v_mfma_f32_16x16x32_bf16 v[68:71], v[144:147], v[220:223], v[68:71]
	s_setprio 0
	s_setprio 1
	v_mfma_f32_16x16x32_bf16 v[32:35], v[148:151], v[174:177], v[32:35]
	v_mfma_f32_16x16x32_bf16 v[28:31], v[166:169], v[174:177], v[28:31]
	v_mfma_f32_16x16x32_bf16 v[24:27], v[148:151], v[182:185], v[24:27]
	v_mfma_f32_16x16x32_bf16 v[12:15], v[166:169], v[182:185], v[12:15]
	v_mfma_f32_16x16x32_bf16 v[20:23], v[148:151], v[204:207], v[20:23]
	v_mfma_f32_16x16x32_bf16 v[8:11], v[166:169], v[204:207], v[8:11]
	v_mfma_f32_16x16x32_bf16 v[16:19], v[148:151], v[212:215], v[16:19]
	v_mfma_f32_16x16x32_bf16 v[4:7], v[166:169], v[212:215], v[4:7]
	v_mfma_f32_16x16x32_bf16 v[32:35], v[162:165], v[178:181], v[32:35]
	v_mfma_f32_16x16x32_bf16 v[28:31], v[170:173], v[178:181], v[28:31]
	v_mfma_f32_16x16x32_bf16 v[24:27], v[162:165], v[186:189], v[24:27]
	v_mfma_f32_16x16x32_bf16 v[12:15], v[170:173], v[186:189], v[12:15]
	v_mfma_f32_16x16x32_bf16 v[20:23], v[162:165], v[208:211], v[20:23]
	v_mfma_f32_16x16x32_bf16 v[8:11], v[170:173], v[208:211], v[8:11]
	v_mfma_f32_16x16x32_bf16 v[16:19], v[162:165], v[220:223], v[16:19]
	v_mfma_f32_16x16x32_bf16 v[4:7], v[170:173], v[220:223], v[4:7]
	s_setprio 0
	s_barrier
	s_add_i32 s41, 0, 0x18000
	s_add_i32 s76, 0, 0x1c000
	v_add_u32_e32 v144, s41, v217
	v_add_u32_e32 v170, s76, v217
	ds_read_b128 v[132:135], v144
	ds_read_b128 v[136:139], v144 offset:1024
	ds_read_b128 v[140:143], v144 offset:2048
	ds_read_b128 v[144:147], v144 offset:3072
	ds_read_b128 v[148:151], v170
	ds_read_b128 v[162:165], v170 offset:1024
	ds_read_b128 v[166:169], v170 offset:2048
	ds_read_b128 v[170:173], v170 offset:3072
	s_add_u32 s38, s38, s10
	s_addc_u32 s39, s39, s11
	s_mov_b32 m0, s52
	v_lshl_add_u64 v[228:229], s[38:39], 0, v[0:1]
	ds_read_b128 v[174:177], v219 offset:32768
	ds_read_b128 v[178:181], v219 offset:33792
	ds_read_b128 v[182:185], v219 offset:34816
	ds_read_b128 v[186:189], v219 offset:35840
	ds_read_b128 v[204:207], v219 offset:36864
	ds_read_b128 v[208:211], v219 offset:37888
	ds_read_b128 v[212:215], v219 offset:38912
	ds_read_b128 v[220:223], v219 offset:39936
	global_load_lds_dwordx4 v[228:229], off
	v_lshl_add_u64 v[228:229], s[38:39], 0, v[154:155]
	s_mov_b32 m0, s53
	s_nop 0
	global_load_lds_dwordx4 v[228:229], off
	s_waitcnt vmcnt(8)
	s_waitcnt lgkmcnt(0)
	s_barrier
	s_setprio 1
	v_mfma_f32_16x16x32_bf16 v[128:131], v[132:135], v[174:177], v[128:131]
	v_mfma_f32_16x16x32_bf16 v[124:127], v[140:143], v[174:177], v[124:127]
	v_mfma_f32_16x16x32_bf16 v[120:123], v[132:135], v[182:185], v[120:123]
	v_mfma_f32_16x16x32_bf16 v[116:119], v[140:143], v[182:185], v[116:119]
	v_mfma_f32_16x16x32_bf16 v[112:115], v[132:135], v[204:207], v[112:115]
	v_mfma_f32_16x16x32_bf16 v[108:111], v[140:143], v[204:207], v[108:111]
	v_mfma_f32_16x16x32_bf16 v[104:107], v[132:135], v[212:215], v[104:107]
	v_mfma_f32_16x16x32_bf16 v[100:103], v[140:143], v[212:215], v[100:103]
	v_mfma_f32_16x16x32_bf16 v[128:131], v[136:139], v[178:181], v[128:131]
	v_mfma_f32_16x16x32_bf16 v[124:127], v[144:147], v[178:181], v[124:127]
	v_mfma_f32_16x16x32_bf16 v[120:123], v[136:139], v[186:189], v[120:123]
	v_mfma_f32_16x16x32_bf16 v[116:119], v[144:147], v[186:189], v[116:119]
	v_mfma_f32_16x16x32_bf16 v[112:115], v[136:139], v[208:211], v[112:115]
	v_mfma_f32_16x16x32_bf16 v[108:111], v[144:147], v[208:211], v[108:111]
	v_mfma_f32_16x16x32_bf16 v[104:107], v[136:139], v[220:223], v[104:107]
	v_mfma_f32_16x16x32_bf16 v[100:103], v[144:147], v[220:223], v[100:103]
	s_setprio 0
	s_setprio 1
	v_mfma_f32_16x16x32_bf16 v[64:67], v[148:151], v[174:177], v[64:67]
	v_mfma_f32_16x16x32_bf16 v[56:59], v[166:169], v[174:177], v[56:59]
	v_mfma_f32_16x16x32_bf16 v[60:63], v[148:151], v[182:185], v[60:63]
	v_mfma_f32_16x16x32_bf16 v[52:55], v[166:169], v[182:185], v[52:55]
	v_mfma_f32_16x16x32_bf16 v[48:51], v[148:151], v[204:207], v[48:51]
	v_mfma_f32_16x16x32_bf16 v[40:43], v[166:169], v[204:207], v[40:43]
	v_mfma_f32_16x16x32_bf16 v[44:47], v[148:151], v[212:215], v[44:47]
	v_mfma_f32_16x16x32_bf16 v[36:39], v[166:169], v[212:215], v[36:39]
	v_mfma_f32_16x16x32_bf16 v[64:67], v[162:165], v[178:181], v[64:67]
	v_mfma_f32_16x16x32_bf16 v[56:59], v[170:173], v[178:181], v[56:59]
	v_mfma_f32_16x16x32_bf16 v[60:63], v[162:165], v[186:189], v[60:63]
	v_mfma_f32_16x16x32_bf16 v[52:55], v[170:173], v[186:189], v[52:55]
	v_mfma_f32_16x16x32_bf16 v[48:51], v[162:165], v[208:211], v[48:51]
	v_mfma_f32_16x16x32_bf16 v[40:43], v[170:173], v[208:211], v[40:43]
	v_mfma_f32_16x16x32_bf16 v[44:47], v[162:165], v[220:223], v[44:47]
	v_mfma_f32_16x16x32_bf16 v[36:39], v[170:173], v[220:223], v[36:39]
	s_setprio 0
	s_barrier
; #define PG8_STAGE(bufoff, gbase, voff) do { _Pragma("unroll") for (int _i = 0; _i < 2; ++_i) \
;         __builtin_amdgcn_global_load_lds((const unsigned*)((const char*)(gbase) + (voff)[_i]), (PG8_LAS unsigned*)(lds + (bufoff) + ldsw + _i * 8192), 16, 0, 0); } while (0)
; #define PG8_LDA(dst, b, h) do { _Pragma("unroll") for (int m = 0; m < 4; ++m) _Pragma("unroll") for (int k = 0; k < 2; ++k) dst[m][k] = *(const PG8_LAS bf16x8*)(lds + PG8_SA(b, h) + aoff + m * 2048 + k * 1024); } while (0)
; #define PG8_MMA(ai, bj, At, Bt) do { __builtin_amdgcn_s_setprio(1); _Pragma("unroll") for (int m = 0; m < 4; ++m) _Pragma("unroll") for (int n = 0; n < 2; ++n) _Pragma("unroll") for (int k = 0; k < 2; ++k) \
;         acc[ai][bj][m][n] = __builtin_amdgcn_mfma_f32_16x16x32_bf16(Bt[n][k], At[m][k], acc[ai][bj][m][n], 0, 0, 0); __builtin_amdgcn_s_setprio(0); } while (0)
; #define PG8_WAIT_V(n) asm volatile("s_waitcnt vmcnt(" #n ")" ::: "memory")
; #define PG8_WAIT_L(n) asm volatile("s_waitcnt lgkmcnt(" #n ")" ::: "memory")
; #define PG8_BAR __builtin_amdgcn_s_barrier()
; #define PG8_SCHED __builtin_amdgcn_sched_barrier(0)
; template <class Epi, class Sched, bool ALIGN_EPI = false, bool SP2 = false>
; __device__ __forceinline__ void gemm_phase(PG8_LAS unsigned char* lds, const Gemm g, const Sched& S, const Epi& E, int tid_in) {
;     ...
;         for (int t = 0; t < nt; t += 2) {
;     ...
;             PG8_LDA(At, 1, 1); PG8_STAGE(PG8_SB(1, 0), b3, voffB); PG8_STAGE(PG8_SB(1, 1), b3 + hsB, voffB); PG8_STAGE(PG8_SA(1, 0), a3, voffA);
;             PG8_WAIT_V(8); PG8_WAIT_L(0); PG8_BAR; PG8_MMA(1, 0, At, B0); PG8_MMA(1, 1, At, B1); PG8_BAR; PG8_SCHED;
	s_add_i32 s38, s41, s49
	v_lshl_add_u64 v[190:191], v[190:191], 0, s[80:81]
	s_mov_b32 m0, s38
	ds_read_b128 v[174:177], v219 offset:49152
	ds_read_b128 v[178:181], v219 offset:50176
	ds_read_b128 v[182:185], v219 offset:51200
	ds_read_b128 v[186:189], v219 offset:52224
	ds_read_b128 v[204:207], v219 offset:53248
	ds_read_b128 v[208:211], v219 offset:54272
	ds_read_b128 v[212:215], v219 offset:55296
	ds_read_b128 v[220:223], v219 offset:56320
	global_load_lds_dwordx4 v[190:191], off
	v_lshl_add_u64 v[190:191], v[192:193], 0, s[80:81]
	s_add_i32 m0, s38, 0x2000
	s_add_i32 s38, s76, s49
	global_load_lds_dwordx4 v[190:191], off
	v_lshl_add_u64 v[190:191], v[196:197], 0, s[80:81]
	s_mov_b32 m0, s38
	s_nop 0
	global_load_lds_dwordx4 v[190:191], off
	v_lshl_add_u64 v[190:191], v[198:199], 0, s[80:81]
	s_add_i32 m0, s38, 0x2000
	s_nop 0
	global_load_lds_dwordx4 v[190:191], off
	v_lshl_add_u64 v[190:191], v[200:201], 0, s[80:81]
	s_mov_b32 m0, s58
	s_nop 0
	global_load_lds_dwordx4 v[190:191], off
	v_lshl_add_u64 v[190:191], v[202:203], 0, s[80:81]
	s_mov_b32 m0, s59
	s_nop 0
	global_load_lds_dwordx4 v[190:191], off
	s_waitcnt vmcnt(8)
	s_waitcnt lgkmcnt(0)
	s_barrier
	s_setprio 1
	v_mfma_f32_16x16x32_bf16 v[96:99], v[132:135], v[174:177], v[96:99]
	v_mfma_f32_16x16x32_bf16 v[92:95], v[140:143], v[174:177], v[92:95]
	v_mfma_f32_16x16x32_bf16 v[88:91], v[132:135], v[182:185], v[88:91]
	v_mfma_f32_16x16x32_bf16 v[84:87], v[140:143], v[182:185], v[84:87]
	v_mfma_f32_16x16x32_bf16 v[80:83], v[132:135], v[204:207], v[80:83]
	v_mfma_f32_16x16x32_bf16 v[76:79], v[140:143], v[204:207], v[76:79]
	v_mfma_f32_16x16x32_bf16 v[72:75], v[132:135], v[212:215], v[72:75]
	v_mfma_f32_16x16x32_bf16 v[68:71], v[140:143], v[212:215], v[68:71]
	v_mfma_f32_16x16x32_bf16 v[96:99], v[136:139], v[178:181], v[96:99]
	v_mfma_f32_16x16x32_bf16 v[92:95], v[144:147], v[178:181], v[92:95]
	v_mfma_f32_16x16x32_bf16 v[88:91], v[136:139], v[186:189], v[88:91]
	v_mfma_f32_16x16x32_bf16 v[84:87], v[144:147], v[186:189], v[84:87]
	v_mfma_f32_16x16x32_bf16 v[80:83], v[136:139], v[208:211], v[80:83]
	v_mfma_f32_16x16x32_bf16 v[76:79], v[144:147], v[208:211], v[76:79]
	v_mfma_f32_16x16x32_bf16 v[72:75], v[136:139], v[220:223], v[72:75]
	v_mfma_f32_16x16x32_bf16 v[68:71], v[144:147], v[220:223], v[68:71]
	s_setprio 0
	s_setprio 1
	v_mfma_f32_16x16x32_bf16 v[32:35], v[148:151], v[174:177], v[32:35]
	v_mfma_f32_16x16x32_bf16 v[28:31], v[166:169], v[174:177], v[28:31]
	v_mfma_f32_16x16x32_bf16 v[24:27], v[148:151], v[182:185], v[24:27]
	v_mfma_f32_16x16x32_bf16 v[12:15], v[166:169], v[182:185], v[12:15]
	v_mfma_f32_16x16x32_bf16 v[20:23], v[148:151], v[204:207], v[20:23]
	v_mfma_f32_16x16x32_bf16 v[8:11], v[166:169], v[204:207], v[8:11]
	v_mfma_f32_16x16x32_bf16 v[16:19], v[148:151], v[212:215], v[16:19]
	v_mfma_f32_16x16x32_bf16 v[4:7], v[166:169], v[212:215], v[4:7]
	v_mfma_f32_16x16x32_bf16 v[32:35], v[162:165], v[178:181], v[32:35]
	v_mfma_f32_16x16x32_bf16 v[28:31], v[170:173], v[178:181], v[28:31]
	v_mfma_f32_16x16x32_bf16 v[24:27], v[162:165], v[186:189], v[24:27]
	v_mfma_f32_16x16x32_bf16 v[12:15], v[170:173], v[186:189], v[12:15]
	v_mfma_f32_16x16x32_bf16 v[20:23], v[162:165], v[208:211], v[20:23]
	v_mfma_f32_16x16x32_bf16 v[8:11], v[170:173], v[208:211], v[8:11]
	v_mfma_f32_16x16x32_bf16 v[16:19], v[162:165], v[220:223], v[16:19]
	v_mfma_f32_16x16x32_bf16 v[4:7], v[170:173], v[220:223], v[4:7]
	s_setprio 0
	s_barrier
	s_add_i32 s38, s40, 2
	s_add_u32 s74, s74, 0x100
	s_addc_u32 s75, s75, 0
	s_add_u32 s4, s4, 0x100
	s_addc_u32 s5, s5, 0
	s_cmp_ge_i32 s40, s60
	s_mov_b32 s40, s38
	s_cbranch_scc0 .LBB0_1331
	s_movk_i32 s74, 0x2c00

; #define PG8_STAGE(bufoff, gbase, voff) do { _Pragma("unroll") for (int _i = 0; _i < 2; ++_i) \
;         __builtin_amdgcn_global_load_lds((const unsigned*)((const char*)(gbase) + (voff)[_i]), (PG8_LAS unsigned*)(lds + (bufoff) + ldsw + _i * 8192), 16, 0, 0); } while (0)
; #define PG8_LDA(dst, b, h) do { _Pragma("unroll") for (int m = 0; m < 4; ++m) _Pragma("unroll") for (int k = 0; k < 2; ++k) dst[m][k] = *(const PG8_LAS bf16x8*)(lds + PG8_SA(b, h) + aoff + m * 2048 + k * 1024); } while (0)
; #define PG8_LDB(dst, b, h) do { _Pragma("unroll") for (int n = 0; n < 2; ++n) _Pragma("unroll") for (int k = 0; k < 2; ++k) dst[n][k] = *(const PG8_LAS bf16x8*)(lds + PG8_SB(b, h) + boff + n * 2048 + k * 1024); } while (0)
; #define PG8_WAIT_V(n) asm volatile("s_waitcnt vmcnt(" #n ")" ::: "memory")
; #define PG8_WAIT_L(n) asm volatile("s_waitcnt lgkmcnt(" #n ")" ::: "memory")
; #define PG8_BAR __builtin_amdgcn_s_barrier()
; #define PG8_SCHED __builtin_amdgcn_sched_barrier(0)
; template <class Epi, class Sched, bool ALIGN_EPI = false, bool SP2 = false>
; __device__ __forceinline__ void gemm_phase(PG8_LAS unsigned char* lds, const Gemm g, const Sched& S, const Epi& E, int tid_in) {
;     ...
;         for (int t = 0; t < nt; t += 2) {
;             const bool last = (t == nt - 2);
;             if constexpr (mid_hook<Epi>::value) { if (t == Epi::H1 || t == Epi::H2) E.mid(acc, cur, wr, wc, fr, fq, t == Epi::H2); }
;             const char* a1 = cA + (size_t)(t + 1) * kstep + (t >= jt ? jb : 0);
;             const char* a2 = last ? nA : cA + (size_t)(t + 2) * kstep + (t + 2 >= jt ? jb : 0); const char* b2 = last ? nB : cB + (size_t)(t + 2) * kstep;
;             const char* a3 = a2 + kstep; const char* b3 = b2 + kstep;
;             if (last && has_next) S.a_ready(nxt);
;             if constexpr (SP2) {
;             PG8_LDB(B0, 0, 0); PG8_LDB(B1, 0, 1); PG8_SCHED; PG8_LDA(At, 0, 0); PG8_STAGE(PG8_SA(1, 1), a1 + hsA, voffA);
;             PG8_WAIT_V(8); PG8_WAIT_L(0); PG8_BAR; PG8_MMA(0, 0, At, B0); PG8_MMA(0, 1, At, B1); PG8_BAR; PG8_SCHED;
;             PG8_LDA(At, 0, 1); PG8_STAGE(PG8_SB(0, 0), b2, voffB); PG8_STAGE(PG8_SB(0, 1), b2 + hsB, voffB); PG8_STAGE(PG8_SA(0, 0), a2, voffA);
;             PG8_WAIT_V(8); PG8_WAIT_L(0); PG8_BAR; PG8_MMA(1, 0, At, B0); PG8_MMA(1, 1, At, B1); PG8_BAR; PG8_SCHED;
.LBB0_1362:
	s_add_i32 s24, s55, -2
	s_cmp_ge_i32 s24, s26
	s_cselect_b32 s58, s27, 0
	s_cselect_b32 s59, s47, 0
	s_cmp_ge_i32 s55, s26
	s_cselect_b32 s25, s27, 0
	s_cselect_b32 s24, s47, 0
	s_add_u32 s25, s22, s25
	s_addc_u32 s24, s23, s24
	s_add_u32 s60, s25, 0x80
	s_addc_u32 s24, s24, 0
	s_add_i32 s62, 0, 0x10000
	s_cmp_eq_u32 s46, s55
	s_cselect_b32 s25, s5, s24
	s_cselect_b32 s24, s4, s60
	s_cselect_b32 s61, s21, s54
	s_cselect_b32 s60, s20, s53
	s_add_i32 s63, 0, 0x14000
	v_add_u32_e32 v160, s62, v3
	v_add_u32_e32 v176, s63, v3
	ds_read_b128 v[148:151], v160
	ds_read_b128 v[152:155], v160 offset:1024
	ds_read_b128 v[156:159], v160 offset:2048
	ds_read_b128 v[160:163], v160 offset:3072
	ds_read_b128 v[164:167], v176
	ds_read_b128 v[168:171], v176 offset:1024
	ds_read_b128 v[172:175], v176 offset:2048
	ds_read_b128 v[176:179], v176 offset:3072
	v_lshl_add_u64 v[192:193], s[22:23], 0, v[140:141]
	v_lshl_add_u64 v[192:193], v[192:193], 0, s[58:59]
	s_add_i32 m0, s33, 0xc000
	ds_read_b128 v[180:183], v147
	ds_read_b128 v[184:187], v147 offset:1024
	ds_read_b128 v[188:191], v147 offset:2048
	ds_read_b128 v[204:207], v147 offset:3072
	ds_read_b128 v[208:211], v147 offset:4096
	ds_read_b128 v[212:215], v147 offset:5120
	ds_read_b128 v[216:219], v147 offset:6144
	ds_read_b128 v[220:223], v147 offset:7168
	global_load_lds_dwordx4 v[192:193], off
	v_lshl_add_u64 v[192:193], s[22:23], 0, v[138:139]
	v_lshl_add_u64 v[192:193], v[192:193], 0, s[58:59]
	s_add_i32 m0, s33, 0xe000
	s_nop 0
	global_load_lds_dwordx4 v[192:193], off
	s_waitcnt vmcnt(8)
	s_waitcnt lgkmcnt(0)
	s_barrier
	s_setprio 1
	v_mfma_f32_16x16x32_bf16 v[124:127], v[148:151], v[180:183], v[124:127]
	v_mfma_f32_16x16x32_bf16 v[128:131], v[156:159], v[180:183], v[128:131]
	v_mfma_f32_16x16x32_bf16 v[112:115], v[148:151], v[188:191], v[112:115]
	v_mfma_f32_16x16x32_bf16 v[108:111], v[156:159], v[188:191], v[108:111]
	v_mfma_f32_16x16x32_bf16 v[96:99], v[148:151], v[208:211], v[96:99]
	v_mfma_f32_16x16x32_bf16 v[92:95], v[156:159], v[208:211], v[92:95]
	v_mfma_f32_16x16x32_bf16 v[80:83], v[148:151], v[216:219], v[80:83]
	v_mfma_f32_16x16x32_bf16 v[76:79], v[156:159], v[216:219], v[76:79]
	v_mfma_f32_16x16x32_bf16 v[124:127], v[152:155], v[184:187], v[124:127]
	v_mfma_f32_16x16x32_bf16 v[128:131], v[160:163], v[184:187], v[128:131]
	v_mfma_f32_16x16x32_bf16 v[112:115], v[152:155], v[204:207], v[112:115]
	v_mfma_f32_16x16x32_bf16 v[108:111], v[160:163], v[204:207], v[108:111]
	v_mfma_f32_16x16x32_bf16 v[96:99], v[152:155], v[212:215], v[96:99]
	v_mfma_f32_16x16x32_bf16 v[92:95], v[160:163], v[212:215], v[92:95]
	v_mfma_f32_16x16x32_bf16 v[80:83], v[152:155], v[220:223], v[80:83]
	v_mfma_f32_16x16x32_bf16 v[76:79], v[160:163], v[220:223], v[76:79]
	s_setprio 0
	s_setprio 1
	v_mfma_f32_16x16x32_bf16 v[120:123], v[164:167], v[180:183], v[120:123]
	v_mfma_f32_16x16x32_bf16 v[116:119], v[172:175], v[180:183], v[116:119]
	v_mfma_f32_16x16x32_bf16 v[104:107], v[164:167], v[188:191], v[104:107]
	v_mfma_f32_16x16x32_bf16 v[100:103], v[172:175], v[188:191], v[100:103]
	v_mfma_f32_16x16x32_bf16 v[88:91], v[164:167], v[208:211], v[88:91]
	v_mfma_f32_16x16x32_bf16 v[84:87], v[172:175], v[208:211], v[84:87]
	v_mfma_f32_16x16x32_bf16 v[72:75], v[164:167], v[216:219], v[72:75]
	v_mfma_f32_16x16x32_bf16 v[68:71], v[172:175], v[216:219], v[68:71]
	v_mfma_f32_16x16x32_bf16 v[120:123], v[168:171], v[184:187], v[120:123]
	v_mfma_f32_16x16x32_bf16 v[116:119], v[176:179], v[184:187], v[116:119]
	v_mfma_f32_16x16x32_bf16 v[104:107], v[168:171], v[204:207], v[104:107]
	v_mfma_f32_16x16x32_bf16 v[100:103], v[176:179], v[204:207], v[100:103]
	v_mfma_f32_16x16x32_bf16 v[88:91], v[168:171], v[212:215], v[88:91]
	v_mfma_f32_16x16x32_bf16 v[84:87], v[176:179], v[212:215], v[84:87]
	v_mfma_f32_16x16x32_bf16 v[72:75], v[168:171], v[220:223], v[72:75]
	v_mfma_f32_16x16x32_bf16 v[68:71], v[176:179], v[220:223], v[68:71]
	s_setprio 0
	s_barrier
	s_add_i32 s58, s62, s30
	v_lshl_add_u64 v[192:193], s[60:61], 0, v[134:135]
	s_mov_b32 m0, s58
	ds_read_b128 v[180:183], v147 offset:16384
	ds_read_b128 v[184:187], v147 offset:17408
	ds_read_b128 v[188:191], v147 offset:18432
	ds_read_b128 v[204:207], v147 offset:19456
	ds_read_b128 v[208:211], v147 offset:20480
	ds_read_b128 v[212:215], v147 offset:21504
	ds_read_b128 v[216:219], v147 offset:22528
	ds_read_b128 v[220:223], v147 offset:23552
	global_load_lds_dwordx4 v[192:193], off
	s_add_i32 m0, s58, 0x2000
	s_add_u32 s58, s60, s8
	v_lshl_add_u64 v[196:197], s[60:61], 0, v[0:1]
	s_addc_u32 s59, s61, s9
	s_add_i32 s60, s63, s30
	global_load_lds_dwordx4 v[196:197], off
	v_lshl_add_u64 v[198:199], s[58:59], 0, v[134:135]
	s_mov_b32 m0, s60
	v_lshl_add_u64 v[200:201], s[58:59], 0, v[0:1]
	global_load_lds_dwordx4 v[198:199], off
	s_add_i32 m0, s60, 0x2000
	v_lshl_add_u64 v[202:203], s[24:25], 0, v[136:137]
	global_load_lds_dwordx4 v[200:201], off
	s_mov_b32 m0, s33
	v_lshl_add_u64 v[228:229], s[24:25], 0, v[132:133]
	global_load_lds_dwordx4 v[202:203], off
	s_mov_b32 m0, s34
	s_nop 0
	global_load_lds_dwordx4 v[228:229], off
	s_waitcnt vmcnt(8)
	s_waitcnt lgkmcnt(0)
	s_barrier
; #define PG8_STAGE(bufoff, gbase, voff) do { _Pragma("unroll") for (int _i = 0; _i < 2; ++_i) \
;         __builtin_amdgcn_global_load_lds((const unsigned*)((const char*)(gbase) + (voff)[_i]), (PG8_LAS unsigned*)(lds + (bufoff) + ldsw + _i * 8192), 16, 0, 0); } while (0)
; #define PG8_LDA(dst, b, h) do { _Pragma("unroll") for (int m = 0; m < 4; ++m) _Pragma("unroll") for (int k = 0; k < 2; ++k) dst[m][k] = *(const PG8_LAS bf16x8*)(lds + PG8_SA(b, h) + aoff + m * 2048 + k * 1024); } while (0)
; #define PG8_LDB(dst, b, h) do { _Pragma("unroll") for (int n = 0; n < 2; ++n) _Pragma("unroll") for (int k = 0; k < 2; ++k) dst[n][k] = *(const PG8_LAS bf16x8*)(lds + PG8_SB(b, h) + boff + n * 2048 + k * 1024); } while (0)
; #define PG8_MMA(ai, bj, At, Bt) do { __builtin_amdgcn_s_setprio(1); _Pragma("unroll") for (int m = 0; m < 4; ++m) _Pragma("unroll") for (int n = 0; n < 2; ++n) _Pragma("unroll") for (int k = 0; k < 2; ++k) \
;         acc[ai][bj][m][n] = __builtin_amdgcn_mfma_f32_16x16x32_bf16(Bt[n][k], At[m][k], acc[ai][bj][m][n], 0, 0, 0); __builtin_amdgcn_s_setprio(0); } while (0)
; #define PG8_WAIT_V(n) asm volatile("s_waitcnt vmcnt(" #n ")" ::: "memory")
; #define PG8_WAIT_L(n) asm volatile("s_waitcnt lgkmcnt(" #n ")" ::: "memory")
; #define PG8_BAR __builtin_amdgcn_s_barrier()
; #define PG8_SCHED __builtin_amdgcn_sched_barrier(0)
; template <class Epi, class Sched, bool ALIGN_EPI = false, bool SP2 = false>
; __device__ __forceinline__ void gemm_phase(PG8_LAS unsigned char* lds, const Gemm g, const Sched& S, const Epi& E, int tid_in) {
;     ...
;             PG8_WAIT_V(8); PG8_WAIT_L(0); PG8_BAR; PG8_MMA(1, 0, At, B0); PG8_MMA(1, 1, At, B1); PG8_BAR; PG8_SCHED;
;             PG8_LDB(B0, 1, 0); PG8_LDB(B1, 1, 1); PG8_SCHED; PG8_LDA(At, 1, 0); PG8_STAGE(PG8_SA(0, 1), a2 + hsA, voffA);
;             PG8_WAIT_V(8); PG8_WAIT_L(0); PG8_BAR; PG8_MMA(0, 0, At, B0); PG8_MMA(0, 1, At, B1); PG8_BAR; PG8_SCHED;
	s_setprio 1
	v_mfma_f32_16x16x32_bf16 v[64:67], v[148:151], v[180:183], v[64:67]
	v_mfma_f32_16x16x32_bf16 v[60:63], v[156:159], v[180:183], v[60:63]
	v_mfma_f32_16x16x32_bf16 v[48:51], v[148:151], v[188:191], v[48:51]
	v_mfma_f32_16x16x32_bf16 v[44:47], v[156:159], v[188:191], v[44:47]
	v_mfma_f32_16x16x32_bf16 v[32:35], v[148:151], v[208:211], v[32:35]
	v_mfma_f32_16x16x32_bf16 v[28:31], v[156:159], v[208:211], v[28:31]
	v_mfma_f32_16x16x32_bf16 v[16:19], v[148:151], v[216:219], v[16:19]
	v_mfma_f32_16x16x32_bf16 v[12:15], v[156:159], v[216:219], v[12:15]
	v_mfma_f32_16x16x32_bf16 v[64:67], v[152:155], v[184:187], v[64:67]
	v_mfma_f32_16x16x32_bf16 v[60:63], v[160:163], v[184:187], v[60:63]
	v_mfma_f32_16x16x32_bf16 v[48:51], v[152:155], v[204:207], v[48:51]
	v_mfma_f32_16x16x32_bf16 v[44:47], v[160:163], v[204:207], v[44:47]
	v_mfma_f32_16x16x32_bf16 v[32:35], v[152:155], v[212:215], v[32:35]
	v_mfma_f32_16x16x32_bf16 v[28:31], v[160:163], v[212:215], v[28:31]
	v_mfma_f32_16x16x32_bf16 v[16:19], v[152:155], v[220:223], v[16:19]
	v_mfma_f32_16x16x32_bf16 v[12:15], v[160:163], v[220:223], v[12:15]
	s_setprio 0
	s_setprio 1
	v_mfma_f32_16x16x32_bf16 v[56:59], v[164:167], v[180:183], v[56:59]
	v_mfma_f32_16x16x32_bf16 v[52:55], v[172:175], v[180:183], v[52:55]
	v_mfma_f32_16x16x32_bf16 v[40:43], v[164:167], v[188:191], v[40:43]
	v_mfma_f32_16x16x32_bf16 v[36:39], v[172:175], v[188:191], v[36:39]
	v_mfma_f32_16x16x32_bf16 v[24:27], v[164:167], v[208:211], v[24:27]
	v_mfma_f32_16x16x32_bf16 v[20:23], v[172:175], v[208:211], v[20:23]
	v_mfma_f32_16x16x32_bf16 v[8:11], v[164:167], v[216:219], v[8:11]
	v_mfma_f32_16x16x32_bf16 v[4:7], v[172:175], v[216:219], v[4:7]
	v_mfma_f32_16x16x32_bf16 v[56:59], v[168:171], v[184:187], v[56:59]
	v_mfma_f32_16x16x32_bf16 v[52:55], v[176:179], v[184:187], v[52:55]
	v_mfma_f32_16x16x32_bf16 v[40:43], v[168:171], v[204:207], v[40:43]
	v_mfma_f32_16x16x32_bf16 v[36:39], v[176:179], v[204:207], v[36:39]
	v_mfma_f32_16x16x32_bf16 v[24:27], v[168:171], v[212:215], v[24:27]
	v_mfma_f32_16x16x32_bf16 v[20:23], v[176:179], v[212:215], v[20:23]
	v_mfma_f32_16x16x32_bf16 v[8:11], v[168:171], v[220:223], v[8:11]
	v_mfma_f32_16x16x32_bf16 v[4:7], v[176:179], v[220:223], v[4:7]
	s_setprio 0
	s_barrier
	s_add_i32 s58, 0, 0x18000
	s_add_i32 s59, 0, 0x1c000
	v_add_u32_e32 v160, s58, v3
	v_add_u32_e32 v176, s59, v3
	ds_read_b128 v[148:151], v160
	ds_read_b128 v[152:155], v160 offset:1024
	ds_read_b128 v[156:159], v160 offset:2048
	ds_read_b128 v[160:163], v160 offset:3072
	ds_read_b128 v[164:167], v176
	ds_read_b128 v[168:171], v176 offset:1024
	ds_read_b128 v[172:175], v176 offset:2048
	ds_read_b128 v[176:179], v176 offset:3072
	s_add_u32 s24, s24, s6
	s_addc_u32 s25, s25, s7
	s_mov_b32 m0, s35
	v_lshl_add_u64 v[230:231], s[24:25], 0, v[136:137]
	ds_read_b128 v[180:183], v147 offset:32768
	ds_read_b128 v[184:187], v147 offset:33792
	ds_read_b128 v[188:191], v147 offset:34816
	ds_read_b128 v[204:207], v147 offset:35840
	ds_read_b128 v[208:211], v147 offset:36864
	ds_read_b128 v[212:215], v147 offset:37888
	ds_read_b128 v[216:219], v147 offset:38912
	ds_read_b128 v[220:223], v147 offset:39936
	global_load_lds_dwordx4 v[230:231], off
	v_lshl_add_u64 v[230:231], s[24:25], 0, v[132:133]
	s_mov_b32 m0, s36
	s_nop 0
	global_load_lds_dwordx4 v[230:231], off
	s_waitcnt vmcnt(8)
	s_waitcnt lgkmcnt(0)
	s_barrier
	s_setprio 1
	v_mfma_f32_16x16x32_bf16 v[124:127], v[148:151], v[180:183], v[124:127]
	v_mfma_f32_16x16x32_bf16 v[128:131], v[156:159], v[180:183], v[128:131]
	v_mfma_f32_16x16x32_bf16 v[112:115], v[148:151], v[188:191], v[112:115]
	v_mfma_f32_16x16x32_bf16 v[108:111], v[156:159], v[188:191], v[108:111]
	v_mfma_f32_16x16x32_bf16 v[96:99], v[148:151], v[208:211], v[96:99]
	v_mfma_f32_16x16x32_bf16 v[92:95], v[156:159], v[208:211], v[92:95]
	v_mfma_f32_16x16x32_bf16 v[80:83], v[148:151], v[216:219], v[80:83]
	v_mfma_f32_16x16x32_bf16 v[76:79], v[156:159], v[216:219], v[76:79]
	v_mfma_f32_16x16x32_bf16 v[124:127], v[152:155], v[184:187], v[124:127]
	v_mfma_f32_16x16x32_bf16 v[128:131], v[160:163], v[184:187], v[128:131]
	v_mfma_f32_16x16x32_bf16 v[112:115], v[152:155], v[204:207], v[112:115]
	v_mfma_f32_16x16x32_bf16 v[108:111], v[160:163], v[204:207], v[108:111]
	v_mfma_f32_16x16x32_bf16 v[96:99], v[152:155], v[212:215], v[96:99]
	v_mfma_f32_16x16x32_bf16 v[92:95], v[160:163], v[212:215], v[92:95]
	v_mfma_f32_16x16x32_bf16 v[80:83], v[152:155], v[220:223], v[80:83]
	v_mfma_f32_16x16x32_bf16 v[76:79], v[160:163], v[220:223], v[76:79]
	s_setprio 0
	s_setprio 1
	v_mfma_f32_16x16x32_bf16 v[120:123], v[164:167], v[180:183], v[120:123]
	v_mfma_f32_16x16x32_bf16 v[116:119], v[172:175], v[180:183], v[116:119]
	v_mfma_f32_16x16x32_bf16 v[104:107], v[164:167], v[188:191], v[104:107]
	v_mfma_f32_16x16x32_bf16 v[100:103], v[172:175], v[188:191], v[100:103]
	v_mfma_f32_16x16x32_bf16 v[88:91], v[164:167], v[208:211], v[88:91]
	v_mfma_f32_16x16x32_bf16 v[84:87], v[172:175], v[208:211], v[84:87]
	v_mfma_f32_16x16x32_bf16 v[72:75], v[164:167], v[216:219], v[72:75]
	v_mfma_f32_16x16x32_bf16 v[68:71], v[172:175], v[216:219], v[68:71]
	v_mfma_f32_16x16x32_bf16 v[120:123], v[168:171], v[184:187], v[120:123]
	v_mfma_f32_16x16x32_bf16 v[116:119], v[176:179], v[184:187], v[116:119]
	v_mfma_f32_16x16x32_bf16 v[104:107], v[168:171], v[204:207], v[104:107]
	v_mfma_f32_16x16x32_bf16 v[100:103], v[176:179], v[204:207], v[100:103]
	v_mfma_f32_16x16x32_bf16 v[88:91], v[168:171], v[212:215], v[88:91]
	v_mfma_f32_16x16x32_bf16 v[84:87], v[176:179], v[212:215], v[84:87]
	v_mfma_f32_16x16x32_bf16 v[72:75], v[168:171], v[220:223], v[72:75]
	v_mfma_f32_16x16x32_bf16 v[68:71], v[176:179], v[220:223], v[68:71]
	s_setprio 0
	s_barrier
; #define PG8_STAGE(bufoff, gbase, voff) do { _Pragma("unroll") for (int _i = 0; _i < 2; ++_i) \
;         __builtin_amdgcn_global_load_lds((const unsigned*)((const char*)(gbase) + (voff)[_i]), (PG8_LAS unsigned*)(lds + (bufoff) + ldsw + _i * 8192), 16, 0, 0); } while (0)
; #define PG8_LDA(dst, b, h) do { _Pragma("unroll") for (int m = 0; m < 4; ++m) _Pragma("unroll") for (int k = 0; k < 2; ++k) dst[m][k] = *(const PG8_LAS bf16x8*)(lds + PG8_SA(b, h) + aoff + m * 2048 + k * 1024); } while (0)
; #define PG8_MMA(ai, bj, At, Bt) do { __builtin_amdgcn_s_setprio(1); _Pragma("unroll") for (int m = 0; m < 4; ++m) _Pragma("unroll") for (int n = 0; n < 2; ++n) _Pragma("unroll") for (int k = 0; k < 2; ++k) \
;         acc[ai][bj][m][n] = __builtin_amdgcn_mfma_f32_16x16x32_bf16(Bt[n][k], At[m][k], acc[ai][bj][m][n], 0, 0, 0); __builtin_amdgcn_s_setprio(0); } while (0)
; #define PG8_WAIT_V(n) asm volatile("s_waitcnt vmcnt(" #n ")" ::: "memory")
; #define PG8_WAIT_L(n) asm volatile("s_waitcnt lgkmcnt(" #n ")" ::: "memory")
; #define PG8_BAR __builtin_amdgcn_s_barrier()
; #define PG8_SCHED __builtin_amdgcn_sched_barrier(0)
; template <class Epi, class Sched, bool ALIGN_EPI = false, bool SP2 = false>
; __device__ __forceinline__ void gemm_phase(PG8_LAS unsigned char* lds, const Gemm g, const Sched& S, const Epi& E, int tid_in) {
;     ...
;         for (int t = 0; t < nt; t += 2) {
;     ...
;             PG8_LDA(At, 1, 1); PG8_STAGE(PG8_SB(1, 0), b3, voffB); PG8_STAGE(PG8_SB(1, 1), b3 + hsB, voffB); PG8_STAGE(PG8_SA(1, 0), a3, voffA);
;             PG8_WAIT_V(8); PG8_WAIT_L(0); PG8_BAR; PG8_MMA(1, 0, At, B0); PG8_MMA(1, 1, At, B1); PG8_BAR; PG8_SCHED;
	s_add_i32 s24, s58, s30
	v_lshl_add_u64 v[192:193], v[192:193], 0, s[80:81]
	s_mov_b32 m0, s24
	ds_read_b128 v[180:183], v147 offset:49152
	ds_read_b128 v[184:187], v147 offset:50176
	ds_read_b128 v[188:191], v147 offset:51200
	ds_read_b128 v[204:207], v147 offset:52224
	ds_read_b128 v[208:211], v147 offset:53248
	ds_read_b128 v[212:215], v147 offset:54272
	ds_read_b128 v[216:219], v147 offset:55296
	ds_read_b128 v[220:223], v147 offset:56320
	global_load_lds_dwordx4 v[192:193], off
	v_lshl_add_u64 v[192:193], v[196:197], 0, s[80:81]
	s_add_i32 m0, s24, 0x2000
	s_add_i32 s24, s59, s30
	global_load_lds_dwordx4 v[192:193], off
	v_lshl_add_u64 v[192:193], v[198:199], 0, s[80:81]
	s_mov_b32 m0, s24
	s_nop 0
	global_load_lds_dwordx4 v[192:193], off
	v_lshl_add_u64 v[192:193], v[200:201], 0, s[80:81]
	s_add_i32 m0, s24, 0x2000
	s_nop 0
	global_load_lds_dwordx4 v[192:193], off
	v_lshl_add_u64 v[192:193], v[202:203], 0, s[80:81]
	s_mov_b32 m0, s39
	s_nop 0
	global_load_lds_dwordx4 v[192:193], off
	v_lshl_add_u64 v[192:193], v[228:229], 0, s[80:81]
	s_mov_b32 m0, s40
	s_nop 0
	global_load_lds_dwordx4 v[192:193], off
	s_waitcnt vmcnt(8)
	s_waitcnt lgkmcnt(0)
	s_barrier
	s_setprio 1
	v_mfma_f32_16x16x32_bf16 v[64:67], v[148:151], v[180:183], v[64:67]
	v_mfma_f32_16x16x32_bf16 v[60:63], v[156:159], v[180:183], v[60:63]
	v_mfma_f32_16x16x32_bf16 v[48:51], v[148:151], v[188:191], v[48:51]
	v_mfma_f32_16x16x32_bf16 v[44:47], v[156:159], v[188:191], v[44:47]
	v_mfma_f32_16x16x32_bf16 v[32:35], v[148:151], v[208:211], v[32:35]
	v_mfma_f32_16x16x32_bf16 v[28:31], v[156:159], v[208:211], v[28:31]
	v_mfma_f32_16x16x32_bf16 v[16:19], v[148:151], v[216:219], v[16:19]
	v_mfma_f32_16x16x32_bf16 v[12:15], v[156:159], v[216:219], v[12:15]
	v_mfma_f32_16x16x32_bf16 v[64:67], v[152:155], v[184:187], v[64:67]
	v_mfma_f32_16x16x32_bf16 v[60:63], v[160:163], v[184:187], v[60:63]
	v_mfma_f32_16x16x32_bf16 v[48:51], v[152:155], v[204:207], v[48:51]
	v_mfma_f32_16x16x32_bf16 v[44:47], v[160:163], v[204:207], v[44:47]
	v_mfma_f32_16x16x32_bf16 v[32:35], v[152:155], v[212:215], v[32:35]
	v_mfma_f32_16x16x32_bf16 v[28:31], v[160:163], v[212:215], v[28:31]
	v_mfma_f32_16x16x32_bf16 v[16:19], v[152:155], v[220:223], v[16:19]
	v_mfma_f32_16x16x32_bf16 v[12:15], v[160:163], v[220:223], v[12:15]
	s_setprio 0
	s_setprio 1
	v_mfma_f32_16x16x32_bf16 v[56:59], v[164:167], v[180:183], v[56:59]
	v_mfma_f32_16x16x32_bf16 v[52:55], v[172:175], v[180:183], v[52:55]
	v_mfma_f32_16x16x32_bf16 v[40:43], v[164:167], v[188:191], v[40:43]
	v_mfma_f32_16x16x32_bf16 v[36:39], v[172:175], v[188:191], v[36:39]
	v_mfma_f32_16x16x32_bf16 v[24:27], v[164:167], v[208:211], v[24:27]
	v_mfma_f32_16x16x32_bf16 v[20:23], v[172:175], v[208:211], v[20:23]
	v_mfma_f32_16x16x32_bf16 v[8:11], v[164:167], v[216:219], v[8:11]
	v_mfma_f32_16x16x32_bf16 v[4:7], v[172:175], v[216:219], v[4:7]
	v_mfma_f32_16x16x32_bf16 v[56:59], v[168:171], v[184:187], v[56:59]
	v_mfma_f32_16x16x32_bf16 v[52:55], v[176:179], v[184:187], v[52:55]
	v_mfma_f32_16x16x32_bf16 v[40:43], v[168:171], v[204:207], v[40:43]
	v_mfma_f32_16x16x32_bf16 v[36:39], v[176:179], v[204:207], v[36:39]
	v_mfma_f32_16x16x32_bf16 v[24:27], v[168:171], v[212:215], v[24:27]
	v_mfma_f32_16x16x32_bf16 v[20:23], v[176:179], v[212:215], v[20:23]
	v_mfma_f32_16x16x32_bf16 v[8:11], v[168:171], v[220:223], v[8:11]
	v_mfma_f32_16x16x32_bf16 v[4:7], v[176:179], v[220:223], v[4:7]
	s_setprio 0
	s_barrier
	s_add_i32 s24, s55, 2
	s_add_u32 s53, s53, 0x100
	s_addc_u32 s54, s54, 0
	s_add_u32 s22, s22, 0x100
	s_addc_u32 s23, s23, 0
	s_cmp_ge_i32 s55, s46
	s_mov_b32 s55, s24
	s_cbranch_scc0 .LBB0_1362
